# stages 0 and 2 of the next prompt item's indexer sweep DMA'd into free LDS ring slots at the start of the sparse QK path; indexer prologue skips them
# baseline (speedup 1.0000x reference)
.LBB0_515:
	s_or_b64 exec, exec, s[0:1]
	s_add_u32 s3, s28, 0xda00000
	s_addc_u32 s23, s29, 0
	s_add_u32 s36, s28, 0xfb00000
	s_mul_i32 s4, s17, s12
	s_addc_u32 s37, s29, 0
	s_sub_i32 s0, s22, s2
	s_sub_i32 s4, s16, s4
	s_add_i32 s1, s0, 0xfff
	s_sub_i32 s5, s4, s12
	s_cmp_ge_u32 s4, s12
	s_cselect_b32 s4, s5, s4
	s_sub_i32 s5, s4, s12
	s_cmp_ge_u32 s4, s12
	s_cselect_b32 s4, s5, s4
	s_xor_b32 s4, s4, s15
	s_sub_i32 s4, s4, s15
	s_add_i32 s33, s4, 0x1000
	s_add_u32 s60, s28, 0x1be80000
	s_addc_u32 s61, s29, 0
	s_add_u32 s38, s28, 0x1c290000
	s_addc_u32 s39, s29, 0
	s_add_u32 s62, s28, 0x9800000
	s_addc_u32 s63, s29, 0
	s_sub_i32 s0, 0xfffff001, s0
	s_max_i32 s0, s1, s0
	s_ashr_i32 s5, s1, 31
	s_mul_hi_u32 s1, s0, s14
	s_mul_i32 s6, s1, s12
	s_sub_i32 s0, s0, s6
	s_xor_b32 s5, s5, s13
	s_add_i32 s6, s1, 1
	s_sub_i32 s7, s0, s12
	s_cmp_ge_u32 s0, s12
	s_cselect_b32 s1, s6, s1
	s_cselect_b32 s0, s7, s0
	s_add_i32 s6, s1, 1
	s_cmp_ge_u32 s0, s12
	s_cselect_b32 s0, s6, s1
	s_xor_b32 s0, s0, s5
	s_sub_i32 s64, s0, s5
	s_cmpk_lt_i32 s4, 0x80
	v_readfirstlane_b32 s1, v194
	s_cselect_b64 s[40:41], -1, 0
	s_sub_i32 s0, s22, s4
	s_lshr_b32 s4, s1, 6
	s_lshr_b32 s65, s1, 7
	s_bfe_u32 s1, s1, 0x10006
	s_lshl_b32 s5, s65, 10
	s_lshl_b32 s4, s4, 12
	s_addk_i32 s0, 0x7f
	s_add_i32 s66, s5, 0
	s_add_i32 s67, s4, 0
	s_lshl_b32 s68, s1, 9
	s_lshl_b32 s4, s1, 8
	s_add_u32 s4, s28, s4
	s_addc_u32 s5, s29, 0
	v_and_b32_e32 v0, 0x60, v211
	v_add_u32_e32 v1, -1, v211
	s_add_u32 s44, s4, 0x19e00000
	v_add_u32_e32 v2, -2, v211
	v_cmp_lt_i32_e32 vcc, v1, v0
	s_addc_u32 s45, s5, 0
	v_add_u32_e32 v3, -4, v211
	v_cndmask_b32_e32 v6, v1, v211, vcc
	v_cmp_lt_i32_e32 vcc, v2, v0
	s_add_u32 s69, s4, 0x1ae40000
	v_add_u32_e32 v4, -8, v211
	v_lshlrev_b32_e32 v111, 2, v6
	v_cndmask_b32_e32 v6, v2, v211, vcc
	v_cmp_lt_i32_e32 vcc, v3, v0
	s_addc_u32 s70, s5, 0
	v_add_u32_e32 v5, -16, v211
	v_lshlrev_b32_e32 v113, 2, v6
	v_cndmask_b32_e32 v6, v3, v211, vcc
	v_cmp_lt_i32_e32 vcc, v4, v0
	s_ashr_i32 s4, s0, 31
	s_abs_i32 s0, s0
	v_lshlrev_b32_e32 v114, 2, v6
	v_cndmask_b32_e32 v6, v4, v211, vcc
	v_cmp_lt_i32_e32 vcc, v5, v0
	s_mul_hi_u32 s5, s0, s14
	s_mul_i32 s6, s5, s12
	v_cndmask_b32_e32 v0, v5, v211, vcc
	v_cmp_lt_i32_e32 vcc, v1, v212
	v_lshlrev_b32_e32 v116, 2, v0
	s_sub_i32 s0, s0, s6
	v_cndmask_b32_e32 v0, v1, v211, vcc
	v_cmp_lt_i32_e32 vcc, v2, v212
	v_lshlrev_b32_e32 v117, 2, v0
	s_xor_b32 s4, s4, s13
	v_cndmask_b32_e32 v0, v2, v211, vcc
	v_cmp_lt_i32_e32 vcc, v3, v212
	s_add_i32 s6, s5, 1
	s_sub_i32 s7, s0, s12
	v_lshlrev_b32_e32 v118, 2, v0
	v_cndmask_b32_e32 v0, v3, v211, vcc
	v_cmp_lt_i32_e32 vcc, v4, v212
	s_cmp_ge_u32 s0, s12
	v_lshlrev_b32_e32 v119, 2, v0
	v_cndmask_b32_e32 v0, v4, v211, vcc
	v_cmp_lt_i32_e32 vcc, v5, v212
	s_cselect_b32 s5, s6, s5
	v_lshlrev_b32_e32 v120, 2, v0
	v_cndmask_b32_e32 v0, v5, v211, vcc
	s_cselect_b32 s0, s7, s0
	s_add_i32 s6, s5, 1
	v_lshlrev_b32_e32 v121, 2, v0
	v_subrev_u32_e32 v0, 32, v211
	s_cmp_ge_u32 s0, s12
	v_cmp_lt_i32_e32 vcc, v0, v212
	s_cselect_b32 s0, s6, s5
	s_mulk_i32 s1, 0xc00
	v_cndmask_b32_e32 v0, v0, v211, vcc
	s_xor_b32 s0, s0, s4
	s_mov_b32 s43, 0
	v_lshlrev_b32_e32 v115, 2, v6
	v_lshlrev_b32_e32 v122, 2, v0
	s_sub_i32 s71, s0, s4
	s_add_i32 s72, s1, 0
	s_add_i32 s73, s67, 0xa900
	s_movk_i32 s74, 0x100
	v_mov_b32_e32 v103, 0
	s_mov_b64 s[46:47], 0x400
	s_mov_b64 s[50:51], 0x800
	s_mov_b64 s[56:57], 0xc00
	s_mov_b64 s[58:59], 0x8000
	s_movk_i32 s75, 0x801
	s_movk_i32 s76, 0xff
	v_mov_b32_e32 v123, 0x7fffff
	v_mov_b32_e32 v124, 0x10000
	v_mov_b32_e32 v125, 0xf149f2ca
	s_mov_b32 s101, 0
	s_mov_b32 s77, 0
	s_waitcnt lgkmcnt(0)
	s_barrier
	s_branch .LBB0_517

.LBB0_532:
	v_mov_b32_e32 v129, v194
	v_readfirstlane_b32 s83, v194
	v_and_b32_e32 v180, 31, v194
	v_bfe_u32 v131, v194, 5, 1
	v_and_b32_e32 v243, 63, v194
	s_ashr_i32 s84, s83, 6
	s_lshl_b32 s0, s84, 5
	v_or_b32_e32 v130, s0, v180
	v_lshlrev_b32_e32 v243, 2, v243
	s_lshl_b32 s0, s2, 17
	s_lshl_b32 s1, s84, 8
	s_add_u32 s0, s0, s1
	s_add_u32 s8, s28, s0
	s_addc_u32 s9, s29, 0
	s_lshl_b32 s21, s84, 12
	s_cmp_lg_u32 s82, 0
	s_cbranch_scc1 .Lix_reload
	s_mov_b32 s100, 0
	v_bfe_u32 v0, v194, 2, 1
	v_lshrrev_b32_e32 v1, 1, v194
	v_and_b32_e32 v1, 12, v1
	v_and_b32_e32 v228, 3, v194
	v_or_b32_e32 v1, v1, v228
	v_add_u32_e32 v0, s34, v0
	v_lshlrev_b32_e32 v0, 11, v0
	v_lshl_add_u32 v0, v1, 7, v0
	v_lshl_add_u32 v0, v131, 4, v0
	v_add_u32_e32 v1, 0x1000, v0
	global_load_dwordx4 v[70:73], v0, s[36:37]
	global_load_dwordx4 v[74:77], v0, s[36:37] offset:32
	global_load_dwordx4 v[78:81], v0, s[36:37] offset:64
	global_load_dwordx4 v[82:85], v0, s[36:37] offset:96
	global_load_dwordx4 v[86:89], v1, s[36:37]
	global_load_dwordx4 v[90:93], v1, s[36:37] offset:32
	global_load_dwordx4 v[94:97], v1, s[36:37] offset:64
	global_load_dwordx4 v[98:101], v1, s[36:37] offset:96
	v_add_u32_e32 v228, s34, v131
	v_lshlrev_b32_e32 v228, 6, v228
	global_load_dwordx4 v[22:25], v228, s[38:39]
	global_load_dwordx4 v[26:29], v228, s[38:39] offset:16
	global_load_dwordx4 v[30:33], v228, s[38:39] offset:32
	global_load_dwordx4 v[34:37], v228, s[38:39] offset:48
	global_load_dwordx2 v[244:245], v228, s[38:39] offset:128
	global_load_dwordx2 v[246:247], v228, s[38:39] offset:136
	global_load_dwordx2 v[248:249], v228, s[38:39] offset:144
	global_load_dwordx2 v[250:251], v228, s[38:39] offset:152
	global_load_dwordx2 v[252:253], v228, s[38:39] offset:160
	global_load_dwordx2 v[254:255], v228, s[38:39] offset:168
	global_load_dwordx2 v[200:201], v228, s[38:39] offset:176
	global_load_dwordx2 v[202:203], v228, s[38:39] offset:184
	v_lshrrev_b32_e32 v0, 2, v243
	v_lshrrev_b32_e32 v1, 3, v0
	v_lshrrev_b32_e32 v228, 4, v0
	v_and_b32_e32 v229, 7, v0
	v_xor_b32_e32 v228, v229, v228
	v_xor_b32_e32 v229, 4, v228
	s_lshl_b32 s0, s84, 12
	v_lshl_add_u32 v1, v1, 7, s0
	v_lshl_add_u32 v102, v228, 4, v1
	v_lshl_add_u32 v110, v229, 4, v1
	v_add_u32_e32 v110, 0x400, v110
	v_add_u32_e32 v112, 0x800, v102
	v_add_u32_e32 v193, 0x800, v110
	v_lshlrev_b32_e32 v0, 7, v130
	v_bfe_u32 v1, v180, 1, 3
	v_or_b32_e32 v228, 0, v131
	v_xor_b32_e32 v228, v228, v1
	v_lshl_add_u32 v5, v228, 4, v0
	v_or_b32_e32 v228, 2, v131
	v_xor_b32_e32 v228, v228, v1
	v_lshl_add_u32 v52, v228, 4, v0
	v_or_b32_e32 v228, 4, v131
	v_xor_b32_e32 v228, v228, v1
	v_lshl_add_u32 v55, v228, 4, v0
	v_or_b32_e32 v228, 6, v131
	v_xor_b32_e32 v228, v228, v1
	v_lshl_add_u32 v56, v228, 4, v0
	s_mov_b32 s6, s14
	s_mov_b32 s7, s15
	s_add_i32 s10, s0, 10496
	s_sub_i32 s11, s35, s84
	s_cmp_eq_u32 s101, 1
	s_cbranch_scc0 .Lix_fullpro
	s_cmp_eq_u32 s42, 0
	s_cbranch_scc0 .Lix_fullpro
	s_add_u32 s6, s6, 0x8000
	s_addc_u32 s7, s7, 0
	s_add_i32 m0, s10, 32768
	s_nop 0
	global_load_lds_dwordx4 v102, s[6:7]
	s_add_i32 m0, s10, 33792
	s_nop 0
	global_load_lds_dwordx4 v110, s[6:7]
	s_add_i32 m0, s10, 34816
	s_nop 0
	global_load_lds_dwordx4 v112, s[6:7]
	s_add_i32 m0, s10, 35840
	s_nop 0
	global_load_lds_dwordx4 v193, s[6:7]
	s_add_u32 s6, s6, 0x8000
	s_addc_u32 s7, s7, 0
	s_add_u32 s6, s6, 0x8000
	s_addc_u32 s7, s7, 0
	s_branch .Lix_projoin
.Lix_fullpro:
	s_add_i32 m0, s10, 0
	s_nop 0
	global_load_lds_dwordx4 v102, s[6:7]
	s_add_i32 m0, s10, 1024
	s_nop 0
	global_load_lds_dwordx4 v110, s[6:7]
	s_add_i32 m0, s10, 2048
	s_nop 0
	global_load_lds_dwordx4 v112, s[6:7]
	s_add_i32 m0, s10, 3072
	s_nop 0
	global_load_lds_dwordx4 v193, s[6:7]
	s_add_u32 s6, s6, 0x8000
	s_addc_u32 s7, s7, 0
	s_add_i32 m0, s10, 32768
	s_nop 0
	global_load_lds_dwordx4 v102, s[6:7]
	s_add_i32 m0, s10, 33792
	s_nop 0
	global_load_lds_dwordx4 v110, s[6:7]
	s_add_i32 m0, s10, 34816
	s_nop 0
	global_load_lds_dwordx4 v112, s[6:7]
	s_add_i32 m0, s10, 35840
	s_nop 0
	global_load_lds_dwordx4 v193, s[6:7]
	s_add_u32 s6, s6, 0x8000
	s_addc_u32 s7, s7, 0
	s_add_i32 m0, s10, 65536
	s_nop 0
	global_load_lds_dwordx4 v102, s[6:7]
	s_add_i32 m0, s10, 66560
	s_nop 0
	global_load_lds_dwordx4 v110, s[6:7]
	s_add_i32 m0, s10, 67584
	s_nop 0
	global_load_lds_dwordx4 v112, s[6:7]
	s_add_i32 m0, s10, 68608
	s_nop 0
	global_load_lds_dwordx4 v193, s[6:7]
	s_add_u32 s6, s6, 0x8000
	s_addc_u32 s7, s7, 0
.Lix_projoin:
	s_mov_b32 s101, 0
	s_waitcnt vmcnt(4)
	ds_read_b128 v[38:41], v5 offset:10496
	ds_read_b128 v[42:45], v52 offset:10496
	ds_read_b128 v[46:49], v55 offset:10496
	ds_read_b128 v[196:199], v56 offset:10496
	s_waitcnt lgkmcnt(3)
	v_mfma_f32_32x32x16_bf16 v[212:227], v[70:73], v[38:41], 0
	s_add_i32 m0, s10, 98304
	s_nop 0
	global_load_lds_dwordx4 v102, s[6:7]
	s_waitcnt lgkmcnt(2)
	v_mfma_f32_32x32x16_bf16 v[212:227], v[74:77], v[42:45], v[212:227]
	s_add_i32 m0, s10, 99328
	s_nop 0
	global_load_lds_dwordx4 v110, s[6:7]
	s_waitcnt lgkmcnt(1)
	v_mfma_f32_32x32x16_bf16 v[212:227], v[78:81], v[46:49], v[212:227]
	s_add_i32 m0, s10, 100352
	s_nop 0
	global_load_lds_dwordx4 v112, s[6:7]
	s_waitcnt lgkmcnt(0)
	v_mfma_f32_32x32x16_bf16 v[212:227], v[82:85], v[196:199], v[212:227]
	s_add_i32 m0, s10, 101376
	s_nop 0
	global_load_lds_dwordx4 v193, s[6:7]
	s_add_u32 s6, s6, 0x8000
	s_addc_u32 s7, s7, 0
	v_mfma_f32_32x32x16_bf16 v[6:21], v[86:89], v[38:41], 0
	s_nop 7
	s_nop 2
	v_max_f32_e32 v108, 0, v212
	v_max_f32_e32 v109, 0, v213
	v_pk_mul_f32 v[0:1], v[22:23], v[108:109]
	v_max_f32_e32 v210, 0, v214
	v_max_f32_e32 v211, 0, v215
	v_pk_fma_f32 v[0:1], v[24:25], v[210:211], v[0:1]
	v_max_f32_e32 v108, 0, v216
	v_max_f32_e32 v109, 0, v217
	v_pk_fma_f32 v[0:1], v[26:27], v[108:109], v[0:1]
	v_mfma_f32_32x32x16_bf16 v[6:21], v[90:93], v[42:45], v[6:21]
	v_max_f32_e32 v210, 0, v218
	v_max_f32_e32 v211, 0, v219
	v_pk_fma_f32 v[0:1], v[28:29], v[210:211], v[0:1]
	v_max_f32_e32 v108, 0, v220
	v_max_f32_e32 v109, 0, v221
	v_pk_fma_f32 v[0:1], v[30:31], v[108:109], v[0:1]
	v_max_f32_e32 v210, 0, v222
	v_max_f32_e32 v211, 0, v223
	v_pk_fma_f32 v[0:1], v[32:33], v[210:211], v[0:1]
	v_mfma_f32_32x32x16_bf16 v[6:21], v[94:97], v[46:49], v[6:21]
	v_max_f32_e32 v108, 0, v224
	v_max_f32_e32 v109, 0, v225
	v_pk_fma_f32 v[0:1], v[34:35], v[108:109], v[0:1]
	v_max_f32_e32 v210, 0, v226
	v_max_f32_e32 v211, 0, v227
	v_pk_fma_f32 v[0:1], v[36:37], v[210:211], v[0:1]
	v_add_f32_e32 v0, v0, v1
	v_ashrrev_i32_e32 v1, 31, v0
	v_mfma_f32_32x32x16_bf16 v[6:21], v[98:101], v[196:199], v[6:21]
	s_waitcnt vmcnt(4)
	ds_read_b128 v[38:41], v5 offset:43264
	ds_read_b128 v[42:45], v52 offset:43264
	ds_read_b128 v[46:49], v55 offset:43264
	ds_read_b128 v[196:199], v56 offset:43264
	v_or_b32_e32 v1, 0x80000000, v1
	s_cmpk_gt_i32 s11, 0
	s_cselect_b64 vcc, -1, 0
	v_xor_b32_e32 v0, v1, v0
	v_cndmask_b32_e32 v133, v123, v0, vcc
	s_nop 3
	s_waitcnt lgkmcnt(3)
	v_mfma_f32_32x32x16_bf16 v[212:227], v[70:73], v[38:41], 0
	v_max_f32_e32 v108, 0, v6
	v_max_f32_e32 v109, 0, v7
	v_pk_mul_f32 v[50:51], v[244:245], v[108:109]
	v_max_f32_e32 v210, 0, v8
	v_max_f32_e32 v211, 0, v9
	v_pk_fma_f32 v[50:51], v[246:247], v[210:211], v[50:51]
	v_max_f32_e32 v108, 0, v10
	v_max_f32_e32 v109, 0, v11
	v_pk_fma_f32 v[50:51], v[248:249], v[108:109], v[50:51]
	s_waitcnt lgkmcnt(2)
	v_mfma_f32_32x32x16_bf16 v[212:227], v[74:77], v[42:45], v[212:227]
	v_max_f32_e32 v210, 0, v12
	v_max_f32_e32 v211, 0, v13
	v_pk_fma_f32 v[50:51], v[250:251], v[210:211], v[50:51]
	v_max_f32_e32 v108, 0, v14
	v_max_f32_e32 v109, 0, v15
	v_pk_fma_f32 v[50:51], v[252:253], v[108:109], v[50:51]
	v_max_f32_e32 v210, 0, v16
	v_max_f32_e32 v211, 0, v17
	v_pk_fma_f32 v[50:51], v[254:255], v[210:211], v[50:51]
	s_waitcnt lgkmcnt(1)
	v_mfma_f32_32x32x16_bf16 v[212:227], v[78:81], v[46:49], v[212:227]
	v_max_f32_e32 v108, 0, v18
	v_max_f32_e32 v109, 0, v19
	v_pk_fma_f32 v[50:51], v[200:201], v[108:109], v[50:51]
	v_max_f32_e32 v210, 0, v20
	v_max_f32_e32 v211, 0, v21
	v_pk_fma_f32 v[50:51], v[202:203], v[210:211], v[50:51]
	v_add_f32_e32 v50, v50, v51
	v_ashrrev_i32_e32 v51, 31, v50
	s_waitcnt lgkmcnt(0)
	v_mfma_f32_32x32x16_bf16 v[212:227], v[82:85], v[196:199], v[212:227]
	v_or_b32_e32 v51, 0x80000000, v51
	s_cmpk_gt_i32 s11, 0
	s_cselect_b64 vcc, -1, 0
	v_xor_b32_e32 v50, v51, v50
	v_cndmask_b32_e32 v50, v123, v50, vcc
	global_store_dword v243, v50, s[8:9]
	v_mfma_f32_32x32x16_bf16 v[6:21], v[86:89], v[38:41], 0
	s_add_i32 m0, s10, 0
	s_nop 0
	global_load_lds_dwordx4 v102, s[6:7]
	s_add_i32 m0, s10, 1024
	s_nop 0
	global_load_lds_dwordx4 v110, s[6:7]
	s_add_i32 m0, s10, 2048
	s_nop 0
	global_load_lds_dwordx4 v112, s[6:7]
	s_add_i32 m0, s10, 3072
	s_nop 0
	global_load_lds_dwordx4 v193, s[6:7]
	s_add_u32 s6, s6, 0x8000
	s_addc_u32 s7, s7, 0
	v_max_f32_e32 v108, 0, v212
	v_max_f32_e32 v109, 0, v213
	v_pk_mul_f32 v[0:1], v[22:23], v[108:109]
	v_max_f32_e32 v210, 0, v214
	v_max_f32_e32 v211, 0, v215
	v_pk_fma_f32 v[0:1], v[24:25], v[210:211], v[0:1]
	v_max_f32_e32 v108, 0, v216
	v_max_f32_e32 v109, 0, v217
	v_pk_fma_f32 v[0:1], v[26:27], v[108:109], v[0:1]
	v_mfma_f32_32x32x16_bf16 v[6:21], v[90:93], v[42:45], v[6:21]
	v_max_f32_e32 v210, 0, v218
	v_max_f32_e32 v211, 0, v219
	v_pk_fma_f32 v[0:1], v[28:29], v[210:211], v[0:1]
	v_max_f32_e32 v108, 0, v220
	v_max_f32_e32 v109, 0, v221
	v_pk_fma_f32 v[0:1], v[30:31], v[108:109], v[0:1]
	v_max_f32_e32 v210, 0, v222
	v_max_f32_e32 v211, 0, v223
	v_pk_fma_f32 v[0:1], v[32:33], v[210:211], v[0:1]
	v_mfma_f32_32x32x16_bf16 v[6:21], v[94:97], v[46:49], v[6:21]
	v_max_f32_e32 v108, 0, v224
	v_max_f32_e32 v109, 0, v225
	v_pk_fma_f32 v[0:1], v[34:35], v[108:109], v[0:1]
	v_max_f32_e32 v210, 0, v226
	v_max_f32_e32 v211, 0, v227
	v_pk_fma_f32 v[0:1], v[36:37], v[210:211], v[0:1]
	v_add_f32_e32 v0, v0, v1
	v_ashrrev_i32_e32 v1, 31, v0
	v_mfma_f32_32x32x16_bf16 v[6:21], v[98:101], v[196:199], v[6:21]
	s_waitcnt vmcnt(9)
	v_add_u32_e32 v228, 0x10000, v5
	ds_read_b128 v[38:41], v228 offset:10496
	v_add_u32_e32 v228, 0x10000, v52
	ds_read_b128 v[42:45], v228 offset:10496
	v_add_u32_e32 v228, 0x10000, v55
	ds_read_b128 v[46:49], v228 offset:10496
	v_add_u32_e32 v228, 0x10000, v56
	ds_read_b128 v[196:199], v228 offset:10496
	v_or_b32_e32 v1, 0x80000000, v1
	s_cmpk_gt_i32 s11, 8
	s_cselect_b64 vcc, -1, 0
	v_xor_b32_e32 v0, v1, v0
	v_cndmask_b32_e32 v132, v123, v0, vcc
	s_nop 3
	s_waitcnt lgkmcnt(3)
	v_mfma_f32_32x32x16_bf16 v[212:227], v[70:73], v[38:41], 0
	v_max_f32_e32 v108, 0, v6
	v_max_f32_e32 v109, 0, v7
	v_pk_mul_f32 v[50:51], v[244:245], v[108:109]
	v_max_f32_e32 v210, 0, v8
	v_max_f32_e32 v211, 0, v9
	v_pk_fma_f32 v[50:51], v[246:247], v[210:211], v[50:51]
	v_max_f32_e32 v108, 0, v10
	v_max_f32_e32 v109, 0, v11
	v_pk_fma_f32 v[50:51], v[248:249], v[108:109], v[50:51]
	s_waitcnt lgkmcnt(2)
	v_mfma_f32_32x32x16_bf16 v[212:227], v[74:77], v[42:45], v[212:227]
	v_max_f32_e32 v210, 0, v12
	v_max_f32_e32 v211, 0, v13
	v_pk_fma_f32 v[50:51], v[250:251], v[210:211], v[50:51]
	v_max_f32_e32 v108, 0, v14
	v_max_f32_e32 v109, 0, v15
	v_pk_fma_f32 v[50:51], v[252:253], v[108:109], v[50:51]
	v_max_f32_e32 v210, 0, v16
	v_max_f32_e32 v211, 0, v17
	v_pk_fma_f32 v[50:51], v[254:255], v[210:211], v[50:51]
	s_waitcnt lgkmcnt(1)
	v_mfma_f32_32x32x16_bf16 v[212:227], v[78:81], v[46:49], v[212:227]
	v_max_f32_e32 v108, 0, v18
	v_max_f32_e32 v109, 0, v19
	v_pk_fma_f32 v[50:51], v[200:201], v[108:109], v[50:51]
	v_max_f32_e32 v210, 0, v20
	v_max_f32_e32 v211, 0, v21
	v_pk_fma_f32 v[50:51], v[202:203], v[210:211], v[50:51]
	v_add_f32_e32 v50, v50, v51
	v_ashrrev_i32_e32 v51, 31, v50
	s_waitcnt lgkmcnt(0)
	v_mfma_f32_32x32x16_bf16 v[212:227], v[82:85], v[196:199], v[212:227]
	v_or_b32_e32 v51, 0x80000000, v51
	s_cmpk_gt_i32 s11, 8
	s_cselect_b64 vcc, -1, 0
	v_xor_b32_e32 v50, v51, v50
	v_cndmask_b32_e32 v50, v123, v50, vcc
	global_store_dword v243, v50, s[8:9] offset:2048
	s_add_u32 s8, s8, 0x1000
	s_addc_u32 s9, s9, 0
	v_mfma_f32_32x32x16_bf16 v[6:21], v[86:89], v[38:41], 0
	s_add_i32 m0, s10, 32768
	s_nop 0
	global_load_lds_dwordx4 v102, s[6:7]
	s_add_i32 m0, s10, 33792
	s_nop 0
	global_load_lds_dwordx4 v110, s[6:7]
	s_add_i32 m0, s10, 34816
	s_nop 0
	global_load_lds_dwordx4 v112, s[6:7]
	s_add_i32 m0, s10, 35840
	s_nop 0
	global_load_lds_dwordx4 v193, s[6:7]
	s_add_u32 s6, s6, 0x8000
	s_addc_u32 s7, s7, 0
	v_max_f32_e32 v108, 0, v212
	v_max_f32_e32 v109, 0, v213
	v_pk_mul_f32 v[0:1], v[22:23], v[108:109]
	v_max_f32_e32 v210, 0, v214
	v_max_f32_e32 v211, 0, v215
	v_pk_fma_f32 v[0:1], v[24:25], v[210:211], v[0:1]
	v_max_f32_e32 v108, 0, v216
	v_max_f32_e32 v109, 0, v217
	v_pk_fma_f32 v[0:1], v[26:27], v[108:109], v[0:1]
	v_mfma_f32_32x32x16_bf16 v[6:21], v[90:93], v[42:45], v[6:21]
	v_max_f32_e32 v210, 0, v218
	v_max_f32_e32 v211, 0, v219
	v_pk_fma_f32 v[0:1], v[28:29], v[210:211], v[0:1]
	v_max_f32_e32 v108, 0, v220
	v_max_f32_e32 v109, 0, v221
	v_pk_fma_f32 v[0:1], v[30:31], v[108:109], v[0:1]
	v_max_f32_e32 v210, 0, v222
	v_max_f32_e32 v211, 0, v223
	v_pk_fma_f32 v[0:1], v[32:33], v[210:211], v[0:1]
	v_mfma_f32_32x32x16_bf16 v[6:21], v[94:97], v[46:49], v[6:21]
	v_max_f32_e32 v108, 0, v224
	v_max_f32_e32 v109, 0, v225
	v_pk_fma_f32 v[0:1], v[34:35], v[108:109], v[0:1]
	v_max_f32_e32 v210, 0, v226
	v_max_f32_e32 v211, 0, v227
	v_pk_fma_f32 v[0:1], v[36:37], v[210:211], v[0:1]
	v_add_f32_e32 v0, v0, v1
	v_ashrrev_i32_e32 v1, 31, v0
	v_mfma_f32_32x32x16_bf16 v[6:21], v[98:101], v[196:199], v[6:21]
	s_waitcnt vmcnt(10)
	v_add_u32_e32 v228, 0x10000, v5
	ds_read_b128 v[38:41], v228 offset:43264
	v_add_u32_e32 v228, 0x10000, v52
	ds_read_b128 v[42:45], v228 offset:43264
	v_add_u32_e32 v228, 0x10000, v55
	ds_read_b128 v[46:49], v228 offset:43264
	v_add_u32_e32 v228, 0x10000, v56
	ds_read_b128 v[196:199], v228 offset:43264
	v_or_b32_e32 v1, 0x80000000, v1
	s_cmpk_gt_i32 s11, 16
	s_cselect_b64 vcc, -1, 0
	v_xor_b32_e32 v0, v1, v0
	v_cndmask_b32_e32 v135, v123, v0, vcc
	s_nop 3
	s_waitcnt lgkmcnt(3)
	v_mfma_f32_32x32x16_bf16 v[212:227], v[70:73], v[38:41], 0
	v_max_f32_e32 v108, 0, v6
	v_max_f32_e32 v109, 0, v7
	v_pk_mul_f32 v[50:51], v[244:245], v[108:109]
	v_max_f32_e32 v210, 0, v8
	v_max_f32_e32 v211, 0, v9
	v_pk_fma_f32 v[50:51], v[246:247], v[210:211], v[50:51]
	v_max_f32_e32 v108, 0, v10
	v_max_f32_e32 v109, 0, v11
	v_pk_fma_f32 v[50:51], v[248:249], v[108:109], v[50:51]
	s_waitcnt lgkmcnt(2)
	v_mfma_f32_32x32x16_bf16 v[212:227], v[74:77], v[42:45], v[212:227]
	v_max_f32_e32 v210, 0, v12
	v_max_f32_e32 v211, 0, v13
	v_pk_fma_f32 v[50:51], v[250:251], v[210:211], v[50:51]
	v_max_f32_e32 v108, 0, v14
	v_max_f32_e32 v109, 0, v15
	v_pk_fma_f32 v[50:51], v[252:253], v[108:109], v[50:51]
	v_max_f32_e32 v210, 0, v16
	v_max_f32_e32 v211, 0, v17
	v_pk_fma_f32 v[50:51], v[254:255], v[210:211], v[50:51]
	s_waitcnt lgkmcnt(1)
	v_mfma_f32_32x32x16_bf16 v[212:227], v[78:81], v[46:49], v[212:227]
	v_max_f32_e32 v108, 0, v18
	v_max_f32_e32 v109, 0, v19
	v_pk_fma_f32 v[50:51], v[200:201], v[108:109], v[50:51]
	v_max_f32_e32 v210, 0, v20
	v_max_f32_e32 v211, 0, v21
	v_pk_fma_f32 v[50:51], v[202:203], v[210:211], v[50:51]
	v_add_f32_e32 v50, v50, v51
	v_ashrrev_i32_e32 v51, 31, v50
	s_waitcnt lgkmcnt(0)
	v_mfma_f32_32x32x16_bf16 v[212:227], v[82:85], v[196:199], v[212:227]
	v_or_b32_e32 v51, 0x80000000, v51
	s_cmpk_gt_i32 s11, 16
	s_cselect_b64 vcc, -1, 0
	v_xor_b32_e32 v50, v51, v50
	v_cndmask_b32_e32 v50, v123, v50, vcc
	global_store_dword v243, v50, s[8:9]
	v_mfma_f32_32x32x16_bf16 v[6:21], v[86:89], v[38:41], 0
	s_add_i32 m0, s10, 65536
	s_nop 0
	global_load_lds_dwordx4 v102, s[6:7]
	s_add_i32 m0, s10, 66560
	s_nop 0
	global_load_lds_dwordx4 v110, s[6:7]
	s_add_i32 m0, s10, 67584
	s_nop 0
	global_load_lds_dwordx4 v112, s[6:7]
	s_add_i32 m0, s10, 68608
	s_nop 0
	global_load_lds_dwordx4 v193, s[6:7]
	s_add_u32 s6, s6, 0x8000
	s_addc_u32 s7, s7, 0
	v_max_f32_e32 v108, 0, v212
	v_max_f32_e32 v109, 0, v213
	v_pk_mul_f32 v[0:1], v[22:23], v[108:109]
	v_max_f32_e32 v210, 0, v214
	v_max_f32_e32 v211, 0, v215
	v_pk_fma_f32 v[0:1], v[24:25], v[210:211], v[0:1]
	v_max_f32_e32 v108, 0, v216
	v_max_f32_e32 v109, 0, v217
	v_pk_fma_f32 v[0:1], v[26:27], v[108:109], v[0:1]
	v_mfma_f32_32x32x16_bf16 v[6:21], v[90:93], v[42:45], v[6:21]
	v_max_f32_e32 v210, 0, v218
	v_max_f32_e32 v211, 0, v219
	v_pk_fma_f32 v[0:1], v[28:29], v[210:211], v[0:1]
	v_max_f32_e32 v108, 0, v220
	v_max_f32_e32 v109, 0, v221
	v_pk_fma_f32 v[0:1], v[30:31], v[108:109], v[0:1]
	v_max_f32_e32 v210, 0, v222
	v_max_f32_e32 v211, 0, v223
	v_pk_fma_f32 v[0:1], v[32:33], v[210:211], v[0:1]
	v_mfma_f32_32x32x16_bf16 v[6:21], v[94:97], v[46:49], v[6:21]
	v_max_f32_e32 v108, 0, v224
	v_max_f32_e32 v109, 0, v225
	v_pk_fma_f32 v[0:1], v[34:35], v[108:109], v[0:1]
	v_max_f32_e32 v210, 0, v226
	v_max_f32_e32 v211, 0, v227
	v_pk_fma_f32 v[0:1], v[36:37], v[210:211], v[0:1]
	v_add_f32_e32 v0, v0, v1
	v_ashrrev_i32_e32 v1, 31, v0
	v_mfma_f32_32x32x16_bf16 v[6:21], v[98:101], v[196:199], v[6:21]
	s_waitcnt vmcnt(10)
	ds_read_b128 v[38:41], v5 offset:10496
	ds_read_b128 v[42:45], v52 offset:10496
	ds_read_b128 v[46:49], v55 offset:10496
	ds_read_b128 v[196:199], v56 offset:10496
	v_or_b32_e32 v1, 0x80000000, v1
	s_cmpk_gt_i32 s11, 24
	s_cselect_b64 vcc, -1, 0
	v_xor_b32_e32 v0, v1, v0
	v_cndmask_b32_e32 v134, v123, v0, vcc
	s_nop 3
	s_waitcnt lgkmcnt(3)
	v_mfma_f32_32x32x16_bf16 v[212:227], v[70:73], v[38:41], 0
	v_max_f32_e32 v108, 0, v6
	v_max_f32_e32 v109, 0, v7
	v_pk_mul_f32 v[50:51], v[244:245], v[108:109]
	v_max_f32_e32 v210, 0, v8
	v_max_f32_e32 v211, 0, v9
	v_pk_fma_f32 v[50:51], v[246:247], v[210:211], v[50:51]
	v_max_f32_e32 v108, 0, v10
	v_max_f32_e32 v109, 0, v11
	v_pk_fma_f32 v[50:51], v[248:249], v[108:109], v[50:51]
	s_waitcnt lgkmcnt(2)
	v_mfma_f32_32x32x16_bf16 v[212:227], v[74:77], v[42:45], v[212:227]
	v_max_f32_e32 v210, 0, v12
	v_max_f32_e32 v211, 0, v13
	v_pk_fma_f32 v[50:51], v[250:251], v[210:211], v[50:51]
	v_max_f32_e32 v108, 0, v14
	v_max_f32_e32 v109, 0, v15
	v_pk_fma_f32 v[50:51], v[252:253], v[108:109], v[50:51]
	v_max_f32_e32 v210, 0, v16
	v_max_f32_e32 v211, 0, v17
	v_pk_fma_f32 v[50:51], v[254:255], v[210:211], v[50:51]
	s_waitcnt lgkmcnt(1)
	v_mfma_f32_32x32x16_bf16 v[212:227], v[78:81], v[46:49], v[212:227]
	v_max_f32_e32 v108, 0, v18
	v_max_f32_e32 v109, 0, v19
	v_pk_fma_f32 v[50:51], v[200:201], v[108:109], v[50:51]
	v_max_f32_e32 v210, 0, v20
	v_max_f32_e32 v211, 0, v21
	v_pk_fma_f32 v[50:51], v[202:203], v[210:211], v[50:51]
	v_add_f32_e32 v50, v50, v51
	v_ashrrev_i32_e32 v51, 31, v50
	s_waitcnt lgkmcnt(0)
	v_mfma_f32_32x32x16_bf16 v[212:227], v[82:85], v[196:199], v[212:227]
	v_or_b32_e32 v51, 0x80000000, v51
	s_cmpk_gt_i32 s11, 24
	s_cselect_b64 vcc, -1, 0
	v_xor_b32_e32 v50, v51, v50
	v_cndmask_b32_e32 v50, v123, v50, vcc
	global_store_dword v243, v50, s[8:9] offset:2048
	s_add_u32 s8, s8, 0x1000
	s_addc_u32 s9, s9, 0
	v_mfma_f32_32x32x16_bf16 v[6:21], v[86:89], v[38:41], 0
	s_add_i32 m0, s10, 98304
	s_nop 0
	global_load_lds_dwordx4 v102, s[6:7]
	s_add_i32 m0, s10, 99328
	s_nop 0
	global_load_lds_dwordx4 v110, s[6:7]
	s_add_i32 m0, s10, 100352
	s_nop 0
	global_load_lds_dwordx4 v112, s[6:7]
	s_add_i32 m0, s10, 101376
	s_nop 0
	global_load_lds_dwordx4 v193, s[6:7]
	s_add_u32 s6, s6, 0x8000
	s_addc_u32 s7, s7, 0
	v_max_f32_e32 v108, 0, v212
	v_max_f32_e32 v109, 0, v213
	v_pk_mul_f32 v[0:1], v[22:23], v[108:109]
	v_max_f32_e32 v210, 0, v214
	v_max_f32_e32 v211, 0, v215
	v_pk_fma_f32 v[0:1], v[24:25], v[210:211], v[0:1]
	v_max_f32_e32 v108, 0, v216
	v_max_f32_e32 v109, 0, v217
	v_pk_fma_f32 v[0:1], v[26:27], v[108:109], v[0:1]
	v_mfma_f32_32x32x16_bf16 v[6:21], v[90:93], v[42:45], v[6:21]
	v_max_f32_e32 v210, 0, v218
	v_max_f32_e32 v211, 0, v219
	v_pk_fma_f32 v[0:1], v[28:29], v[210:211], v[0:1]
	v_max_f32_e32 v108, 0, v220
	v_max_f32_e32 v109, 0, v221
	v_pk_fma_f32 v[0:1], v[30:31], v[108:109], v[0:1]
	v_max_f32_e32 v210, 0, v222
	v_max_f32_e32 v211, 0, v223
	v_pk_fma_f32 v[0:1], v[32:33], v[210:211], v[0:1]
	v_mfma_f32_32x32x16_bf16 v[6:21], v[94:97], v[46:49], v[6:21]
	v_max_f32_e32 v108, 0, v224
	v_max_f32_e32 v109, 0, v225
	v_pk_fma_f32 v[0:1], v[34:35], v[108:109], v[0:1]
	v_max_f32_e32 v210, 0, v226
	v_max_f32_e32 v211, 0, v227
	v_pk_fma_f32 v[0:1], v[36:37], v[210:211], v[0:1]
	v_add_f32_e32 v0, v0, v1
	v_ashrrev_i32_e32 v1, 31, v0
	v_mfma_f32_32x32x16_bf16 v[6:21], v[98:101], v[196:199], v[6:21]
	s_waitcnt vmcnt(10)
	ds_read_b128 v[38:41], v5 offset:43264
	ds_read_b128 v[42:45], v52 offset:43264
	ds_read_b128 v[46:49], v55 offset:43264
	ds_read_b128 v[196:199], v56 offset:43264
	v_or_b32_e32 v1, 0x80000000, v1
	s_cmpk_gt_i32 s11, 32
	s_cselect_b64 vcc, -1, 0
	v_xor_b32_e32 v0, v1, v0
	v_cndmask_b32_e32 v138, v123, v0, vcc
	s_nop 3
	s_waitcnt lgkmcnt(3)
	v_mfma_f32_32x32x16_bf16 v[212:227], v[70:73], v[38:41], 0
	v_max_f32_e32 v108, 0, v6
	v_max_f32_e32 v109, 0, v7
	v_pk_mul_f32 v[50:51], v[244:245], v[108:109]
	v_max_f32_e32 v210, 0, v8
	v_max_f32_e32 v211, 0, v9
	v_pk_fma_f32 v[50:51], v[246:247], v[210:211], v[50:51]
	v_max_f32_e32 v108, 0, v10
	v_max_f32_e32 v109, 0, v11
	v_pk_fma_f32 v[50:51], v[248:249], v[108:109], v[50:51]
	s_waitcnt lgkmcnt(2)
	v_mfma_f32_32x32x16_bf16 v[212:227], v[74:77], v[42:45], v[212:227]
	v_max_f32_e32 v210, 0, v12
	v_max_f32_e32 v211, 0, v13
	v_pk_fma_f32 v[50:51], v[250:251], v[210:211], v[50:51]
	v_max_f32_e32 v108, 0, v14
	v_max_f32_e32 v109, 0, v15
	v_pk_fma_f32 v[50:51], v[252:253], v[108:109], v[50:51]
	v_max_f32_e32 v210, 0, v16
	v_max_f32_e32 v211, 0, v17
	v_pk_fma_f32 v[50:51], v[254:255], v[210:211], v[50:51]
	s_waitcnt lgkmcnt(1)
	v_mfma_f32_32x32x16_bf16 v[212:227], v[78:81], v[46:49], v[212:227]
	v_max_f32_e32 v108, 0, v18
	v_max_f32_e32 v109, 0, v19
	v_pk_fma_f32 v[50:51], v[200:201], v[108:109], v[50:51]
	v_max_f32_e32 v210, 0, v20
	v_max_f32_e32 v211, 0, v21
	v_pk_fma_f32 v[50:51], v[202:203], v[210:211], v[50:51]
	v_add_f32_e32 v50, v50, v51
	v_ashrrev_i32_e32 v51, 31, v50
	s_waitcnt lgkmcnt(0)
	v_mfma_f32_32x32x16_bf16 v[212:227], v[82:85], v[196:199], v[212:227]
	v_or_b32_e32 v51, 0x80000000, v51
	s_cmpk_gt_i32 s11, 32
	s_cselect_b64 vcc, -1, 0
	v_xor_b32_e32 v50, v51, v50
	v_cndmask_b32_e32 v50, v123, v50, vcc
	global_store_dword v243, v50, s[8:9]
	v_mfma_f32_32x32x16_bf16 v[6:21], v[86:89], v[38:41], 0
	s_add_i32 m0, s10, 0
	s_nop 0
	global_load_lds_dwordx4 v102, s[6:7]
	s_add_i32 m0, s10, 1024
	s_nop 0
	global_load_lds_dwordx4 v110, s[6:7]
	s_add_i32 m0, s10, 2048
	s_nop 0
	global_load_lds_dwordx4 v112, s[6:7]
	s_add_i32 m0, s10, 3072
	s_nop 0
	global_load_lds_dwordx4 v193, s[6:7]
	s_add_u32 s6, s6, 0x8000
	s_addc_u32 s7, s7, 0
	v_max_f32_e32 v108, 0, v212
	v_max_f32_e32 v109, 0, v213
	v_pk_mul_f32 v[0:1], v[22:23], v[108:109]
	v_max_f32_e32 v210, 0, v214
	v_max_f32_e32 v211, 0, v215
	v_pk_fma_f32 v[0:1], v[24:25], v[210:211], v[0:1]
	v_max_f32_e32 v108, 0, v216
	v_max_f32_e32 v109, 0, v217
	v_pk_fma_f32 v[0:1], v[26:27], v[108:109], v[0:1]
	v_mfma_f32_32x32x16_bf16 v[6:21], v[90:93], v[42:45], v[6:21]
	v_max_f32_e32 v210, 0, v218
	v_max_f32_e32 v211, 0, v219
	v_pk_fma_f32 v[0:1], v[28:29], v[210:211], v[0:1]
	v_max_f32_e32 v108, 0, v220
	v_max_f32_e32 v109, 0, v221
	v_pk_fma_f32 v[0:1], v[30:31], v[108:109], v[0:1]
	v_max_f32_e32 v210, 0, v222
	v_max_f32_e32 v211, 0, v223
	v_pk_fma_f32 v[0:1], v[32:33], v[210:211], v[0:1]
	v_mfma_f32_32x32x16_bf16 v[6:21], v[94:97], v[46:49], v[6:21]
	v_max_f32_e32 v108, 0, v224
	v_max_f32_e32 v109, 0, v225
	v_pk_fma_f32 v[0:1], v[34:35], v[108:109], v[0:1]
	v_max_f32_e32 v210, 0, v226
	v_max_f32_e32 v211, 0, v227
	v_pk_fma_f32 v[0:1], v[36:37], v[210:211], v[0:1]
	v_add_f32_e32 v0, v0, v1
	v_ashrrev_i32_e32 v1, 31, v0
	v_mfma_f32_32x32x16_bf16 v[6:21], v[98:101], v[196:199], v[6:21]
	s_waitcnt vmcnt(10)
	v_add_u32_e32 v228, 0x10000, v5
	ds_read_b128 v[38:41], v228 offset:10496
	v_add_u32_e32 v228, 0x10000, v52
	ds_read_b128 v[42:45], v228 offset:10496
	v_add_u32_e32 v228, 0x10000, v55
	ds_read_b128 v[46:49], v228 offset:10496
	v_add_u32_e32 v228, 0x10000, v56
	ds_read_b128 v[196:199], v228 offset:10496
	v_or_b32_e32 v1, 0x80000000, v1
	s_cmpk_gt_i32 s11, 40
	s_cselect_b64 vcc, -1, 0
	v_xor_b32_e32 v0, v1, v0
	v_cndmask_b32_e32 v137, v123, v0, vcc
	s_nop 3
	s_waitcnt lgkmcnt(3)
	v_mfma_f32_32x32x16_bf16 v[212:227], v[70:73], v[38:41], 0
	v_max_f32_e32 v108, 0, v6
	v_max_f32_e32 v109, 0, v7
	v_pk_mul_f32 v[50:51], v[244:245], v[108:109]
	v_max_f32_e32 v210, 0, v8
	v_max_f32_e32 v211, 0, v9
	v_pk_fma_f32 v[50:51], v[246:247], v[210:211], v[50:51]
	v_max_f32_e32 v108, 0, v10
	v_max_f32_e32 v109, 0, v11
	v_pk_fma_f32 v[50:51], v[248:249], v[108:109], v[50:51]
	s_waitcnt lgkmcnt(2)
	v_mfma_f32_32x32x16_bf16 v[212:227], v[74:77], v[42:45], v[212:227]
	v_max_f32_e32 v210, 0, v12
	v_max_f32_e32 v211, 0, v13
	v_pk_fma_f32 v[50:51], v[250:251], v[210:211], v[50:51]
	v_max_f32_e32 v108, 0, v14
	v_max_f32_e32 v109, 0, v15
	v_pk_fma_f32 v[50:51], v[252:253], v[108:109], v[50:51]
	v_max_f32_e32 v210, 0, v16
	v_max_f32_e32 v211, 0, v17
	v_pk_fma_f32 v[50:51], v[254:255], v[210:211], v[50:51]
	s_waitcnt lgkmcnt(1)
	v_mfma_f32_32x32x16_bf16 v[212:227], v[78:81], v[46:49], v[212:227]
	v_max_f32_e32 v108, 0, v18
	v_max_f32_e32 v109, 0, v19
	v_pk_fma_f32 v[50:51], v[200:201], v[108:109], v[50:51]
	v_max_f32_e32 v210, 0, v20
	v_max_f32_e32 v211, 0, v21
	v_pk_fma_f32 v[50:51], v[202:203], v[210:211], v[50:51]
	v_add_f32_e32 v50, v50, v51
	v_ashrrev_i32_e32 v51, 31, v50
	s_waitcnt lgkmcnt(0)
	v_mfma_f32_32x32x16_bf16 v[212:227], v[82:85], v[196:199], v[212:227]
	v_or_b32_e32 v51, 0x80000000, v51
	s_cmpk_gt_i32 s11, 40
	s_cselect_b64 vcc, -1, 0
	v_xor_b32_e32 v50, v51, v50
	v_cndmask_b32_e32 v50, v123, v50, vcc
	global_store_dword v243, v50, s[8:9] offset:2048
	s_add_u32 s8, s8, 0x1000
	s_addc_u32 s9, s9, 0
	v_mfma_f32_32x32x16_bf16 v[6:21], v[86:89], v[38:41], 0
	s_add_i32 m0, s10, 32768
	s_nop 0
	global_load_lds_dwordx4 v102, s[6:7]
	s_add_i32 m0, s10, 33792
	s_nop 0
	global_load_lds_dwordx4 v110, s[6:7]
	s_add_i32 m0, s10, 34816
	s_nop 0
	global_load_lds_dwordx4 v112, s[6:7]
	s_add_i32 m0, s10, 35840
	s_nop 0
	global_load_lds_dwordx4 v193, s[6:7]
	s_add_u32 s6, s6, 0x8000
	s_addc_u32 s7, s7, 0
	v_max_f32_e32 v108, 0, v212
	v_max_f32_e32 v109, 0, v213
	v_pk_mul_f32 v[0:1], v[22:23], v[108:109]
	v_max_f32_e32 v210, 0, v214
	v_max_f32_e32 v211, 0, v215
	v_pk_fma_f32 v[0:1], v[24:25], v[210:211], v[0:1]
	v_max_f32_e32 v108, 0, v216
	v_max_f32_e32 v109, 0, v217
	v_pk_fma_f32 v[0:1], v[26:27], v[108:109], v[0:1]
	v_mfma_f32_32x32x16_bf16 v[6:21], v[90:93], v[42:45], v[6:21]
	v_max_f32_e32 v210, 0, v218
	v_max_f32_e32 v211, 0, v219
	v_pk_fma_f32 v[0:1], v[28:29], v[210:211], v[0:1]
	v_max_f32_e32 v108, 0, v220
	v_max_f32_e32 v109, 0, v221
	v_pk_fma_f32 v[0:1], v[30:31], v[108:109], v[0:1]
	v_max_f32_e32 v210, 0, v222
	v_max_f32_e32 v211, 0, v223
	v_pk_fma_f32 v[0:1], v[32:33], v[210:211], v[0:1]
	v_mfma_f32_32x32x16_bf16 v[6:21], v[94:97], v[46:49], v[6:21]
	v_max_f32_e32 v108, 0, v224
	v_max_f32_e32 v109, 0, v225
	v_pk_fma_f32 v[0:1], v[34:35], v[108:109], v[0:1]
	v_max_f32_e32 v210, 0, v226
	v_max_f32_e32 v211, 0, v227
	v_pk_fma_f32 v[0:1], v[36:37], v[210:211], v[0:1]
	v_add_f32_e32 v0, v0, v1
	v_ashrrev_i32_e32 v1, 31, v0
	v_mfma_f32_32x32x16_bf16 v[6:21], v[98:101], v[196:199], v[6:21]
	s_waitcnt vmcnt(10)
	v_add_u32_e32 v228, 0x10000, v5
	ds_read_b128 v[38:41], v228 offset:43264
	v_add_u32_e32 v228, 0x10000, v52
	ds_read_b128 v[42:45], v228 offset:43264
	v_add_u32_e32 v228, 0x10000, v55
	ds_read_b128 v[46:49], v228 offset:43264
	v_add_u32_e32 v228, 0x10000, v56
	ds_read_b128 v[196:199], v228 offset:43264
	v_or_b32_e32 v1, 0x80000000, v1
	s_cmpk_gt_i32 s11, 48
	s_cselect_b64 vcc, -1, 0
	v_xor_b32_e32 v0, v1, v0
	v_cndmask_b32_e32 v140, v123, v0, vcc
	s_nop 3
	s_waitcnt lgkmcnt(3)
	v_mfma_f32_32x32x16_bf16 v[212:227], v[70:73], v[38:41], 0
	v_max_f32_e32 v108, 0, v6
	v_max_f32_e32 v109, 0, v7
	v_pk_mul_f32 v[50:51], v[244:245], v[108:109]
	v_max_f32_e32 v210, 0, v8
	v_max_f32_e32 v211, 0, v9
	v_pk_fma_f32 v[50:51], v[246:247], v[210:211], v[50:51]
	v_max_f32_e32 v108, 0, v10
	v_max_f32_e32 v109, 0, v11
	v_pk_fma_f32 v[50:51], v[248:249], v[108:109], v[50:51]
	s_waitcnt lgkmcnt(2)
	v_mfma_f32_32x32x16_bf16 v[212:227], v[74:77], v[42:45], v[212:227]
	v_max_f32_e32 v210, 0, v12
	v_max_f32_e32 v211, 0, v13
	v_pk_fma_f32 v[50:51], v[250:251], v[210:211], v[50:51]
	v_max_f32_e32 v108, 0, v14
	v_max_f32_e32 v109, 0, v15
	v_pk_fma_f32 v[50:51], v[252:253], v[108:109], v[50:51]
	v_max_f32_e32 v210, 0, v16
	v_max_f32_e32 v211, 0, v17
	v_pk_fma_f32 v[50:51], v[254:255], v[210:211], v[50:51]
	s_waitcnt lgkmcnt(1)
	v_mfma_f32_32x32x16_bf16 v[212:227], v[78:81], v[46:49], v[212:227]
	v_max_f32_e32 v108, 0, v18
	v_max_f32_e32 v109, 0, v19
	v_pk_fma_f32 v[50:51], v[200:201], v[108:109], v[50:51]
	v_max_f32_e32 v210, 0, v20
	v_max_f32_e32 v211, 0, v21
	v_pk_fma_f32 v[50:51], v[202:203], v[210:211], v[50:51]
	v_add_f32_e32 v50, v50, v51
	v_ashrrev_i32_e32 v51, 31, v50
	s_waitcnt lgkmcnt(0)
	v_mfma_f32_32x32x16_bf16 v[212:227], v[82:85], v[196:199], v[212:227]
	v_or_b32_e32 v51, 0x80000000, v51
	s_cmpk_gt_i32 s11, 48
	s_cselect_b64 vcc, -1, 0
	v_xor_b32_e32 v50, v51, v50
	v_cndmask_b32_e32 v50, v123, v50, vcc
	global_store_dword v243, v50, s[8:9]
	v_mfma_f32_32x32x16_bf16 v[6:21], v[86:89], v[38:41], 0
	s_add_i32 m0, s10, 65536
	s_nop 0
	global_load_lds_dwordx4 v102, s[6:7]
	s_add_i32 m0, s10, 66560
	s_nop 0
	global_load_lds_dwordx4 v110, s[6:7]
	s_add_i32 m0, s10, 67584
	s_nop 0
	global_load_lds_dwordx4 v112, s[6:7]
	s_add_i32 m0, s10, 68608
	s_nop 0
	global_load_lds_dwordx4 v193, s[6:7]
	s_add_u32 s6, s6, 0x8000
	s_addc_u32 s7, s7, 0
	v_max_f32_e32 v108, 0, v212
	v_max_f32_e32 v109, 0, v213
	v_pk_mul_f32 v[0:1], v[22:23], v[108:109]
	v_max_f32_e32 v210, 0, v214
	v_max_f32_e32 v211, 0, v215
	v_pk_fma_f32 v[0:1], v[24:25], v[210:211], v[0:1]
	v_max_f32_e32 v108, 0, v216
	v_max_f32_e32 v109, 0, v217
	v_pk_fma_f32 v[0:1], v[26:27], v[108:109], v[0:1]
	v_mfma_f32_32x32x16_bf16 v[6:21], v[90:93], v[42:45], v[6:21]
	v_max_f32_e32 v210, 0, v218
	v_max_f32_e32 v211, 0, v219
	v_pk_fma_f32 v[0:1], v[28:29], v[210:211], v[0:1]
	v_max_f32_e32 v108, 0, v220
	v_max_f32_e32 v109, 0, v221
	v_pk_fma_f32 v[0:1], v[30:31], v[108:109], v[0:1]
	v_max_f32_e32 v210, 0, v222
	v_max_f32_e32 v211, 0, v223
	v_pk_fma_f32 v[0:1], v[32:33], v[210:211], v[0:1]
	v_mfma_f32_32x32x16_bf16 v[6:21], v[94:97], v[46:49], v[6:21]
	v_max_f32_e32 v108, 0, v224
	v_max_f32_e32 v109, 0, v225
	v_pk_fma_f32 v[0:1], v[34:35], v[108:109], v[0:1]
	v_max_f32_e32 v210, 0, v226
	v_max_f32_e32 v211, 0, v227
	v_pk_fma_f32 v[0:1], v[36:37], v[210:211], v[0:1]
	v_add_f32_e32 v0, v0, v1
	v_ashrrev_i32_e32 v1, 31, v0
	v_mfma_f32_32x32x16_bf16 v[6:21], v[98:101], v[196:199], v[6:21]
	s_waitcnt vmcnt(10)
	ds_read_b128 v[38:41], v5 offset:10496
	ds_read_b128 v[42:45], v52 offset:10496
	ds_read_b128 v[46:49], v55 offset:10496
	ds_read_b128 v[196:199], v56 offset:10496
	v_or_b32_e32 v1, 0x80000000, v1
	s_cmpk_gt_i32 s11, 56
	s_cselect_b64 vcc, -1, 0
	v_xor_b32_e32 v0, v1, v0
	v_cndmask_b32_e32 v139, v123, v0, vcc
	s_nop 3
	v_max_f32_e32 v108, 0, v6
	v_max_f32_e32 v109, 0, v7
	v_pk_mul_f32 v[50:51], v[244:245], v[108:109]
	v_max_f32_e32 v210, 0, v8
	v_max_f32_e32 v211, 0, v9
	v_pk_fma_f32 v[50:51], v[246:247], v[210:211], v[50:51]
	v_max_f32_e32 v108, 0, v10
	v_max_f32_e32 v109, 0, v11
	v_pk_fma_f32 v[50:51], v[248:249], v[108:109], v[50:51]
	v_max_f32_e32 v210, 0, v12
	v_max_f32_e32 v211, 0, v13
	v_pk_fma_f32 v[50:51], v[250:251], v[210:211], v[50:51]
	v_max_f32_e32 v108, 0, v14
	v_max_f32_e32 v109, 0, v15
	v_pk_fma_f32 v[50:51], v[252:253], v[108:109], v[50:51]
	v_max_f32_e32 v210, 0, v16
	v_max_f32_e32 v211, 0, v17
	v_pk_fma_f32 v[50:51], v[254:255], v[210:211], v[50:51]
	v_max_f32_e32 v108, 0, v18
	v_max_f32_e32 v109, 0, v19
	v_pk_fma_f32 v[50:51], v[200:201], v[108:109], v[50:51]
	v_max_f32_e32 v210, 0, v20
	v_max_f32_e32 v211, 0, v21
	v_pk_fma_f32 v[50:51], v[202:203], v[210:211], v[50:51]
	v_add_f32_e32 v50, v50, v51
	v_ashrrev_i32_e32 v51, 31, v50
	v_or_b32_e32 v51, 0x80000000, v51
	s_cmpk_gt_i32 s11, 56
	s_cselect_b64 vcc, -1, 0
	v_xor_b32_e32 v50, v51, v50
	v_cndmask_b32_e32 v50, v123, v50, vcc
	global_store_dword v243, v50, s[8:9] offset:2048
	s_add_u32 s8, s8, 0x1000
	s_addc_u32 s9, s9, 0
	s_cmpk_gt_i32 s81, 8
	s_cbranch_scc0 .Lix_fill_1
	s_waitcnt lgkmcnt(3)
	v_mfma_f32_32x32x16_bf16 v[212:227], v[70:73], v[38:41], 0
	s_add_i32 m0, s10, 98304
	s_nop 0
	global_load_lds_dwordx4 v102, s[6:7]
	s_waitcnt lgkmcnt(2)
	v_mfma_f32_32x32x16_bf16 v[212:227], v[74:77], v[42:45], v[212:227]
	s_add_i32 m0, s10, 99328
	s_nop 0
	global_load_lds_dwordx4 v110, s[6:7]
	s_waitcnt lgkmcnt(1)
	v_mfma_f32_32x32x16_bf16 v[212:227], v[78:81], v[46:49], v[212:227]
	s_add_i32 m0, s10, 100352
	s_nop 0
	global_load_lds_dwordx4 v112, s[6:7]
	s_waitcnt lgkmcnt(0)
	v_mfma_f32_32x32x16_bf16 v[212:227], v[82:85], v[196:199], v[212:227]
	s_add_i32 m0, s10, 101376
	s_nop 0
	global_load_lds_dwordx4 v193, s[6:7]
	s_add_u32 s6, s6, 0x8000
	s_addc_u32 s7, s7, 0
	v_mfma_f32_32x32x16_bf16 v[6:21], v[86:89], v[38:41], 0
	s_nop 7
	s_nop 2
	v_max_f32_e32 v108, 0, v212
	v_max_f32_e32 v109, 0, v213
	v_pk_mul_f32 v[0:1], v[22:23], v[108:109]
	v_max_f32_e32 v210, 0, v214
	v_max_f32_e32 v211, 0, v215
	v_pk_fma_f32 v[0:1], v[24:25], v[210:211], v[0:1]
	v_max_f32_e32 v108, 0, v216
	v_max_f32_e32 v109, 0, v217
	v_pk_fma_f32 v[0:1], v[26:27], v[108:109], v[0:1]
	v_mfma_f32_32x32x16_bf16 v[6:21], v[90:93], v[42:45], v[6:21]
	v_max_f32_e32 v210, 0, v218
	v_max_f32_e32 v211, 0, v219
	v_pk_fma_f32 v[0:1], v[28:29], v[210:211], v[0:1]
	v_max_f32_e32 v108, 0, v220
	v_max_f32_e32 v109, 0, v221
	v_pk_fma_f32 v[0:1], v[30:31], v[108:109], v[0:1]
	v_max_f32_e32 v210, 0, v222
	v_max_f32_e32 v211, 0, v223
	v_pk_fma_f32 v[0:1], v[32:33], v[210:211], v[0:1]
	v_mfma_f32_32x32x16_bf16 v[6:21], v[94:97], v[46:49], v[6:21]
	v_max_f32_e32 v108, 0, v224
	v_max_f32_e32 v109, 0, v225
	v_pk_fma_f32 v[0:1], v[34:35], v[108:109], v[0:1]
	v_max_f32_e32 v210, 0, v226
	v_max_f32_e32 v211, 0, v227
	v_pk_fma_f32 v[0:1], v[36:37], v[210:211], v[0:1]
	v_add_f32_e32 v0, v0, v1
	v_ashrrev_i32_e32 v1, 31, v0
	v_mfma_f32_32x32x16_bf16 v[6:21], v[98:101], v[196:199], v[6:21]
	s_waitcnt vmcnt(10)
	ds_read_b128 v[38:41], v5 offset:43264
	ds_read_b128 v[42:45], v52 offset:43264
	ds_read_b128 v[46:49], v55 offset:43264
	ds_read_b128 v[196:199], v56 offset:43264
	v_or_b32_e32 v1, 0x80000000, v1
	s_cmpk_gt_i32 s11, 64
	s_cselect_b64 vcc, -1, 0
	v_xor_b32_e32 v0, v1, v0
	v_cndmask_b32_e32 v142, v123, v0, vcc
	s_nop 3
	s_waitcnt lgkmcnt(3)
	v_mfma_f32_32x32x16_bf16 v[212:227], v[70:73], v[38:41], 0
	v_max_f32_e32 v108, 0, v6
	v_max_f32_e32 v109, 0, v7
	v_pk_mul_f32 v[50:51], v[244:245], v[108:109]
	v_max_f32_e32 v210, 0, v8
	v_max_f32_e32 v211, 0, v9
	v_pk_fma_f32 v[50:51], v[246:247], v[210:211], v[50:51]
	v_max_f32_e32 v108, 0, v10
	v_max_f32_e32 v109, 0, v11
	v_pk_fma_f32 v[50:51], v[248:249], v[108:109], v[50:51]
	s_waitcnt lgkmcnt(2)
	v_mfma_f32_32x32x16_bf16 v[212:227], v[74:77], v[42:45], v[212:227]
	v_max_f32_e32 v210, 0, v12
	v_max_f32_e32 v211, 0, v13
	v_pk_fma_f32 v[50:51], v[250:251], v[210:211], v[50:51]
	v_max_f32_e32 v108, 0, v14
	v_max_f32_e32 v109, 0, v15
	v_pk_fma_f32 v[50:51], v[252:253], v[108:109], v[50:51]
	v_max_f32_e32 v210, 0, v16
	v_max_f32_e32 v211, 0, v17
	v_pk_fma_f32 v[50:51], v[254:255], v[210:211], v[50:51]
	s_waitcnt lgkmcnt(1)
	v_mfma_f32_32x32x16_bf16 v[212:227], v[78:81], v[46:49], v[212:227]
	v_max_f32_e32 v108, 0, v18
	v_max_f32_e32 v109, 0, v19
	v_pk_fma_f32 v[50:51], v[200:201], v[108:109], v[50:51]
	v_max_f32_e32 v210, 0, v20
	v_max_f32_e32 v211, 0, v21
	v_pk_fma_f32 v[50:51], v[202:203], v[210:211], v[50:51]
	v_add_f32_e32 v50, v50, v51
	v_ashrrev_i32_e32 v51, 31, v50
	s_waitcnt lgkmcnt(0)
	v_mfma_f32_32x32x16_bf16 v[212:227], v[82:85], v[196:199], v[212:227]
	v_or_b32_e32 v51, 0x80000000, v51
	s_cmpk_gt_i32 s11, 64
	s_cselect_b64 vcc, -1, 0
	v_xor_b32_e32 v50, v51, v50
	v_cndmask_b32_e32 v50, v123, v50, vcc
	global_store_dword v243, v50, s[8:9]
	v_mfma_f32_32x32x16_bf16 v[6:21], v[86:89], v[38:41], 0
	s_add_i32 m0, s10, 0
	s_nop 0
	global_load_lds_dwordx4 v102, s[6:7]
	s_add_i32 m0, s10, 1024
	s_nop 0
	global_load_lds_dwordx4 v110, s[6:7]
	s_add_i32 m0, s10, 2048
	s_nop 0
	global_load_lds_dwordx4 v112, s[6:7]
	s_add_i32 m0, s10, 3072
	s_nop 0
	global_load_lds_dwordx4 v193, s[6:7]
	s_add_u32 s6, s6, 0x8000
	s_addc_u32 s7, s7, 0
	v_max_f32_e32 v108, 0, v212
	v_max_f32_e32 v109, 0, v213
	v_pk_mul_f32 v[0:1], v[22:23], v[108:109]
	v_max_f32_e32 v210, 0, v214
	v_max_f32_e32 v211, 0, v215
	v_pk_fma_f32 v[0:1], v[24:25], v[210:211], v[0:1]
	v_max_f32_e32 v108, 0, v216
	v_max_f32_e32 v109, 0, v217
	v_pk_fma_f32 v[0:1], v[26:27], v[108:109], v[0:1]
	v_mfma_f32_32x32x16_bf16 v[6:21], v[90:93], v[42:45], v[6:21]
	v_max_f32_e32 v210, 0, v218
	v_max_f32_e32 v211, 0, v219
	v_pk_fma_f32 v[0:1], v[28:29], v[210:211], v[0:1]
	v_max_f32_e32 v108, 0, v220
	v_max_f32_e32 v109, 0, v221
	v_pk_fma_f32 v[0:1], v[30:31], v[108:109], v[0:1]
	v_max_f32_e32 v210, 0, v222
	v_max_f32_e32 v211, 0, v223
	v_pk_fma_f32 v[0:1], v[32:33], v[210:211], v[0:1]
	v_mfma_f32_32x32x16_bf16 v[6:21], v[94:97], v[46:49], v[6:21]
	v_max_f32_e32 v108, 0, v224
	v_max_f32_e32 v109, 0, v225
	v_pk_fma_f32 v[0:1], v[34:35], v[108:109], v[0:1]
	v_max_f32_e32 v210, 0, v226
	v_max_f32_e32 v211, 0, v227
	v_pk_fma_f32 v[0:1], v[36:37], v[210:211], v[0:1]
	v_add_f32_e32 v0, v0, v1
	v_ashrrev_i32_e32 v1, 31, v0
	v_mfma_f32_32x32x16_bf16 v[6:21], v[98:101], v[196:199], v[6:21]
	s_waitcnt vmcnt(10)
	v_add_u32_e32 v228, 0x10000, v5
	ds_read_b128 v[38:41], v228 offset:10496
	v_add_u32_e32 v228, 0x10000, v52
	ds_read_b128 v[42:45], v228 offset:10496
	v_add_u32_e32 v228, 0x10000, v55
	ds_read_b128 v[46:49], v228 offset:10496
	v_add_u32_e32 v228, 0x10000, v56
	ds_read_b128 v[196:199], v228 offset:10496
	v_or_b32_e32 v1, 0x80000000, v1
	s_cmpk_gt_i32 s11, 72
	s_cselect_b64 vcc, -1, 0
	v_xor_b32_e32 v0, v1, v0
	v_cndmask_b32_e32 v141, v123, v0, vcc
	s_nop 3
	s_waitcnt lgkmcnt(3)
	v_mfma_f32_32x32x16_bf16 v[212:227], v[70:73], v[38:41], 0
	v_max_f32_e32 v108, 0, v6
	v_max_f32_e32 v109, 0, v7
	v_pk_mul_f32 v[50:51], v[244:245], v[108:109]
	v_max_f32_e32 v210, 0, v8
	v_max_f32_e32 v211, 0, v9
	v_pk_fma_f32 v[50:51], v[246:247], v[210:211], v[50:51]
	v_max_f32_e32 v108, 0, v10
	v_max_f32_e32 v109, 0, v11
	v_pk_fma_f32 v[50:51], v[248:249], v[108:109], v[50:51]
	s_waitcnt lgkmcnt(2)
	v_mfma_f32_32x32x16_bf16 v[212:227], v[74:77], v[42:45], v[212:227]
	v_max_f32_e32 v210, 0, v12
	v_max_f32_e32 v211, 0, v13
	v_pk_fma_f32 v[50:51], v[250:251], v[210:211], v[50:51]
	v_max_f32_e32 v108, 0, v14
	v_max_f32_e32 v109, 0, v15
	v_pk_fma_f32 v[50:51], v[252:253], v[108:109], v[50:51]
	v_max_f32_e32 v210, 0, v16
	v_max_f32_e32 v211, 0, v17
	v_pk_fma_f32 v[50:51], v[254:255], v[210:211], v[50:51]
	s_waitcnt lgkmcnt(1)
	v_mfma_f32_32x32x16_bf16 v[212:227], v[78:81], v[46:49], v[212:227]
	v_max_f32_e32 v108, 0, v18
	v_max_f32_e32 v109, 0, v19
	v_pk_fma_f32 v[50:51], v[200:201], v[108:109], v[50:51]
	v_max_f32_e32 v210, 0, v20
	v_max_f32_e32 v211, 0, v21
	v_pk_fma_f32 v[50:51], v[202:203], v[210:211], v[50:51]
	v_add_f32_e32 v50, v50, v51
	v_ashrrev_i32_e32 v51, 31, v50
	s_waitcnt lgkmcnt(0)
	v_mfma_f32_32x32x16_bf16 v[212:227], v[82:85], v[196:199], v[212:227]
	v_or_b32_e32 v51, 0x80000000, v51
	s_cmpk_gt_i32 s11, 72
	s_cselect_b64 vcc, -1, 0
	v_xor_b32_e32 v50, v51, v50
	v_cndmask_b32_e32 v50, v123, v50, vcc
	global_store_dword v243, v50, s[8:9] offset:2048
	s_add_u32 s8, s8, 0x1000
	s_addc_u32 s9, s9, 0
	v_mfma_f32_32x32x16_bf16 v[6:21], v[86:89], v[38:41], 0
	s_add_i32 m0, s10, 32768
	s_nop 0
	global_load_lds_dwordx4 v102, s[6:7]
	s_add_i32 m0, s10, 33792
	s_nop 0
	global_load_lds_dwordx4 v110, s[6:7]
	s_add_i32 m0, s10, 34816
	s_nop 0
	global_load_lds_dwordx4 v112, s[6:7]
	s_add_i32 m0, s10, 35840
	s_nop 0
	global_load_lds_dwordx4 v193, s[6:7]
	s_add_u32 s6, s6, 0x8000
	s_addc_u32 s7, s7, 0
	v_max_f32_e32 v108, 0, v212
	v_max_f32_e32 v109, 0, v213
	v_pk_mul_f32 v[0:1], v[22:23], v[108:109]
	v_max_f32_e32 v210, 0, v214
	v_max_f32_e32 v211, 0, v215
	v_pk_fma_f32 v[0:1], v[24:25], v[210:211], v[0:1]
	v_max_f32_e32 v108, 0, v216
	v_max_f32_e32 v109, 0, v217
	v_pk_fma_f32 v[0:1], v[26:27], v[108:109], v[0:1]
	v_mfma_f32_32x32x16_bf16 v[6:21], v[90:93], v[42:45], v[6:21]
	v_max_f32_e32 v210, 0, v218
	v_max_f32_e32 v211, 0, v219
	v_pk_fma_f32 v[0:1], v[28:29], v[210:211], v[0:1]
	v_max_f32_e32 v108, 0, v220
	v_max_f32_e32 v109, 0, v221
	v_pk_fma_f32 v[0:1], v[30:31], v[108:109], v[0:1]
	v_max_f32_e32 v210, 0, v222
	v_max_f32_e32 v211, 0, v223
	v_pk_fma_f32 v[0:1], v[32:33], v[210:211], v[0:1]
	v_mfma_f32_32x32x16_bf16 v[6:21], v[94:97], v[46:49], v[6:21]
	v_max_f32_e32 v108, 0, v224
	v_max_f32_e32 v109, 0, v225
	v_pk_fma_f32 v[0:1], v[34:35], v[108:109], v[0:1]
	v_max_f32_e32 v210, 0, v226
	v_max_f32_e32 v211, 0, v227
	v_pk_fma_f32 v[0:1], v[36:37], v[210:211], v[0:1]
	v_add_f32_e32 v0, v0, v1
	v_ashrrev_i32_e32 v1, 31, v0
	v_mfma_f32_32x32x16_bf16 v[6:21], v[98:101], v[196:199], v[6:21]
	s_waitcnt vmcnt(10)
	v_add_u32_e32 v228, 0x10000, v5
	ds_read_b128 v[38:41], v228 offset:43264
	v_add_u32_e32 v228, 0x10000, v52
	ds_read_b128 v[42:45], v228 offset:43264
	v_add_u32_e32 v228, 0x10000, v55
	ds_read_b128 v[46:49], v228 offset:43264
	v_add_u32_e32 v228, 0x10000, v56
	ds_read_b128 v[196:199], v228 offset:43264
	v_or_b32_e32 v1, 0x80000000, v1
	s_cmpk_gt_i32 s11, 80
	s_cselect_b64 vcc, -1, 0
	v_xor_b32_e32 v0, v1, v0
	v_cndmask_b32_e32 v144, v123, v0, vcc
	s_nop 3
	s_waitcnt lgkmcnt(3)
	v_mfma_f32_32x32x16_bf16 v[212:227], v[70:73], v[38:41], 0
	v_max_f32_e32 v108, 0, v6
	v_max_f32_e32 v109, 0, v7
	v_pk_mul_f32 v[50:51], v[244:245], v[108:109]
	v_max_f32_e32 v210, 0, v8
	v_max_f32_e32 v211, 0, v9
	v_pk_fma_f32 v[50:51], v[246:247], v[210:211], v[50:51]
	v_max_f32_e32 v108, 0, v10
	v_max_f32_e32 v109, 0, v11
	v_pk_fma_f32 v[50:51], v[248:249], v[108:109], v[50:51]
	s_waitcnt lgkmcnt(2)
	v_mfma_f32_32x32x16_bf16 v[212:227], v[74:77], v[42:45], v[212:227]
	v_max_f32_e32 v210, 0, v12
	v_max_f32_e32 v211, 0, v13
	v_pk_fma_f32 v[50:51], v[250:251], v[210:211], v[50:51]
	v_max_f32_e32 v108, 0, v14
	v_max_f32_e32 v109, 0, v15
	v_pk_fma_f32 v[50:51], v[252:253], v[108:109], v[50:51]
	v_max_f32_e32 v210, 0, v16
	v_max_f32_e32 v211, 0, v17
	v_pk_fma_f32 v[50:51], v[254:255], v[210:211], v[50:51]
	s_waitcnt lgkmcnt(1)
	v_mfma_f32_32x32x16_bf16 v[212:227], v[78:81], v[46:49], v[212:227]
	v_max_f32_e32 v108, 0, v18
	v_max_f32_e32 v109, 0, v19
	v_pk_fma_f32 v[50:51], v[200:201], v[108:109], v[50:51]
	v_max_f32_e32 v210, 0, v20
	v_max_f32_e32 v211, 0, v21
	v_pk_fma_f32 v[50:51], v[202:203], v[210:211], v[50:51]
	v_add_f32_e32 v50, v50, v51
	v_ashrrev_i32_e32 v51, 31, v50
	s_waitcnt lgkmcnt(0)
	v_mfma_f32_32x32x16_bf16 v[212:227], v[82:85], v[196:199], v[212:227]
	v_or_b32_e32 v51, 0x80000000, v51
	s_cmpk_gt_i32 s11, 80
	s_cselect_b64 vcc, -1, 0
	v_xor_b32_e32 v50, v51, v50
	v_cndmask_b32_e32 v50, v123, v50, vcc
	global_store_dword v243, v50, s[8:9]
	v_mfma_f32_32x32x16_bf16 v[6:21], v[86:89], v[38:41], 0
	s_add_i32 m0, s10, 65536
	s_nop 0
	global_load_lds_dwordx4 v102, s[6:7]
	s_add_i32 m0, s10, 66560
	s_nop 0
	global_load_lds_dwordx4 v110, s[6:7]
	s_add_i32 m0, s10, 67584
	s_nop 0
	global_load_lds_dwordx4 v112, s[6:7]
	s_add_i32 m0, s10, 68608
	s_nop 0
	global_load_lds_dwordx4 v193, s[6:7]
	s_add_u32 s6, s6, 0x8000
	s_addc_u32 s7, s7, 0
	v_max_f32_e32 v108, 0, v212
	v_max_f32_e32 v109, 0, v213
	v_pk_mul_f32 v[0:1], v[22:23], v[108:109]
	v_max_f32_e32 v210, 0, v214
	v_max_f32_e32 v211, 0, v215
	v_pk_fma_f32 v[0:1], v[24:25], v[210:211], v[0:1]
	v_max_f32_e32 v108, 0, v216
	v_max_f32_e32 v109, 0, v217
	v_pk_fma_f32 v[0:1], v[26:27], v[108:109], v[0:1]
	v_mfma_f32_32x32x16_bf16 v[6:21], v[90:93], v[42:45], v[6:21]
	v_max_f32_e32 v210, 0, v218
	v_max_f32_e32 v211, 0, v219
	v_pk_fma_f32 v[0:1], v[28:29], v[210:211], v[0:1]
	v_max_f32_e32 v108, 0, v220
	v_max_f32_e32 v109, 0, v221
	v_pk_fma_f32 v[0:1], v[30:31], v[108:109], v[0:1]
	v_max_f32_e32 v210, 0, v222
	v_max_f32_e32 v211, 0, v223
	v_pk_fma_f32 v[0:1], v[32:33], v[210:211], v[0:1]
	v_mfma_f32_32x32x16_bf16 v[6:21], v[94:97], v[46:49], v[6:21]
	v_max_f32_e32 v108, 0, v224
	v_max_f32_e32 v109, 0, v225
	v_pk_fma_f32 v[0:1], v[34:35], v[108:109], v[0:1]
	v_max_f32_e32 v210, 0, v226
	v_max_f32_e32 v211, 0, v227
	v_pk_fma_f32 v[0:1], v[36:37], v[210:211], v[0:1]
	v_add_f32_e32 v0, v0, v1
	v_ashrrev_i32_e32 v1, 31, v0
	v_mfma_f32_32x32x16_bf16 v[6:21], v[98:101], v[196:199], v[6:21]
	s_waitcnt vmcnt(10)
	ds_read_b128 v[38:41], v5 offset:10496
	ds_read_b128 v[42:45], v52 offset:10496
	ds_read_b128 v[46:49], v55 offset:10496
	ds_read_b128 v[196:199], v56 offset:10496
	v_or_b32_e32 v1, 0x80000000, v1
	s_cmpk_gt_i32 s11, 88
	s_cselect_b64 vcc, -1, 0
	v_xor_b32_e32 v0, v1, v0
	v_cndmask_b32_e32 v143, v123, v0, vcc
	s_nop 3
	s_waitcnt lgkmcnt(3)
	v_mfma_f32_32x32x16_bf16 v[212:227], v[70:73], v[38:41], 0
	v_max_f32_e32 v108, 0, v6
	v_max_f32_e32 v109, 0, v7
	v_pk_mul_f32 v[50:51], v[244:245], v[108:109]
	v_max_f32_e32 v210, 0, v8
	v_max_f32_e32 v211, 0, v9
	v_pk_fma_f32 v[50:51], v[246:247], v[210:211], v[50:51]
	v_max_f32_e32 v108, 0, v10
	v_max_f32_e32 v109, 0, v11
	v_pk_fma_f32 v[50:51], v[248:249], v[108:109], v[50:51]
	s_waitcnt lgkmcnt(2)
	v_mfma_f32_32x32x16_bf16 v[212:227], v[74:77], v[42:45], v[212:227]
	v_max_f32_e32 v210, 0, v12
	v_max_f32_e32 v211, 0, v13
	v_pk_fma_f32 v[50:51], v[250:251], v[210:211], v[50:51]
	v_max_f32_e32 v108, 0, v14
	v_max_f32_e32 v109, 0, v15
	v_pk_fma_f32 v[50:51], v[252:253], v[108:109], v[50:51]
	v_max_f32_e32 v210, 0, v16
	v_max_f32_e32 v211, 0, v17
	v_pk_fma_f32 v[50:51], v[254:255], v[210:211], v[50:51]
	s_waitcnt lgkmcnt(1)
	v_mfma_f32_32x32x16_bf16 v[212:227], v[78:81], v[46:49], v[212:227]
	v_max_f32_e32 v108, 0, v18
	v_max_f32_e32 v109, 0, v19
	v_pk_fma_f32 v[50:51], v[200:201], v[108:109], v[50:51]
	v_max_f32_e32 v210, 0, v20
	v_max_f32_e32 v211, 0, v21
	v_pk_fma_f32 v[50:51], v[202:203], v[210:211], v[50:51]
	v_add_f32_e32 v50, v50, v51
	v_ashrrev_i32_e32 v51, 31, v50
	s_waitcnt lgkmcnt(0)
	v_mfma_f32_32x32x16_bf16 v[212:227], v[82:85], v[196:199], v[212:227]
	v_or_b32_e32 v51, 0x80000000, v51
	s_cmpk_gt_i32 s11, 88
	s_cselect_b64 vcc, -1, 0
	v_xor_b32_e32 v50, v51, v50
	v_cndmask_b32_e32 v50, v123, v50, vcc
	global_store_dword v243, v50, s[8:9] offset:2048
	s_add_u32 s8, s8, 0x1000
	s_addc_u32 s9, s9, 0
	v_mfma_f32_32x32x16_bf16 v[6:21], v[86:89], v[38:41], 0
	s_add_i32 m0, s10, 98304
	s_nop 0
	global_load_lds_dwordx4 v102, s[6:7]
	s_add_i32 m0, s10, 99328
	s_nop 0
	global_load_lds_dwordx4 v110, s[6:7]
	s_add_i32 m0, s10, 100352
	s_nop 0
	global_load_lds_dwordx4 v112, s[6:7]
	s_add_i32 m0, s10, 101376
	s_nop 0
	global_load_lds_dwordx4 v193, s[6:7]
	s_add_u32 s6, s6, 0x8000
	s_addc_u32 s7, s7, 0
	v_max_f32_e32 v108, 0, v212
	v_max_f32_e32 v109, 0, v213
	v_pk_mul_f32 v[0:1], v[22:23], v[108:109]
	v_max_f32_e32 v210, 0, v214
	v_max_f32_e32 v211, 0, v215
	v_pk_fma_f32 v[0:1], v[24:25], v[210:211], v[0:1]
	v_max_f32_e32 v108, 0, v216
	v_max_f32_e32 v109, 0, v217
	v_pk_fma_f32 v[0:1], v[26:27], v[108:109], v[0:1]
	v_mfma_f32_32x32x16_bf16 v[6:21], v[90:93], v[42:45], v[6:21]
	v_max_f32_e32 v210, 0, v218
	v_max_f32_e32 v211, 0, v219
	v_pk_fma_f32 v[0:1], v[28:29], v[210:211], v[0:1]
	v_max_f32_e32 v108, 0, v220
	v_max_f32_e32 v109, 0, v221
	v_pk_fma_f32 v[0:1], v[30:31], v[108:109], v[0:1]
	v_max_f32_e32 v210, 0, v222
	v_max_f32_e32 v211, 0, v223
	v_pk_fma_f32 v[0:1], v[32:33], v[210:211], v[0:1]
	v_mfma_f32_32x32x16_bf16 v[6:21], v[94:97], v[46:49], v[6:21]
	v_max_f32_e32 v108, 0, v224
	v_max_f32_e32 v109, 0, v225
	v_pk_fma_f32 v[0:1], v[34:35], v[108:109], v[0:1]
	v_max_f32_e32 v210, 0, v226
	v_max_f32_e32 v211, 0, v227
	v_pk_fma_f32 v[0:1], v[36:37], v[210:211], v[0:1]
	v_add_f32_e32 v0, v0, v1
	v_ashrrev_i32_e32 v1, 31, v0
	v_mfma_f32_32x32x16_bf16 v[6:21], v[98:101], v[196:199], v[6:21]
	s_waitcnt vmcnt(10)
	ds_read_b128 v[38:41], v5 offset:43264
	ds_read_b128 v[42:45], v52 offset:43264
	ds_read_b128 v[46:49], v55 offset:43264
	ds_read_b128 v[196:199], v56 offset:43264
	v_or_b32_e32 v1, 0x80000000, v1
	s_cmpk_gt_i32 s11, 96
	s_cselect_b64 vcc, -1, 0
	v_xor_b32_e32 v0, v1, v0
	v_cndmask_b32_e32 v146, v123, v0, vcc
	s_nop 3
	s_waitcnt lgkmcnt(3)
	v_mfma_f32_32x32x16_bf16 v[212:227], v[70:73], v[38:41], 0
	v_max_f32_e32 v108, 0, v6
	v_max_f32_e32 v109, 0, v7
	v_pk_mul_f32 v[50:51], v[244:245], v[108:109]
	v_max_f32_e32 v210, 0, v8
	v_max_f32_e32 v211, 0, v9
	v_pk_fma_f32 v[50:51], v[246:247], v[210:211], v[50:51]
	v_max_f32_e32 v108, 0, v10
	v_max_f32_e32 v109, 0, v11
	v_pk_fma_f32 v[50:51], v[248:249], v[108:109], v[50:51]
	s_waitcnt lgkmcnt(2)
	v_mfma_f32_32x32x16_bf16 v[212:227], v[74:77], v[42:45], v[212:227]
	v_max_f32_e32 v210, 0, v12
	v_max_f32_e32 v211, 0, v13
	v_pk_fma_f32 v[50:51], v[250:251], v[210:211], v[50:51]
	v_max_f32_e32 v108, 0, v14
	v_max_f32_e32 v109, 0, v15
	v_pk_fma_f32 v[50:51], v[252:253], v[108:109], v[50:51]
	v_max_f32_e32 v210, 0, v16
	v_max_f32_e32 v211, 0, v17
	v_pk_fma_f32 v[50:51], v[254:255], v[210:211], v[50:51]
	s_waitcnt lgkmcnt(1)
	v_mfma_f32_32x32x16_bf16 v[212:227], v[78:81], v[46:49], v[212:227]
	v_max_f32_e32 v108, 0, v18
	v_max_f32_e32 v109, 0, v19
	v_pk_fma_f32 v[50:51], v[200:201], v[108:109], v[50:51]
	v_max_f32_e32 v210, 0, v20
	v_max_f32_e32 v211, 0, v21
	v_pk_fma_f32 v[50:51], v[202:203], v[210:211], v[50:51]
	v_add_f32_e32 v50, v50, v51
	v_ashrrev_i32_e32 v51, 31, v50
	s_waitcnt lgkmcnt(0)
	v_mfma_f32_32x32x16_bf16 v[212:227], v[82:85], v[196:199], v[212:227]
	v_or_b32_e32 v51, 0x80000000, v51
	s_cmpk_gt_i32 s11, 96
	s_cselect_b64 vcc, -1, 0
	v_xor_b32_e32 v50, v51, v50
	v_cndmask_b32_e32 v50, v123, v50, vcc
	global_store_dword v243, v50, s[8:9]
	v_mfma_f32_32x32x16_bf16 v[6:21], v[86:89], v[38:41], 0
	s_add_i32 m0, s10, 0
	s_nop 0
	global_load_lds_dwordx4 v102, s[6:7]
	s_add_i32 m0, s10, 1024
	s_nop 0
	global_load_lds_dwordx4 v110, s[6:7]
	s_add_i32 m0, s10, 2048
	s_nop 0
	global_load_lds_dwordx4 v112, s[6:7]
	s_add_i32 m0, s10, 3072
	s_nop 0
	global_load_lds_dwordx4 v193, s[6:7]
	s_add_u32 s6, s6, 0x8000
	s_addc_u32 s7, s7, 0
	v_max_f32_e32 v108, 0, v212
	v_max_f32_e32 v109, 0, v213
	v_pk_mul_f32 v[0:1], v[22:23], v[108:109]
	v_max_f32_e32 v210, 0, v214
	v_max_f32_e32 v211, 0, v215
	v_pk_fma_f32 v[0:1], v[24:25], v[210:211], v[0:1]
	v_max_f32_e32 v108, 0, v216
	v_max_f32_e32 v109, 0, v217
	v_pk_fma_f32 v[0:1], v[26:27], v[108:109], v[0:1]
	v_mfma_f32_32x32x16_bf16 v[6:21], v[90:93], v[42:45], v[6:21]
	v_max_f32_e32 v210, 0, v218
	v_max_f32_e32 v211, 0, v219
	v_pk_fma_f32 v[0:1], v[28:29], v[210:211], v[0:1]
	v_max_f32_e32 v108, 0, v220
	v_max_f32_e32 v109, 0, v221
	v_pk_fma_f32 v[0:1], v[30:31], v[108:109], v[0:1]
	v_max_f32_e32 v210, 0, v222
	v_max_f32_e32 v211, 0, v223
	v_pk_fma_f32 v[0:1], v[32:33], v[210:211], v[0:1]
	v_mfma_f32_32x32x16_bf16 v[6:21], v[94:97], v[46:49], v[6:21]
	v_max_f32_e32 v108, 0, v224
	v_max_f32_e32 v109, 0, v225
	v_pk_fma_f32 v[0:1], v[34:35], v[108:109], v[0:1]
	v_max_f32_e32 v210, 0, v226
	v_max_f32_e32 v211, 0, v227
	v_pk_fma_f32 v[0:1], v[36:37], v[210:211], v[0:1]
	v_add_f32_e32 v0, v0, v1
	v_ashrrev_i32_e32 v1, 31, v0
	v_mfma_f32_32x32x16_bf16 v[6:21], v[98:101], v[196:199], v[6:21]
	s_waitcnt vmcnt(10)
	v_add_u32_e32 v228, 0x10000, v5
	ds_read_b128 v[38:41], v228 offset:10496
	v_add_u32_e32 v228, 0x10000, v52
	ds_read_b128 v[42:45], v228 offset:10496
	v_add_u32_e32 v228, 0x10000, v55
	ds_read_b128 v[46:49], v228 offset:10496
	v_add_u32_e32 v228, 0x10000, v56
	ds_read_b128 v[196:199], v228 offset:10496
	v_or_b32_e32 v1, 0x80000000, v1
	s_cmpk_gt_i32 s11, 104
	s_cselect_b64 vcc, -1, 0
	v_xor_b32_e32 v0, v1, v0
	v_cndmask_b32_e32 v145, v123, v0, vcc
	s_nop 3
	s_waitcnt lgkmcnt(3)
	v_mfma_f32_32x32x16_bf16 v[212:227], v[70:73], v[38:41], 0
	v_max_f32_e32 v108, 0, v6
	v_max_f32_e32 v109, 0, v7
	v_pk_mul_f32 v[50:51], v[244:245], v[108:109]
	v_max_f32_e32 v210, 0, v8
	v_max_f32_e32 v211, 0, v9
	v_pk_fma_f32 v[50:51], v[246:247], v[210:211], v[50:51]
	v_max_f32_e32 v108, 0, v10
	v_max_f32_e32 v109, 0, v11
	v_pk_fma_f32 v[50:51], v[248:249], v[108:109], v[50:51]
	s_waitcnt lgkmcnt(2)
	v_mfma_f32_32x32x16_bf16 v[212:227], v[74:77], v[42:45], v[212:227]
	v_max_f32_e32 v210, 0, v12
	v_max_f32_e32 v211, 0, v13
	v_pk_fma_f32 v[50:51], v[250:251], v[210:211], v[50:51]
	v_max_f32_e32 v108, 0, v14
	v_max_f32_e32 v109, 0, v15
	v_pk_fma_f32 v[50:51], v[252:253], v[108:109], v[50:51]
	v_max_f32_e32 v210, 0, v16
	v_max_f32_e32 v211, 0, v17
	v_pk_fma_f32 v[50:51], v[254:255], v[210:211], v[50:51]
	s_waitcnt lgkmcnt(1)
	v_mfma_f32_32x32x16_bf16 v[212:227], v[78:81], v[46:49], v[212:227]
	v_max_f32_e32 v108, 0, v18
	v_max_f32_e32 v109, 0, v19
	v_pk_fma_f32 v[50:51], v[200:201], v[108:109], v[50:51]
	v_max_f32_e32 v210, 0, v20
	v_max_f32_e32 v211, 0, v21
	v_pk_fma_f32 v[50:51], v[202:203], v[210:211], v[50:51]
	v_add_f32_e32 v50, v50, v51
	v_ashrrev_i32_e32 v51, 31, v50
	s_waitcnt lgkmcnt(0)
	v_mfma_f32_32x32x16_bf16 v[212:227], v[82:85], v[196:199], v[212:227]
	v_or_b32_e32 v51, 0x80000000, v51
	s_cmpk_gt_i32 s11, 104
	s_cselect_b64 vcc, -1, 0
	v_xor_b32_e32 v50, v51, v50
	v_cndmask_b32_e32 v50, v123, v50, vcc
	global_store_dword v243, v50, s[8:9] offset:2048
	s_add_u32 s8, s8, 0x1000
	s_addc_u32 s9, s9, 0
	v_mfma_f32_32x32x16_bf16 v[6:21], v[86:89], v[38:41], 0
	s_add_i32 m0, s10, 32768
	s_nop 0
	global_load_lds_dwordx4 v102, s[6:7]
	s_add_i32 m0, s10, 33792
	s_nop 0
	global_load_lds_dwordx4 v110, s[6:7]
	s_add_i32 m0, s10, 34816
	s_nop 0
	global_load_lds_dwordx4 v112, s[6:7]
	s_add_i32 m0, s10, 35840
	s_nop 0
	global_load_lds_dwordx4 v193, s[6:7]
	s_add_u32 s6, s6, 0x8000
	s_addc_u32 s7, s7, 0
	v_max_f32_e32 v108, 0, v212
	v_max_f32_e32 v109, 0, v213
	v_pk_mul_f32 v[0:1], v[22:23], v[108:109]
	v_max_f32_e32 v210, 0, v214
	v_max_f32_e32 v211, 0, v215
	v_pk_fma_f32 v[0:1], v[24:25], v[210:211], v[0:1]
	v_max_f32_e32 v108, 0, v216
	v_max_f32_e32 v109, 0, v217
	v_pk_fma_f32 v[0:1], v[26:27], v[108:109], v[0:1]
	v_mfma_f32_32x32x16_bf16 v[6:21], v[90:93], v[42:45], v[6:21]
	v_max_f32_e32 v210, 0, v218
	v_max_f32_e32 v211, 0, v219
	v_pk_fma_f32 v[0:1], v[28:29], v[210:211], v[0:1]
	v_max_f32_e32 v108, 0, v220
	v_max_f32_e32 v109, 0, v221
	v_pk_fma_f32 v[0:1], v[30:31], v[108:109], v[0:1]
	v_max_f32_e32 v210, 0, v222
	v_max_f32_e32 v211, 0, v223
	v_pk_fma_f32 v[0:1], v[32:33], v[210:211], v[0:1]
	v_mfma_f32_32x32x16_bf16 v[6:21], v[94:97], v[46:49], v[6:21]
	v_max_f32_e32 v108, 0, v224
	v_max_f32_e32 v109, 0, v225
	v_pk_fma_f32 v[0:1], v[34:35], v[108:109], v[0:1]
	v_max_f32_e32 v210, 0, v226
	v_max_f32_e32 v211, 0, v227
	v_pk_fma_f32 v[0:1], v[36:37], v[210:211], v[0:1]
	v_add_f32_e32 v0, v0, v1
	v_ashrrev_i32_e32 v1, 31, v0
	v_mfma_f32_32x32x16_bf16 v[6:21], v[98:101], v[196:199], v[6:21]
	s_waitcnt vmcnt(10)
	v_add_u32_e32 v228, 0x10000, v5
	ds_read_b128 v[38:41], v228 offset:43264
	v_add_u32_e32 v228, 0x10000, v52
	ds_read_b128 v[42:45], v228 offset:43264
	v_add_u32_e32 v228, 0x10000, v55
	ds_read_b128 v[46:49], v228 offset:43264
	v_add_u32_e32 v228, 0x10000, v56
	ds_read_b128 v[196:199], v228 offset:43264
	v_or_b32_e32 v1, 0x80000000, v1
	s_cmpk_gt_i32 s11, 112
	s_cselect_b64 vcc, -1, 0
	v_xor_b32_e32 v0, v1, v0
	v_cndmask_b32_e32 v147, v123, v0, vcc
	s_nop 3
	s_waitcnt lgkmcnt(3)
	v_mfma_f32_32x32x16_bf16 v[212:227], v[70:73], v[38:41], 0
	v_max_f32_e32 v108, 0, v6
	v_max_f32_e32 v109, 0, v7
	v_pk_mul_f32 v[50:51], v[244:245], v[108:109]
	v_max_f32_e32 v210, 0, v8
	v_max_f32_e32 v211, 0, v9
	v_pk_fma_f32 v[50:51], v[246:247], v[210:211], v[50:51]
	v_max_f32_e32 v108, 0, v10
	v_max_f32_e32 v109, 0, v11
	v_pk_fma_f32 v[50:51], v[248:249], v[108:109], v[50:51]
	s_waitcnt lgkmcnt(2)
	v_mfma_f32_32x32x16_bf16 v[212:227], v[74:77], v[42:45], v[212:227]
	v_max_f32_e32 v210, 0, v12
	v_max_f32_e32 v211, 0, v13
	v_pk_fma_f32 v[50:51], v[250:251], v[210:211], v[50:51]
	v_max_f32_e32 v108, 0, v14
	v_max_f32_e32 v109, 0, v15
	v_pk_fma_f32 v[50:51], v[252:253], v[108:109], v[50:51]
	v_max_f32_e32 v210, 0, v16
	v_max_f32_e32 v211, 0, v17
	v_pk_fma_f32 v[50:51], v[254:255], v[210:211], v[50:51]
	s_waitcnt lgkmcnt(1)
	v_mfma_f32_32x32x16_bf16 v[212:227], v[78:81], v[46:49], v[212:227]
	v_max_f32_e32 v108, 0, v18
	v_max_f32_e32 v109, 0, v19
	v_pk_fma_f32 v[50:51], v[200:201], v[108:109], v[50:51]
	v_max_f32_e32 v210, 0, v20
	v_max_f32_e32 v211, 0, v21
	v_pk_fma_f32 v[50:51], v[202:203], v[210:211], v[50:51]
	v_add_f32_e32 v50, v50, v51
	v_ashrrev_i32_e32 v51, 31, v50
	s_waitcnt lgkmcnt(0)
	v_mfma_f32_32x32x16_bf16 v[212:227], v[82:85], v[196:199], v[212:227]
	v_or_b32_e32 v51, 0x80000000, v51
	s_cmpk_gt_i32 s11, 112
	s_cselect_b64 vcc, -1, 0
	v_xor_b32_e32 v50, v51, v50
	v_cndmask_b32_e32 v50, v123, v50, vcc
	global_store_dword v243, v50, s[8:9]
	v_mfma_f32_32x32x16_bf16 v[6:21], v[86:89], v[38:41], 0
	s_add_i32 m0, s10, 65536
	s_nop 0
	global_load_lds_dwordx4 v102, s[6:7]
	s_add_i32 m0, s10, 66560
	s_nop 0
	global_load_lds_dwordx4 v110, s[6:7]
	s_add_i32 m0, s10, 67584
	s_nop 0
	global_load_lds_dwordx4 v112, s[6:7]
	s_add_i32 m0, s10, 68608
	s_nop 0
	global_load_lds_dwordx4 v193, s[6:7]
	s_add_u32 s6, s6, 0x8000
	s_addc_u32 s7, s7, 0
	v_max_f32_e32 v108, 0, v212
	v_max_f32_e32 v109, 0, v213
	v_pk_mul_f32 v[0:1], v[22:23], v[108:109]
	v_max_f32_e32 v210, 0, v214
	v_max_f32_e32 v211, 0, v215
	v_pk_fma_f32 v[0:1], v[24:25], v[210:211], v[0:1]
	v_max_f32_e32 v108, 0, v216
	v_max_f32_e32 v109, 0, v217
	v_pk_fma_f32 v[0:1], v[26:27], v[108:109], v[0:1]
	v_mfma_f32_32x32x16_bf16 v[6:21], v[90:93], v[42:45], v[6:21]
	v_max_f32_e32 v210, 0, v218
	v_max_f32_e32 v211, 0, v219
	v_pk_fma_f32 v[0:1], v[28:29], v[210:211], v[0:1]
	v_max_f32_e32 v108, 0, v220
	v_max_f32_e32 v109, 0, v221
	v_pk_fma_f32 v[0:1], v[30:31], v[108:109], v[0:1]
	v_max_f32_e32 v210, 0, v222
	v_max_f32_e32 v211, 0, v223
	v_pk_fma_f32 v[0:1], v[32:33], v[210:211], v[0:1]
	v_mfma_f32_32x32x16_bf16 v[6:21], v[94:97], v[46:49], v[6:21]
	v_max_f32_e32 v108, 0, v224
	v_max_f32_e32 v109, 0, v225
	v_pk_fma_f32 v[0:1], v[34:35], v[108:109], v[0:1]
	v_max_f32_e32 v210, 0, v226
	v_max_f32_e32 v211, 0, v227
	v_pk_fma_f32 v[0:1], v[36:37], v[210:211], v[0:1]
	v_add_f32_e32 v0, v0, v1
	v_ashrrev_i32_e32 v1, 31, v0
	v_mfma_f32_32x32x16_bf16 v[6:21], v[98:101], v[196:199], v[6:21]
	s_waitcnt vmcnt(10)
	ds_read_b128 v[38:41], v5 offset:10496
	ds_read_b128 v[42:45], v52 offset:10496
	ds_read_b128 v[46:49], v55 offset:10496
	ds_read_b128 v[196:199], v56 offset:10496
	v_or_b32_e32 v1, 0x80000000, v1
	s_cmpk_gt_i32 s11, 120
	s_cselect_b64 vcc, -1, 0
	v_xor_b32_e32 v0, v1, v0
	v_cndmask_b32_e32 v136, v123, v0, vcc
	s_nop 3
	v_max_f32_e32 v108, 0, v6
	v_max_f32_e32 v109, 0, v7
	v_pk_mul_f32 v[50:51], v[244:245], v[108:109]
	v_max_f32_e32 v210, 0, v8
	v_max_f32_e32 v211, 0, v9
	v_pk_fma_f32 v[50:51], v[246:247], v[210:211], v[50:51]
	v_max_f32_e32 v108, 0, v10
	v_max_f32_e32 v109, 0, v11
	v_pk_fma_f32 v[50:51], v[248:249], v[108:109], v[50:51]
	v_max_f32_e32 v210, 0, v12
	v_max_f32_e32 v211, 0, v13
	v_pk_fma_f32 v[50:51], v[250:251], v[210:211], v[50:51]
	v_max_f32_e32 v108, 0, v14
	v_max_f32_e32 v109, 0, v15
	v_pk_fma_f32 v[50:51], v[252:253], v[108:109], v[50:51]
	v_max_f32_e32 v210, 0, v16
	v_max_f32_e32 v211, 0, v17
	v_pk_fma_f32 v[50:51], v[254:255], v[210:211], v[50:51]
	v_max_f32_e32 v108, 0, v18
	v_max_f32_e32 v109, 0, v19
	v_pk_fma_f32 v[50:51], v[200:201], v[108:109], v[50:51]
	v_max_f32_e32 v210, 0, v20
	v_max_f32_e32 v211, 0, v21
	v_pk_fma_f32 v[50:51], v[202:203], v[210:211], v[50:51]
	v_add_f32_e32 v50, v50, v51
	v_ashrrev_i32_e32 v51, 31, v50
	v_or_b32_e32 v51, 0x80000000, v51
	s_cmpk_gt_i32 s11, 120
	s_cselect_b64 vcc, -1, 0
	v_xor_b32_e32 v50, v51, v50
	v_cndmask_b32_e32 v50, v123, v50, vcc
	global_store_dword v243, v50, s[8:9] offset:2048
	s_add_u32 s8, s8, 0x1000
	s_addc_u32 s9, s9, 0
	s_cmpk_gt_i32 s81, 16
	s_cbranch_scc0 .Lix_fill_2
	s_waitcnt lgkmcnt(3)
	v_mfma_f32_32x32x16_bf16 v[212:227], v[70:73], v[38:41], 0
	s_add_i32 m0, s10, 98304
	s_nop 0
	global_load_lds_dwordx4 v102, s[6:7]
	s_waitcnt lgkmcnt(2)
	v_mfma_f32_32x32x16_bf16 v[212:227], v[74:77], v[42:45], v[212:227]
	s_add_i32 m0, s10, 99328
	s_nop 0
	global_load_lds_dwordx4 v110, s[6:7]
	s_waitcnt lgkmcnt(1)
	v_mfma_f32_32x32x16_bf16 v[212:227], v[78:81], v[46:49], v[212:227]
	s_add_i32 m0, s10, 100352
	s_nop 0
	global_load_lds_dwordx4 v112, s[6:7]
	s_waitcnt lgkmcnt(0)
	v_mfma_f32_32x32x16_bf16 v[212:227], v[82:85], v[196:199], v[212:227]
	s_add_i32 m0, s10, 101376
	s_nop 0
	global_load_lds_dwordx4 v193, s[6:7]
	s_add_u32 s6, s6, 0x8000
	s_addc_u32 s7, s7, 0
	v_mfma_f32_32x32x16_bf16 v[6:21], v[86:89], v[38:41], 0
	s_nop 7
	s_nop 2
	v_max_f32_e32 v108, 0, v212
	v_max_f32_e32 v109, 0, v213
	v_pk_mul_f32 v[0:1], v[22:23], v[108:109]
	v_max_f32_e32 v210, 0, v214
	v_max_f32_e32 v211, 0, v215
	v_pk_fma_f32 v[0:1], v[24:25], v[210:211], v[0:1]
	v_max_f32_e32 v108, 0, v216
	v_max_f32_e32 v109, 0, v217
	v_pk_fma_f32 v[0:1], v[26:27], v[108:109], v[0:1]
	v_mfma_f32_32x32x16_bf16 v[6:21], v[90:93], v[42:45], v[6:21]
	v_max_f32_e32 v210, 0, v218
	v_max_f32_e32 v211, 0, v219
	v_pk_fma_f32 v[0:1], v[28:29], v[210:211], v[0:1]
	v_max_f32_e32 v108, 0, v220
	v_max_f32_e32 v109, 0, v221
	v_pk_fma_f32 v[0:1], v[30:31], v[108:109], v[0:1]
	v_max_f32_e32 v210, 0, v222
	v_max_f32_e32 v211, 0, v223
	v_pk_fma_f32 v[0:1], v[32:33], v[210:211], v[0:1]
	v_mfma_f32_32x32x16_bf16 v[6:21], v[94:97], v[46:49], v[6:21]
	v_max_f32_e32 v108, 0, v224
	v_max_f32_e32 v109, 0, v225
	v_pk_fma_f32 v[0:1], v[34:35], v[108:109], v[0:1]
	v_max_f32_e32 v210, 0, v226
	v_max_f32_e32 v211, 0, v227
	v_pk_fma_f32 v[0:1], v[36:37], v[210:211], v[0:1]
	v_add_f32_e32 v0, v0, v1
	v_ashrrev_i32_e32 v1, 31, v0
	v_mfma_f32_32x32x16_bf16 v[6:21], v[98:101], v[196:199], v[6:21]
	s_waitcnt vmcnt(10)
	ds_read_b128 v[38:41], v5 offset:43264
	ds_read_b128 v[42:45], v52 offset:43264
	ds_read_b128 v[46:49], v55 offset:43264
	ds_read_b128 v[196:199], v56 offset:43264
	v_or_b32_e32 v1, 0x80000000, v1
	s_cmpk_gt_i32 s11, 128
	s_cselect_b64 vcc, -1, 0
	v_xor_b32_e32 v0, v1, v0
	v_cndmask_b32_e32 v149, v123, v0, vcc
	s_nop 3
	s_waitcnt lgkmcnt(3)
	v_mfma_f32_32x32x16_bf16 v[212:227], v[70:73], v[38:41], 0
	v_max_f32_e32 v108, 0, v6
	v_max_f32_e32 v109, 0, v7
	v_pk_mul_f32 v[50:51], v[244:245], v[108:109]
	v_max_f32_e32 v210, 0, v8
	v_max_f32_e32 v211, 0, v9
	v_pk_fma_f32 v[50:51], v[246:247], v[210:211], v[50:51]
	v_max_f32_e32 v108, 0, v10
	v_max_f32_e32 v109, 0, v11
	v_pk_fma_f32 v[50:51], v[248:249], v[108:109], v[50:51]
	s_waitcnt lgkmcnt(2)
	v_mfma_f32_32x32x16_bf16 v[212:227], v[74:77], v[42:45], v[212:227]
	v_max_f32_e32 v210, 0, v12
	v_max_f32_e32 v211, 0, v13
	v_pk_fma_f32 v[50:51], v[250:251], v[210:211], v[50:51]
	v_max_f32_e32 v108, 0, v14
	v_max_f32_e32 v109, 0, v15
	v_pk_fma_f32 v[50:51], v[252:253], v[108:109], v[50:51]
	v_max_f32_e32 v210, 0, v16
	v_max_f32_e32 v211, 0, v17
	v_pk_fma_f32 v[50:51], v[254:255], v[210:211], v[50:51]
	s_waitcnt lgkmcnt(1)
	v_mfma_f32_32x32x16_bf16 v[212:227], v[78:81], v[46:49], v[212:227]
	v_max_f32_e32 v108, 0, v18
	v_max_f32_e32 v109, 0, v19
	v_pk_fma_f32 v[50:51], v[200:201], v[108:109], v[50:51]
	v_max_f32_e32 v210, 0, v20
	v_max_f32_e32 v211, 0, v21
	v_pk_fma_f32 v[50:51], v[202:203], v[210:211], v[50:51]
	v_add_f32_e32 v50, v50, v51
	v_ashrrev_i32_e32 v51, 31, v50
	s_waitcnt lgkmcnt(0)
	v_mfma_f32_32x32x16_bf16 v[212:227], v[82:85], v[196:199], v[212:227]
	v_or_b32_e32 v51, 0x80000000, v51
	s_cmpk_gt_i32 s11, 128
	s_cselect_b64 vcc, -1, 0
	v_xor_b32_e32 v50, v51, v50
	v_cndmask_b32_e32 v50, v123, v50, vcc
	global_store_dword v243, v50, s[8:9]
	v_mfma_f32_32x32x16_bf16 v[6:21], v[86:89], v[38:41], 0
	s_add_i32 m0, s10, 0
	s_nop 0
	global_load_lds_dwordx4 v102, s[6:7]
	s_add_i32 m0, s10, 1024
	s_nop 0
	global_load_lds_dwordx4 v110, s[6:7]
	s_add_i32 m0, s10, 2048
	s_nop 0
	global_load_lds_dwordx4 v112, s[6:7]
	s_add_i32 m0, s10, 3072
	s_nop 0
	global_load_lds_dwordx4 v193, s[6:7]
	s_add_u32 s6, s6, 0x8000
	s_addc_u32 s7, s7, 0
	v_max_f32_e32 v108, 0, v212
	v_max_f32_e32 v109, 0, v213
	v_pk_mul_f32 v[0:1], v[22:23], v[108:109]
	v_max_f32_e32 v210, 0, v214
	v_max_f32_e32 v211, 0, v215
	v_pk_fma_f32 v[0:1], v[24:25], v[210:211], v[0:1]
	v_max_f32_e32 v108, 0, v216
	v_max_f32_e32 v109, 0, v217
	v_pk_fma_f32 v[0:1], v[26:27], v[108:109], v[0:1]
	v_mfma_f32_32x32x16_bf16 v[6:21], v[90:93], v[42:45], v[6:21]
	v_max_f32_e32 v210, 0, v218
	v_max_f32_e32 v211, 0, v219
	v_pk_fma_f32 v[0:1], v[28:29], v[210:211], v[0:1]
	v_max_f32_e32 v108, 0, v220
	v_max_f32_e32 v109, 0, v221
	v_pk_fma_f32 v[0:1], v[30:31], v[108:109], v[0:1]
	v_max_f32_e32 v210, 0, v222
	v_max_f32_e32 v211, 0, v223
	v_pk_fma_f32 v[0:1], v[32:33], v[210:211], v[0:1]
	v_mfma_f32_32x32x16_bf16 v[6:21], v[94:97], v[46:49], v[6:21]
	v_max_f32_e32 v108, 0, v224
	v_max_f32_e32 v109, 0, v225
	v_pk_fma_f32 v[0:1], v[34:35], v[108:109], v[0:1]
	v_max_f32_e32 v210, 0, v226
	v_max_f32_e32 v211, 0, v227
	v_pk_fma_f32 v[0:1], v[36:37], v[210:211], v[0:1]
	v_add_f32_e32 v0, v0, v1
	v_ashrrev_i32_e32 v1, 31, v0
	v_mfma_f32_32x32x16_bf16 v[6:21], v[98:101], v[196:199], v[6:21]
	s_waitcnt vmcnt(10)
	v_add_u32_e32 v228, 0x10000, v5
	ds_read_b128 v[38:41], v228 offset:10496
	v_add_u32_e32 v228, 0x10000, v52
	ds_read_b128 v[42:45], v228 offset:10496
	v_add_u32_e32 v228, 0x10000, v55
	ds_read_b128 v[46:49], v228 offset:10496
	v_add_u32_e32 v228, 0x10000, v56
	ds_read_b128 v[196:199], v228 offset:10496
	v_or_b32_e32 v1, 0x80000000, v1
	s_cmpk_gt_i32 s11, 136
	s_cselect_b64 vcc, -1, 0
	v_xor_b32_e32 v0, v1, v0
	v_cndmask_b32_e32 v148, v123, v0, vcc
	s_nop 3
	s_waitcnt lgkmcnt(3)
	v_mfma_f32_32x32x16_bf16 v[212:227], v[70:73], v[38:41], 0
	v_max_f32_e32 v108, 0, v6
	v_max_f32_e32 v109, 0, v7
	v_pk_mul_f32 v[50:51], v[244:245], v[108:109]
	v_max_f32_e32 v210, 0, v8
	v_max_f32_e32 v211, 0, v9
	v_pk_fma_f32 v[50:51], v[246:247], v[210:211], v[50:51]
	v_max_f32_e32 v108, 0, v10
	v_max_f32_e32 v109, 0, v11
	v_pk_fma_f32 v[50:51], v[248:249], v[108:109], v[50:51]
	s_waitcnt lgkmcnt(2)
	v_mfma_f32_32x32x16_bf16 v[212:227], v[74:77], v[42:45], v[212:227]
	v_max_f32_e32 v210, 0, v12
	v_max_f32_e32 v211, 0, v13
	v_pk_fma_f32 v[50:51], v[250:251], v[210:211], v[50:51]
	v_max_f32_e32 v108, 0, v14
	v_max_f32_e32 v109, 0, v15
	v_pk_fma_f32 v[50:51], v[252:253], v[108:109], v[50:51]
	v_max_f32_e32 v210, 0, v16
	v_max_f32_e32 v211, 0, v17
	v_pk_fma_f32 v[50:51], v[254:255], v[210:211], v[50:51]
	s_waitcnt lgkmcnt(1)
	v_mfma_f32_32x32x16_bf16 v[212:227], v[78:81], v[46:49], v[212:227]
	v_max_f32_e32 v108, 0, v18
	v_max_f32_e32 v109, 0, v19
	v_pk_fma_f32 v[50:51], v[200:201], v[108:109], v[50:51]
	v_max_f32_e32 v210, 0, v20
	v_max_f32_e32 v211, 0, v21
	v_pk_fma_f32 v[50:51], v[202:203], v[210:211], v[50:51]
	v_add_f32_e32 v50, v50, v51
	v_ashrrev_i32_e32 v51, 31, v50
	s_waitcnt lgkmcnt(0)
	v_mfma_f32_32x32x16_bf16 v[212:227], v[82:85], v[196:199], v[212:227]
	v_or_b32_e32 v51, 0x80000000, v51
	s_cmpk_gt_i32 s11, 136
	s_cselect_b64 vcc, -1, 0
	v_xor_b32_e32 v50, v51, v50
	v_cndmask_b32_e32 v50, v123, v50, vcc
	global_store_dword v243, v50, s[8:9] offset:2048
	s_add_u32 s8, s8, 0x1000
	s_addc_u32 s9, s9, 0
	v_mfma_f32_32x32x16_bf16 v[6:21], v[86:89], v[38:41], 0
	s_add_i32 m0, s10, 32768
	s_nop 0
	global_load_lds_dwordx4 v102, s[6:7]
	s_add_i32 m0, s10, 33792
	s_nop 0
	global_load_lds_dwordx4 v110, s[6:7]
	s_add_i32 m0, s10, 34816
	s_nop 0
	global_load_lds_dwordx4 v112, s[6:7]
	s_add_i32 m0, s10, 35840
	s_nop 0
	global_load_lds_dwordx4 v193, s[6:7]
	s_add_u32 s6, s6, 0x8000
	s_addc_u32 s7, s7, 0
	v_max_f32_e32 v108, 0, v212
	v_max_f32_e32 v109, 0, v213
	v_pk_mul_f32 v[0:1], v[22:23], v[108:109]
	v_max_f32_e32 v210, 0, v214
	v_max_f32_e32 v211, 0, v215
	v_pk_fma_f32 v[0:1], v[24:25], v[210:211], v[0:1]
	v_max_f32_e32 v108, 0, v216
	v_max_f32_e32 v109, 0, v217
	v_pk_fma_f32 v[0:1], v[26:27], v[108:109], v[0:1]
	v_mfma_f32_32x32x16_bf16 v[6:21], v[90:93], v[42:45], v[6:21]
	v_max_f32_e32 v210, 0, v218
	v_max_f32_e32 v211, 0, v219
	v_pk_fma_f32 v[0:1], v[28:29], v[210:211], v[0:1]
	v_max_f32_e32 v108, 0, v220
	v_max_f32_e32 v109, 0, v221
	v_pk_fma_f32 v[0:1], v[30:31], v[108:109], v[0:1]
	v_max_f32_e32 v210, 0, v222
	v_max_f32_e32 v211, 0, v223
	v_pk_fma_f32 v[0:1], v[32:33], v[210:211], v[0:1]
	v_mfma_f32_32x32x16_bf16 v[6:21], v[94:97], v[46:49], v[6:21]
	v_max_f32_e32 v108, 0, v224
	v_max_f32_e32 v109, 0, v225
	v_pk_fma_f32 v[0:1], v[34:35], v[108:109], v[0:1]
	v_max_f32_e32 v210, 0, v226
	v_max_f32_e32 v211, 0, v227
	v_pk_fma_f32 v[0:1], v[36:37], v[210:211], v[0:1]
	v_add_f32_e32 v0, v0, v1
	v_ashrrev_i32_e32 v1, 31, v0
	v_mfma_f32_32x32x16_bf16 v[6:21], v[98:101], v[196:199], v[6:21]
	s_waitcnt vmcnt(10)
	v_add_u32_e32 v228, 0x10000, v5
	ds_read_b128 v[38:41], v228 offset:43264
	v_add_u32_e32 v228, 0x10000, v52
	ds_read_b128 v[42:45], v228 offset:43264
	v_add_u32_e32 v228, 0x10000, v55
	ds_read_b128 v[46:49], v228 offset:43264
	v_add_u32_e32 v228, 0x10000, v56
	ds_read_b128 v[196:199], v228 offset:43264
	v_or_b32_e32 v1, 0x80000000, v1
	s_cmpk_gt_i32 s11, 144
	s_cselect_b64 vcc, -1, 0
	v_xor_b32_e32 v0, v1, v0
	v_cndmask_b32_e32 v151, v123, v0, vcc
	s_nop 3
	s_waitcnt lgkmcnt(3)
	v_mfma_f32_32x32x16_bf16 v[212:227], v[70:73], v[38:41], 0
	v_max_f32_e32 v108, 0, v6
	v_max_f32_e32 v109, 0, v7
	v_pk_mul_f32 v[50:51], v[244:245], v[108:109]
	v_max_f32_e32 v210, 0, v8
	v_max_f32_e32 v211, 0, v9
	v_pk_fma_f32 v[50:51], v[246:247], v[210:211], v[50:51]
	v_max_f32_e32 v108, 0, v10
	v_max_f32_e32 v109, 0, v11
	v_pk_fma_f32 v[50:51], v[248:249], v[108:109], v[50:51]
	s_waitcnt lgkmcnt(2)
	v_mfma_f32_32x32x16_bf16 v[212:227], v[74:77], v[42:45], v[212:227]
	v_max_f32_e32 v210, 0, v12
	v_max_f32_e32 v211, 0, v13
	v_pk_fma_f32 v[50:51], v[250:251], v[210:211], v[50:51]
	v_max_f32_e32 v108, 0, v14
	v_max_f32_e32 v109, 0, v15
	v_pk_fma_f32 v[50:51], v[252:253], v[108:109], v[50:51]
	v_max_f32_e32 v210, 0, v16
	v_max_f32_e32 v211, 0, v17
	v_pk_fma_f32 v[50:51], v[254:255], v[210:211], v[50:51]
	s_waitcnt lgkmcnt(1)
	v_mfma_f32_32x32x16_bf16 v[212:227], v[78:81], v[46:49], v[212:227]
	v_max_f32_e32 v108, 0, v18
	v_max_f32_e32 v109, 0, v19
	v_pk_fma_f32 v[50:51], v[200:201], v[108:109], v[50:51]
	v_max_f32_e32 v210, 0, v20
	v_max_f32_e32 v211, 0, v21
	v_pk_fma_f32 v[50:51], v[202:203], v[210:211], v[50:51]
	v_add_f32_e32 v50, v50, v51
	v_ashrrev_i32_e32 v51, 31, v50
	s_waitcnt lgkmcnt(0)
	v_mfma_f32_32x32x16_bf16 v[212:227], v[82:85], v[196:199], v[212:227]
	v_or_b32_e32 v51, 0x80000000, v51
	s_cmpk_gt_i32 s11, 144
	s_cselect_b64 vcc, -1, 0
	v_xor_b32_e32 v50, v51, v50
	v_cndmask_b32_e32 v50, v123, v50, vcc
	global_store_dword v243, v50, s[8:9]
	v_mfma_f32_32x32x16_bf16 v[6:21], v[86:89], v[38:41], 0
	s_add_i32 m0, s10, 65536
	s_nop 0
	global_load_lds_dwordx4 v102, s[6:7]
	s_add_i32 m0, s10, 66560
	s_nop 0
	global_load_lds_dwordx4 v110, s[6:7]
	s_add_i32 m0, s10, 67584
	s_nop 0
	global_load_lds_dwordx4 v112, s[6:7]
	s_add_i32 m0, s10, 68608
	s_nop 0
	global_load_lds_dwordx4 v193, s[6:7]
	s_add_u32 s6, s6, 0x8000
	s_addc_u32 s7, s7, 0
	v_max_f32_e32 v108, 0, v212
	v_max_f32_e32 v109, 0, v213
	v_pk_mul_f32 v[0:1], v[22:23], v[108:109]
	v_max_f32_e32 v210, 0, v214
	v_max_f32_e32 v211, 0, v215
	v_pk_fma_f32 v[0:1], v[24:25], v[210:211], v[0:1]
	v_max_f32_e32 v108, 0, v216
	v_max_f32_e32 v109, 0, v217
	v_pk_fma_f32 v[0:1], v[26:27], v[108:109], v[0:1]
	v_mfma_f32_32x32x16_bf16 v[6:21], v[90:93], v[42:45], v[6:21]
	v_max_f32_e32 v210, 0, v218
	v_max_f32_e32 v211, 0, v219
	v_pk_fma_f32 v[0:1], v[28:29], v[210:211], v[0:1]
	v_max_f32_e32 v108, 0, v220
	v_max_f32_e32 v109, 0, v221
	v_pk_fma_f32 v[0:1], v[30:31], v[108:109], v[0:1]
	v_max_f32_e32 v210, 0, v222
	v_max_f32_e32 v211, 0, v223
	v_pk_fma_f32 v[0:1], v[32:33], v[210:211], v[0:1]
	v_mfma_f32_32x32x16_bf16 v[6:21], v[94:97], v[46:49], v[6:21]
	v_max_f32_e32 v108, 0, v224
	v_max_f32_e32 v109, 0, v225
	v_pk_fma_f32 v[0:1], v[34:35], v[108:109], v[0:1]
	v_max_f32_e32 v210, 0, v226
	v_max_f32_e32 v211, 0, v227
	v_pk_fma_f32 v[0:1], v[36:37], v[210:211], v[0:1]
	v_add_f32_e32 v0, v0, v1
	v_ashrrev_i32_e32 v1, 31, v0
	v_mfma_f32_32x32x16_bf16 v[6:21], v[98:101], v[196:199], v[6:21]
	s_waitcnt vmcnt(10)
	ds_read_b128 v[38:41], v5 offset:10496
	ds_read_b128 v[42:45], v52 offset:10496
	ds_read_b128 v[46:49], v55 offset:10496
	ds_read_b128 v[196:199], v56 offset:10496
	v_or_b32_e32 v1, 0x80000000, v1
	s_cmpk_gt_i32 s11, 152
	s_cselect_b64 vcc, -1, 0
	v_xor_b32_e32 v0, v1, v0
	v_cndmask_b32_e32 v150, v123, v0, vcc
	s_nop 3
	s_waitcnt lgkmcnt(3)
	v_mfma_f32_32x32x16_bf16 v[212:227], v[70:73], v[38:41], 0
	v_max_f32_e32 v108, 0, v6
	v_max_f32_e32 v109, 0, v7
	v_pk_mul_f32 v[50:51], v[244:245], v[108:109]
	v_max_f32_e32 v210, 0, v8
	v_max_f32_e32 v211, 0, v9
	v_pk_fma_f32 v[50:51], v[246:247], v[210:211], v[50:51]
	v_max_f32_e32 v108, 0, v10
	v_max_f32_e32 v109, 0, v11
	v_pk_fma_f32 v[50:51], v[248:249], v[108:109], v[50:51]
	s_waitcnt lgkmcnt(2)
	v_mfma_f32_32x32x16_bf16 v[212:227], v[74:77], v[42:45], v[212:227]
	v_max_f32_e32 v210, 0, v12
	v_max_f32_e32 v211, 0, v13
	v_pk_fma_f32 v[50:51], v[250:251], v[210:211], v[50:51]
	v_max_f32_e32 v108, 0, v14
	v_max_f32_e32 v109, 0, v15
	v_pk_fma_f32 v[50:51], v[252:253], v[108:109], v[50:51]
	v_max_f32_e32 v210, 0, v16
	v_max_f32_e32 v211, 0, v17
	v_pk_fma_f32 v[50:51], v[254:255], v[210:211], v[50:51]
	s_waitcnt lgkmcnt(1)
	v_mfma_f32_32x32x16_bf16 v[212:227], v[78:81], v[46:49], v[212:227]
	v_max_f32_e32 v108, 0, v18
	v_max_f32_e32 v109, 0, v19
	v_pk_fma_f32 v[50:51], v[200:201], v[108:109], v[50:51]
	v_max_f32_e32 v210, 0, v20
	v_max_f32_e32 v211, 0, v21
	v_pk_fma_f32 v[50:51], v[202:203], v[210:211], v[50:51]
	v_add_f32_e32 v50, v50, v51
	v_ashrrev_i32_e32 v51, 31, v50
	s_waitcnt lgkmcnt(0)
	v_mfma_f32_32x32x16_bf16 v[212:227], v[82:85], v[196:199], v[212:227]
	v_or_b32_e32 v51, 0x80000000, v51
	s_cmpk_gt_i32 s11, 152
	s_cselect_b64 vcc, -1, 0
	v_xor_b32_e32 v50, v51, v50
	v_cndmask_b32_e32 v50, v123, v50, vcc
	global_store_dword v243, v50, s[8:9] offset:2048
	s_add_u32 s8, s8, 0x1000
	s_addc_u32 s9, s9, 0
	v_mfma_f32_32x32x16_bf16 v[6:21], v[86:89], v[38:41], 0
	s_add_i32 m0, s10, 98304
	s_nop 0
	global_load_lds_dwordx4 v102, s[6:7]
	s_add_i32 m0, s10, 99328
	s_nop 0
	global_load_lds_dwordx4 v110, s[6:7]
	s_add_i32 m0, s10, 100352
	s_nop 0
	global_load_lds_dwordx4 v112, s[6:7]
	s_add_i32 m0, s10, 101376
	s_nop 0
	global_load_lds_dwordx4 v193, s[6:7]
	s_add_u32 s6, s6, 0x8000
	s_addc_u32 s7, s7, 0
	v_max_f32_e32 v108, 0, v212
	v_max_f32_e32 v109, 0, v213
	v_pk_mul_f32 v[0:1], v[22:23], v[108:109]
	v_max_f32_e32 v210, 0, v214
	v_max_f32_e32 v211, 0, v215
	v_pk_fma_f32 v[0:1], v[24:25], v[210:211], v[0:1]
	v_max_f32_e32 v108, 0, v216
	v_max_f32_e32 v109, 0, v217
	v_pk_fma_f32 v[0:1], v[26:27], v[108:109], v[0:1]
	v_mfma_f32_32x32x16_bf16 v[6:21], v[90:93], v[42:45], v[6:21]
	v_max_f32_e32 v210, 0, v218
	v_max_f32_e32 v211, 0, v219
	v_pk_fma_f32 v[0:1], v[28:29], v[210:211], v[0:1]
	v_max_f32_e32 v108, 0, v220
	v_max_f32_e32 v109, 0, v221
	v_pk_fma_f32 v[0:1], v[30:31], v[108:109], v[0:1]
	v_max_f32_e32 v210, 0, v222
	v_max_f32_e32 v211, 0, v223
	v_pk_fma_f32 v[0:1], v[32:33], v[210:211], v[0:1]
	v_mfma_f32_32x32x16_bf16 v[6:21], v[94:97], v[46:49], v[6:21]
	v_max_f32_e32 v108, 0, v224
	v_max_f32_e32 v109, 0, v225
	v_pk_fma_f32 v[0:1], v[34:35], v[108:109], v[0:1]
	v_max_f32_e32 v210, 0, v226
	v_max_f32_e32 v211, 0, v227
	v_pk_fma_f32 v[0:1], v[36:37], v[210:211], v[0:1]
	v_add_f32_e32 v0, v0, v1
	v_ashrrev_i32_e32 v1, 31, v0
	v_mfma_f32_32x32x16_bf16 v[6:21], v[98:101], v[196:199], v[6:21]
	s_waitcnt vmcnt(10)
	ds_read_b128 v[38:41], v5 offset:43264
	ds_read_b128 v[42:45], v52 offset:43264
	ds_read_b128 v[46:49], v55 offset:43264
	ds_read_b128 v[196:199], v56 offset:43264
	v_or_b32_e32 v1, 0x80000000, v1
	s_cmpk_gt_i32 s11, 160
	s_cselect_b64 vcc, -1, 0
	v_xor_b32_e32 v0, v1, v0
	v_cndmask_b32_e32 v154, v123, v0, vcc
	s_nop 3
	s_waitcnt lgkmcnt(3)
	v_mfma_f32_32x32x16_bf16 v[212:227], v[70:73], v[38:41], 0
	v_max_f32_e32 v108, 0, v6
	v_max_f32_e32 v109, 0, v7
	v_pk_mul_f32 v[50:51], v[244:245], v[108:109]
	v_max_f32_e32 v210, 0, v8
	v_max_f32_e32 v211, 0, v9
	v_pk_fma_f32 v[50:51], v[246:247], v[210:211], v[50:51]
	v_max_f32_e32 v108, 0, v10
	v_max_f32_e32 v109, 0, v11
	v_pk_fma_f32 v[50:51], v[248:249], v[108:109], v[50:51]
	s_waitcnt lgkmcnt(2)
	v_mfma_f32_32x32x16_bf16 v[212:227], v[74:77], v[42:45], v[212:227]
	v_max_f32_e32 v210, 0, v12
	v_max_f32_e32 v211, 0, v13
	v_pk_fma_f32 v[50:51], v[250:251], v[210:211], v[50:51]
	v_max_f32_e32 v108, 0, v14
	v_max_f32_e32 v109, 0, v15
	v_pk_fma_f32 v[50:51], v[252:253], v[108:109], v[50:51]
	v_max_f32_e32 v210, 0, v16
	v_max_f32_e32 v211, 0, v17
	v_pk_fma_f32 v[50:51], v[254:255], v[210:211], v[50:51]
	s_waitcnt lgkmcnt(1)
	v_mfma_f32_32x32x16_bf16 v[212:227], v[78:81], v[46:49], v[212:227]
	v_max_f32_e32 v108, 0, v18
	v_max_f32_e32 v109, 0, v19
	v_pk_fma_f32 v[50:51], v[200:201], v[108:109], v[50:51]
	v_max_f32_e32 v210, 0, v20
	v_max_f32_e32 v211, 0, v21
	v_pk_fma_f32 v[50:51], v[202:203], v[210:211], v[50:51]
	v_add_f32_e32 v50, v50, v51
	v_ashrrev_i32_e32 v51, 31, v50
	s_waitcnt lgkmcnt(0)
	v_mfma_f32_32x32x16_bf16 v[212:227], v[82:85], v[196:199], v[212:227]
	v_or_b32_e32 v51, 0x80000000, v51
	s_cmpk_gt_i32 s11, 160
	s_cselect_b64 vcc, -1, 0
	v_xor_b32_e32 v50, v51, v50
	v_cndmask_b32_e32 v50, v123, v50, vcc
	global_store_dword v243, v50, s[8:9]
	v_mfma_f32_32x32x16_bf16 v[6:21], v[86:89], v[38:41], 0
	s_add_i32 m0, s10, 0
	s_nop 0
	global_load_lds_dwordx4 v102, s[6:7]
	s_add_i32 m0, s10, 1024
	s_nop 0
	global_load_lds_dwordx4 v110, s[6:7]
	s_add_i32 m0, s10, 2048
	s_nop 0
	global_load_lds_dwordx4 v112, s[6:7]
	s_add_i32 m0, s10, 3072
	s_nop 0
	global_load_lds_dwordx4 v193, s[6:7]
	s_add_u32 s6, s6, 0x8000
	s_addc_u32 s7, s7, 0
	v_max_f32_e32 v108, 0, v212
	v_max_f32_e32 v109, 0, v213
	v_pk_mul_f32 v[0:1], v[22:23], v[108:109]
	v_max_f32_e32 v210, 0, v214
	v_max_f32_e32 v211, 0, v215
	v_pk_fma_f32 v[0:1], v[24:25], v[210:211], v[0:1]
	v_max_f32_e32 v108, 0, v216
	v_max_f32_e32 v109, 0, v217
	v_pk_fma_f32 v[0:1], v[26:27], v[108:109], v[0:1]
	v_mfma_f32_32x32x16_bf16 v[6:21], v[90:93], v[42:45], v[6:21]
	v_max_f32_e32 v210, 0, v218
	v_max_f32_e32 v211, 0, v219
	v_pk_fma_f32 v[0:1], v[28:29], v[210:211], v[0:1]
	v_max_f32_e32 v108, 0, v220
	v_max_f32_e32 v109, 0, v221
	v_pk_fma_f32 v[0:1], v[30:31], v[108:109], v[0:1]
	v_max_f32_e32 v210, 0, v222
	v_max_f32_e32 v211, 0, v223
	v_pk_fma_f32 v[0:1], v[32:33], v[210:211], v[0:1]
	v_mfma_f32_32x32x16_bf16 v[6:21], v[94:97], v[46:49], v[6:21]
	v_max_f32_e32 v108, 0, v224
	v_max_f32_e32 v109, 0, v225
	v_pk_fma_f32 v[0:1], v[34:35], v[108:109], v[0:1]
	v_max_f32_e32 v210, 0, v226
	v_max_f32_e32 v211, 0, v227
	v_pk_fma_f32 v[0:1], v[36:37], v[210:211], v[0:1]
	v_add_f32_e32 v0, v0, v1
	v_ashrrev_i32_e32 v1, 31, v0
	v_mfma_f32_32x32x16_bf16 v[6:21], v[98:101], v[196:199], v[6:21]
	s_waitcnt vmcnt(10)
	v_add_u32_e32 v228, 0x10000, v5
	ds_read_b128 v[38:41], v228 offset:10496
	v_add_u32_e32 v228, 0x10000, v52
	ds_read_b128 v[42:45], v228 offset:10496
	v_add_u32_e32 v228, 0x10000, v55
	ds_read_b128 v[46:49], v228 offset:10496
	v_add_u32_e32 v228, 0x10000, v56
	ds_read_b128 v[196:199], v228 offset:10496
	v_or_b32_e32 v1, 0x80000000, v1
	s_cmpk_gt_i32 s11, 168
	s_cselect_b64 vcc, -1, 0
	v_xor_b32_e32 v0, v1, v0
	v_cndmask_b32_e32 v153, v123, v0, vcc
	s_nop 3
	s_waitcnt lgkmcnt(3)
	v_mfma_f32_32x32x16_bf16 v[212:227], v[70:73], v[38:41], 0
	v_max_f32_e32 v108, 0, v6
	v_max_f32_e32 v109, 0, v7
	v_pk_mul_f32 v[50:51], v[244:245], v[108:109]
	v_max_f32_e32 v210, 0, v8
	v_max_f32_e32 v211, 0, v9
	v_pk_fma_f32 v[50:51], v[246:247], v[210:211], v[50:51]
	v_max_f32_e32 v108, 0, v10
	v_max_f32_e32 v109, 0, v11
	v_pk_fma_f32 v[50:51], v[248:249], v[108:109], v[50:51]
	s_waitcnt lgkmcnt(2)
	v_mfma_f32_32x32x16_bf16 v[212:227], v[74:77], v[42:45], v[212:227]
	v_max_f32_e32 v210, 0, v12
	v_max_f32_e32 v211, 0, v13
	v_pk_fma_f32 v[50:51], v[250:251], v[210:211], v[50:51]
	v_max_f32_e32 v108, 0, v14
	v_max_f32_e32 v109, 0, v15
	v_pk_fma_f32 v[50:51], v[252:253], v[108:109], v[50:51]
	v_max_f32_e32 v210, 0, v16
	v_max_f32_e32 v211, 0, v17
	v_pk_fma_f32 v[50:51], v[254:255], v[210:211], v[50:51]
	s_waitcnt lgkmcnt(1)
	v_mfma_f32_32x32x16_bf16 v[212:227], v[78:81], v[46:49], v[212:227]
	v_max_f32_e32 v108, 0, v18
	v_max_f32_e32 v109, 0, v19
	v_pk_fma_f32 v[50:51], v[200:201], v[108:109], v[50:51]
	v_max_f32_e32 v210, 0, v20
	v_max_f32_e32 v211, 0, v21
	v_pk_fma_f32 v[50:51], v[202:203], v[210:211], v[50:51]
	v_add_f32_e32 v50, v50, v51
	v_ashrrev_i32_e32 v51, 31, v50
	s_waitcnt lgkmcnt(0)
	v_mfma_f32_32x32x16_bf16 v[212:227], v[82:85], v[196:199], v[212:227]
	v_or_b32_e32 v51, 0x80000000, v51
	s_cmpk_gt_i32 s11, 168
	s_cselect_b64 vcc, -1, 0
	v_xor_b32_e32 v50, v51, v50
	v_cndmask_b32_e32 v50, v123, v50, vcc
	global_store_dword v243, v50, s[8:9] offset:2048
	s_add_u32 s8, s8, 0x1000
	s_addc_u32 s9, s9, 0
	v_mfma_f32_32x32x16_bf16 v[6:21], v[86:89], v[38:41], 0
	s_add_i32 m0, s10, 32768
	s_nop 0
	global_load_lds_dwordx4 v102, s[6:7]
	s_add_i32 m0, s10, 33792
	s_nop 0
	global_load_lds_dwordx4 v110, s[6:7]
	s_add_i32 m0, s10, 34816
	s_nop 0
	global_load_lds_dwordx4 v112, s[6:7]
	s_add_i32 m0, s10, 35840
	s_nop 0
	global_load_lds_dwordx4 v193, s[6:7]
	s_add_u32 s6, s6, 0x8000
	s_addc_u32 s7, s7, 0
	v_max_f32_e32 v108, 0, v212
	v_max_f32_e32 v109, 0, v213
	v_pk_mul_f32 v[0:1], v[22:23], v[108:109]
	v_max_f32_e32 v210, 0, v214
	v_max_f32_e32 v211, 0, v215
	v_pk_fma_f32 v[0:1], v[24:25], v[210:211], v[0:1]
	v_max_f32_e32 v108, 0, v216
	v_max_f32_e32 v109, 0, v217
	v_pk_fma_f32 v[0:1], v[26:27], v[108:109], v[0:1]
	v_mfma_f32_32x32x16_bf16 v[6:21], v[90:93], v[42:45], v[6:21]
	v_max_f32_e32 v210, 0, v218
	v_max_f32_e32 v211, 0, v219
	v_pk_fma_f32 v[0:1], v[28:29], v[210:211], v[0:1]
	v_max_f32_e32 v108, 0, v220
	v_max_f32_e32 v109, 0, v221
	v_pk_fma_f32 v[0:1], v[30:31], v[108:109], v[0:1]
	v_max_f32_e32 v210, 0, v222
	v_max_f32_e32 v211, 0, v223
	v_pk_fma_f32 v[0:1], v[32:33], v[210:211], v[0:1]
	v_mfma_f32_32x32x16_bf16 v[6:21], v[94:97], v[46:49], v[6:21]
	v_max_f32_e32 v108, 0, v224
	v_max_f32_e32 v109, 0, v225
	v_pk_fma_f32 v[0:1], v[34:35], v[108:109], v[0:1]
	v_max_f32_e32 v210, 0, v226
	v_max_f32_e32 v211, 0, v227
	v_pk_fma_f32 v[0:1], v[36:37], v[210:211], v[0:1]
	v_add_f32_e32 v0, v0, v1
	v_ashrrev_i32_e32 v1, 31, v0
	v_mfma_f32_32x32x16_bf16 v[6:21], v[98:101], v[196:199], v[6:21]
	s_waitcnt vmcnt(10)
	v_add_u32_e32 v228, 0x10000, v5
	ds_read_b128 v[38:41], v228 offset:43264
	v_add_u32_e32 v228, 0x10000, v52
	ds_read_b128 v[42:45], v228 offset:43264
	v_add_u32_e32 v228, 0x10000, v55
	ds_read_b128 v[46:49], v228 offset:43264
	v_add_u32_e32 v228, 0x10000, v56
	ds_read_b128 v[196:199], v228 offset:43264
	v_or_b32_e32 v1, 0x80000000, v1
	s_cmpk_gt_i32 s11, 176
	s_cselect_b64 vcc, -1, 0
	v_xor_b32_e32 v0, v1, v0
	v_cndmask_b32_e32 v156, v123, v0, vcc
	s_nop 3
	s_waitcnt lgkmcnt(3)
	v_mfma_f32_32x32x16_bf16 v[212:227], v[70:73], v[38:41], 0
	v_max_f32_e32 v108, 0, v6
	v_max_f32_e32 v109, 0, v7
	v_pk_mul_f32 v[50:51], v[244:245], v[108:109]
	v_max_f32_e32 v210, 0, v8
	v_max_f32_e32 v211, 0, v9
	v_pk_fma_f32 v[50:51], v[246:247], v[210:211], v[50:51]
	v_max_f32_e32 v108, 0, v10
	v_max_f32_e32 v109, 0, v11
	v_pk_fma_f32 v[50:51], v[248:249], v[108:109], v[50:51]
	s_waitcnt lgkmcnt(2)
	v_mfma_f32_32x32x16_bf16 v[212:227], v[74:77], v[42:45], v[212:227]
	v_max_f32_e32 v210, 0, v12
	v_max_f32_e32 v211, 0, v13
	v_pk_fma_f32 v[50:51], v[250:251], v[210:211], v[50:51]
	v_max_f32_e32 v108, 0, v14
	v_max_f32_e32 v109, 0, v15
	v_pk_fma_f32 v[50:51], v[252:253], v[108:109], v[50:51]
	v_max_f32_e32 v210, 0, v16
	v_max_f32_e32 v211, 0, v17
	v_pk_fma_f32 v[50:51], v[254:255], v[210:211], v[50:51]
	s_waitcnt lgkmcnt(1)
	v_mfma_f32_32x32x16_bf16 v[212:227], v[78:81], v[46:49], v[212:227]
	v_max_f32_e32 v108, 0, v18
	v_max_f32_e32 v109, 0, v19
	v_pk_fma_f32 v[50:51], v[200:201], v[108:109], v[50:51]
	v_max_f32_e32 v210, 0, v20
	v_max_f32_e32 v211, 0, v21
	v_pk_fma_f32 v[50:51], v[202:203], v[210:211], v[50:51]
	v_add_f32_e32 v50, v50, v51
	v_ashrrev_i32_e32 v51, 31, v50
	s_waitcnt lgkmcnt(0)
	v_mfma_f32_32x32x16_bf16 v[212:227], v[82:85], v[196:199], v[212:227]
	v_or_b32_e32 v51, 0x80000000, v51
	s_cmpk_gt_i32 s11, 176
	s_cselect_b64 vcc, -1, 0
	v_xor_b32_e32 v50, v51, v50
	v_cndmask_b32_e32 v50, v123, v50, vcc
	global_store_dword v243, v50, s[8:9]
	v_mfma_f32_32x32x16_bf16 v[6:21], v[86:89], v[38:41], 0
	s_add_i32 m0, s10, 65536
	s_nop 0
	global_load_lds_dwordx4 v102, s[6:7]
	s_add_i32 m0, s10, 66560
	s_nop 0
	global_load_lds_dwordx4 v110, s[6:7]
	s_add_i32 m0, s10, 67584
	s_nop 0
	global_load_lds_dwordx4 v112, s[6:7]
	s_add_i32 m0, s10, 68608
	s_nop 0
	global_load_lds_dwordx4 v193, s[6:7]
	s_add_u32 s6, s6, 0x8000
	s_addc_u32 s7, s7, 0
	v_max_f32_e32 v108, 0, v212
	v_max_f32_e32 v109, 0, v213
	v_pk_mul_f32 v[0:1], v[22:23], v[108:109]
	v_max_f32_e32 v210, 0, v214
	v_max_f32_e32 v211, 0, v215
	v_pk_fma_f32 v[0:1], v[24:25], v[210:211], v[0:1]
	v_max_f32_e32 v108, 0, v216
	v_max_f32_e32 v109, 0, v217
	v_pk_fma_f32 v[0:1], v[26:27], v[108:109], v[0:1]
	v_mfma_f32_32x32x16_bf16 v[6:21], v[90:93], v[42:45], v[6:21]
	v_max_f32_e32 v210, 0, v218
	v_max_f32_e32 v211, 0, v219
	v_pk_fma_f32 v[0:1], v[28:29], v[210:211], v[0:1]
	v_max_f32_e32 v108, 0, v220
	v_max_f32_e32 v109, 0, v221
	v_pk_fma_f32 v[0:1], v[30:31], v[108:109], v[0:1]
	v_max_f32_e32 v210, 0, v222
	v_max_f32_e32 v211, 0, v223
	v_pk_fma_f32 v[0:1], v[32:33], v[210:211], v[0:1]
	v_mfma_f32_32x32x16_bf16 v[6:21], v[94:97], v[46:49], v[6:21]
	v_max_f32_e32 v108, 0, v224
	v_max_f32_e32 v109, 0, v225
	v_pk_fma_f32 v[0:1], v[34:35], v[108:109], v[0:1]
	v_max_f32_e32 v210, 0, v226
	v_max_f32_e32 v211, 0, v227
	v_pk_fma_f32 v[0:1], v[36:37], v[210:211], v[0:1]
	v_add_f32_e32 v0, v0, v1
	v_ashrrev_i32_e32 v1, 31, v0
	v_mfma_f32_32x32x16_bf16 v[6:21], v[98:101], v[196:199], v[6:21]
	s_waitcnt vmcnt(10)
	ds_read_b128 v[38:41], v5 offset:10496
	ds_read_b128 v[42:45], v52 offset:10496
	ds_read_b128 v[46:49], v55 offset:10496
	ds_read_b128 v[196:199], v56 offset:10496
	v_or_b32_e32 v1, 0x80000000, v1
	s_cmpk_gt_i32 s11, 184
	s_cselect_b64 vcc, -1, 0
	v_xor_b32_e32 v0, v1, v0
	v_cndmask_b32_e32 v155, v123, v0, vcc
	s_nop 3
	v_max_f32_e32 v108, 0, v6
	v_max_f32_e32 v109, 0, v7
	v_pk_mul_f32 v[50:51], v[244:245], v[108:109]
	v_max_f32_e32 v210, 0, v8
	v_max_f32_e32 v211, 0, v9
	v_pk_fma_f32 v[50:51], v[246:247], v[210:211], v[50:51]
	v_max_f32_e32 v108, 0, v10
	v_max_f32_e32 v109, 0, v11
	v_pk_fma_f32 v[50:51], v[248:249], v[108:109], v[50:51]
	v_max_f32_e32 v210, 0, v12
	v_max_f32_e32 v211, 0, v13
	v_pk_fma_f32 v[50:51], v[250:251], v[210:211], v[50:51]
	v_max_f32_e32 v108, 0, v14
	v_max_f32_e32 v109, 0, v15
	v_pk_fma_f32 v[50:51], v[252:253], v[108:109], v[50:51]
	v_max_f32_e32 v210, 0, v16
	v_max_f32_e32 v211, 0, v17
	v_pk_fma_f32 v[50:51], v[254:255], v[210:211], v[50:51]
	v_max_f32_e32 v108, 0, v18
	v_max_f32_e32 v109, 0, v19
	v_pk_fma_f32 v[50:51], v[200:201], v[108:109], v[50:51]
	v_max_f32_e32 v210, 0, v20
	v_max_f32_e32 v211, 0, v21
	v_pk_fma_f32 v[50:51], v[202:203], v[210:211], v[50:51]
	v_add_f32_e32 v50, v50, v51
	v_ashrrev_i32_e32 v51, 31, v50
	v_or_b32_e32 v51, 0x80000000, v51
	s_cmpk_gt_i32 s11, 184
	s_cselect_b64 vcc, -1, 0
	v_xor_b32_e32 v50, v51, v50
	v_cndmask_b32_e32 v50, v123, v50, vcc
	global_store_dword v243, v50, s[8:9] offset:2048
	s_add_u32 s8, s8, 0x1000
	s_addc_u32 s9, s9, 0
	s_cmpk_gt_i32 s81, 24
	s_cbranch_scc0 .Lix_fill_3
	s_waitcnt lgkmcnt(3)
	v_mfma_f32_32x32x16_bf16 v[212:227], v[70:73], v[38:41], 0
	s_add_i32 m0, s10, 98304
	s_nop 0
	global_load_lds_dwordx4 v102, s[6:7]
	s_waitcnt lgkmcnt(2)
	v_mfma_f32_32x32x16_bf16 v[212:227], v[74:77], v[42:45], v[212:227]
	s_add_i32 m0, s10, 99328
	s_nop 0
	global_load_lds_dwordx4 v110, s[6:7]
	s_waitcnt lgkmcnt(1)
	v_mfma_f32_32x32x16_bf16 v[212:227], v[78:81], v[46:49], v[212:227]
	s_add_i32 m0, s10, 100352
	s_nop 0
	global_load_lds_dwordx4 v112, s[6:7]
	s_waitcnt lgkmcnt(0)
	v_mfma_f32_32x32x16_bf16 v[212:227], v[82:85], v[196:199], v[212:227]
	s_add_i32 m0, s10, 101376
	s_nop 0
	global_load_lds_dwordx4 v193, s[6:7]
	s_add_u32 s6, s6, 0x8000
	s_addc_u32 s7, s7, 0
	v_mfma_f32_32x32x16_bf16 v[6:21], v[86:89], v[38:41], 0
	s_nop 7
	s_nop 2
	v_max_f32_e32 v108, 0, v212
	v_max_f32_e32 v109, 0, v213
	v_pk_mul_f32 v[0:1], v[22:23], v[108:109]
	v_max_f32_e32 v210, 0, v214
	v_max_f32_e32 v211, 0, v215
	v_pk_fma_f32 v[0:1], v[24:25], v[210:211], v[0:1]
	v_max_f32_e32 v108, 0, v216
	v_max_f32_e32 v109, 0, v217
	v_pk_fma_f32 v[0:1], v[26:27], v[108:109], v[0:1]
	v_mfma_f32_32x32x16_bf16 v[6:21], v[90:93], v[42:45], v[6:21]
	v_max_f32_e32 v210, 0, v218
	v_max_f32_e32 v211, 0, v219
	v_pk_fma_f32 v[0:1], v[28:29], v[210:211], v[0:1]
	v_max_f32_e32 v108, 0, v220
	v_max_f32_e32 v109, 0, v221
	v_pk_fma_f32 v[0:1], v[30:31], v[108:109], v[0:1]
	v_max_f32_e32 v210, 0, v222
	v_max_f32_e32 v211, 0, v223
	v_pk_fma_f32 v[0:1], v[32:33], v[210:211], v[0:1]
	v_mfma_f32_32x32x16_bf16 v[6:21], v[94:97], v[46:49], v[6:21]
	v_max_f32_e32 v108, 0, v224
	v_max_f32_e32 v109, 0, v225
	v_pk_fma_f32 v[0:1], v[34:35], v[108:109], v[0:1]
	v_max_f32_e32 v210, 0, v226
	v_max_f32_e32 v211, 0, v227
	v_pk_fma_f32 v[0:1], v[36:37], v[210:211], v[0:1]
	v_add_f32_e32 v0, v0, v1
	v_ashrrev_i32_e32 v1, 31, v0
	v_mfma_f32_32x32x16_bf16 v[6:21], v[98:101], v[196:199], v[6:21]
	s_waitcnt vmcnt(10)
	ds_read_b128 v[38:41], v5 offset:43264
	ds_read_b128 v[42:45], v52 offset:43264
	ds_read_b128 v[46:49], v55 offset:43264
	ds_read_b128 v[196:199], v56 offset:43264
	v_or_b32_e32 v1, 0x80000000, v1
	s_cmpk_gt_i32 s11, 192
	s_cselect_b64 vcc, -1, 0
	v_xor_b32_e32 v0, v1, v0
	v_cndmask_b32_e32 v158, v123, v0, vcc
	s_nop 3
	s_waitcnt lgkmcnt(3)
	v_mfma_f32_32x32x16_bf16 v[212:227], v[70:73], v[38:41], 0
	v_max_f32_e32 v108, 0, v6
	v_max_f32_e32 v109, 0, v7
	v_pk_mul_f32 v[50:51], v[244:245], v[108:109]
	v_max_f32_e32 v210, 0, v8
	v_max_f32_e32 v211, 0, v9
	v_pk_fma_f32 v[50:51], v[246:247], v[210:211], v[50:51]
	v_max_f32_e32 v108, 0, v10
	v_max_f32_e32 v109, 0, v11
	v_pk_fma_f32 v[50:51], v[248:249], v[108:109], v[50:51]
	s_waitcnt lgkmcnt(2)
	v_mfma_f32_32x32x16_bf16 v[212:227], v[74:77], v[42:45], v[212:227]
	v_max_f32_e32 v210, 0, v12
	v_max_f32_e32 v211, 0, v13
	v_pk_fma_f32 v[50:51], v[250:251], v[210:211], v[50:51]
	v_max_f32_e32 v108, 0, v14
	v_max_f32_e32 v109, 0, v15
	v_pk_fma_f32 v[50:51], v[252:253], v[108:109], v[50:51]
	v_max_f32_e32 v210, 0, v16
	v_max_f32_e32 v211, 0, v17
	v_pk_fma_f32 v[50:51], v[254:255], v[210:211], v[50:51]
	s_waitcnt lgkmcnt(1)
	v_mfma_f32_32x32x16_bf16 v[212:227], v[78:81], v[46:49], v[212:227]
	v_max_f32_e32 v108, 0, v18
	v_max_f32_e32 v109, 0, v19
	v_pk_fma_f32 v[50:51], v[200:201], v[108:109], v[50:51]
	v_max_f32_e32 v210, 0, v20
	v_max_f32_e32 v211, 0, v21
	v_pk_fma_f32 v[50:51], v[202:203], v[210:211], v[50:51]
	v_add_f32_e32 v50, v50, v51
	v_ashrrev_i32_e32 v51, 31, v50
	s_waitcnt lgkmcnt(0)
	v_mfma_f32_32x32x16_bf16 v[212:227], v[82:85], v[196:199], v[212:227]
	v_or_b32_e32 v51, 0x80000000, v51
	s_cmpk_gt_i32 s11, 192
	s_cselect_b64 vcc, -1, 0
	v_xor_b32_e32 v50, v51, v50
	v_cndmask_b32_e32 v50, v123, v50, vcc
	global_store_dword v243, v50, s[8:9]
	v_mfma_f32_32x32x16_bf16 v[6:21], v[86:89], v[38:41], 0
	s_add_i32 m0, s10, 0
	s_nop 0
	global_load_lds_dwordx4 v102, s[6:7]
	s_add_i32 m0, s10, 1024
	s_nop 0
	global_load_lds_dwordx4 v110, s[6:7]
	s_add_i32 m0, s10, 2048
	s_nop 0
	global_load_lds_dwordx4 v112, s[6:7]
	s_add_i32 m0, s10, 3072
	s_nop 0
	global_load_lds_dwordx4 v193, s[6:7]
	s_add_u32 s6, s6, 0x8000
	s_addc_u32 s7, s7, 0
	v_max_f32_e32 v108, 0, v212
	v_max_f32_e32 v109, 0, v213
	v_pk_mul_f32 v[0:1], v[22:23], v[108:109]
	v_max_f32_e32 v210, 0, v214
	v_max_f32_e32 v211, 0, v215
	v_pk_fma_f32 v[0:1], v[24:25], v[210:211], v[0:1]
	v_max_f32_e32 v108, 0, v216
	v_max_f32_e32 v109, 0, v217
	v_pk_fma_f32 v[0:1], v[26:27], v[108:109], v[0:1]
	v_mfma_f32_32x32x16_bf16 v[6:21], v[90:93], v[42:45], v[6:21]
	v_max_f32_e32 v210, 0, v218
	v_max_f32_e32 v211, 0, v219
	v_pk_fma_f32 v[0:1], v[28:29], v[210:211], v[0:1]
	v_max_f32_e32 v108, 0, v220
	v_max_f32_e32 v109, 0, v221
	v_pk_fma_f32 v[0:1], v[30:31], v[108:109], v[0:1]
	v_max_f32_e32 v210, 0, v222
	v_max_f32_e32 v211, 0, v223
	v_pk_fma_f32 v[0:1], v[32:33], v[210:211], v[0:1]
	v_mfma_f32_32x32x16_bf16 v[6:21], v[94:97], v[46:49], v[6:21]
	v_max_f32_e32 v108, 0, v224
	v_max_f32_e32 v109, 0, v225
	v_pk_fma_f32 v[0:1], v[34:35], v[108:109], v[0:1]
	v_max_f32_e32 v210, 0, v226
	v_max_f32_e32 v211, 0, v227
	v_pk_fma_f32 v[0:1], v[36:37], v[210:211], v[0:1]
	v_add_f32_e32 v0, v0, v1
	v_ashrrev_i32_e32 v1, 31, v0
	v_mfma_f32_32x32x16_bf16 v[6:21], v[98:101], v[196:199], v[6:21]
	s_waitcnt vmcnt(10)
	v_add_u32_e32 v228, 0x10000, v5
	ds_read_b128 v[38:41], v228 offset:10496
	v_add_u32_e32 v228, 0x10000, v52
	ds_read_b128 v[42:45], v228 offset:10496
	v_add_u32_e32 v228, 0x10000, v55
	ds_read_b128 v[46:49], v228 offset:10496
	v_add_u32_e32 v228, 0x10000, v56
	ds_read_b128 v[196:199], v228 offset:10496
	v_or_b32_e32 v1, 0x80000000, v1
	s_cmpk_gt_i32 s11, 200
	s_cselect_b64 vcc, -1, 0
	v_xor_b32_e32 v0, v1, v0
	v_cndmask_b32_e32 v157, v123, v0, vcc
	s_nop 3
	s_waitcnt lgkmcnt(3)
	v_mfma_f32_32x32x16_bf16 v[212:227], v[70:73], v[38:41], 0
	v_max_f32_e32 v108, 0, v6
	v_max_f32_e32 v109, 0, v7
	v_pk_mul_f32 v[50:51], v[244:245], v[108:109]
	v_max_f32_e32 v210, 0, v8
	v_max_f32_e32 v211, 0, v9
	v_pk_fma_f32 v[50:51], v[246:247], v[210:211], v[50:51]
	v_max_f32_e32 v108, 0, v10
	v_max_f32_e32 v109, 0, v11
	v_pk_fma_f32 v[50:51], v[248:249], v[108:109], v[50:51]
	s_waitcnt lgkmcnt(2)
	v_mfma_f32_32x32x16_bf16 v[212:227], v[74:77], v[42:45], v[212:227]
	v_max_f32_e32 v210, 0, v12
	v_max_f32_e32 v211, 0, v13
	v_pk_fma_f32 v[50:51], v[250:251], v[210:211], v[50:51]
	v_max_f32_e32 v108, 0, v14
	v_max_f32_e32 v109, 0, v15
	v_pk_fma_f32 v[50:51], v[252:253], v[108:109], v[50:51]
	v_max_f32_e32 v210, 0, v16
	v_max_f32_e32 v211, 0, v17
	v_pk_fma_f32 v[50:51], v[254:255], v[210:211], v[50:51]
	s_waitcnt lgkmcnt(1)
	v_mfma_f32_32x32x16_bf16 v[212:227], v[78:81], v[46:49], v[212:227]
	v_max_f32_e32 v108, 0, v18
	v_max_f32_e32 v109, 0, v19
	v_pk_fma_f32 v[50:51], v[200:201], v[108:109], v[50:51]
	v_max_f32_e32 v210, 0, v20
	v_max_f32_e32 v211, 0, v21
	v_pk_fma_f32 v[50:51], v[202:203], v[210:211], v[50:51]
	v_add_f32_e32 v50, v50, v51
	v_ashrrev_i32_e32 v51, 31, v50
	s_waitcnt lgkmcnt(0)
	v_mfma_f32_32x32x16_bf16 v[212:227], v[82:85], v[196:199], v[212:227]
	v_or_b32_e32 v51, 0x80000000, v51
	s_cmpk_gt_i32 s11, 200
	s_cselect_b64 vcc, -1, 0
	v_xor_b32_e32 v50, v51, v50
	v_cndmask_b32_e32 v50, v123, v50, vcc
	global_store_dword v243, v50, s[8:9] offset:2048
	s_add_u32 s8, s8, 0x1000
	s_addc_u32 s9, s9, 0
	v_mfma_f32_32x32x16_bf16 v[6:21], v[86:89], v[38:41], 0
	s_add_i32 m0, s10, 32768
	s_nop 0
	global_load_lds_dwordx4 v102, s[6:7]
	s_add_i32 m0, s10, 33792
	s_nop 0
	global_load_lds_dwordx4 v110, s[6:7]
	s_add_i32 m0, s10, 34816
	s_nop 0
	global_load_lds_dwordx4 v112, s[6:7]
	s_add_i32 m0, s10, 35840
	s_nop 0
	global_load_lds_dwordx4 v193, s[6:7]
	s_add_u32 s6, s6, 0x8000
	s_addc_u32 s7, s7, 0
	v_max_f32_e32 v108, 0, v212
	v_max_f32_e32 v109, 0, v213
	v_pk_mul_f32 v[0:1], v[22:23], v[108:109]
	v_max_f32_e32 v210, 0, v214
	v_max_f32_e32 v211, 0, v215
	v_pk_fma_f32 v[0:1], v[24:25], v[210:211], v[0:1]
	v_max_f32_e32 v108, 0, v216
	v_max_f32_e32 v109, 0, v217
	v_pk_fma_f32 v[0:1], v[26:27], v[108:109], v[0:1]
	v_mfma_f32_32x32x16_bf16 v[6:21], v[90:93], v[42:45], v[6:21]
	v_max_f32_e32 v210, 0, v218
	v_max_f32_e32 v211, 0, v219
	v_pk_fma_f32 v[0:1], v[28:29], v[210:211], v[0:1]
	v_max_f32_e32 v108, 0, v220
	v_max_f32_e32 v109, 0, v221
	v_pk_fma_f32 v[0:1], v[30:31], v[108:109], v[0:1]
	v_max_f32_e32 v210, 0, v222
	v_max_f32_e32 v211, 0, v223
	v_pk_fma_f32 v[0:1], v[32:33], v[210:211], v[0:1]
	v_mfma_f32_32x32x16_bf16 v[6:21], v[94:97], v[46:49], v[6:21]
	v_max_f32_e32 v108, 0, v224
	v_max_f32_e32 v109, 0, v225
	v_pk_fma_f32 v[0:1], v[34:35], v[108:109], v[0:1]
	v_max_f32_e32 v210, 0, v226
	v_max_f32_e32 v211, 0, v227
	v_pk_fma_f32 v[0:1], v[36:37], v[210:211], v[0:1]
	v_add_f32_e32 v0, v0, v1
	v_ashrrev_i32_e32 v1, 31, v0
	v_mfma_f32_32x32x16_bf16 v[6:21], v[98:101], v[196:199], v[6:21]
	s_waitcnt vmcnt(10)
	v_add_u32_e32 v228, 0x10000, v5
	ds_read_b128 v[38:41], v228 offset:43264
	v_add_u32_e32 v228, 0x10000, v52
	ds_read_b128 v[42:45], v228 offset:43264
	v_add_u32_e32 v228, 0x10000, v55
	ds_read_b128 v[46:49], v228 offset:43264
	v_add_u32_e32 v228, 0x10000, v56
	ds_read_b128 v[196:199], v228 offset:43264
	v_or_b32_e32 v1, 0x80000000, v1
	s_cmpk_gt_i32 s11, 208
	s_cselect_b64 vcc, -1, 0
	v_xor_b32_e32 v0, v1, v0
	v_cndmask_b32_e32 v160, v123, v0, vcc
	s_nop 3
	s_waitcnt lgkmcnt(3)
	v_mfma_f32_32x32x16_bf16 v[212:227], v[70:73], v[38:41], 0
	v_max_f32_e32 v108, 0, v6
	v_max_f32_e32 v109, 0, v7
	v_pk_mul_f32 v[50:51], v[244:245], v[108:109]
	v_max_f32_e32 v210, 0, v8
	v_max_f32_e32 v211, 0, v9
	v_pk_fma_f32 v[50:51], v[246:247], v[210:211], v[50:51]
	v_max_f32_e32 v108, 0, v10
	v_max_f32_e32 v109, 0, v11
	v_pk_fma_f32 v[50:51], v[248:249], v[108:109], v[50:51]
	s_waitcnt lgkmcnt(2)
	v_mfma_f32_32x32x16_bf16 v[212:227], v[74:77], v[42:45], v[212:227]
	v_max_f32_e32 v210, 0, v12
	v_max_f32_e32 v211, 0, v13
	v_pk_fma_f32 v[50:51], v[250:251], v[210:211], v[50:51]
	v_max_f32_e32 v108, 0, v14
	v_max_f32_e32 v109, 0, v15
	v_pk_fma_f32 v[50:51], v[252:253], v[108:109], v[50:51]
	v_max_f32_e32 v210, 0, v16
	v_max_f32_e32 v211, 0, v17
	v_pk_fma_f32 v[50:51], v[254:255], v[210:211], v[50:51]
	s_waitcnt lgkmcnt(1)
	v_mfma_f32_32x32x16_bf16 v[212:227], v[78:81], v[46:49], v[212:227]
	v_max_f32_e32 v108, 0, v18
	v_max_f32_e32 v109, 0, v19
	v_pk_fma_f32 v[50:51], v[200:201], v[108:109], v[50:51]
	v_max_f32_e32 v210, 0, v20
	v_max_f32_e32 v211, 0, v21
	v_pk_fma_f32 v[50:51], v[202:203], v[210:211], v[50:51]
	v_add_f32_e32 v50, v50, v51
	v_ashrrev_i32_e32 v51, 31, v50
	s_waitcnt lgkmcnt(0)
	v_mfma_f32_32x32x16_bf16 v[212:227], v[82:85], v[196:199], v[212:227]
	v_or_b32_e32 v51, 0x80000000, v51
	s_cmpk_gt_i32 s11, 208
	s_cselect_b64 vcc, -1, 0
	v_xor_b32_e32 v50, v51, v50
	v_cndmask_b32_e32 v50, v123, v50, vcc
	global_store_dword v243, v50, s[8:9]
	v_mfma_f32_32x32x16_bf16 v[6:21], v[86:89], v[38:41], 0
	s_add_i32 m0, s10, 65536
	s_nop 0
	global_load_lds_dwordx4 v102, s[6:7]
	s_add_i32 m0, s10, 66560
	s_nop 0
	global_load_lds_dwordx4 v110, s[6:7]
	s_add_i32 m0, s10, 67584
	s_nop 0
	global_load_lds_dwordx4 v112, s[6:7]
	s_add_i32 m0, s10, 68608
	s_nop 0
	global_load_lds_dwordx4 v193, s[6:7]
	s_add_u32 s6, s6, 0x8000
	s_addc_u32 s7, s7, 0
	v_max_f32_e32 v108, 0, v212
	v_max_f32_e32 v109, 0, v213
	v_pk_mul_f32 v[0:1], v[22:23], v[108:109]
	v_max_f32_e32 v210, 0, v214
	v_max_f32_e32 v211, 0, v215
	v_pk_fma_f32 v[0:1], v[24:25], v[210:211], v[0:1]
	v_max_f32_e32 v108, 0, v216
	v_max_f32_e32 v109, 0, v217
	v_pk_fma_f32 v[0:1], v[26:27], v[108:109], v[0:1]
	v_mfma_f32_32x32x16_bf16 v[6:21], v[90:93], v[42:45], v[6:21]
	v_max_f32_e32 v210, 0, v218
	v_max_f32_e32 v211, 0, v219
	v_pk_fma_f32 v[0:1], v[28:29], v[210:211], v[0:1]
	v_max_f32_e32 v108, 0, v220
	v_max_f32_e32 v109, 0, v221
	v_pk_fma_f32 v[0:1], v[30:31], v[108:109], v[0:1]
	v_max_f32_e32 v210, 0, v222
	v_max_f32_e32 v211, 0, v223
	v_pk_fma_f32 v[0:1], v[32:33], v[210:211], v[0:1]
	v_mfma_f32_32x32x16_bf16 v[6:21], v[94:97], v[46:49], v[6:21]
	v_max_f32_e32 v108, 0, v224
	v_max_f32_e32 v109, 0, v225
	v_pk_fma_f32 v[0:1], v[34:35], v[108:109], v[0:1]
	v_max_f32_e32 v210, 0, v226
	v_max_f32_e32 v211, 0, v227
	v_pk_fma_f32 v[0:1], v[36:37], v[210:211], v[0:1]
	v_add_f32_e32 v0, v0, v1
	v_ashrrev_i32_e32 v1, 31, v0
	v_mfma_f32_32x32x16_bf16 v[6:21], v[98:101], v[196:199], v[6:21]
	s_waitcnt vmcnt(10)
	ds_read_b128 v[38:41], v5 offset:10496
	ds_read_b128 v[42:45], v52 offset:10496
	ds_read_b128 v[46:49], v55 offset:10496
	ds_read_b128 v[196:199], v56 offset:10496
	v_or_b32_e32 v1, 0x80000000, v1
	s_cmpk_gt_i32 s11, 216
	s_cselect_b64 vcc, -1, 0
	v_xor_b32_e32 v0, v1, v0
	v_cndmask_b32_e32 v159, v123, v0, vcc
	s_nop 3
	s_waitcnt lgkmcnt(3)
	v_mfma_f32_32x32x16_bf16 v[212:227], v[70:73], v[38:41], 0
	v_max_f32_e32 v108, 0, v6
	v_max_f32_e32 v109, 0, v7
	v_pk_mul_f32 v[50:51], v[244:245], v[108:109]
	v_max_f32_e32 v210, 0, v8
	v_max_f32_e32 v211, 0, v9
	v_pk_fma_f32 v[50:51], v[246:247], v[210:211], v[50:51]
	v_max_f32_e32 v108, 0, v10
	v_max_f32_e32 v109, 0, v11
	v_pk_fma_f32 v[50:51], v[248:249], v[108:109], v[50:51]
	s_waitcnt lgkmcnt(2)
	v_mfma_f32_32x32x16_bf16 v[212:227], v[74:77], v[42:45], v[212:227]
	v_max_f32_e32 v210, 0, v12
	v_max_f32_e32 v211, 0, v13
	v_pk_fma_f32 v[50:51], v[250:251], v[210:211], v[50:51]
	v_max_f32_e32 v108, 0, v14
	v_max_f32_e32 v109, 0, v15
	v_pk_fma_f32 v[50:51], v[252:253], v[108:109], v[50:51]
	v_max_f32_e32 v210, 0, v16
	v_max_f32_e32 v211, 0, v17
	v_pk_fma_f32 v[50:51], v[254:255], v[210:211], v[50:51]
	s_waitcnt lgkmcnt(1)
	v_mfma_f32_32x32x16_bf16 v[212:227], v[78:81], v[46:49], v[212:227]
	v_max_f32_e32 v108, 0, v18
	v_max_f32_e32 v109, 0, v19
	v_pk_fma_f32 v[50:51], v[200:201], v[108:109], v[50:51]
	v_max_f32_e32 v210, 0, v20
	v_max_f32_e32 v211, 0, v21
	v_pk_fma_f32 v[50:51], v[202:203], v[210:211], v[50:51]
	v_add_f32_e32 v50, v50, v51
	v_ashrrev_i32_e32 v51, 31, v50
	s_waitcnt lgkmcnt(0)
	v_mfma_f32_32x32x16_bf16 v[212:227], v[82:85], v[196:199], v[212:227]
	v_or_b32_e32 v51, 0x80000000, v51
	s_cmpk_gt_i32 s11, 216
	s_cselect_b64 vcc, -1, 0
	v_xor_b32_e32 v50, v51, v50
	v_cndmask_b32_e32 v50, v123, v50, vcc
	global_store_dword v243, v50, s[8:9] offset:2048
	s_add_u32 s8, s8, 0x1000
	s_addc_u32 s9, s9, 0
	v_mfma_f32_32x32x16_bf16 v[6:21], v[86:89], v[38:41], 0
	s_add_i32 m0, s10, 98304
	s_nop 0
	global_load_lds_dwordx4 v102, s[6:7]
	s_add_i32 m0, s10, 99328
	s_nop 0
	global_load_lds_dwordx4 v110, s[6:7]
	s_add_i32 m0, s10, 100352
	s_nop 0
	global_load_lds_dwordx4 v112, s[6:7]
	s_add_i32 m0, s10, 101376
	s_nop 0
	global_load_lds_dwordx4 v193, s[6:7]
	s_add_u32 s6, s6, 0x8000
	s_addc_u32 s7, s7, 0
	v_max_f32_e32 v108, 0, v212
	v_max_f32_e32 v109, 0, v213
	v_pk_mul_f32 v[0:1], v[22:23], v[108:109]
	v_max_f32_e32 v210, 0, v214
	v_max_f32_e32 v211, 0, v215
	v_pk_fma_f32 v[0:1], v[24:25], v[210:211], v[0:1]
	v_max_f32_e32 v108, 0, v216
	v_max_f32_e32 v109, 0, v217
	v_pk_fma_f32 v[0:1], v[26:27], v[108:109], v[0:1]
	v_mfma_f32_32x32x16_bf16 v[6:21], v[90:93], v[42:45], v[6:21]
	v_max_f32_e32 v210, 0, v218
	v_max_f32_e32 v211, 0, v219
	v_pk_fma_f32 v[0:1], v[28:29], v[210:211], v[0:1]
	v_max_f32_e32 v108, 0, v220
	v_max_f32_e32 v109, 0, v221
	v_pk_fma_f32 v[0:1], v[30:31], v[108:109], v[0:1]
	v_max_f32_e32 v210, 0, v222
	v_max_f32_e32 v211, 0, v223
	v_pk_fma_f32 v[0:1], v[32:33], v[210:211], v[0:1]
	v_mfma_f32_32x32x16_bf16 v[6:21], v[94:97], v[46:49], v[6:21]
	v_max_f32_e32 v108, 0, v224
	v_max_f32_e32 v109, 0, v225
	v_pk_fma_f32 v[0:1], v[34:35], v[108:109], v[0:1]
	v_max_f32_e32 v210, 0, v226
	v_max_f32_e32 v211, 0, v227
	v_pk_fma_f32 v[0:1], v[36:37], v[210:211], v[0:1]
	v_add_f32_e32 v0, v0, v1
	v_ashrrev_i32_e32 v1, 31, v0
	v_mfma_f32_32x32x16_bf16 v[6:21], v[98:101], v[196:199], v[6:21]
	s_waitcnt vmcnt(10)
	ds_read_b128 v[38:41], v5 offset:43264
	ds_read_b128 v[42:45], v52 offset:43264
	ds_read_b128 v[46:49], v55 offset:43264
	ds_read_b128 v[196:199], v56 offset:43264
	v_or_b32_e32 v1, 0x80000000, v1
	s_cmpk_gt_i32 s11, 224
	s_cselect_b64 vcc, -1, 0
	v_xor_b32_e32 v0, v1, v0
	v_cndmask_b32_e32 v162, v123, v0, vcc
	s_nop 3
	s_waitcnt lgkmcnt(3)
	v_mfma_f32_32x32x16_bf16 v[212:227], v[70:73], v[38:41], 0
	v_max_f32_e32 v108, 0, v6
	v_max_f32_e32 v109, 0, v7
	v_pk_mul_f32 v[50:51], v[244:245], v[108:109]
	v_max_f32_e32 v210, 0, v8
	v_max_f32_e32 v211, 0, v9
	v_pk_fma_f32 v[50:51], v[246:247], v[210:211], v[50:51]
	v_max_f32_e32 v108, 0, v10
	v_max_f32_e32 v109, 0, v11
	v_pk_fma_f32 v[50:51], v[248:249], v[108:109], v[50:51]
	s_waitcnt lgkmcnt(2)
	v_mfma_f32_32x32x16_bf16 v[212:227], v[74:77], v[42:45], v[212:227]
	v_max_f32_e32 v210, 0, v12
	v_max_f32_e32 v211, 0, v13
	v_pk_fma_f32 v[50:51], v[250:251], v[210:211], v[50:51]
	v_max_f32_e32 v108, 0, v14
	v_max_f32_e32 v109, 0, v15
	v_pk_fma_f32 v[50:51], v[252:253], v[108:109], v[50:51]
	v_max_f32_e32 v210, 0, v16
	v_max_f32_e32 v211, 0, v17
	v_pk_fma_f32 v[50:51], v[254:255], v[210:211], v[50:51]
	s_waitcnt lgkmcnt(1)
	v_mfma_f32_32x32x16_bf16 v[212:227], v[78:81], v[46:49], v[212:227]
	v_max_f32_e32 v108, 0, v18
	v_max_f32_e32 v109, 0, v19
	v_pk_fma_f32 v[50:51], v[200:201], v[108:109], v[50:51]
	v_max_f32_e32 v210, 0, v20
	v_max_f32_e32 v211, 0, v21
	v_pk_fma_f32 v[50:51], v[202:203], v[210:211], v[50:51]
	v_add_f32_e32 v50, v50, v51
	v_ashrrev_i32_e32 v51, 31, v50
	s_waitcnt lgkmcnt(0)
	v_mfma_f32_32x32x16_bf16 v[212:227], v[82:85], v[196:199], v[212:227]
	v_or_b32_e32 v51, 0x80000000, v51
	s_cmpk_gt_i32 s11, 224
	s_cselect_b64 vcc, -1, 0
	v_xor_b32_e32 v50, v51, v50
	v_cndmask_b32_e32 v50, v123, v50, vcc
	global_store_dword v243, v50, s[8:9]
	v_mfma_f32_32x32x16_bf16 v[6:21], v[86:89], v[38:41], 0
	s_add_i32 m0, s10, 0
	s_nop 0
	global_load_lds_dwordx4 v102, s[6:7]
	s_add_i32 m0, s10, 1024
	s_nop 0
	global_load_lds_dwordx4 v110, s[6:7]
	s_add_i32 m0, s10, 2048
	s_nop 0
	global_load_lds_dwordx4 v112, s[6:7]
	s_add_i32 m0, s10, 3072
	s_nop 0
	global_load_lds_dwordx4 v193, s[6:7]
	s_add_u32 s6, s6, 0x8000
	s_addc_u32 s7, s7, 0
	v_max_f32_e32 v108, 0, v212
	v_max_f32_e32 v109, 0, v213
	v_pk_mul_f32 v[0:1], v[22:23], v[108:109]
	v_max_f32_e32 v210, 0, v214
	v_max_f32_e32 v211, 0, v215
	v_pk_fma_f32 v[0:1], v[24:25], v[210:211], v[0:1]
	v_max_f32_e32 v108, 0, v216
	v_max_f32_e32 v109, 0, v217
	v_pk_fma_f32 v[0:1], v[26:27], v[108:109], v[0:1]
	v_mfma_f32_32x32x16_bf16 v[6:21], v[90:93], v[42:45], v[6:21]
	v_max_f32_e32 v210, 0, v218
	v_max_f32_e32 v211, 0, v219
	v_pk_fma_f32 v[0:1], v[28:29], v[210:211], v[0:1]
	v_max_f32_e32 v108, 0, v220
	v_max_f32_e32 v109, 0, v221
	v_pk_fma_f32 v[0:1], v[30:31], v[108:109], v[0:1]
	v_max_f32_e32 v210, 0, v222
	v_max_f32_e32 v211, 0, v223
	v_pk_fma_f32 v[0:1], v[32:33], v[210:211], v[0:1]
	v_mfma_f32_32x32x16_bf16 v[6:21], v[94:97], v[46:49], v[6:21]
	v_max_f32_e32 v108, 0, v224
	v_max_f32_e32 v109, 0, v225
	v_pk_fma_f32 v[0:1], v[34:35], v[108:109], v[0:1]
	v_max_f32_e32 v210, 0, v226
	v_max_f32_e32 v211, 0, v227
	v_pk_fma_f32 v[0:1], v[36:37], v[210:211], v[0:1]
	v_add_f32_e32 v0, v0, v1
	v_ashrrev_i32_e32 v1, 31, v0
	v_mfma_f32_32x32x16_bf16 v[6:21], v[98:101], v[196:199], v[6:21]
	s_waitcnt vmcnt(10)
	v_add_u32_e32 v228, 0x10000, v5
	ds_read_b128 v[38:41], v228 offset:10496
	v_add_u32_e32 v228, 0x10000, v52
	ds_read_b128 v[42:45], v228 offset:10496
	v_add_u32_e32 v228, 0x10000, v55
	ds_read_b128 v[46:49], v228 offset:10496
	v_add_u32_e32 v228, 0x10000, v56
	ds_read_b128 v[196:199], v228 offset:10496
	v_or_b32_e32 v1, 0x80000000, v1
	s_cmpk_gt_i32 s11, 232
	s_cselect_b64 vcc, -1, 0
	v_xor_b32_e32 v0, v1, v0
	v_cndmask_b32_e32 v161, v123, v0, vcc
	s_nop 3
	s_waitcnt lgkmcnt(3)
	v_mfma_f32_32x32x16_bf16 v[212:227], v[70:73], v[38:41], 0
	v_max_f32_e32 v108, 0, v6
	v_max_f32_e32 v109, 0, v7
	v_pk_mul_f32 v[50:51], v[244:245], v[108:109]
	v_max_f32_e32 v210, 0, v8
	v_max_f32_e32 v211, 0, v9
	v_pk_fma_f32 v[50:51], v[246:247], v[210:211], v[50:51]
	v_max_f32_e32 v108, 0, v10
	v_max_f32_e32 v109, 0, v11
	v_pk_fma_f32 v[50:51], v[248:249], v[108:109], v[50:51]
	s_waitcnt lgkmcnt(2)
	v_mfma_f32_32x32x16_bf16 v[212:227], v[74:77], v[42:45], v[212:227]
	v_max_f32_e32 v210, 0, v12
	v_max_f32_e32 v211, 0, v13
	v_pk_fma_f32 v[50:51], v[250:251], v[210:211], v[50:51]
	v_max_f32_e32 v108, 0, v14
	v_max_f32_e32 v109, 0, v15
	v_pk_fma_f32 v[50:51], v[252:253], v[108:109], v[50:51]
	v_max_f32_e32 v210, 0, v16
	v_max_f32_e32 v211, 0, v17
	v_pk_fma_f32 v[50:51], v[254:255], v[210:211], v[50:51]
	s_waitcnt lgkmcnt(1)
	v_mfma_f32_32x32x16_bf16 v[212:227], v[78:81], v[46:49], v[212:227]
	v_max_f32_e32 v108, 0, v18
	v_max_f32_e32 v109, 0, v19
	v_pk_fma_f32 v[50:51], v[200:201], v[108:109], v[50:51]
	v_max_f32_e32 v210, 0, v20
	v_max_f32_e32 v211, 0, v21
	v_pk_fma_f32 v[50:51], v[202:203], v[210:211], v[50:51]
	v_add_f32_e32 v50, v50, v51
	v_ashrrev_i32_e32 v51, 31, v50
	s_waitcnt lgkmcnt(0)
	v_mfma_f32_32x32x16_bf16 v[212:227], v[82:85], v[196:199], v[212:227]
	v_or_b32_e32 v51, 0x80000000, v51
	s_cmpk_gt_i32 s11, 232
	s_cselect_b64 vcc, -1, 0
	v_xor_b32_e32 v50, v51, v50
	v_cndmask_b32_e32 v50, v123, v50, vcc
	global_store_dword v243, v50, s[8:9] offset:2048
	s_add_u32 s8, s8, 0x1000
	s_addc_u32 s9, s9, 0
	v_mfma_f32_32x32x16_bf16 v[6:21], v[86:89], v[38:41], 0
	s_add_i32 m0, s10, 32768
	s_nop 0
	global_load_lds_dwordx4 v102, s[6:7]
	s_add_i32 m0, s10, 33792
	s_nop 0
	global_load_lds_dwordx4 v110, s[6:7]
	s_add_i32 m0, s10, 34816
	s_nop 0
	global_load_lds_dwordx4 v112, s[6:7]
	s_add_i32 m0, s10, 35840
	s_nop 0
	global_load_lds_dwordx4 v193, s[6:7]
	s_add_u32 s6, s6, 0x8000
	s_addc_u32 s7, s7, 0
	v_max_f32_e32 v108, 0, v212
	v_max_f32_e32 v109, 0, v213
	v_pk_mul_f32 v[0:1], v[22:23], v[108:109]
	v_max_f32_e32 v210, 0, v214
	v_max_f32_e32 v211, 0, v215
	v_pk_fma_f32 v[0:1], v[24:25], v[210:211], v[0:1]
	v_max_f32_e32 v108, 0, v216
	v_max_f32_e32 v109, 0, v217
	v_pk_fma_f32 v[0:1], v[26:27], v[108:109], v[0:1]
	v_mfma_f32_32x32x16_bf16 v[6:21], v[90:93], v[42:45], v[6:21]
	v_max_f32_e32 v210, 0, v218
	v_max_f32_e32 v211, 0, v219
	v_pk_fma_f32 v[0:1], v[28:29], v[210:211], v[0:1]
	v_max_f32_e32 v108, 0, v220
	v_max_f32_e32 v109, 0, v221
	v_pk_fma_f32 v[0:1], v[30:31], v[108:109], v[0:1]
	v_max_f32_e32 v210, 0, v222
	v_max_f32_e32 v211, 0, v223
	v_pk_fma_f32 v[0:1], v[32:33], v[210:211], v[0:1]
	v_mfma_f32_32x32x16_bf16 v[6:21], v[94:97], v[46:49], v[6:21]
	v_max_f32_e32 v108, 0, v224
	v_max_f32_e32 v109, 0, v225
	v_pk_fma_f32 v[0:1], v[34:35], v[108:109], v[0:1]
	v_max_f32_e32 v210, 0, v226
	v_max_f32_e32 v211, 0, v227
	v_pk_fma_f32 v[0:1], v[36:37], v[210:211], v[0:1]
	v_add_f32_e32 v0, v0, v1
	v_ashrrev_i32_e32 v1, 31, v0
	v_mfma_f32_32x32x16_bf16 v[6:21], v[98:101], v[196:199], v[6:21]
	s_waitcnt vmcnt(10)
	v_add_u32_e32 v228, 0x10000, v5
	ds_read_b128 v[38:41], v228 offset:43264
	v_add_u32_e32 v228, 0x10000, v52
	ds_read_b128 v[42:45], v228 offset:43264
	v_add_u32_e32 v228, 0x10000, v55
	ds_read_b128 v[46:49], v228 offset:43264
	v_add_u32_e32 v228, 0x10000, v56
	ds_read_b128 v[196:199], v228 offset:43264
	v_or_b32_e32 v1, 0x80000000, v1
	s_cmpk_gt_i32 s11, 240
	s_cselect_b64 vcc, -1, 0
	v_xor_b32_e32 v0, v1, v0
	v_cndmask_b32_e32 v163, v123, v0, vcc
	s_nop 3
	s_waitcnt lgkmcnt(3)
	v_mfma_f32_32x32x16_bf16 v[212:227], v[70:73], v[38:41], 0
	v_max_f32_e32 v108, 0, v6
	v_max_f32_e32 v109, 0, v7
	v_pk_mul_f32 v[50:51], v[244:245], v[108:109]
	v_max_f32_e32 v210, 0, v8
	v_max_f32_e32 v211, 0, v9
	v_pk_fma_f32 v[50:51], v[246:247], v[210:211], v[50:51]
	v_max_f32_e32 v108, 0, v10
	v_max_f32_e32 v109, 0, v11
	v_pk_fma_f32 v[50:51], v[248:249], v[108:109], v[50:51]
	s_waitcnt lgkmcnt(2)
	v_mfma_f32_32x32x16_bf16 v[212:227], v[74:77], v[42:45], v[212:227]
	v_max_f32_e32 v210, 0, v12
	v_max_f32_e32 v211, 0, v13
	v_pk_fma_f32 v[50:51], v[250:251], v[210:211], v[50:51]
	v_max_f32_e32 v108, 0, v14
	v_max_f32_e32 v109, 0, v15
	v_pk_fma_f32 v[50:51], v[252:253], v[108:109], v[50:51]
	v_max_f32_e32 v210, 0, v16
	v_max_f32_e32 v211, 0, v17
	v_pk_fma_f32 v[50:51], v[254:255], v[210:211], v[50:51]
	s_waitcnt lgkmcnt(1)
	v_mfma_f32_32x32x16_bf16 v[212:227], v[78:81], v[46:49], v[212:227]
	v_max_f32_e32 v108, 0, v18
	v_max_f32_e32 v109, 0, v19
	v_pk_fma_f32 v[50:51], v[200:201], v[108:109], v[50:51]
	v_max_f32_e32 v210, 0, v20
	v_max_f32_e32 v211, 0, v21
	v_pk_fma_f32 v[50:51], v[202:203], v[210:211], v[50:51]
	v_add_f32_e32 v50, v50, v51
	v_ashrrev_i32_e32 v51, 31, v50
	s_waitcnt lgkmcnt(0)
	v_mfma_f32_32x32x16_bf16 v[212:227], v[82:85], v[196:199], v[212:227]
	v_or_b32_e32 v51, 0x80000000, v51
	s_cmpk_gt_i32 s11, 240
	s_cselect_b64 vcc, -1, 0
	v_xor_b32_e32 v50, v51, v50
	v_cndmask_b32_e32 v50, v123, v50, vcc
	global_store_dword v243, v50, s[8:9]
	v_mfma_f32_32x32x16_bf16 v[6:21], v[86:89], v[38:41], 0
	s_add_i32 m0, s10, 65536
	s_nop 0
	global_load_lds_dwordx4 v102, s[6:7]
	s_add_i32 m0, s10, 66560
	s_nop 0
	global_load_lds_dwordx4 v110, s[6:7]
	s_add_i32 m0, s10, 67584
	s_nop 0
	global_load_lds_dwordx4 v112, s[6:7]
	s_add_i32 m0, s10, 68608
	s_nop 0
	global_load_lds_dwordx4 v193, s[6:7]
	s_add_u32 s6, s6, 0x8000
	s_addc_u32 s7, s7, 0
	v_max_f32_e32 v108, 0, v212
	v_max_f32_e32 v109, 0, v213
	v_pk_mul_f32 v[0:1], v[22:23], v[108:109]
	v_max_f32_e32 v210, 0, v214
	v_max_f32_e32 v211, 0, v215
	v_pk_fma_f32 v[0:1], v[24:25], v[210:211], v[0:1]
	v_max_f32_e32 v108, 0, v216
	v_max_f32_e32 v109, 0, v217
	v_pk_fma_f32 v[0:1], v[26:27], v[108:109], v[0:1]
	v_mfma_f32_32x32x16_bf16 v[6:21], v[90:93], v[42:45], v[6:21]
	v_max_f32_e32 v210, 0, v218
	v_max_f32_e32 v211, 0, v219
	v_pk_fma_f32 v[0:1], v[28:29], v[210:211], v[0:1]
	v_max_f32_e32 v108, 0, v220
	v_max_f32_e32 v109, 0, v221
	v_pk_fma_f32 v[0:1], v[30:31], v[108:109], v[0:1]
	v_max_f32_e32 v210, 0, v222
	v_max_f32_e32 v211, 0, v223
	v_pk_fma_f32 v[0:1], v[32:33], v[210:211], v[0:1]
	v_mfma_f32_32x32x16_bf16 v[6:21], v[94:97], v[46:49], v[6:21]
	v_max_f32_e32 v108, 0, v224
	v_max_f32_e32 v109, 0, v225
	v_pk_fma_f32 v[0:1], v[34:35], v[108:109], v[0:1]
	v_max_f32_e32 v210, 0, v226
	v_max_f32_e32 v211, 0, v227
	v_pk_fma_f32 v[0:1], v[36:37], v[210:211], v[0:1]
	v_add_f32_e32 v0, v0, v1
	v_ashrrev_i32_e32 v1, 31, v0
	v_mfma_f32_32x32x16_bf16 v[6:21], v[98:101], v[196:199], v[6:21]
	s_waitcnt vmcnt(10)
	ds_read_b128 v[38:41], v5 offset:10496
	ds_read_b128 v[42:45], v52 offset:10496
	ds_read_b128 v[46:49], v55 offset:10496
	ds_read_b128 v[196:199], v56 offset:10496
	v_or_b32_e32 v1, 0x80000000, v1
	s_cmpk_gt_i32 s11, 248
	s_cselect_b64 vcc, -1, 0
	v_xor_b32_e32 v0, v1, v0
	v_cndmask_b32_e32 v152, v123, v0, vcc
	s_nop 3
	v_max_f32_e32 v108, 0, v6
	v_max_f32_e32 v109, 0, v7
	v_pk_mul_f32 v[50:51], v[244:245], v[108:109]
	v_max_f32_e32 v210, 0, v8
	v_max_f32_e32 v211, 0, v9
	v_pk_fma_f32 v[50:51], v[246:247], v[210:211], v[50:51]
	v_max_f32_e32 v108, 0, v10
	v_max_f32_e32 v109, 0, v11
	v_pk_fma_f32 v[50:51], v[248:249], v[108:109], v[50:51]
	v_max_f32_e32 v210, 0, v12
	v_max_f32_e32 v211, 0, v13
	v_pk_fma_f32 v[50:51], v[250:251], v[210:211], v[50:51]
	v_max_f32_e32 v108, 0, v14
	v_max_f32_e32 v109, 0, v15
	v_pk_fma_f32 v[50:51], v[252:253], v[108:109], v[50:51]
	v_max_f32_e32 v210, 0, v16
	v_max_f32_e32 v211, 0, v17
	v_pk_fma_f32 v[50:51], v[254:255], v[210:211], v[50:51]
	v_max_f32_e32 v108, 0, v18
	v_max_f32_e32 v109, 0, v19
	v_pk_fma_f32 v[50:51], v[200:201], v[108:109], v[50:51]
	v_max_f32_e32 v210, 0, v20
	v_max_f32_e32 v211, 0, v21
	v_pk_fma_f32 v[50:51], v[202:203], v[210:211], v[50:51]
	v_add_f32_e32 v50, v50, v51
	v_ashrrev_i32_e32 v51, 31, v50
	v_or_b32_e32 v51, 0x80000000, v51
	s_cmpk_gt_i32 s11, 248
	s_cselect_b64 vcc, -1, 0
	v_xor_b32_e32 v50, v51, v50
	v_cndmask_b32_e32 v50, v123, v50, vcc
	global_store_dword v243, v50, s[8:9] offset:2048
	s_add_u32 s8, s8, 0x1000
	s_addc_u32 s9, s9, 0
	s_cmpk_gt_i32 s81, 32
	s_cbranch_scc0 .Lix_fill_4
	s_waitcnt lgkmcnt(3)
	v_mfma_f32_32x32x16_bf16 v[212:227], v[70:73], v[38:41], 0
	s_add_i32 m0, s10, 98304
	s_nop 0
	global_load_lds_dwordx4 v102, s[6:7]
	s_waitcnt lgkmcnt(2)
	v_mfma_f32_32x32x16_bf16 v[212:227], v[74:77], v[42:45], v[212:227]
	s_add_i32 m0, s10, 99328
	s_nop 0
	global_load_lds_dwordx4 v110, s[6:7]
	s_waitcnt lgkmcnt(1)
	v_mfma_f32_32x32x16_bf16 v[212:227], v[78:81], v[46:49], v[212:227]
	s_add_i32 m0, s10, 100352
	s_nop 0
	global_load_lds_dwordx4 v112, s[6:7]
	s_waitcnt lgkmcnt(0)
	v_mfma_f32_32x32x16_bf16 v[212:227], v[82:85], v[196:199], v[212:227]
	s_add_i32 m0, s10, 101376
	s_nop 0
	global_load_lds_dwordx4 v193, s[6:7]
	s_add_u32 s6, s6, 0x8000
	s_addc_u32 s7, s7, 0
	v_mfma_f32_32x32x16_bf16 v[6:21], v[86:89], v[38:41], 0
	s_nop 7
	s_nop 2
	v_max_f32_e32 v108, 0, v212
	v_max_f32_e32 v109, 0, v213
	v_pk_mul_f32 v[0:1], v[22:23], v[108:109]
	v_max_f32_e32 v210, 0, v214
	v_max_f32_e32 v211, 0, v215
	v_pk_fma_f32 v[0:1], v[24:25], v[210:211], v[0:1]
	v_max_f32_e32 v108, 0, v216
	v_max_f32_e32 v109, 0, v217
	v_pk_fma_f32 v[0:1], v[26:27], v[108:109], v[0:1]
	v_mfma_f32_32x32x16_bf16 v[6:21], v[90:93], v[42:45], v[6:21]
	v_max_f32_e32 v210, 0, v218
	v_max_f32_e32 v211, 0, v219
	v_pk_fma_f32 v[0:1], v[28:29], v[210:211], v[0:1]
	v_max_f32_e32 v108, 0, v220
	v_max_f32_e32 v109, 0, v221
	v_pk_fma_f32 v[0:1], v[30:31], v[108:109], v[0:1]
	v_max_f32_e32 v210, 0, v222
	v_max_f32_e32 v211, 0, v223
	v_pk_fma_f32 v[0:1], v[32:33], v[210:211], v[0:1]
	v_mfma_f32_32x32x16_bf16 v[6:21], v[94:97], v[46:49], v[6:21]
	v_max_f32_e32 v108, 0, v224
	v_max_f32_e32 v109, 0, v225
	v_pk_fma_f32 v[0:1], v[34:35], v[108:109], v[0:1]
	v_max_f32_e32 v210, 0, v226
	v_max_f32_e32 v211, 0, v227
	v_pk_fma_f32 v[0:1], v[36:37], v[210:211], v[0:1]
	v_add_f32_e32 v0, v0, v1
	v_ashrrev_i32_e32 v1, 31, v0
	v_mfma_f32_32x32x16_bf16 v[6:21], v[98:101], v[196:199], v[6:21]
	s_waitcnt vmcnt(10)
	ds_read_b128 v[38:41], v5 offset:43264
	ds_read_b128 v[42:45], v52 offset:43264
	ds_read_b128 v[46:49], v55 offset:43264
	ds_read_b128 v[196:199], v56 offset:43264
	v_or_b32_e32 v1, 0x80000000, v1
	s_cmpk_gt_i32 s11, 256
	s_cselect_b64 vcc, -1, 0
	v_xor_b32_e32 v0, v1, v0
	v_cndmask_b32_e32 v165, v123, v0, vcc
	s_nop 3
	s_waitcnt lgkmcnt(3)
	v_mfma_f32_32x32x16_bf16 v[212:227], v[70:73], v[38:41], 0
	v_max_f32_e32 v108, 0, v6
	v_max_f32_e32 v109, 0, v7
	v_pk_mul_f32 v[50:51], v[244:245], v[108:109]
	v_max_f32_e32 v210, 0, v8
	v_max_f32_e32 v211, 0, v9
	v_pk_fma_f32 v[50:51], v[246:247], v[210:211], v[50:51]
	v_max_f32_e32 v108, 0, v10
	v_max_f32_e32 v109, 0, v11
	v_pk_fma_f32 v[50:51], v[248:249], v[108:109], v[50:51]
	s_waitcnt lgkmcnt(2)
	v_mfma_f32_32x32x16_bf16 v[212:227], v[74:77], v[42:45], v[212:227]
	v_max_f32_e32 v210, 0, v12
	v_max_f32_e32 v211, 0, v13
	v_pk_fma_f32 v[50:51], v[250:251], v[210:211], v[50:51]
	v_max_f32_e32 v108, 0, v14
	v_max_f32_e32 v109, 0, v15
	v_pk_fma_f32 v[50:51], v[252:253], v[108:109], v[50:51]
	v_max_f32_e32 v210, 0, v16
	v_max_f32_e32 v211, 0, v17
	v_pk_fma_f32 v[50:51], v[254:255], v[210:211], v[50:51]
	s_waitcnt lgkmcnt(1)
	v_mfma_f32_32x32x16_bf16 v[212:227], v[78:81], v[46:49], v[212:227]
	v_max_f32_e32 v108, 0, v18
	v_max_f32_e32 v109, 0, v19
	v_pk_fma_f32 v[50:51], v[200:201], v[108:109], v[50:51]
	v_max_f32_e32 v210, 0, v20
	v_max_f32_e32 v211, 0, v21
	v_pk_fma_f32 v[50:51], v[202:203], v[210:211], v[50:51]
	v_add_f32_e32 v50, v50, v51
	v_ashrrev_i32_e32 v51, 31, v50
	s_waitcnt lgkmcnt(0)
	v_mfma_f32_32x32x16_bf16 v[212:227], v[82:85], v[196:199], v[212:227]
	v_or_b32_e32 v51, 0x80000000, v51
	s_cmpk_gt_i32 s11, 256
	s_cselect_b64 vcc, -1, 0
	v_xor_b32_e32 v50, v51, v50
	v_cndmask_b32_e32 v50, v123, v50, vcc
	global_store_dword v243, v50, s[8:9]
	v_mfma_f32_32x32x16_bf16 v[6:21], v[86:89], v[38:41], 0
	s_add_i32 m0, s10, 0
	s_nop 0
	global_load_lds_dwordx4 v102, s[6:7]
	s_add_i32 m0, s10, 1024
	s_nop 0
	global_load_lds_dwordx4 v110, s[6:7]
	s_add_i32 m0, s10, 2048
	s_nop 0
	global_load_lds_dwordx4 v112, s[6:7]
	s_add_i32 m0, s10, 3072
	s_nop 0
	global_load_lds_dwordx4 v193, s[6:7]
	s_add_u32 s6, s6, 0x8000
	s_addc_u32 s7, s7, 0
	v_max_f32_e32 v108, 0, v212
	v_max_f32_e32 v109, 0, v213
	v_pk_mul_f32 v[0:1], v[22:23], v[108:109]
	v_max_f32_e32 v210, 0, v214
	v_max_f32_e32 v211, 0, v215
	v_pk_fma_f32 v[0:1], v[24:25], v[210:211], v[0:1]
	v_max_f32_e32 v108, 0, v216
	v_max_f32_e32 v109, 0, v217
	v_pk_fma_f32 v[0:1], v[26:27], v[108:109], v[0:1]
	v_mfma_f32_32x32x16_bf16 v[6:21], v[90:93], v[42:45], v[6:21]
	v_max_f32_e32 v210, 0, v218
	v_max_f32_e32 v211, 0, v219
	v_pk_fma_f32 v[0:1], v[28:29], v[210:211], v[0:1]
	v_max_f32_e32 v108, 0, v220
	v_max_f32_e32 v109, 0, v221
	v_pk_fma_f32 v[0:1], v[30:31], v[108:109], v[0:1]
	v_max_f32_e32 v210, 0, v222
	v_max_f32_e32 v211, 0, v223
	v_pk_fma_f32 v[0:1], v[32:33], v[210:211], v[0:1]
	v_mfma_f32_32x32x16_bf16 v[6:21], v[94:97], v[46:49], v[6:21]
	v_max_f32_e32 v108, 0, v224
	v_max_f32_e32 v109, 0, v225
	v_pk_fma_f32 v[0:1], v[34:35], v[108:109], v[0:1]
	v_max_f32_e32 v210, 0, v226
	v_max_f32_e32 v211, 0, v227
	v_pk_fma_f32 v[0:1], v[36:37], v[210:211], v[0:1]
	v_add_f32_e32 v0, v0, v1
	v_ashrrev_i32_e32 v1, 31, v0
	v_mfma_f32_32x32x16_bf16 v[6:21], v[98:101], v[196:199], v[6:21]
	s_waitcnt vmcnt(10)
	v_add_u32_e32 v228, 0x10000, v5
	ds_read_b128 v[38:41], v228 offset:10496
	v_add_u32_e32 v228, 0x10000, v52
	ds_read_b128 v[42:45], v228 offset:10496
	v_add_u32_e32 v228, 0x10000, v55
	ds_read_b128 v[46:49], v228 offset:10496
	v_add_u32_e32 v228, 0x10000, v56
	ds_read_b128 v[196:199], v228 offset:10496
	v_or_b32_e32 v1, 0x80000000, v1
	s_cmpk_gt_i32 s11, 264
	s_cselect_b64 vcc, -1, 0
	v_xor_b32_e32 v0, v1, v0
	v_cndmask_b32_e32 v164, v123, v0, vcc
	s_nop 3
	s_waitcnt lgkmcnt(3)
	v_mfma_f32_32x32x16_bf16 v[212:227], v[70:73], v[38:41], 0
	v_max_f32_e32 v108, 0, v6
	v_max_f32_e32 v109, 0, v7
	v_pk_mul_f32 v[50:51], v[244:245], v[108:109]
	v_max_f32_e32 v210, 0, v8
	v_max_f32_e32 v211, 0, v9
	v_pk_fma_f32 v[50:51], v[246:247], v[210:211], v[50:51]
	v_max_f32_e32 v108, 0, v10
	v_max_f32_e32 v109, 0, v11
	v_pk_fma_f32 v[50:51], v[248:249], v[108:109], v[50:51]
	s_waitcnt lgkmcnt(2)
	v_mfma_f32_32x32x16_bf16 v[212:227], v[74:77], v[42:45], v[212:227]
	v_max_f32_e32 v210, 0, v12
	v_max_f32_e32 v211, 0, v13
	v_pk_fma_f32 v[50:51], v[250:251], v[210:211], v[50:51]
	v_max_f32_e32 v108, 0, v14
	v_max_f32_e32 v109, 0, v15
	v_pk_fma_f32 v[50:51], v[252:253], v[108:109], v[50:51]
	v_max_f32_e32 v210, 0, v16
	v_max_f32_e32 v211, 0, v17
	v_pk_fma_f32 v[50:51], v[254:255], v[210:211], v[50:51]
	s_waitcnt lgkmcnt(1)
	v_mfma_f32_32x32x16_bf16 v[212:227], v[78:81], v[46:49], v[212:227]
	v_max_f32_e32 v108, 0, v18
	v_max_f32_e32 v109, 0, v19
	v_pk_fma_f32 v[50:51], v[200:201], v[108:109], v[50:51]
	v_max_f32_e32 v210, 0, v20
	v_max_f32_e32 v211, 0, v21
	v_pk_fma_f32 v[50:51], v[202:203], v[210:211], v[50:51]
	v_add_f32_e32 v50, v50, v51
	v_ashrrev_i32_e32 v51, 31, v50
	s_waitcnt lgkmcnt(0)
	v_mfma_f32_32x32x16_bf16 v[212:227], v[82:85], v[196:199], v[212:227]
	v_or_b32_e32 v51, 0x80000000, v51
	s_cmpk_gt_i32 s11, 264
	s_cselect_b64 vcc, -1, 0
	v_xor_b32_e32 v50, v51, v50
	v_cndmask_b32_e32 v50, v123, v50, vcc
	global_store_dword v243, v50, s[8:9] offset:2048
	s_add_u32 s8, s8, 0x1000
	s_addc_u32 s9, s9, 0
	v_mfma_f32_32x32x16_bf16 v[6:21], v[86:89], v[38:41], 0
	s_add_i32 m0, s10, 32768
	s_nop 0
	global_load_lds_dwordx4 v102, s[6:7]
	s_add_i32 m0, s10, 33792
	s_nop 0
	global_load_lds_dwordx4 v110, s[6:7]
	s_add_i32 m0, s10, 34816
	s_nop 0
	global_load_lds_dwordx4 v112, s[6:7]
	s_add_i32 m0, s10, 35840
	s_nop 0
	global_load_lds_dwordx4 v193, s[6:7]
	s_add_u32 s6, s6, 0x8000
	s_addc_u32 s7, s7, 0
	v_max_f32_e32 v108, 0, v212
	v_max_f32_e32 v109, 0, v213
	v_pk_mul_f32 v[0:1], v[22:23], v[108:109]
	v_max_f32_e32 v210, 0, v214
	v_max_f32_e32 v211, 0, v215
	v_pk_fma_f32 v[0:1], v[24:25], v[210:211], v[0:1]
	v_max_f32_e32 v108, 0, v216
	v_max_f32_e32 v109, 0, v217
	v_pk_fma_f32 v[0:1], v[26:27], v[108:109], v[0:1]
	v_mfma_f32_32x32x16_bf16 v[6:21], v[90:93], v[42:45], v[6:21]
	v_max_f32_e32 v210, 0, v218
	v_max_f32_e32 v211, 0, v219
	v_pk_fma_f32 v[0:1], v[28:29], v[210:211], v[0:1]
	v_max_f32_e32 v108, 0, v220
	v_max_f32_e32 v109, 0, v221
	v_pk_fma_f32 v[0:1], v[30:31], v[108:109], v[0:1]
	v_max_f32_e32 v210, 0, v222
	v_max_f32_e32 v211, 0, v223
	v_pk_fma_f32 v[0:1], v[32:33], v[210:211], v[0:1]
	v_mfma_f32_32x32x16_bf16 v[6:21], v[94:97], v[46:49], v[6:21]
	v_max_f32_e32 v108, 0, v224
	v_max_f32_e32 v109, 0, v225
	v_pk_fma_f32 v[0:1], v[34:35], v[108:109], v[0:1]
	v_max_f32_e32 v210, 0, v226
	v_max_f32_e32 v211, 0, v227
	v_pk_fma_f32 v[0:1], v[36:37], v[210:211], v[0:1]
	v_add_f32_e32 v0, v0, v1
	v_ashrrev_i32_e32 v1, 31, v0
	v_mfma_f32_32x32x16_bf16 v[6:21], v[98:101], v[196:199], v[6:21]
	s_waitcnt vmcnt(10)
	v_add_u32_e32 v228, 0x10000, v5
	ds_read_b128 v[38:41], v228 offset:43264
	v_add_u32_e32 v228, 0x10000, v52
	ds_read_b128 v[42:45], v228 offset:43264
	v_add_u32_e32 v228, 0x10000, v55
	ds_read_b128 v[46:49], v228 offset:43264
	v_add_u32_e32 v228, 0x10000, v56
	ds_read_b128 v[196:199], v228 offset:43264
	v_or_b32_e32 v1, 0x80000000, v1
	s_cmpk_gt_i32 s11, 272
	s_cselect_b64 vcc, -1, 0
	v_xor_b32_e32 v0, v1, v0
	v_cndmask_b32_e32 v167, v123, v0, vcc
	s_nop 3
	s_waitcnt lgkmcnt(3)
	v_mfma_f32_32x32x16_bf16 v[212:227], v[70:73], v[38:41], 0
	v_max_f32_e32 v108, 0, v6
	v_max_f32_e32 v109, 0, v7
	v_pk_mul_f32 v[50:51], v[244:245], v[108:109]
	v_max_f32_e32 v210, 0, v8
	v_max_f32_e32 v211, 0, v9
	v_pk_fma_f32 v[50:51], v[246:247], v[210:211], v[50:51]
	v_max_f32_e32 v108, 0, v10
	v_max_f32_e32 v109, 0, v11
	v_pk_fma_f32 v[50:51], v[248:249], v[108:109], v[50:51]
	s_waitcnt lgkmcnt(2)
	v_mfma_f32_32x32x16_bf16 v[212:227], v[74:77], v[42:45], v[212:227]
	v_max_f32_e32 v210, 0, v12
	v_max_f32_e32 v211, 0, v13
	v_pk_fma_f32 v[50:51], v[250:251], v[210:211], v[50:51]
	v_max_f32_e32 v108, 0, v14
	v_max_f32_e32 v109, 0, v15
	v_pk_fma_f32 v[50:51], v[252:253], v[108:109], v[50:51]
	v_max_f32_e32 v210, 0, v16
	v_max_f32_e32 v211, 0, v17
	v_pk_fma_f32 v[50:51], v[254:255], v[210:211], v[50:51]
	s_waitcnt lgkmcnt(1)
	v_mfma_f32_32x32x16_bf16 v[212:227], v[78:81], v[46:49], v[212:227]
	v_max_f32_e32 v108, 0, v18
	v_max_f32_e32 v109, 0, v19
	v_pk_fma_f32 v[50:51], v[200:201], v[108:109], v[50:51]
	v_max_f32_e32 v210, 0, v20
	v_max_f32_e32 v211, 0, v21
	v_pk_fma_f32 v[50:51], v[202:203], v[210:211], v[50:51]
	v_add_f32_e32 v50, v50, v51
	v_ashrrev_i32_e32 v51, 31, v50
	s_waitcnt lgkmcnt(0)
	v_mfma_f32_32x32x16_bf16 v[212:227], v[82:85], v[196:199], v[212:227]
	v_or_b32_e32 v51, 0x80000000, v51
	s_cmpk_gt_i32 s11, 272
	s_cselect_b64 vcc, -1, 0
	v_xor_b32_e32 v50, v51, v50
	v_cndmask_b32_e32 v50, v123, v50, vcc
	global_store_dword v243, v50, s[8:9]
	v_mfma_f32_32x32x16_bf16 v[6:21], v[86:89], v[38:41], 0
	s_add_i32 m0, s10, 65536
	s_nop 0
	global_load_lds_dwordx4 v102, s[6:7]
	s_add_i32 m0, s10, 66560
	s_nop 0
	global_load_lds_dwordx4 v110, s[6:7]
	s_add_i32 m0, s10, 67584
	s_nop 0
	global_load_lds_dwordx4 v112, s[6:7]
	s_add_i32 m0, s10, 68608
	s_nop 0
	global_load_lds_dwordx4 v193, s[6:7]
	s_add_u32 s6, s6, 0x8000
	s_addc_u32 s7, s7, 0
	v_max_f32_e32 v108, 0, v212
	v_max_f32_e32 v109, 0, v213
	v_pk_mul_f32 v[0:1], v[22:23], v[108:109]
	v_max_f32_e32 v210, 0, v214
	v_max_f32_e32 v211, 0, v215
	v_pk_fma_f32 v[0:1], v[24:25], v[210:211], v[0:1]
	v_max_f32_e32 v108, 0, v216
	v_max_f32_e32 v109, 0, v217
	v_pk_fma_f32 v[0:1], v[26:27], v[108:109], v[0:1]
	v_mfma_f32_32x32x16_bf16 v[6:21], v[90:93], v[42:45], v[6:21]
	v_max_f32_e32 v210, 0, v218
	v_max_f32_e32 v211, 0, v219
	v_pk_fma_f32 v[0:1], v[28:29], v[210:211], v[0:1]
	v_max_f32_e32 v108, 0, v220
	v_max_f32_e32 v109, 0, v221
	v_pk_fma_f32 v[0:1], v[30:31], v[108:109], v[0:1]
	v_max_f32_e32 v210, 0, v222
	v_max_f32_e32 v211, 0, v223
	v_pk_fma_f32 v[0:1], v[32:33], v[210:211], v[0:1]
	v_mfma_f32_32x32x16_bf16 v[6:21], v[94:97], v[46:49], v[6:21]
	v_max_f32_e32 v108, 0, v224
	v_max_f32_e32 v109, 0, v225
	v_pk_fma_f32 v[0:1], v[34:35], v[108:109], v[0:1]
	v_max_f32_e32 v210, 0, v226
	v_max_f32_e32 v211, 0, v227
	v_pk_fma_f32 v[0:1], v[36:37], v[210:211], v[0:1]
	v_add_f32_e32 v0, v0, v1
	v_ashrrev_i32_e32 v1, 31, v0
	v_mfma_f32_32x32x16_bf16 v[6:21], v[98:101], v[196:199], v[6:21]
	s_waitcnt vmcnt(10)
	ds_read_b128 v[38:41], v5 offset:10496
	ds_read_b128 v[42:45], v52 offset:10496
	ds_read_b128 v[46:49], v55 offset:10496
	ds_read_b128 v[196:199], v56 offset:10496
	v_or_b32_e32 v1, 0x80000000, v1
	s_cmpk_gt_i32 s11, 280
	s_cselect_b64 vcc, -1, 0
	v_xor_b32_e32 v0, v1, v0
	v_cndmask_b32_e32 v166, v123, v0, vcc
	s_nop 3
	s_waitcnt lgkmcnt(3)
	v_mfma_f32_32x32x16_bf16 v[212:227], v[70:73], v[38:41], 0
	v_max_f32_e32 v108, 0, v6
	v_max_f32_e32 v109, 0, v7
	v_pk_mul_f32 v[50:51], v[244:245], v[108:109]
	v_max_f32_e32 v210, 0, v8
	v_max_f32_e32 v211, 0, v9
	v_pk_fma_f32 v[50:51], v[246:247], v[210:211], v[50:51]
	v_max_f32_e32 v108, 0, v10
	v_max_f32_e32 v109, 0, v11
	v_pk_fma_f32 v[50:51], v[248:249], v[108:109], v[50:51]
	s_waitcnt lgkmcnt(2)
	v_mfma_f32_32x32x16_bf16 v[212:227], v[74:77], v[42:45], v[212:227]
	v_max_f32_e32 v210, 0, v12
	v_max_f32_e32 v211, 0, v13
	v_pk_fma_f32 v[50:51], v[250:251], v[210:211], v[50:51]
	v_max_f32_e32 v108, 0, v14
	v_max_f32_e32 v109, 0, v15
	v_pk_fma_f32 v[50:51], v[252:253], v[108:109], v[50:51]
	v_max_f32_e32 v210, 0, v16
	v_max_f32_e32 v211, 0, v17
	v_pk_fma_f32 v[50:51], v[254:255], v[210:211], v[50:51]
	s_waitcnt lgkmcnt(1)
	v_mfma_f32_32x32x16_bf16 v[212:227], v[78:81], v[46:49], v[212:227]
	v_max_f32_e32 v108, 0, v18
	v_max_f32_e32 v109, 0, v19
	v_pk_fma_f32 v[50:51], v[200:201], v[108:109], v[50:51]
	v_max_f32_e32 v210, 0, v20
	v_max_f32_e32 v211, 0, v21
	v_pk_fma_f32 v[50:51], v[202:203], v[210:211], v[50:51]
	v_add_f32_e32 v50, v50, v51
	v_ashrrev_i32_e32 v51, 31, v50
	s_waitcnt lgkmcnt(0)
	v_mfma_f32_32x32x16_bf16 v[212:227], v[82:85], v[196:199], v[212:227]
	v_or_b32_e32 v51, 0x80000000, v51
	s_cmpk_gt_i32 s11, 280
	s_cselect_b64 vcc, -1, 0
	v_xor_b32_e32 v50, v51, v50
	v_cndmask_b32_e32 v50, v123, v50, vcc
	global_store_dword v243, v50, s[8:9] offset:2048
	s_add_u32 s8, s8, 0x1000
	s_addc_u32 s9, s9, 0
	v_mfma_f32_32x32x16_bf16 v[6:21], v[86:89], v[38:41], 0
	s_add_i32 m0, s10, 98304
	s_nop 0
	global_load_lds_dwordx4 v102, s[6:7]
	s_add_i32 m0, s10, 99328
	s_nop 0
	global_load_lds_dwordx4 v110, s[6:7]
	s_add_i32 m0, s10, 100352
	s_nop 0
	global_load_lds_dwordx4 v112, s[6:7]
	s_add_i32 m0, s10, 101376
	s_nop 0
	global_load_lds_dwordx4 v193, s[6:7]
	s_add_u32 s6, s6, 0x8000
	s_addc_u32 s7, s7, 0
	v_max_f32_e32 v108, 0, v212
	v_max_f32_e32 v109, 0, v213
	v_pk_mul_f32 v[0:1], v[22:23], v[108:109]
	v_max_f32_e32 v210, 0, v214
	v_max_f32_e32 v211, 0, v215
	v_pk_fma_f32 v[0:1], v[24:25], v[210:211], v[0:1]
	v_max_f32_e32 v108, 0, v216
	v_max_f32_e32 v109, 0, v217
	v_pk_fma_f32 v[0:1], v[26:27], v[108:109], v[0:1]
	v_mfma_f32_32x32x16_bf16 v[6:21], v[90:93], v[42:45], v[6:21]
	v_max_f32_e32 v210, 0, v218
	v_max_f32_e32 v211, 0, v219
	v_pk_fma_f32 v[0:1], v[28:29], v[210:211], v[0:1]
	v_max_f32_e32 v108, 0, v220
	v_max_f32_e32 v109, 0, v221
	v_pk_fma_f32 v[0:1], v[30:31], v[108:109], v[0:1]
	v_max_f32_e32 v210, 0, v222
	v_max_f32_e32 v211, 0, v223
	v_pk_fma_f32 v[0:1], v[32:33], v[210:211], v[0:1]
	v_mfma_f32_32x32x16_bf16 v[6:21], v[94:97], v[46:49], v[6:21]
	v_max_f32_e32 v108, 0, v224
	v_max_f32_e32 v109, 0, v225
	v_pk_fma_f32 v[0:1], v[34:35], v[108:109], v[0:1]
	v_max_f32_e32 v210, 0, v226
	v_max_f32_e32 v211, 0, v227
	v_pk_fma_f32 v[0:1], v[36:37], v[210:211], v[0:1]
	v_add_f32_e32 v0, v0, v1
	v_ashrrev_i32_e32 v1, 31, v0
	v_mfma_f32_32x32x16_bf16 v[6:21], v[98:101], v[196:199], v[6:21]
	s_waitcnt vmcnt(10)
	ds_read_b128 v[38:41], v5 offset:43264
	ds_read_b128 v[42:45], v52 offset:43264
	ds_read_b128 v[46:49], v55 offset:43264
	ds_read_b128 v[196:199], v56 offset:43264
	v_or_b32_e32 v1, 0x80000000, v1
	s_cmpk_gt_i32 s11, 288
	s_cselect_b64 vcc, -1, 0
	v_xor_b32_e32 v0, v1, v0
	v_cndmask_b32_e32 v170, v123, v0, vcc
	s_nop 3
	s_waitcnt lgkmcnt(3)
	v_mfma_f32_32x32x16_bf16 v[212:227], v[70:73], v[38:41], 0
	v_max_f32_e32 v108, 0, v6
	v_max_f32_e32 v109, 0, v7
	v_pk_mul_f32 v[50:51], v[244:245], v[108:109]
	v_max_f32_e32 v210, 0, v8
	v_max_f32_e32 v211, 0, v9
	v_pk_fma_f32 v[50:51], v[246:247], v[210:211], v[50:51]
	v_max_f32_e32 v108, 0, v10
	v_max_f32_e32 v109, 0, v11
	v_pk_fma_f32 v[50:51], v[248:249], v[108:109], v[50:51]
	s_waitcnt lgkmcnt(2)
	v_mfma_f32_32x32x16_bf16 v[212:227], v[74:77], v[42:45], v[212:227]
	v_max_f32_e32 v210, 0, v12
	v_max_f32_e32 v211, 0, v13
	v_pk_fma_f32 v[50:51], v[250:251], v[210:211], v[50:51]
	v_max_f32_e32 v108, 0, v14
	v_max_f32_e32 v109, 0, v15
	v_pk_fma_f32 v[50:51], v[252:253], v[108:109], v[50:51]
	v_max_f32_e32 v210, 0, v16
	v_max_f32_e32 v211, 0, v17
	v_pk_fma_f32 v[50:51], v[254:255], v[210:211], v[50:51]
	s_waitcnt lgkmcnt(1)
	v_mfma_f32_32x32x16_bf16 v[212:227], v[78:81], v[46:49], v[212:227]
	v_max_f32_e32 v108, 0, v18
	v_max_f32_e32 v109, 0, v19
	v_pk_fma_f32 v[50:51], v[200:201], v[108:109], v[50:51]
	v_max_f32_e32 v210, 0, v20
	v_max_f32_e32 v211, 0, v21
	v_pk_fma_f32 v[50:51], v[202:203], v[210:211], v[50:51]
	v_add_f32_e32 v50, v50, v51
	v_ashrrev_i32_e32 v51, 31, v50
	s_waitcnt lgkmcnt(0)
	v_mfma_f32_32x32x16_bf16 v[212:227], v[82:85], v[196:199], v[212:227]
	v_or_b32_e32 v51, 0x80000000, v51
	s_cmpk_gt_i32 s11, 288
	s_cselect_b64 vcc, -1, 0
	v_xor_b32_e32 v50, v51, v50
	v_cndmask_b32_e32 v50, v123, v50, vcc
	global_store_dword v243, v50, s[8:9]
	v_mfma_f32_32x32x16_bf16 v[6:21], v[86:89], v[38:41], 0
	s_add_i32 m0, s10, 0
	s_nop 0
	global_load_lds_dwordx4 v102, s[6:7]
	s_add_i32 m0, s10, 1024
	s_nop 0
	global_load_lds_dwordx4 v110, s[6:7]
	s_add_i32 m0, s10, 2048
	s_nop 0
	global_load_lds_dwordx4 v112, s[6:7]
	s_add_i32 m0, s10, 3072
	s_nop 0
	global_load_lds_dwordx4 v193, s[6:7]
	s_add_u32 s6, s6, 0x8000
	s_addc_u32 s7, s7, 0
	v_max_f32_e32 v108, 0, v212
	v_max_f32_e32 v109, 0, v213
	v_pk_mul_f32 v[0:1], v[22:23], v[108:109]
	v_max_f32_e32 v210, 0, v214
	v_max_f32_e32 v211, 0, v215
	v_pk_fma_f32 v[0:1], v[24:25], v[210:211], v[0:1]
	v_max_f32_e32 v108, 0, v216
	v_max_f32_e32 v109, 0, v217
	v_pk_fma_f32 v[0:1], v[26:27], v[108:109], v[0:1]
	v_mfma_f32_32x32x16_bf16 v[6:21], v[90:93], v[42:45], v[6:21]
	v_max_f32_e32 v210, 0, v218
	v_max_f32_e32 v211, 0, v219
	v_pk_fma_f32 v[0:1], v[28:29], v[210:211], v[0:1]
	v_max_f32_e32 v108, 0, v220
	v_max_f32_e32 v109, 0, v221
	v_pk_fma_f32 v[0:1], v[30:31], v[108:109], v[0:1]
	v_max_f32_e32 v210, 0, v222
	v_max_f32_e32 v211, 0, v223
	v_pk_fma_f32 v[0:1], v[32:33], v[210:211], v[0:1]
	v_mfma_f32_32x32x16_bf16 v[6:21], v[94:97], v[46:49], v[6:21]
	v_max_f32_e32 v108, 0, v224
	v_max_f32_e32 v109, 0, v225
	v_pk_fma_f32 v[0:1], v[34:35], v[108:109], v[0:1]
	v_max_f32_e32 v210, 0, v226
	v_max_f32_e32 v211, 0, v227
	v_pk_fma_f32 v[0:1], v[36:37], v[210:211], v[0:1]
	v_add_f32_e32 v0, v0, v1
	v_ashrrev_i32_e32 v1, 31, v0
	v_mfma_f32_32x32x16_bf16 v[6:21], v[98:101], v[196:199], v[6:21]
	s_waitcnt vmcnt(10)
	v_add_u32_e32 v228, 0x10000, v5
	ds_read_b128 v[38:41], v228 offset:10496
	v_add_u32_e32 v228, 0x10000, v52
	ds_read_b128 v[42:45], v228 offset:10496
	v_add_u32_e32 v228, 0x10000, v55
	ds_read_b128 v[46:49], v228 offset:10496
	v_add_u32_e32 v228, 0x10000, v56
	ds_read_b128 v[196:199], v228 offset:10496
	v_or_b32_e32 v1, 0x80000000, v1
	s_cmpk_gt_i32 s11, 296
	s_cselect_b64 vcc, -1, 0
	v_xor_b32_e32 v0, v1, v0
	v_cndmask_b32_e32 v169, v123, v0, vcc
	s_nop 3
	s_waitcnt lgkmcnt(3)
	v_mfma_f32_32x32x16_bf16 v[212:227], v[70:73], v[38:41], 0
	v_max_f32_e32 v108, 0, v6
	v_max_f32_e32 v109, 0, v7
	v_pk_mul_f32 v[50:51], v[244:245], v[108:109]
	v_max_f32_e32 v210, 0, v8
	v_max_f32_e32 v211, 0, v9
	v_pk_fma_f32 v[50:51], v[246:247], v[210:211], v[50:51]
	v_max_f32_e32 v108, 0, v10
	v_max_f32_e32 v109, 0, v11
	v_pk_fma_f32 v[50:51], v[248:249], v[108:109], v[50:51]
	s_waitcnt lgkmcnt(2)
	v_mfma_f32_32x32x16_bf16 v[212:227], v[74:77], v[42:45], v[212:227]
	v_max_f32_e32 v210, 0, v12
	v_max_f32_e32 v211, 0, v13
	v_pk_fma_f32 v[50:51], v[250:251], v[210:211], v[50:51]
	v_max_f32_e32 v108, 0, v14
	v_max_f32_e32 v109, 0, v15
	v_pk_fma_f32 v[50:51], v[252:253], v[108:109], v[50:51]
	v_max_f32_e32 v210, 0, v16
	v_max_f32_e32 v211, 0, v17
	v_pk_fma_f32 v[50:51], v[254:255], v[210:211], v[50:51]
	s_waitcnt lgkmcnt(1)
	v_mfma_f32_32x32x16_bf16 v[212:227], v[78:81], v[46:49], v[212:227]
	v_max_f32_e32 v108, 0, v18
	v_max_f32_e32 v109, 0, v19
	v_pk_fma_f32 v[50:51], v[200:201], v[108:109], v[50:51]
	v_max_f32_e32 v210, 0, v20
	v_max_f32_e32 v211, 0, v21
	v_pk_fma_f32 v[50:51], v[202:203], v[210:211], v[50:51]
	v_add_f32_e32 v50, v50, v51
	v_ashrrev_i32_e32 v51, 31, v50
	s_waitcnt lgkmcnt(0)
	v_mfma_f32_32x32x16_bf16 v[212:227], v[82:85], v[196:199], v[212:227]
	v_or_b32_e32 v51, 0x80000000, v51
	s_cmpk_gt_i32 s11, 296
	s_cselect_b64 vcc, -1, 0
	v_xor_b32_e32 v50, v51, v50
	v_cndmask_b32_e32 v50, v123, v50, vcc
	global_store_dword v243, v50, s[8:9] offset:2048
	s_add_u32 s8, s8, 0x1000
	s_addc_u32 s9, s9, 0
	v_mfma_f32_32x32x16_bf16 v[6:21], v[86:89], v[38:41], 0
	s_add_i32 m0, s10, 32768
	s_nop 0
	global_load_lds_dwordx4 v102, s[6:7]
	s_add_i32 m0, s10, 33792
	s_nop 0
	global_load_lds_dwordx4 v110, s[6:7]
	s_add_i32 m0, s10, 34816
	s_nop 0
	global_load_lds_dwordx4 v112, s[6:7]
	s_add_i32 m0, s10, 35840
	s_nop 0
	global_load_lds_dwordx4 v193, s[6:7]
	s_add_u32 s6, s6, 0x8000
	s_addc_u32 s7, s7, 0
	v_max_f32_e32 v108, 0, v212
	v_max_f32_e32 v109, 0, v213
	v_pk_mul_f32 v[0:1], v[22:23], v[108:109]
	v_max_f32_e32 v210, 0, v214
	v_max_f32_e32 v211, 0, v215
	v_pk_fma_f32 v[0:1], v[24:25], v[210:211], v[0:1]
	v_max_f32_e32 v108, 0, v216
	v_max_f32_e32 v109, 0, v217
	v_pk_fma_f32 v[0:1], v[26:27], v[108:109], v[0:1]
	v_mfma_f32_32x32x16_bf16 v[6:21], v[90:93], v[42:45], v[6:21]
	v_max_f32_e32 v210, 0, v218
	v_max_f32_e32 v211, 0, v219
	v_pk_fma_f32 v[0:1], v[28:29], v[210:211], v[0:1]
	v_max_f32_e32 v108, 0, v220
	v_max_f32_e32 v109, 0, v221
	v_pk_fma_f32 v[0:1], v[30:31], v[108:109], v[0:1]
	v_max_f32_e32 v210, 0, v222
	v_max_f32_e32 v211, 0, v223
	v_pk_fma_f32 v[0:1], v[32:33], v[210:211], v[0:1]
	v_mfma_f32_32x32x16_bf16 v[6:21], v[94:97], v[46:49], v[6:21]
	v_max_f32_e32 v108, 0, v224
	v_max_f32_e32 v109, 0, v225
	v_pk_fma_f32 v[0:1], v[34:35], v[108:109], v[0:1]
	v_max_f32_e32 v210, 0, v226
	v_max_f32_e32 v211, 0, v227
	v_pk_fma_f32 v[0:1], v[36:37], v[210:211], v[0:1]
	v_add_f32_e32 v0, v0, v1
	v_ashrrev_i32_e32 v1, 31, v0
	v_mfma_f32_32x32x16_bf16 v[6:21], v[98:101], v[196:199], v[6:21]
	s_waitcnt vmcnt(10)
	v_add_u32_e32 v228, 0x10000, v5
	ds_read_b128 v[38:41], v228 offset:43264
	v_add_u32_e32 v228, 0x10000, v52
	ds_read_b128 v[42:45], v228 offset:43264
	v_add_u32_e32 v228, 0x10000, v55
	ds_read_b128 v[46:49], v228 offset:43264
	v_add_u32_e32 v228, 0x10000, v56
	ds_read_b128 v[196:199], v228 offset:43264
	v_or_b32_e32 v1, 0x80000000, v1
	s_cmpk_gt_i32 s11, 304
	s_cselect_b64 vcc, -1, 0
	v_xor_b32_e32 v0, v1, v0
	v_cndmask_b32_e32 v172, v123, v0, vcc
	s_nop 3
	s_waitcnt lgkmcnt(3)
	v_mfma_f32_32x32x16_bf16 v[212:227], v[70:73], v[38:41], 0
	v_max_f32_e32 v108, 0, v6
	v_max_f32_e32 v109, 0, v7
	v_pk_mul_f32 v[50:51], v[244:245], v[108:109]
	v_max_f32_e32 v210, 0, v8
	v_max_f32_e32 v211, 0, v9
	v_pk_fma_f32 v[50:51], v[246:247], v[210:211], v[50:51]
	v_max_f32_e32 v108, 0, v10
	v_max_f32_e32 v109, 0, v11
	v_pk_fma_f32 v[50:51], v[248:249], v[108:109], v[50:51]
	s_waitcnt lgkmcnt(2)
	v_mfma_f32_32x32x16_bf16 v[212:227], v[74:77], v[42:45], v[212:227]
	v_max_f32_e32 v210, 0, v12
	v_max_f32_e32 v211, 0, v13
	v_pk_fma_f32 v[50:51], v[250:251], v[210:211], v[50:51]
	v_max_f32_e32 v108, 0, v14
	v_max_f32_e32 v109, 0, v15
	v_pk_fma_f32 v[50:51], v[252:253], v[108:109], v[50:51]
	v_max_f32_e32 v210, 0, v16
	v_max_f32_e32 v211, 0, v17
	v_pk_fma_f32 v[50:51], v[254:255], v[210:211], v[50:51]
	s_waitcnt lgkmcnt(1)
	v_mfma_f32_32x32x16_bf16 v[212:227], v[78:81], v[46:49], v[212:227]
	v_max_f32_e32 v108, 0, v18
	v_max_f32_e32 v109, 0, v19
	v_pk_fma_f32 v[50:51], v[200:201], v[108:109], v[50:51]
	v_max_f32_e32 v210, 0, v20
	v_max_f32_e32 v211, 0, v21
	v_pk_fma_f32 v[50:51], v[202:203], v[210:211], v[50:51]
	v_add_f32_e32 v50, v50, v51
	v_ashrrev_i32_e32 v51, 31, v50
	s_waitcnt lgkmcnt(0)
	v_mfma_f32_32x32x16_bf16 v[212:227], v[82:85], v[196:199], v[212:227]
	v_or_b32_e32 v51, 0x80000000, v51
	s_cmpk_gt_i32 s11, 304
	s_cselect_b64 vcc, -1, 0
	v_xor_b32_e32 v50, v51, v50
	v_cndmask_b32_e32 v50, v123, v50, vcc
	global_store_dword v243, v50, s[8:9]
	v_mfma_f32_32x32x16_bf16 v[6:21], v[86:89], v[38:41], 0
	s_add_i32 m0, s10, 65536
	s_nop 0
	global_load_lds_dwordx4 v102, s[6:7]
	s_add_i32 m0, s10, 66560
	s_nop 0
	global_load_lds_dwordx4 v110, s[6:7]
	s_add_i32 m0, s10, 67584
	s_nop 0
	global_load_lds_dwordx4 v112, s[6:7]
	s_add_i32 m0, s10, 68608
	s_nop 0
	global_load_lds_dwordx4 v193, s[6:7]
	s_add_u32 s6, s6, 0x8000
	s_addc_u32 s7, s7, 0
	v_max_f32_e32 v108, 0, v212
	v_max_f32_e32 v109, 0, v213
	v_pk_mul_f32 v[0:1], v[22:23], v[108:109]
	v_max_f32_e32 v210, 0, v214
	v_max_f32_e32 v211, 0, v215
	v_pk_fma_f32 v[0:1], v[24:25], v[210:211], v[0:1]
	v_max_f32_e32 v108, 0, v216
	v_max_f32_e32 v109, 0, v217
	v_pk_fma_f32 v[0:1], v[26:27], v[108:109], v[0:1]
	v_mfma_f32_32x32x16_bf16 v[6:21], v[90:93], v[42:45], v[6:21]
	v_max_f32_e32 v210, 0, v218
	v_max_f32_e32 v211, 0, v219
	v_pk_fma_f32 v[0:1], v[28:29], v[210:211], v[0:1]
	v_max_f32_e32 v108, 0, v220
	v_max_f32_e32 v109, 0, v221
	v_pk_fma_f32 v[0:1], v[30:31], v[108:109], v[0:1]
	v_max_f32_e32 v210, 0, v222
	v_max_f32_e32 v211, 0, v223
	v_pk_fma_f32 v[0:1], v[32:33], v[210:211], v[0:1]
	v_mfma_f32_32x32x16_bf16 v[6:21], v[94:97], v[46:49], v[6:21]
	v_max_f32_e32 v108, 0, v224
	v_max_f32_e32 v109, 0, v225
	v_pk_fma_f32 v[0:1], v[34:35], v[108:109], v[0:1]
	v_max_f32_e32 v210, 0, v226
	v_max_f32_e32 v211, 0, v227
	v_pk_fma_f32 v[0:1], v[36:37], v[210:211], v[0:1]
	v_add_f32_e32 v0, v0, v1
	v_ashrrev_i32_e32 v1, 31, v0
	v_mfma_f32_32x32x16_bf16 v[6:21], v[98:101], v[196:199], v[6:21]
	s_waitcnt vmcnt(10)
	ds_read_b128 v[38:41], v5 offset:10496
	ds_read_b128 v[42:45], v52 offset:10496
	ds_read_b128 v[46:49], v55 offset:10496
	ds_read_b128 v[196:199], v56 offset:10496
	v_or_b32_e32 v1, 0x80000000, v1
	s_cmpk_gt_i32 s11, 312
	s_cselect_b64 vcc, -1, 0
	v_xor_b32_e32 v0, v1, v0
	v_cndmask_b32_e32 v171, v123, v0, vcc
	s_nop 3
	v_max_f32_e32 v108, 0, v6
	v_max_f32_e32 v109, 0, v7
	v_pk_mul_f32 v[50:51], v[244:245], v[108:109]
	v_max_f32_e32 v210, 0, v8
	v_max_f32_e32 v211, 0, v9
	v_pk_fma_f32 v[50:51], v[246:247], v[210:211], v[50:51]
	v_max_f32_e32 v108, 0, v10
	v_max_f32_e32 v109, 0, v11
	v_pk_fma_f32 v[50:51], v[248:249], v[108:109], v[50:51]
	v_max_f32_e32 v210, 0, v12
	v_max_f32_e32 v211, 0, v13
	v_pk_fma_f32 v[50:51], v[250:251], v[210:211], v[50:51]
	v_max_f32_e32 v108, 0, v14
	v_max_f32_e32 v109, 0, v15
	v_pk_fma_f32 v[50:51], v[252:253], v[108:109], v[50:51]
	v_max_f32_e32 v210, 0, v16
	v_max_f32_e32 v211, 0, v17
	v_pk_fma_f32 v[50:51], v[254:255], v[210:211], v[50:51]
	v_max_f32_e32 v108, 0, v18
	v_max_f32_e32 v109, 0, v19
	v_pk_fma_f32 v[50:51], v[200:201], v[108:109], v[50:51]
	v_max_f32_e32 v210, 0, v20
	v_max_f32_e32 v211, 0, v21
	v_pk_fma_f32 v[50:51], v[202:203], v[210:211], v[50:51]
	v_add_f32_e32 v50, v50, v51
	v_ashrrev_i32_e32 v51, 31, v50
	v_or_b32_e32 v51, 0x80000000, v51
	s_cmpk_gt_i32 s11, 312
	s_cselect_b64 vcc, -1, 0
	v_xor_b32_e32 v50, v51, v50
	v_cndmask_b32_e32 v50, v123, v50, vcc
	global_store_dword v243, v50, s[8:9] offset:2048
	s_add_u32 s8, s8, 0x1000
	s_addc_u32 s9, s9, 0
	s_cmpk_gt_i32 s81, 40
	s_cbranch_scc0 .Lix_fill_5
	s_waitcnt lgkmcnt(3)
	v_mfma_f32_32x32x16_bf16 v[212:227], v[70:73], v[38:41], 0
	s_add_i32 m0, s10, 98304
	s_nop 0
	global_load_lds_dwordx4 v102, s[6:7]
	s_waitcnt lgkmcnt(2)
	v_mfma_f32_32x32x16_bf16 v[212:227], v[74:77], v[42:45], v[212:227]
	s_add_i32 m0, s10, 99328
	s_nop 0
	global_load_lds_dwordx4 v110, s[6:7]
	s_waitcnt lgkmcnt(1)
	v_mfma_f32_32x32x16_bf16 v[212:227], v[78:81], v[46:49], v[212:227]
	s_add_i32 m0, s10, 100352
	s_nop 0
	global_load_lds_dwordx4 v112, s[6:7]
	s_waitcnt lgkmcnt(0)
	v_mfma_f32_32x32x16_bf16 v[212:227], v[82:85], v[196:199], v[212:227]
	s_add_i32 m0, s10, 101376
	s_nop 0
	global_load_lds_dwordx4 v193, s[6:7]
	s_add_u32 s6, s6, 0x8000
	s_addc_u32 s7, s7, 0
	v_mfma_f32_32x32x16_bf16 v[6:21], v[86:89], v[38:41], 0
	s_nop 7
	s_nop 2
	v_max_f32_e32 v108, 0, v212
	v_max_f32_e32 v109, 0, v213
	v_pk_mul_f32 v[0:1], v[22:23], v[108:109]
	v_max_f32_e32 v210, 0, v214
	v_max_f32_e32 v211, 0, v215
	v_pk_fma_f32 v[0:1], v[24:25], v[210:211], v[0:1]
	v_max_f32_e32 v108, 0, v216
	v_max_f32_e32 v109, 0, v217
	v_pk_fma_f32 v[0:1], v[26:27], v[108:109], v[0:1]
	v_mfma_f32_32x32x16_bf16 v[6:21], v[90:93], v[42:45], v[6:21]
	v_max_f32_e32 v210, 0, v218
	v_max_f32_e32 v211, 0, v219
	v_pk_fma_f32 v[0:1], v[28:29], v[210:211], v[0:1]
	v_max_f32_e32 v108, 0, v220
	v_max_f32_e32 v109, 0, v221
	v_pk_fma_f32 v[0:1], v[30:31], v[108:109], v[0:1]
	v_max_f32_e32 v210, 0, v222
	v_max_f32_e32 v211, 0, v223
	v_pk_fma_f32 v[0:1], v[32:33], v[210:211], v[0:1]
	v_mfma_f32_32x32x16_bf16 v[6:21], v[94:97], v[46:49], v[6:21]
	v_max_f32_e32 v108, 0, v224
	v_max_f32_e32 v109, 0, v225
	v_pk_fma_f32 v[0:1], v[34:35], v[108:109], v[0:1]
	v_max_f32_e32 v210, 0, v226
	v_max_f32_e32 v211, 0, v227
	v_pk_fma_f32 v[0:1], v[36:37], v[210:211], v[0:1]
	v_add_f32_e32 v0, v0, v1
	v_ashrrev_i32_e32 v1, 31, v0
	v_mfma_f32_32x32x16_bf16 v[6:21], v[98:101], v[196:199], v[6:21]
	s_waitcnt vmcnt(10)
	ds_read_b128 v[38:41], v5 offset:43264
	ds_read_b128 v[42:45], v52 offset:43264
	ds_read_b128 v[46:49], v55 offset:43264
	ds_read_b128 v[196:199], v56 offset:43264
	v_or_b32_e32 v1, 0x80000000, v1
	s_cmpk_gt_i32 s11, 320
	s_cselect_b64 vcc, -1, 0
	v_xor_b32_e32 v0, v1, v0
	v_cndmask_b32_e32 v174, v123, v0, vcc
	s_nop 3
	s_waitcnt lgkmcnt(3)
	v_mfma_f32_32x32x16_bf16 v[212:227], v[70:73], v[38:41], 0
	v_max_f32_e32 v108, 0, v6
	v_max_f32_e32 v109, 0, v7
	v_pk_mul_f32 v[50:51], v[244:245], v[108:109]
	v_max_f32_e32 v210, 0, v8
	v_max_f32_e32 v211, 0, v9
	v_pk_fma_f32 v[50:51], v[246:247], v[210:211], v[50:51]
	v_max_f32_e32 v108, 0, v10
	v_max_f32_e32 v109, 0, v11
	v_pk_fma_f32 v[50:51], v[248:249], v[108:109], v[50:51]
	s_waitcnt lgkmcnt(2)
	v_mfma_f32_32x32x16_bf16 v[212:227], v[74:77], v[42:45], v[212:227]
	v_max_f32_e32 v210, 0, v12
	v_max_f32_e32 v211, 0, v13
	v_pk_fma_f32 v[50:51], v[250:251], v[210:211], v[50:51]
	v_max_f32_e32 v108, 0, v14
	v_max_f32_e32 v109, 0, v15
	v_pk_fma_f32 v[50:51], v[252:253], v[108:109], v[50:51]
	v_max_f32_e32 v210, 0, v16
	v_max_f32_e32 v211, 0, v17
	v_pk_fma_f32 v[50:51], v[254:255], v[210:211], v[50:51]
	s_waitcnt lgkmcnt(1)
	v_mfma_f32_32x32x16_bf16 v[212:227], v[78:81], v[46:49], v[212:227]
	v_max_f32_e32 v108, 0, v18
	v_max_f32_e32 v109, 0, v19
	v_pk_fma_f32 v[50:51], v[200:201], v[108:109], v[50:51]
	v_max_f32_e32 v210, 0, v20
	v_max_f32_e32 v211, 0, v21
	v_pk_fma_f32 v[50:51], v[202:203], v[210:211], v[50:51]
	v_add_f32_e32 v50, v50, v51
	v_ashrrev_i32_e32 v51, 31, v50
	s_waitcnt lgkmcnt(0)
	v_mfma_f32_32x32x16_bf16 v[212:227], v[82:85], v[196:199], v[212:227]
	v_or_b32_e32 v51, 0x80000000, v51
	s_cmpk_gt_i32 s11, 320
	s_cselect_b64 vcc, -1, 0
	v_xor_b32_e32 v50, v51, v50
	v_cndmask_b32_e32 v50, v123, v50, vcc
	global_store_dword v243, v50, s[8:9]
	v_mfma_f32_32x32x16_bf16 v[6:21], v[86:89], v[38:41], 0
	s_add_i32 m0, s10, 0
	s_nop 0
	global_load_lds_dwordx4 v102, s[6:7]
	s_add_i32 m0, s10, 1024
	s_nop 0
	global_load_lds_dwordx4 v110, s[6:7]
	s_add_i32 m0, s10, 2048
	s_nop 0
	global_load_lds_dwordx4 v112, s[6:7]
	s_add_i32 m0, s10, 3072
	s_nop 0
	global_load_lds_dwordx4 v193, s[6:7]
	s_add_u32 s6, s6, 0x8000
	s_addc_u32 s7, s7, 0
	v_max_f32_e32 v108, 0, v212
	v_max_f32_e32 v109, 0, v213
	v_pk_mul_f32 v[0:1], v[22:23], v[108:109]
	v_max_f32_e32 v210, 0, v214
	v_max_f32_e32 v211, 0, v215
	v_pk_fma_f32 v[0:1], v[24:25], v[210:211], v[0:1]
	v_max_f32_e32 v108, 0, v216
	v_max_f32_e32 v109, 0, v217
	v_pk_fma_f32 v[0:1], v[26:27], v[108:109], v[0:1]
	v_mfma_f32_32x32x16_bf16 v[6:21], v[90:93], v[42:45], v[6:21]
	v_max_f32_e32 v210, 0, v218
	v_max_f32_e32 v211, 0, v219
	v_pk_fma_f32 v[0:1], v[28:29], v[210:211], v[0:1]
	v_max_f32_e32 v108, 0, v220
	v_max_f32_e32 v109, 0, v221
	v_pk_fma_f32 v[0:1], v[30:31], v[108:109], v[0:1]
	v_max_f32_e32 v210, 0, v222
	v_max_f32_e32 v211, 0, v223
	v_pk_fma_f32 v[0:1], v[32:33], v[210:211], v[0:1]
	v_mfma_f32_32x32x16_bf16 v[6:21], v[94:97], v[46:49], v[6:21]
	v_max_f32_e32 v108, 0, v224
	v_max_f32_e32 v109, 0, v225
	v_pk_fma_f32 v[0:1], v[34:35], v[108:109], v[0:1]
	v_max_f32_e32 v210, 0, v226
	v_max_f32_e32 v211, 0, v227
	v_pk_fma_f32 v[0:1], v[36:37], v[210:211], v[0:1]
	v_add_f32_e32 v0, v0, v1
	v_ashrrev_i32_e32 v1, 31, v0
	v_mfma_f32_32x32x16_bf16 v[6:21], v[98:101], v[196:199], v[6:21]
	s_waitcnt vmcnt(10)
	v_add_u32_e32 v228, 0x10000, v5
	ds_read_b128 v[38:41], v228 offset:10496
	v_add_u32_e32 v228, 0x10000, v52
	ds_read_b128 v[42:45], v228 offset:10496
	v_add_u32_e32 v228, 0x10000, v55
	ds_read_b128 v[46:49], v228 offset:10496
	v_add_u32_e32 v228, 0x10000, v56
	ds_read_b128 v[196:199], v228 offset:10496
	v_or_b32_e32 v1, 0x80000000, v1
	s_cmpk_gt_i32 s11, 328
	s_cselect_b64 vcc, -1, 0
	v_xor_b32_e32 v0, v1, v0
	v_cndmask_b32_e32 v173, v123, v0, vcc
	s_nop 3
	s_waitcnt lgkmcnt(3)
	v_mfma_f32_32x32x16_bf16 v[212:227], v[70:73], v[38:41], 0
	v_max_f32_e32 v108, 0, v6
	v_max_f32_e32 v109, 0, v7
	v_pk_mul_f32 v[50:51], v[244:245], v[108:109]
	v_max_f32_e32 v210, 0, v8
	v_max_f32_e32 v211, 0, v9
	v_pk_fma_f32 v[50:51], v[246:247], v[210:211], v[50:51]
	v_max_f32_e32 v108, 0, v10
	v_max_f32_e32 v109, 0, v11
	v_pk_fma_f32 v[50:51], v[248:249], v[108:109], v[50:51]
	s_waitcnt lgkmcnt(2)
	v_mfma_f32_32x32x16_bf16 v[212:227], v[74:77], v[42:45], v[212:227]
	v_max_f32_e32 v210, 0, v12
	v_max_f32_e32 v211, 0, v13
	v_pk_fma_f32 v[50:51], v[250:251], v[210:211], v[50:51]
	v_max_f32_e32 v108, 0, v14
	v_max_f32_e32 v109, 0, v15
	v_pk_fma_f32 v[50:51], v[252:253], v[108:109], v[50:51]
	v_max_f32_e32 v210, 0, v16
	v_max_f32_e32 v211, 0, v17
	v_pk_fma_f32 v[50:51], v[254:255], v[210:211], v[50:51]
	s_waitcnt lgkmcnt(1)
	v_mfma_f32_32x32x16_bf16 v[212:227], v[78:81], v[46:49], v[212:227]
	v_max_f32_e32 v108, 0, v18
	v_max_f32_e32 v109, 0, v19
	v_pk_fma_f32 v[50:51], v[200:201], v[108:109], v[50:51]
	v_max_f32_e32 v210, 0, v20
	v_max_f32_e32 v211, 0, v21
	v_pk_fma_f32 v[50:51], v[202:203], v[210:211], v[50:51]
	v_add_f32_e32 v50, v50, v51
	v_ashrrev_i32_e32 v51, 31, v50
	s_waitcnt lgkmcnt(0)
	v_mfma_f32_32x32x16_bf16 v[212:227], v[82:85], v[196:199], v[212:227]
	v_or_b32_e32 v51, 0x80000000, v51
	s_cmpk_gt_i32 s11, 328
	s_cselect_b64 vcc, -1, 0
	v_xor_b32_e32 v50, v51, v50
	v_cndmask_b32_e32 v50, v123, v50, vcc
	global_store_dword v243, v50, s[8:9] offset:2048
	s_add_u32 s8, s8, 0x1000
	s_addc_u32 s9, s9, 0
	v_mfma_f32_32x32x16_bf16 v[6:21], v[86:89], v[38:41], 0
	s_add_i32 m0, s10, 32768
	s_nop 0
	global_load_lds_dwordx4 v102, s[6:7]
	s_add_i32 m0, s10, 33792
	s_nop 0
	global_load_lds_dwordx4 v110, s[6:7]
	s_add_i32 m0, s10, 34816
	s_nop 0
	global_load_lds_dwordx4 v112, s[6:7]
	s_add_i32 m0, s10, 35840
	s_nop 0
	global_load_lds_dwordx4 v193, s[6:7]
	s_add_u32 s6, s6, 0x8000
	s_addc_u32 s7, s7, 0
	v_max_f32_e32 v108, 0, v212
	v_max_f32_e32 v109, 0, v213
	v_pk_mul_f32 v[0:1], v[22:23], v[108:109]
	v_max_f32_e32 v210, 0, v214
	v_max_f32_e32 v211, 0, v215
	v_pk_fma_f32 v[0:1], v[24:25], v[210:211], v[0:1]
	v_max_f32_e32 v108, 0, v216
	v_max_f32_e32 v109, 0, v217
	v_pk_fma_f32 v[0:1], v[26:27], v[108:109], v[0:1]
	v_mfma_f32_32x32x16_bf16 v[6:21], v[90:93], v[42:45], v[6:21]
	v_max_f32_e32 v210, 0, v218
	v_max_f32_e32 v211, 0, v219
	v_pk_fma_f32 v[0:1], v[28:29], v[210:211], v[0:1]
	v_max_f32_e32 v108, 0, v220
	v_max_f32_e32 v109, 0, v221
	v_pk_fma_f32 v[0:1], v[30:31], v[108:109], v[0:1]
	v_max_f32_e32 v210, 0, v222
	v_max_f32_e32 v211, 0, v223
	v_pk_fma_f32 v[0:1], v[32:33], v[210:211], v[0:1]
	v_mfma_f32_32x32x16_bf16 v[6:21], v[94:97], v[46:49], v[6:21]
	v_max_f32_e32 v108, 0, v224
	v_max_f32_e32 v109, 0, v225
	v_pk_fma_f32 v[0:1], v[34:35], v[108:109], v[0:1]
	v_max_f32_e32 v210, 0, v226
	v_max_f32_e32 v211, 0, v227
	v_pk_fma_f32 v[0:1], v[36:37], v[210:211], v[0:1]
	v_add_f32_e32 v0, v0, v1
	v_ashrrev_i32_e32 v1, 31, v0
	v_mfma_f32_32x32x16_bf16 v[6:21], v[98:101], v[196:199], v[6:21]
	s_waitcnt vmcnt(10)
	v_add_u32_e32 v228, 0x10000, v5
	ds_read_b128 v[38:41], v228 offset:43264
	v_add_u32_e32 v228, 0x10000, v52
	ds_read_b128 v[42:45], v228 offset:43264
	v_add_u32_e32 v228, 0x10000, v55
	ds_read_b128 v[46:49], v228 offset:43264
	v_add_u32_e32 v228, 0x10000, v56
	ds_read_b128 v[196:199], v228 offset:43264
	v_or_b32_e32 v1, 0x80000000, v1
	s_cmpk_gt_i32 s11, 336
	s_cselect_b64 vcc, -1, 0
	v_xor_b32_e32 v0, v1, v0
	v_cndmask_b32_e32 v176, v123, v0, vcc
	s_nop 3
	s_waitcnt lgkmcnt(3)
	v_mfma_f32_32x32x16_bf16 v[212:227], v[70:73], v[38:41], 0
	v_max_f32_e32 v108, 0, v6
	v_max_f32_e32 v109, 0, v7
	v_pk_mul_f32 v[50:51], v[244:245], v[108:109]
	v_max_f32_e32 v210, 0, v8
	v_max_f32_e32 v211, 0, v9
	v_pk_fma_f32 v[50:51], v[246:247], v[210:211], v[50:51]
	v_max_f32_e32 v108, 0, v10
	v_max_f32_e32 v109, 0, v11
	v_pk_fma_f32 v[50:51], v[248:249], v[108:109], v[50:51]
	s_waitcnt lgkmcnt(2)
	v_mfma_f32_32x32x16_bf16 v[212:227], v[74:77], v[42:45], v[212:227]
	v_max_f32_e32 v210, 0, v12
	v_max_f32_e32 v211, 0, v13
	v_pk_fma_f32 v[50:51], v[250:251], v[210:211], v[50:51]
	v_max_f32_e32 v108, 0, v14
	v_max_f32_e32 v109, 0, v15
	v_pk_fma_f32 v[50:51], v[252:253], v[108:109], v[50:51]
	v_max_f32_e32 v210, 0, v16
	v_max_f32_e32 v211, 0, v17
	v_pk_fma_f32 v[50:51], v[254:255], v[210:211], v[50:51]
	s_waitcnt lgkmcnt(1)
	v_mfma_f32_32x32x16_bf16 v[212:227], v[78:81], v[46:49], v[212:227]
	v_max_f32_e32 v108, 0, v18
	v_max_f32_e32 v109, 0, v19
	v_pk_fma_f32 v[50:51], v[200:201], v[108:109], v[50:51]
	v_max_f32_e32 v210, 0, v20
	v_max_f32_e32 v211, 0, v21
	v_pk_fma_f32 v[50:51], v[202:203], v[210:211], v[50:51]
	v_add_f32_e32 v50, v50, v51
	v_ashrrev_i32_e32 v51, 31, v50
	s_waitcnt lgkmcnt(0)
	v_mfma_f32_32x32x16_bf16 v[212:227], v[82:85], v[196:199], v[212:227]
	v_or_b32_e32 v51, 0x80000000, v51
	s_cmpk_gt_i32 s11, 336
	s_cselect_b64 vcc, -1, 0
	v_xor_b32_e32 v50, v51, v50
	v_cndmask_b32_e32 v50, v123, v50, vcc
	global_store_dword v243, v50, s[8:9]
	v_mfma_f32_32x32x16_bf16 v[6:21], v[86:89], v[38:41], 0
	s_add_i32 m0, s10, 65536
	s_nop 0
	global_load_lds_dwordx4 v102, s[6:7]
	s_add_i32 m0, s10, 66560
	s_nop 0
	global_load_lds_dwordx4 v110, s[6:7]
	s_add_i32 m0, s10, 67584
	s_nop 0
	global_load_lds_dwordx4 v112, s[6:7]
	s_add_i32 m0, s10, 68608
	s_nop 0
	global_load_lds_dwordx4 v193, s[6:7]
	s_add_u32 s6, s6, 0x8000
	s_addc_u32 s7, s7, 0
	v_max_f32_e32 v108, 0, v212
	v_max_f32_e32 v109, 0, v213
	v_pk_mul_f32 v[0:1], v[22:23], v[108:109]
	v_max_f32_e32 v210, 0, v214
	v_max_f32_e32 v211, 0, v215
	v_pk_fma_f32 v[0:1], v[24:25], v[210:211], v[0:1]
	v_max_f32_e32 v108, 0, v216
	v_max_f32_e32 v109, 0, v217
	v_pk_fma_f32 v[0:1], v[26:27], v[108:109], v[0:1]
	v_mfma_f32_32x32x16_bf16 v[6:21], v[90:93], v[42:45], v[6:21]
	v_max_f32_e32 v210, 0, v218
	v_max_f32_e32 v211, 0, v219
	v_pk_fma_f32 v[0:1], v[28:29], v[210:211], v[0:1]
	v_max_f32_e32 v108, 0, v220
	v_max_f32_e32 v109, 0, v221
	v_pk_fma_f32 v[0:1], v[30:31], v[108:109], v[0:1]
	v_max_f32_e32 v210, 0, v222
	v_max_f32_e32 v211, 0, v223
	v_pk_fma_f32 v[0:1], v[32:33], v[210:211], v[0:1]
	v_mfma_f32_32x32x16_bf16 v[6:21], v[94:97], v[46:49], v[6:21]
	v_max_f32_e32 v108, 0, v224
	v_max_f32_e32 v109, 0, v225
	v_pk_fma_f32 v[0:1], v[34:35], v[108:109], v[0:1]
	v_max_f32_e32 v210, 0, v226
	v_max_f32_e32 v211, 0, v227
	v_pk_fma_f32 v[0:1], v[36:37], v[210:211], v[0:1]
	v_add_f32_e32 v0, v0, v1
	v_ashrrev_i32_e32 v1, 31, v0
	v_mfma_f32_32x32x16_bf16 v[6:21], v[98:101], v[196:199], v[6:21]
	s_waitcnt vmcnt(10)
	ds_read_b128 v[38:41], v5 offset:10496
	ds_read_b128 v[42:45], v52 offset:10496
	ds_read_b128 v[46:49], v55 offset:10496
	ds_read_b128 v[196:199], v56 offset:10496
	v_or_b32_e32 v1, 0x80000000, v1
	s_cmpk_gt_i32 s11, 344
	s_cselect_b64 vcc, -1, 0
	v_xor_b32_e32 v0, v1, v0
	v_cndmask_b32_e32 v175, v123, v0, vcc
	s_nop 3
	s_waitcnt lgkmcnt(3)
	v_mfma_f32_32x32x16_bf16 v[212:227], v[70:73], v[38:41], 0
	v_max_f32_e32 v108, 0, v6
	v_max_f32_e32 v109, 0, v7
	v_pk_mul_f32 v[50:51], v[244:245], v[108:109]
	v_max_f32_e32 v210, 0, v8
	v_max_f32_e32 v211, 0, v9
	v_pk_fma_f32 v[50:51], v[246:247], v[210:211], v[50:51]
	v_max_f32_e32 v108, 0, v10
	v_max_f32_e32 v109, 0, v11
	v_pk_fma_f32 v[50:51], v[248:249], v[108:109], v[50:51]
	s_waitcnt lgkmcnt(2)
	v_mfma_f32_32x32x16_bf16 v[212:227], v[74:77], v[42:45], v[212:227]
	v_max_f32_e32 v210, 0, v12
	v_max_f32_e32 v211, 0, v13
	v_pk_fma_f32 v[50:51], v[250:251], v[210:211], v[50:51]
	v_max_f32_e32 v108, 0, v14
	v_max_f32_e32 v109, 0, v15
	v_pk_fma_f32 v[50:51], v[252:253], v[108:109], v[50:51]
	v_max_f32_e32 v210, 0, v16
	v_max_f32_e32 v211, 0, v17
	v_pk_fma_f32 v[50:51], v[254:255], v[210:211], v[50:51]
	s_waitcnt lgkmcnt(1)
	v_mfma_f32_32x32x16_bf16 v[212:227], v[78:81], v[46:49], v[212:227]
	v_max_f32_e32 v108, 0, v18
	v_max_f32_e32 v109, 0, v19
	v_pk_fma_f32 v[50:51], v[200:201], v[108:109], v[50:51]
	v_max_f32_e32 v210, 0, v20
	v_max_f32_e32 v211, 0, v21
	v_pk_fma_f32 v[50:51], v[202:203], v[210:211], v[50:51]
	v_add_f32_e32 v50, v50, v51
	v_ashrrev_i32_e32 v51, 31, v50
	s_waitcnt lgkmcnt(0)
	v_mfma_f32_32x32x16_bf16 v[212:227], v[82:85], v[196:199], v[212:227]
	v_or_b32_e32 v51, 0x80000000, v51
	s_cmpk_gt_i32 s11, 344
	s_cselect_b64 vcc, -1, 0
	v_xor_b32_e32 v50, v51, v50
	v_cndmask_b32_e32 v50, v123, v50, vcc
	global_store_dword v243, v50, s[8:9] offset:2048
	s_add_u32 s8, s8, 0x1000
	s_addc_u32 s9, s9, 0
	v_mfma_f32_32x32x16_bf16 v[6:21], v[86:89], v[38:41], 0
	s_add_i32 m0, s10, 98304
	s_nop 0
	global_load_lds_dwordx4 v102, s[6:7]
	s_add_i32 m0, s10, 99328
	s_nop 0
	global_load_lds_dwordx4 v110, s[6:7]
	s_add_i32 m0, s10, 100352
	s_nop 0
	global_load_lds_dwordx4 v112, s[6:7]
	s_add_i32 m0, s10, 101376
	s_nop 0
	global_load_lds_dwordx4 v193, s[6:7]
	s_add_u32 s6, s6, 0x8000
	s_addc_u32 s7, s7, 0
	v_max_f32_e32 v108, 0, v212
	v_max_f32_e32 v109, 0, v213
	v_pk_mul_f32 v[0:1], v[22:23], v[108:109]
	v_max_f32_e32 v210, 0, v214
	v_max_f32_e32 v211, 0, v215
	v_pk_fma_f32 v[0:1], v[24:25], v[210:211], v[0:1]
	v_max_f32_e32 v108, 0, v216
	v_max_f32_e32 v109, 0, v217
	v_pk_fma_f32 v[0:1], v[26:27], v[108:109], v[0:1]
	v_mfma_f32_32x32x16_bf16 v[6:21], v[90:93], v[42:45], v[6:21]
	v_max_f32_e32 v210, 0, v218
	v_max_f32_e32 v211, 0, v219
	v_pk_fma_f32 v[0:1], v[28:29], v[210:211], v[0:1]
	v_max_f32_e32 v108, 0, v220
	v_max_f32_e32 v109, 0, v221
	v_pk_fma_f32 v[0:1], v[30:31], v[108:109], v[0:1]
	v_max_f32_e32 v210, 0, v222
	v_max_f32_e32 v211, 0, v223
	v_pk_fma_f32 v[0:1], v[32:33], v[210:211], v[0:1]
	v_mfma_f32_32x32x16_bf16 v[6:21], v[94:97], v[46:49], v[6:21]
	v_max_f32_e32 v108, 0, v224
	v_max_f32_e32 v109, 0, v225
	v_pk_fma_f32 v[0:1], v[34:35], v[108:109], v[0:1]
	v_max_f32_e32 v210, 0, v226
	v_max_f32_e32 v211, 0, v227
	v_pk_fma_f32 v[0:1], v[36:37], v[210:211], v[0:1]
	v_add_f32_e32 v0, v0, v1
	v_ashrrev_i32_e32 v1, 31, v0
	v_mfma_f32_32x32x16_bf16 v[6:21], v[98:101], v[196:199], v[6:21]
	s_waitcnt vmcnt(10)
	ds_read_b128 v[38:41], v5 offset:43264
	ds_read_b128 v[42:45], v52 offset:43264
	ds_read_b128 v[46:49], v55 offset:43264
	ds_read_b128 v[196:199], v56 offset:43264
	v_or_b32_e32 v1, 0x80000000, v1
	s_cmpk_gt_i32 s11, 352
	s_cselect_b64 vcc, -1, 0
	v_xor_b32_e32 v0, v1, v0
	v_cndmask_b32_e32 v178, v123, v0, vcc
	s_nop 3
	s_waitcnt lgkmcnt(3)
	v_mfma_f32_32x32x16_bf16 v[212:227], v[70:73], v[38:41], 0
	v_max_f32_e32 v108, 0, v6
	v_max_f32_e32 v109, 0, v7
	v_pk_mul_f32 v[50:51], v[244:245], v[108:109]
	v_max_f32_e32 v210, 0, v8
	v_max_f32_e32 v211, 0, v9
	v_pk_fma_f32 v[50:51], v[246:247], v[210:211], v[50:51]
	v_max_f32_e32 v108, 0, v10
	v_max_f32_e32 v109, 0, v11
	v_pk_fma_f32 v[50:51], v[248:249], v[108:109], v[50:51]
	s_waitcnt lgkmcnt(2)
	v_mfma_f32_32x32x16_bf16 v[212:227], v[74:77], v[42:45], v[212:227]
	v_max_f32_e32 v210, 0, v12
	v_max_f32_e32 v211, 0, v13
	v_pk_fma_f32 v[50:51], v[250:251], v[210:211], v[50:51]
	v_max_f32_e32 v108, 0, v14
	v_max_f32_e32 v109, 0, v15
	v_pk_fma_f32 v[50:51], v[252:253], v[108:109], v[50:51]
	v_max_f32_e32 v210, 0, v16
	v_max_f32_e32 v211, 0, v17
	v_pk_fma_f32 v[50:51], v[254:255], v[210:211], v[50:51]
	s_waitcnt lgkmcnt(1)
	v_mfma_f32_32x32x16_bf16 v[212:227], v[78:81], v[46:49], v[212:227]
	v_max_f32_e32 v108, 0, v18
	v_max_f32_e32 v109, 0, v19
	v_pk_fma_f32 v[50:51], v[200:201], v[108:109], v[50:51]
	v_max_f32_e32 v210, 0, v20
	v_max_f32_e32 v211, 0, v21
	v_pk_fma_f32 v[50:51], v[202:203], v[210:211], v[50:51]
	v_add_f32_e32 v50, v50, v51
	v_ashrrev_i32_e32 v51, 31, v50
	s_waitcnt lgkmcnt(0)
	v_mfma_f32_32x32x16_bf16 v[212:227], v[82:85], v[196:199], v[212:227]
	v_or_b32_e32 v51, 0x80000000, v51
	s_cmpk_gt_i32 s11, 352
	s_cselect_b64 vcc, -1, 0
	v_xor_b32_e32 v50, v51, v50
	v_cndmask_b32_e32 v50, v123, v50, vcc
	global_store_dword v243, v50, s[8:9]
	v_mfma_f32_32x32x16_bf16 v[6:21], v[86:89], v[38:41], 0
	s_add_i32 m0, s10, 0
	s_nop 0
	global_load_lds_dwordx4 v102, s[6:7]
	s_add_i32 m0, s10, 1024
	s_nop 0
	global_load_lds_dwordx4 v110, s[6:7]
	s_add_i32 m0, s10, 2048
	s_nop 0
	global_load_lds_dwordx4 v112, s[6:7]
	s_add_i32 m0, s10, 3072
	s_nop 0
	global_load_lds_dwordx4 v193, s[6:7]
	s_add_u32 s6, s6, 0x8000
	s_addc_u32 s7, s7, 0
	v_max_f32_e32 v108, 0, v212
	v_max_f32_e32 v109, 0, v213
	v_pk_mul_f32 v[0:1], v[22:23], v[108:109]
	v_max_f32_e32 v210, 0, v214
	v_max_f32_e32 v211, 0, v215
	v_pk_fma_f32 v[0:1], v[24:25], v[210:211], v[0:1]
	v_max_f32_e32 v108, 0, v216
	v_max_f32_e32 v109, 0, v217
	v_pk_fma_f32 v[0:1], v[26:27], v[108:109], v[0:1]
	v_mfma_f32_32x32x16_bf16 v[6:21], v[90:93], v[42:45], v[6:21]
	v_max_f32_e32 v210, 0, v218
	v_max_f32_e32 v211, 0, v219
	v_pk_fma_f32 v[0:1], v[28:29], v[210:211], v[0:1]
	v_max_f32_e32 v108, 0, v220
	v_max_f32_e32 v109, 0, v221
	v_pk_fma_f32 v[0:1], v[30:31], v[108:109], v[0:1]
	v_max_f32_e32 v210, 0, v222
	v_max_f32_e32 v211, 0, v223
	v_pk_fma_f32 v[0:1], v[32:33], v[210:211], v[0:1]
	v_mfma_f32_32x32x16_bf16 v[6:21], v[94:97], v[46:49], v[6:21]
	v_max_f32_e32 v108, 0, v224
	v_max_f32_e32 v109, 0, v225
	v_pk_fma_f32 v[0:1], v[34:35], v[108:109], v[0:1]
	v_max_f32_e32 v210, 0, v226
	v_max_f32_e32 v211, 0, v227
	v_pk_fma_f32 v[0:1], v[36:37], v[210:211], v[0:1]
	v_add_f32_e32 v0, v0, v1
	v_ashrrev_i32_e32 v1, 31, v0
	v_mfma_f32_32x32x16_bf16 v[6:21], v[98:101], v[196:199], v[6:21]
	s_waitcnt vmcnt(10)
	v_add_u32_e32 v228, 0x10000, v5
	ds_read_b128 v[38:41], v228 offset:10496
	v_add_u32_e32 v228, 0x10000, v52
	ds_read_b128 v[42:45], v228 offset:10496
	v_add_u32_e32 v228, 0x10000, v55
	ds_read_b128 v[46:49], v228 offset:10496
	v_add_u32_e32 v228, 0x10000, v56
	ds_read_b128 v[196:199], v228 offset:10496
	v_or_b32_e32 v1, 0x80000000, v1
	s_cmpk_gt_i32 s11, 360
	s_cselect_b64 vcc, -1, 0
	v_xor_b32_e32 v0, v1, v0
	v_cndmask_b32_e32 v177, v123, v0, vcc
	s_nop 3
	s_waitcnt lgkmcnt(3)
	v_mfma_f32_32x32x16_bf16 v[212:227], v[70:73], v[38:41], 0
	v_max_f32_e32 v108, 0, v6
	v_max_f32_e32 v109, 0, v7
	v_pk_mul_f32 v[50:51], v[244:245], v[108:109]
	v_max_f32_e32 v210, 0, v8
	v_max_f32_e32 v211, 0, v9
	v_pk_fma_f32 v[50:51], v[246:247], v[210:211], v[50:51]
	v_max_f32_e32 v108, 0, v10
	v_max_f32_e32 v109, 0, v11
	v_pk_fma_f32 v[50:51], v[248:249], v[108:109], v[50:51]
	s_waitcnt lgkmcnt(2)
	v_mfma_f32_32x32x16_bf16 v[212:227], v[74:77], v[42:45], v[212:227]
	v_max_f32_e32 v210, 0, v12
	v_max_f32_e32 v211, 0, v13
	v_pk_fma_f32 v[50:51], v[250:251], v[210:211], v[50:51]
	v_max_f32_e32 v108, 0, v14
	v_max_f32_e32 v109, 0, v15
	v_pk_fma_f32 v[50:51], v[252:253], v[108:109], v[50:51]
	v_max_f32_e32 v210, 0, v16
	v_max_f32_e32 v211, 0, v17
	v_pk_fma_f32 v[50:51], v[254:255], v[210:211], v[50:51]
	s_waitcnt lgkmcnt(1)
	v_mfma_f32_32x32x16_bf16 v[212:227], v[78:81], v[46:49], v[212:227]
	v_max_f32_e32 v108, 0, v18
	v_max_f32_e32 v109, 0, v19
	v_pk_fma_f32 v[50:51], v[200:201], v[108:109], v[50:51]
	v_max_f32_e32 v210, 0, v20
	v_max_f32_e32 v211, 0, v21
	v_pk_fma_f32 v[50:51], v[202:203], v[210:211], v[50:51]
	v_add_f32_e32 v50, v50, v51
	v_ashrrev_i32_e32 v51, 31, v50
	s_waitcnt lgkmcnt(0)
	v_mfma_f32_32x32x16_bf16 v[212:227], v[82:85], v[196:199], v[212:227]
	v_or_b32_e32 v51, 0x80000000, v51
	s_cmpk_gt_i32 s11, 360
	s_cselect_b64 vcc, -1, 0
	v_xor_b32_e32 v50, v51, v50
	v_cndmask_b32_e32 v50, v123, v50, vcc
	global_store_dword v243, v50, s[8:9] offset:2048
	s_add_u32 s8, s8, 0x1000
	s_addc_u32 s9, s9, 0
	v_mfma_f32_32x32x16_bf16 v[6:21], v[86:89], v[38:41], 0
	s_add_i32 m0, s10, 32768
	s_nop 0
	global_load_lds_dwordx4 v102, s[6:7]
	s_add_i32 m0, s10, 33792
	s_nop 0
	global_load_lds_dwordx4 v110, s[6:7]
	s_add_i32 m0, s10, 34816
	s_nop 0
	global_load_lds_dwordx4 v112, s[6:7]
	s_add_i32 m0, s10, 35840
	s_nop 0
	global_load_lds_dwordx4 v193, s[6:7]
	s_add_u32 s6, s6, 0x8000
	s_addc_u32 s7, s7, 0
	v_max_f32_e32 v108, 0, v212
	v_max_f32_e32 v109, 0, v213
	v_pk_mul_f32 v[0:1], v[22:23], v[108:109]
	v_max_f32_e32 v210, 0, v214
	v_max_f32_e32 v211, 0, v215
	v_pk_fma_f32 v[0:1], v[24:25], v[210:211], v[0:1]
	v_max_f32_e32 v108, 0, v216
	v_max_f32_e32 v109, 0, v217
	v_pk_fma_f32 v[0:1], v[26:27], v[108:109], v[0:1]
	v_mfma_f32_32x32x16_bf16 v[6:21], v[90:93], v[42:45], v[6:21]
	v_max_f32_e32 v210, 0, v218
	v_max_f32_e32 v211, 0, v219
	v_pk_fma_f32 v[0:1], v[28:29], v[210:211], v[0:1]
	v_max_f32_e32 v108, 0, v220
	v_max_f32_e32 v109, 0, v221
	v_pk_fma_f32 v[0:1], v[30:31], v[108:109], v[0:1]
	v_max_f32_e32 v210, 0, v222
	v_max_f32_e32 v211, 0, v223
	v_pk_fma_f32 v[0:1], v[32:33], v[210:211], v[0:1]
	v_mfma_f32_32x32x16_bf16 v[6:21], v[94:97], v[46:49], v[6:21]
	v_max_f32_e32 v108, 0, v224
	v_max_f32_e32 v109, 0, v225
	v_pk_fma_f32 v[0:1], v[34:35], v[108:109], v[0:1]
	v_max_f32_e32 v210, 0, v226
	v_max_f32_e32 v211, 0, v227
	v_pk_fma_f32 v[0:1], v[36:37], v[210:211], v[0:1]
	v_add_f32_e32 v0, v0, v1
	v_ashrrev_i32_e32 v1, 31, v0
	v_mfma_f32_32x32x16_bf16 v[6:21], v[98:101], v[196:199], v[6:21]
	s_waitcnt vmcnt(10)
	v_add_u32_e32 v228, 0x10000, v5
	ds_read_b128 v[38:41], v228 offset:43264
	v_add_u32_e32 v228, 0x10000, v52
	ds_read_b128 v[42:45], v228 offset:43264
	v_add_u32_e32 v228, 0x10000, v55
	ds_read_b128 v[46:49], v228 offset:43264
	v_add_u32_e32 v228, 0x10000, v56
	ds_read_b128 v[196:199], v228 offset:43264
	v_or_b32_e32 v1, 0x80000000, v1
	s_cmpk_gt_i32 s11, 368
	s_cselect_b64 vcc, -1, 0
	v_xor_b32_e32 v0, v1, v0
	v_cndmask_b32_e32 v179, v123, v0, vcc
	s_nop 3
	s_waitcnt lgkmcnt(3)
	v_mfma_f32_32x32x16_bf16 v[212:227], v[70:73], v[38:41], 0
	v_max_f32_e32 v108, 0, v6
	v_max_f32_e32 v109, 0, v7
	v_pk_mul_f32 v[50:51], v[244:245], v[108:109]
	v_max_f32_e32 v210, 0, v8
	v_max_f32_e32 v211, 0, v9
	v_pk_fma_f32 v[50:51], v[246:247], v[210:211], v[50:51]
	v_max_f32_e32 v108, 0, v10
	v_max_f32_e32 v109, 0, v11
	v_pk_fma_f32 v[50:51], v[248:249], v[108:109], v[50:51]
	s_waitcnt lgkmcnt(2)
	v_mfma_f32_32x32x16_bf16 v[212:227], v[74:77], v[42:45], v[212:227]
	v_max_f32_e32 v210, 0, v12
	v_max_f32_e32 v211, 0, v13
	v_pk_fma_f32 v[50:51], v[250:251], v[210:211], v[50:51]
	v_max_f32_e32 v108, 0, v14
	v_max_f32_e32 v109, 0, v15
	v_pk_fma_f32 v[50:51], v[252:253], v[108:109], v[50:51]
	v_max_f32_e32 v210, 0, v16
	v_max_f32_e32 v211, 0, v17
	v_pk_fma_f32 v[50:51], v[254:255], v[210:211], v[50:51]
	s_waitcnt lgkmcnt(1)
	v_mfma_f32_32x32x16_bf16 v[212:227], v[78:81], v[46:49], v[212:227]
	v_max_f32_e32 v108, 0, v18
	v_max_f32_e32 v109, 0, v19
	v_pk_fma_f32 v[50:51], v[200:201], v[108:109], v[50:51]
	v_max_f32_e32 v210, 0, v20
	v_max_f32_e32 v211, 0, v21
	v_pk_fma_f32 v[50:51], v[202:203], v[210:211], v[50:51]
	v_add_f32_e32 v50, v50, v51
	v_ashrrev_i32_e32 v51, 31, v50
	s_waitcnt lgkmcnt(0)
	v_mfma_f32_32x32x16_bf16 v[212:227], v[82:85], v[196:199], v[212:227]
	v_or_b32_e32 v51, 0x80000000, v51
	s_cmpk_gt_i32 s11, 368
	s_cselect_b64 vcc, -1, 0
	v_xor_b32_e32 v50, v51, v50
	v_cndmask_b32_e32 v50, v123, v50, vcc
	global_store_dword v243, v50, s[8:9]
	v_mfma_f32_32x32x16_bf16 v[6:21], v[86:89], v[38:41], 0
	s_add_i32 m0, s10, 65536
	s_nop 0
	global_load_lds_dwordx4 v102, s[6:7]
	s_add_i32 m0, s10, 66560
	s_nop 0
	global_load_lds_dwordx4 v110, s[6:7]
	s_add_i32 m0, s10, 67584
	s_nop 0
	global_load_lds_dwordx4 v112, s[6:7]
	s_add_i32 m0, s10, 68608
	s_nop 0
	global_load_lds_dwordx4 v193, s[6:7]
	s_add_u32 s6, s6, 0x8000
	s_addc_u32 s7, s7, 0
	v_max_f32_e32 v108, 0, v212
	v_max_f32_e32 v109, 0, v213
	v_pk_mul_f32 v[0:1], v[22:23], v[108:109]
	v_max_f32_e32 v210, 0, v214
	v_max_f32_e32 v211, 0, v215
	v_pk_fma_f32 v[0:1], v[24:25], v[210:211], v[0:1]
	v_max_f32_e32 v108, 0, v216
	v_max_f32_e32 v109, 0, v217
	v_pk_fma_f32 v[0:1], v[26:27], v[108:109], v[0:1]
	v_mfma_f32_32x32x16_bf16 v[6:21], v[90:93], v[42:45], v[6:21]
	v_max_f32_e32 v210, 0, v218
	v_max_f32_e32 v211, 0, v219
	v_pk_fma_f32 v[0:1], v[28:29], v[210:211], v[0:1]
	v_max_f32_e32 v108, 0, v220
	v_max_f32_e32 v109, 0, v221
	v_pk_fma_f32 v[0:1], v[30:31], v[108:109], v[0:1]
	v_max_f32_e32 v210, 0, v222
	v_max_f32_e32 v211, 0, v223
	v_pk_fma_f32 v[0:1], v[32:33], v[210:211], v[0:1]
	v_mfma_f32_32x32x16_bf16 v[6:21], v[94:97], v[46:49], v[6:21]
	v_max_f32_e32 v108, 0, v224
	v_max_f32_e32 v109, 0, v225
	v_pk_fma_f32 v[0:1], v[34:35], v[108:109], v[0:1]
	v_max_f32_e32 v210, 0, v226
	v_max_f32_e32 v211, 0, v227
	v_pk_fma_f32 v[0:1], v[36:37], v[210:211], v[0:1]
	v_add_f32_e32 v0, v0, v1
	v_ashrrev_i32_e32 v1, 31, v0
	v_mfma_f32_32x32x16_bf16 v[6:21], v[98:101], v[196:199], v[6:21]
	s_waitcnt vmcnt(10)
	ds_read_b128 v[38:41], v5 offset:10496
	ds_read_b128 v[42:45], v52 offset:10496
	ds_read_b128 v[46:49], v55 offset:10496
	ds_read_b128 v[196:199], v56 offset:10496
	v_or_b32_e32 v1, 0x80000000, v1
	s_cmpk_gt_i32 s11, 376
	s_cselect_b64 vcc, -1, 0
	v_xor_b32_e32 v0, v1, v0
	v_cndmask_b32_e32 v168, v123, v0, vcc
	s_nop 3
	v_max_f32_e32 v108, 0, v6
	v_max_f32_e32 v109, 0, v7
	v_pk_mul_f32 v[50:51], v[244:245], v[108:109]
	v_max_f32_e32 v210, 0, v8
	v_max_f32_e32 v211, 0, v9
	v_pk_fma_f32 v[50:51], v[246:247], v[210:211], v[50:51]
	v_max_f32_e32 v108, 0, v10
	v_max_f32_e32 v109, 0, v11
	v_pk_fma_f32 v[50:51], v[248:249], v[108:109], v[50:51]
	v_max_f32_e32 v210, 0, v12
	v_max_f32_e32 v211, 0, v13
	v_pk_fma_f32 v[50:51], v[250:251], v[210:211], v[50:51]
	v_max_f32_e32 v108, 0, v14
	v_max_f32_e32 v109, 0, v15
	v_pk_fma_f32 v[50:51], v[252:253], v[108:109], v[50:51]
	v_max_f32_e32 v210, 0, v16
	v_max_f32_e32 v211, 0, v17
	v_pk_fma_f32 v[50:51], v[254:255], v[210:211], v[50:51]
	v_max_f32_e32 v108, 0, v18
	v_max_f32_e32 v109, 0, v19
	v_pk_fma_f32 v[50:51], v[200:201], v[108:109], v[50:51]
	v_max_f32_e32 v210, 0, v20
	v_max_f32_e32 v211, 0, v21
	v_pk_fma_f32 v[50:51], v[202:203], v[210:211], v[50:51]
	v_add_f32_e32 v50, v50, v51
	v_ashrrev_i32_e32 v51, 31, v50
	v_or_b32_e32 v51, 0x80000000, v51
	s_cmpk_gt_i32 s11, 376
	s_cselect_b64 vcc, -1, 0
	v_xor_b32_e32 v50, v51, v50
	v_cndmask_b32_e32 v50, v123, v50, vcc
	global_store_dword v243, v50, s[8:9] offset:2048
	s_add_u32 s8, s8, 0x1000
	s_addc_u32 s9, s9, 0
	s_cmpk_gt_i32 s81, 48
	s_cbranch_scc0 .Lix_fill_6
	s_waitcnt lgkmcnt(3)
	v_mfma_f32_32x32x16_bf16 v[212:227], v[70:73], v[38:41], 0
	s_add_i32 m0, s10, 98304
	s_nop 0
	global_load_lds_dwordx4 v102, s[6:7]
	s_waitcnt lgkmcnt(2)
	v_mfma_f32_32x32x16_bf16 v[212:227], v[74:77], v[42:45], v[212:227]
	s_add_i32 m0, s10, 99328
	s_nop 0
	global_load_lds_dwordx4 v110, s[6:7]
	s_waitcnt lgkmcnt(1)
	v_mfma_f32_32x32x16_bf16 v[212:227], v[78:81], v[46:49], v[212:227]
	s_add_i32 m0, s10, 100352
	s_nop 0
	global_load_lds_dwordx4 v112, s[6:7]
	s_waitcnt lgkmcnt(0)
	v_mfma_f32_32x32x16_bf16 v[212:227], v[82:85], v[196:199], v[212:227]
	s_add_i32 m0, s10, 101376
	s_nop 0
	global_load_lds_dwordx4 v193, s[6:7]
	s_add_u32 s6, s6, 0x8000
	s_addc_u32 s7, s7, 0
	v_mfma_f32_32x32x16_bf16 v[6:21], v[86:89], v[38:41], 0
	s_nop 7
	s_nop 2
	v_max_f32_e32 v108, 0, v212
	v_max_f32_e32 v109, 0, v213
	v_pk_mul_f32 v[0:1], v[22:23], v[108:109]
	v_max_f32_e32 v210, 0, v214
	v_max_f32_e32 v211, 0, v215
	v_pk_fma_f32 v[0:1], v[24:25], v[210:211], v[0:1]
	v_max_f32_e32 v108, 0, v216
	v_max_f32_e32 v109, 0, v217
	v_pk_fma_f32 v[0:1], v[26:27], v[108:109], v[0:1]
	v_mfma_f32_32x32x16_bf16 v[6:21], v[90:93], v[42:45], v[6:21]
	v_max_f32_e32 v210, 0, v218
	v_max_f32_e32 v211, 0, v219
	v_pk_fma_f32 v[0:1], v[28:29], v[210:211], v[0:1]
	v_max_f32_e32 v108, 0, v220
	v_max_f32_e32 v109, 0, v221
	v_pk_fma_f32 v[0:1], v[30:31], v[108:109], v[0:1]
	v_max_f32_e32 v210, 0, v222
	v_max_f32_e32 v211, 0, v223
	v_pk_fma_f32 v[0:1], v[32:33], v[210:211], v[0:1]
	v_mfma_f32_32x32x16_bf16 v[6:21], v[94:97], v[46:49], v[6:21]
	v_max_f32_e32 v108, 0, v224
	v_max_f32_e32 v109, 0, v225
	v_pk_fma_f32 v[0:1], v[34:35], v[108:109], v[0:1]
	v_max_f32_e32 v210, 0, v226
	v_max_f32_e32 v211, 0, v227
	v_pk_fma_f32 v[0:1], v[36:37], v[210:211], v[0:1]
	v_add_f32_e32 v0, v0, v1
	v_ashrrev_i32_e32 v1, 31, v0
	v_mfma_f32_32x32x16_bf16 v[6:21], v[98:101], v[196:199], v[6:21]
	s_waitcnt vmcnt(10)
	ds_read_b128 v[38:41], v5 offset:43264
	ds_read_b128 v[42:45], v52 offset:43264
	ds_read_b128 v[46:49], v55 offset:43264
	ds_read_b128 v[196:199], v56 offset:43264
	v_or_b32_e32 v1, 0x80000000, v1
	s_cmpk_gt_i32 s11, 384
	s_cselect_b64 vcc, -1, 0
	v_xor_b32_e32 v0, v1, v0
	v_cndmask_b32_e32 v182, v123, v0, vcc
	s_nop 3
	s_waitcnt lgkmcnt(3)
	v_mfma_f32_32x32x16_bf16 v[212:227], v[70:73], v[38:41], 0
	v_max_f32_e32 v108, 0, v6
	v_max_f32_e32 v109, 0, v7
	v_pk_mul_f32 v[50:51], v[244:245], v[108:109]
	v_max_f32_e32 v210, 0, v8
	v_max_f32_e32 v211, 0, v9
	v_pk_fma_f32 v[50:51], v[246:247], v[210:211], v[50:51]
	v_max_f32_e32 v108, 0, v10
	v_max_f32_e32 v109, 0, v11
	v_pk_fma_f32 v[50:51], v[248:249], v[108:109], v[50:51]
	s_waitcnt lgkmcnt(2)
	v_mfma_f32_32x32x16_bf16 v[212:227], v[74:77], v[42:45], v[212:227]
	v_max_f32_e32 v210, 0, v12
	v_max_f32_e32 v211, 0, v13
	v_pk_fma_f32 v[50:51], v[250:251], v[210:211], v[50:51]
	v_max_f32_e32 v108, 0, v14
	v_max_f32_e32 v109, 0, v15
	v_pk_fma_f32 v[50:51], v[252:253], v[108:109], v[50:51]
	v_max_f32_e32 v210, 0, v16
	v_max_f32_e32 v211, 0, v17
	v_pk_fma_f32 v[50:51], v[254:255], v[210:211], v[50:51]
	s_waitcnt lgkmcnt(1)
	v_mfma_f32_32x32x16_bf16 v[212:227], v[78:81], v[46:49], v[212:227]
	v_max_f32_e32 v108, 0, v18
	v_max_f32_e32 v109, 0, v19
	v_pk_fma_f32 v[50:51], v[200:201], v[108:109], v[50:51]
	v_max_f32_e32 v210, 0, v20
	v_max_f32_e32 v211, 0, v21
	v_pk_fma_f32 v[50:51], v[202:203], v[210:211], v[50:51]
	v_add_f32_e32 v50, v50, v51
	v_ashrrev_i32_e32 v51, 31, v50
	s_waitcnt lgkmcnt(0)
	v_mfma_f32_32x32x16_bf16 v[212:227], v[82:85], v[196:199], v[212:227]
	v_or_b32_e32 v51, 0x80000000, v51
	s_cmpk_gt_i32 s11, 384
	s_cselect_b64 vcc, -1, 0
	v_xor_b32_e32 v50, v51, v50
	v_cndmask_b32_e32 v50, v123, v50, vcc
	global_store_dword v243, v50, s[8:9]
	v_mfma_f32_32x32x16_bf16 v[6:21], v[86:89], v[38:41], 0
	s_add_i32 m0, s10, 0
	s_nop 0
	global_load_lds_dwordx4 v102, s[6:7]
	s_add_i32 m0, s10, 1024
	s_nop 0
	global_load_lds_dwordx4 v110, s[6:7]
	s_add_i32 m0, s10, 2048
	s_nop 0
	global_load_lds_dwordx4 v112, s[6:7]
	s_add_i32 m0, s10, 3072
	s_nop 0
	global_load_lds_dwordx4 v193, s[6:7]
	s_add_u32 s6, s6, 0x8000
	s_addc_u32 s7, s7, 0
	v_max_f32_e32 v108, 0, v212
	v_max_f32_e32 v109, 0, v213
	v_pk_mul_f32 v[0:1], v[22:23], v[108:109]
	v_max_f32_e32 v210, 0, v214
	v_max_f32_e32 v211, 0, v215
	v_pk_fma_f32 v[0:1], v[24:25], v[210:211], v[0:1]
	v_max_f32_e32 v108, 0, v216
	v_max_f32_e32 v109, 0, v217
	v_pk_fma_f32 v[0:1], v[26:27], v[108:109], v[0:1]
	v_mfma_f32_32x32x16_bf16 v[6:21], v[90:93], v[42:45], v[6:21]
	v_max_f32_e32 v210, 0, v218
	v_max_f32_e32 v211, 0, v219
	v_pk_fma_f32 v[0:1], v[28:29], v[210:211], v[0:1]
	v_max_f32_e32 v108, 0, v220
	v_max_f32_e32 v109, 0, v221
	v_pk_fma_f32 v[0:1], v[30:31], v[108:109], v[0:1]
	v_max_f32_e32 v210, 0, v222
	v_max_f32_e32 v211, 0, v223
	v_pk_fma_f32 v[0:1], v[32:33], v[210:211], v[0:1]
	v_mfma_f32_32x32x16_bf16 v[6:21], v[94:97], v[46:49], v[6:21]
	v_max_f32_e32 v108, 0, v224
	v_max_f32_e32 v109, 0, v225
	v_pk_fma_f32 v[0:1], v[34:35], v[108:109], v[0:1]
	v_max_f32_e32 v210, 0, v226
	v_max_f32_e32 v211, 0, v227
	v_pk_fma_f32 v[0:1], v[36:37], v[210:211], v[0:1]
	v_add_f32_e32 v0, v0, v1
	v_ashrrev_i32_e32 v1, 31, v0
	v_mfma_f32_32x32x16_bf16 v[6:21], v[98:101], v[196:199], v[6:21]
	s_waitcnt vmcnt(10)
	v_add_u32_e32 v228, 0x10000, v5
	ds_read_b128 v[38:41], v228 offset:10496
	v_add_u32_e32 v228, 0x10000, v52
	ds_read_b128 v[42:45], v228 offset:10496
	v_add_u32_e32 v228, 0x10000, v55
	ds_read_b128 v[46:49], v228 offset:10496
	v_add_u32_e32 v228, 0x10000, v56
	ds_read_b128 v[196:199], v228 offset:10496
	v_or_b32_e32 v1, 0x80000000, v1
	s_cmpk_gt_i32 s11, 392
	s_cselect_b64 vcc, -1, 0
	v_xor_b32_e32 v0, v1, v0
	v_cndmask_b32_e32 v181, v123, v0, vcc
	s_nop 3
	s_waitcnt lgkmcnt(3)
	v_mfma_f32_32x32x16_bf16 v[212:227], v[70:73], v[38:41], 0
	v_max_f32_e32 v108, 0, v6
	v_max_f32_e32 v109, 0, v7
	v_pk_mul_f32 v[50:51], v[244:245], v[108:109]
	v_max_f32_e32 v210, 0, v8
	v_max_f32_e32 v211, 0, v9
	v_pk_fma_f32 v[50:51], v[246:247], v[210:211], v[50:51]
	v_max_f32_e32 v108, 0, v10
	v_max_f32_e32 v109, 0, v11
	v_pk_fma_f32 v[50:51], v[248:249], v[108:109], v[50:51]
	s_waitcnt lgkmcnt(2)
	v_mfma_f32_32x32x16_bf16 v[212:227], v[74:77], v[42:45], v[212:227]
	v_max_f32_e32 v210, 0, v12
	v_max_f32_e32 v211, 0, v13
	v_pk_fma_f32 v[50:51], v[250:251], v[210:211], v[50:51]
	v_max_f32_e32 v108, 0, v14
	v_max_f32_e32 v109, 0, v15
	v_pk_fma_f32 v[50:51], v[252:253], v[108:109], v[50:51]
	v_max_f32_e32 v210, 0, v16
	v_max_f32_e32 v211, 0, v17
	v_pk_fma_f32 v[50:51], v[254:255], v[210:211], v[50:51]
	s_waitcnt lgkmcnt(1)
	v_mfma_f32_32x32x16_bf16 v[212:227], v[78:81], v[46:49], v[212:227]
	v_max_f32_e32 v108, 0, v18
	v_max_f32_e32 v109, 0, v19
	v_pk_fma_f32 v[50:51], v[200:201], v[108:109], v[50:51]
	v_max_f32_e32 v210, 0, v20
	v_max_f32_e32 v211, 0, v21
	v_pk_fma_f32 v[50:51], v[202:203], v[210:211], v[50:51]
	v_add_f32_e32 v50, v50, v51
	v_ashrrev_i32_e32 v51, 31, v50
	s_waitcnt lgkmcnt(0)
	v_mfma_f32_32x32x16_bf16 v[212:227], v[82:85], v[196:199], v[212:227]
	v_or_b32_e32 v51, 0x80000000, v51
	s_cmpk_gt_i32 s11, 392
	s_cselect_b64 vcc, -1, 0
	v_xor_b32_e32 v50, v51, v50
	v_cndmask_b32_e32 v50, v123, v50, vcc
	global_store_dword v243, v50, s[8:9] offset:2048
	s_add_u32 s8, s8, 0x1000
	s_addc_u32 s9, s9, 0
	v_mfma_f32_32x32x16_bf16 v[6:21], v[86:89], v[38:41], 0
	s_add_i32 m0, s10, 32768
	s_nop 0
	global_load_lds_dwordx4 v102, s[6:7]
	s_add_i32 m0, s10, 33792
	s_nop 0
	global_load_lds_dwordx4 v110, s[6:7]
	s_add_i32 m0, s10, 34816
	s_nop 0
	global_load_lds_dwordx4 v112, s[6:7]
	s_add_i32 m0, s10, 35840
	s_nop 0
	global_load_lds_dwordx4 v193, s[6:7]
	s_add_u32 s6, s6, 0x8000
	s_addc_u32 s7, s7, 0
	v_max_f32_e32 v108, 0, v212
	v_max_f32_e32 v109, 0, v213
	v_pk_mul_f32 v[0:1], v[22:23], v[108:109]
	v_max_f32_e32 v210, 0, v214
	v_max_f32_e32 v211, 0, v215
	v_pk_fma_f32 v[0:1], v[24:25], v[210:211], v[0:1]
	v_max_f32_e32 v108, 0, v216
	v_max_f32_e32 v109, 0, v217
	v_pk_fma_f32 v[0:1], v[26:27], v[108:109], v[0:1]
	v_mfma_f32_32x32x16_bf16 v[6:21], v[90:93], v[42:45], v[6:21]
	v_max_f32_e32 v210, 0, v218
	v_max_f32_e32 v211, 0, v219
	v_pk_fma_f32 v[0:1], v[28:29], v[210:211], v[0:1]
	v_max_f32_e32 v108, 0, v220
	v_max_f32_e32 v109, 0, v221
	v_pk_fma_f32 v[0:1], v[30:31], v[108:109], v[0:1]
	v_max_f32_e32 v210, 0, v222
	v_max_f32_e32 v211, 0, v223
	v_pk_fma_f32 v[0:1], v[32:33], v[210:211], v[0:1]
	v_mfma_f32_32x32x16_bf16 v[6:21], v[94:97], v[46:49], v[6:21]
	v_max_f32_e32 v108, 0, v224
	v_max_f32_e32 v109, 0, v225
	v_pk_fma_f32 v[0:1], v[34:35], v[108:109], v[0:1]
	v_max_f32_e32 v210, 0, v226
	v_max_f32_e32 v211, 0, v227
	v_pk_fma_f32 v[0:1], v[36:37], v[210:211], v[0:1]
	v_add_f32_e32 v0, v0, v1
	v_ashrrev_i32_e32 v1, 31, v0
	v_mfma_f32_32x32x16_bf16 v[6:21], v[98:101], v[196:199], v[6:21]
	s_waitcnt vmcnt(10)
	v_add_u32_e32 v228, 0x10000, v5
	ds_read_b128 v[38:41], v228 offset:43264
	v_add_u32_e32 v228, 0x10000, v52
	ds_read_b128 v[42:45], v228 offset:43264
	v_add_u32_e32 v228, 0x10000, v55
	ds_read_b128 v[46:49], v228 offset:43264
	v_add_u32_e32 v228, 0x10000, v56
	ds_read_b128 v[196:199], v228 offset:43264
	v_or_b32_e32 v1, 0x80000000, v1
	s_cmpk_gt_i32 s11, 400
	s_cselect_b64 vcc, -1, 0
	v_xor_b32_e32 v0, v1, v0
	v_cndmask_b32_e32 v184, v123, v0, vcc
	s_nop 3
	s_waitcnt lgkmcnt(3)
	v_mfma_f32_32x32x16_bf16 v[212:227], v[70:73], v[38:41], 0
	v_max_f32_e32 v108, 0, v6
	v_max_f32_e32 v109, 0, v7
	v_pk_mul_f32 v[50:51], v[244:245], v[108:109]
	v_max_f32_e32 v210, 0, v8
	v_max_f32_e32 v211, 0, v9
	v_pk_fma_f32 v[50:51], v[246:247], v[210:211], v[50:51]
	v_max_f32_e32 v108, 0, v10
	v_max_f32_e32 v109, 0, v11
	v_pk_fma_f32 v[50:51], v[248:249], v[108:109], v[50:51]
	s_waitcnt lgkmcnt(2)
	v_mfma_f32_32x32x16_bf16 v[212:227], v[74:77], v[42:45], v[212:227]
	v_max_f32_e32 v210, 0, v12
	v_max_f32_e32 v211, 0, v13
	v_pk_fma_f32 v[50:51], v[250:251], v[210:211], v[50:51]
	v_max_f32_e32 v108, 0, v14
	v_max_f32_e32 v109, 0, v15
	v_pk_fma_f32 v[50:51], v[252:253], v[108:109], v[50:51]
	v_max_f32_e32 v210, 0, v16
	v_max_f32_e32 v211, 0, v17
	v_pk_fma_f32 v[50:51], v[254:255], v[210:211], v[50:51]
	s_waitcnt lgkmcnt(1)
	v_mfma_f32_32x32x16_bf16 v[212:227], v[78:81], v[46:49], v[212:227]
	v_max_f32_e32 v108, 0, v18
	v_max_f32_e32 v109, 0, v19
	v_pk_fma_f32 v[50:51], v[200:201], v[108:109], v[50:51]
	v_max_f32_e32 v210, 0, v20
	v_max_f32_e32 v211, 0, v21
	v_pk_fma_f32 v[50:51], v[202:203], v[210:211], v[50:51]
	v_add_f32_e32 v50, v50, v51
	v_ashrrev_i32_e32 v51, 31, v50
	s_waitcnt lgkmcnt(0)
	v_mfma_f32_32x32x16_bf16 v[212:227], v[82:85], v[196:199], v[212:227]
	v_or_b32_e32 v51, 0x80000000, v51
	s_cmpk_gt_i32 s11, 400
	s_cselect_b64 vcc, -1, 0
	v_xor_b32_e32 v50, v51, v50
	v_cndmask_b32_e32 v50, v123, v50, vcc
	global_store_dword v243, v50, s[8:9]
	v_mfma_f32_32x32x16_bf16 v[6:21], v[86:89], v[38:41], 0
	s_add_i32 m0, s10, 65536
	s_nop 0
	global_load_lds_dwordx4 v102, s[6:7]
	s_add_i32 m0, s10, 66560
	s_nop 0
	global_load_lds_dwordx4 v110, s[6:7]
	s_add_i32 m0, s10, 67584
	s_nop 0
	global_load_lds_dwordx4 v112, s[6:7]
	s_add_i32 m0, s10, 68608
	s_nop 0
	global_load_lds_dwordx4 v193, s[6:7]
	s_add_u32 s6, s6, 0x8000
	s_addc_u32 s7, s7, 0
	v_max_f32_e32 v108, 0, v212
	v_max_f32_e32 v109, 0, v213
	v_pk_mul_f32 v[0:1], v[22:23], v[108:109]
	v_max_f32_e32 v210, 0, v214
	v_max_f32_e32 v211, 0, v215
	v_pk_fma_f32 v[0:1], v[24:25], v[210:211], v[0:1]
	v_max_f32_e32 v108, 0, v216
	v_max_f32_e32 v109, 0, v217
	v_pk_fma_f32 v[0:1], v[26:27], v[108:109], v[0:1]
	v_mfma_f32_32x32x16_bf16 v[6:21], v[90:93], v[42:45], v[6:21]
	v_max_f32_e32 v210, 0, v218
	v_max_f32_e32 v211, 0, v219
	v_pk_fma_f32 v[0:1], v[28:29], v[210:211], v[0:1]
	v_max_f32_e32 v108, 0, v220
	v_max_f32_e32 v109, 0, v221
	v_pk_fma_f32 v[0:1], v[30:31], v[108:109], v[0:1]
	v_max_f32_e32 v210, 0, v222
	v_max_f32_e32 v211, 0, v223
	v_pk_fma_f32 v[0:1], v[32:33], v[210:211], v[0:1]
	v_mfma_f32_32x32x16_bf16 v[6:21], v[94:97], v[46:49], v[6:21]
	v_max_f32_e32 v108, 0, v224
	v_max_f32_e32 v109, 0, v225
	v_pk_fma_f32 v[0:1], v[34:35], v[108:109], v[0:1]
	v_max_f32_e32 v210, 0, v226
	v_max_f32_e32 v211, 0, v227
	v_pk_fma_f32 v[0:1], v[36:37], v[210:211], v[0:1]
	v_add_f32_e32 v0, v0, v1
	v_ashrrev_i32_e32 v1, 31, v0
	v_mfma_f32_32x32x16_bf16 v[6:21], v[98:101], v[196:199], v[6:21]
	s_waitcnt vmcnt(10)
	ds_read_b128 v[38:41], v5 offset:10496
	ds_read_b128 v[42:45], v52 offset:10496
	ds_read_b128 v[46:49], v55 offset:10496
	ds_read_b128 v[196:199], v56 offset:10496
	v_or_b32_e32 v1, 0x80000000, v1
	s_cmpk_gt_i32 s11, 408
	s_cselect_b64 vcc, -1, 0
	v_xor_b32_e32 v0, v1, v0
	v_cndmask_b32_e32 v183, v123, v0, vcc
	s_nop 3
	s_waitcnt lgkmcnt(3)
	v_mfma_f32_32x32x16_bf16 v[212:227], v[70:73], v[38:41], 0
	v_max_f32_e32 v108, 0, v6
	v_max_f32_e32 v109, 0, v7
	v_pk_mul_f32 v[50:51], v[244:245], v[108:109]
	v_max_f32_e32 v210, 0, v8
	v_max_f32_e32 v211, 0, v9
	v_pk_fma_f32 v[50:51], v[246:247], v[210:211], v[50:51]
	v_max_f32_e32 v108, 0, v10
	v_max_f32_e32 v109, 0, v11
	v_pk_fma_f32 v[50:51], v[248:249], v[108:109], v[50:51]
	s_waitcnt lgkmcnt(2)
	v_mfma_f32_32x32x16_bf16 v[212:227], v[74:77], v[42:45], v[212:227]
	v_max_f32_e32 v210, 0, v12
	v_max_f32_e32 v211, 0, v13
	v_pk_fma_f32 v[50:51], v[250:251], v[210:211], v[50:51]
	v_max_f32_e32 v108, 0, v14
	v_max_f32_e32 v109, 0, v15
	v_pk_fma_f32 v[50:51], v[252:253], v[108:109], v[50:51]
	v_max_f32_e32 v210, 0, v16
	v_max_f32_e32 v211, 0, v17
	v_pk_fma_f32 v[50:51], v[254:255], v[210:211], v[50:51]
	s_waitcnt lgkmcnt(1)
	v_mfma_f32_32x32x16_bf16 v[212:227], v[78:81], v[46:49], v[212:227]
	v_max_f32_e32 v108, 0, v18
	v_max_f32_e32 v109, 0, v19
	v_pk_fma_f32 v[50:51], v[200:201], v[108:109], v[50:51]
	v_max_f32_e32 v210, 0, v20
	v_max_f32_e32 v211, 0, v21
	v_pk_fma_f32 v[50:51], v[202:203], v[210:211], v[50:51]
	v_add_f32_e32 v50, v50, v51
	v_ashrrev_i32_e32 v51, 31, v50
	s_waitcnt lgkmcnt(0)
	v_mfma_f32_32x32x16_bf16 v[212:227], v[82:85], v[196:199], v[212:227]
	v_or_b32_e32 v51, 0x80000000, v51
	s_cmpk_gt_i32 s11, 408
	s_cselect_b64 vcc, -1, 0
	v_xor_b32_e32 v50, v51, v50
	v_cndmask_b32_e32 v50, v123, v50, vcc
	global_store_dword v243, v50, s[8:9] offset:2048
	s_add_u32 s8, s8, 0x1000
	s_addc_u32 s9, s9, 0
	v_mfma_f32_32x32x16_bf16 v[6:21], v[86:89], v[38:41], 0
	s_add_i32 m0, s10, 98304
	s_nop 0
	global_load_lds_dwordx4 v102, s[6:7]
	s_add_i32 m0, s10, 99328
	s_nop 0
	global_load_lds_dwordx4 v110, s[6:7]
	s_add_i32 m0, s10, 100352
	s_nop 0
	global_load_lds_dwordx4 v112, s[6:7]
	s_add_i32 m0, s10, 101376
	s_nop 0
	global_load_lds_dwordx4 v193, s[6:7]
	s_add_u32 s6, s6, 0x8000
	s_addc_u32 s7, s7, 0
	v_max_f32_e32 v108, 0, v212
	v_max_f32_e32 v109, 0, v213
	v_pk_mul_f32 v[0:1], v[22:23], v[108:109]
	v_max_f32_e32 v210, 0, v214
	v_max_f32_e32 v211, 0, v215
	v_pk_fma_f32 v[0:1], v[24:25], v[210:211], v[0:1]
	v_max_f32_e32 v108, 0, v216
	v_max_f32_e32 v109, 0, v217
	v_pk_fma_f32 v[0:1], v[26:27], v[108:109], v[0:1]
	v_mfma_f32_32x32x16_bf16 v[6:21], v[90:93], v[42:45], v[6:21]
	v_max_f32_e32 v210, 0, v218
	v_max_f32_e32 v211, 0, v219
	v_pk_fma_f32 v[0:1], v[28:29], v[210:211], v[0:1]
	v_max_f32_e32 v108, 0, v220
	v_max_f32_e32 v109, 0, v221
	v_pk_fma_f32 v[0:1], v[30:31], v[108:109], v[0:1]
	v_max_f32_e32 v210, 0, v222
	v_max_f32_e32 v211, 0, v223
	v_pk_fma_f32 v[0:1], v[32:33], v[210:211], v[0:1]
	v_mfma_f32_32x32x16_bf16 v[6:21], v[94:97], v[46:49], v[6:21]
	v_max_f32_e32 v108, 0, v224
	v_max_f32_e32 v109, 0, v225
	v_pk_fma_f32 v[0:1], v[34:35], v[108:109], v[0:1]
	v_max_f32_e32 v210, 0, v226
	v_max_f32_e32 v211, 0, v227
	v_pk_fma_f32 v[0:1], v[36:37], v[210:211], v[0:1]
	v_add_f32_e32 v0, v0, v1
	v_ashrrev_i32_e32 v1, 31, v0
	v_mfma_f32_32x32x16_bf16 v[6:21], v[98:101], v[196:199], v[6:21]
	s_waitcnt vmcnt(10)
	ds_read_b128 v[38:41], v5 offset:43264
	ds_read_b128 v[42:45], v52 offset:43264
	ds_read_b128 v[46:49], v55 offset:43264
	ds_read_b128 v[196:199], v56 offset:43264
	v_or_b32_e32 v1, 0x80000000, v1
	s_cmpk_gt_i32 s11, 416
	s_cselect_b64 vcc, -1, 0
	v_xor_b32_e32 v0, v1, v0
	v_cndmask_b32_e32 v187, v123, v0, vcc
	s_nop 3
	s_waitcnt lgkmcnt(3)
	v_mfma_f32_32x32x16_bf16 v[212:227], v[70:73], v[38:41], 0
	v_max_f32_e32 v108, 0, v6
	v_max_f32_e32 v109, 0, v7
	v_pk_mul_f32 v[50:51], v[244:245], v[108:109]
	v_max_f32_e32 v210, 0, v8
	v_max_f32_e32 v211, 0, v9
	v_pk_fma_f32 v[50:51], v[246:247], v[210:211], v[50:51]
	v_max_f32_e32 v108, 0, v10
	v_max_f32_e32 v109, 0, v11
	v_pk_fma_f32 v[50:51], v[248:249], v[108:109], v[50:51]
	s_waitcnt lgkmcnt(2)
	v_mfma_f32_32x32x16_bf16 v[212:227], v[74:77], v[42:45], v[212:227]
	v_max_f32_e32 v210, 0, v12
	v_max_f32_e32 v211, 0, v13
	v_pk_fma_f32 v[50:51], v[250:251], v[210:211], v[50:51]
	v_max_f32_e32 v108, 0, v14
	v_max_f32_e32 v109, 0, v15
	v_pk_fma_f32 v[50:51], v[252:253], v[108:109], v[50:51]
	v_max_f32_e32 v210, 0, v16
	v_max_f32_e32 v211, 0, v17
	v_pk_fma_f32 v[50:51], v[254:255], v[210:211], v[50:51]
	s_waitcnt lgkmcnt(1)
	v_mfma_f32_32x32x16_bf16 v[212:227], v[78:81], v[46:49], v[212:227]
	v_max_f32_e32 v108, 0, v18
	v_max_f32_e32 v109, 0, v19
	v_pk_fma_f32 v[50:51], v[200:201], v[108:109], v[50:51]
	v_max_f32_e32 v210, 0, v20
	v_max_f32_e32 v211, 0, v21
	v_pk_fma_f32 v[50:51], v[202:203], v[210:211], v[50:51]
	v_add_f32_e32 v50, v50, v51
	v_ashrrev_i32_e32 v51, 31, v50
	s_waitcnt lgkmcnt(0)
	v_mfma_f32_32x32x16_bf16 v[212:227], v[82:85], v[196:199], v[212:227]
	v_or_b32_e32 v51, 0x80000000, v51
	s_cmpk_gt_i32 s11, 416
	s_cselect_b64 vcc, -1, 0
	v_xor_b32_e32 v50, v51, v50
	v_cndmask_b32_e32 v50, v123, v50, vcc
	global_store_dword v243, v50, s[8:9]
	v_mfma_f32_32x32x16_bf16 v[6:21], v[86:89], v[38:41], 0
	s_add_i32 m0, s10, 0
	s_nop 0
	global_load_lds_dwordx4 v102, s[6:7]
	s_add_i32 m0, s10, 1024
	s_nop 0
	global_load_lds_dwordx4 v110, s[6:7]
	s_add_i32 m0, s10, 2048
	s_nop 0
	global_load_lds_dwordx4 v112, s[6:7]
	s_add_i32 m0, s10, 3072
	s_nop 0
	global_load_lds_dwordx4 v193, s[6:7]
	s_add_u32 s6, s6, 0x8000
	s_addc_u32 s7, s7, 0
	v_max_f32_e32 v108, 0, v212
	v_max_f32_e32 v109, 0, v213
	v_pk_mul_f32 v[0:1], v[22:23], v[108:109]
	v_max_f32_e32 v210, 0, v214
	v_max_f32_e32 v211, 0, v215
	v_pk_fma_f32 v[0:1], v[24:25], v[210:211], v[0:1]
	v_max_f32_e32 v108, 0, v216
	v_max_f32_e32 v109, 0, v217
	v_pk_fma_f32 v[0:1], v[26:27], v[108:109], v[0:1]
	v_mfma_f32_32x32x16_bf16 v[6:21], v[90:93], v[42:45], v[6:21]
	v_max_f32_e32 v210, 0, v218
	v_max_f32_e32 v211, 0, v219
	v_pk_fma_f32 v[0:1], v[28:29], v[210:211], v[0:1]
	v_max_f32_e32 v108, 0, v220
	v_max_f32_e32 v109, 0, v221
	v_pk_fma_f32 v[0:1], v[30:31], v[108:109], v[0:1]
	v_max_f32_e32 v210, 0, v222
	v_max_f32_e32 v211, 0, v223
	v_pk_fma_f32 v[0:1], v[32:33], v[210:211], v[0:1]
	v_mfma_f32_32x32x16_bf16 v[6:21], v[94:97], v[46:49], v[6:21]
	v_max_f32_e32 v108, 0, v224
	v_max_f32_e32 v109, 0, v225
	v_pk_fma_f32 v[0:1], v[34:35], v[108:109], v[0:1]
	v_max_f32_e32 v210, 0, v226
	v_max_f32_e32 v211, 0, v227
	v_pk_fma_f32 v[0:1], v[36:37], v[210:211], v[0:1]
	v_add_f32_e32 v0, v0, v1
	v_ashrrev_i32_e32 v1, 31, v0
	v_mfma_f32_32x32x16_bf16 v[6:21], v[98:101], v[196:199], v[6:21]
	s_waitcnt vmcnt(10)
	v_add_u32_e32 v228, 0x10000, v5
	ds_read_b128 v[38:41], v228 offset:10496
	v_add_u32_e32 v228, 0x10000, v52
	ds_read_b128 v[42:45], v228 offset:10496
	v_add_u32_e32 v228, 0x10000, v55
	ds_read_b128 v[46:49], v228 offset:10496
	v_add_u32_e32 v228, 0x10000, v56
	ds_read_b128 v[196:199], v228 offset:10496
	v_or_b32_e32 v1, 0x80000000, v1
	s_cmpk_gt_i32 s11, 424
	s_cselect_b64 vcc, -1, 0
	v_xor_b32_e32 v0, v1, v0
	v_cndmask_b32_e32 v186, v123, v0, vcc
	s_nop 3
	s_waitcnt lgkmcnt(3)
	v_mfma_f32_32x32x16_bf16 v[212:227], v[70:73], v[38:41], 0
	v_max_f32_e32 v108, 0, v6
	v_max_f32_e32 v109, 0, v7
	v_pk_mul_f32 v[50:51], v[244:245], v[108:109]
	v_max_f32_e32 v210, 0, v8
	v_max_f32_e32 v211, 0, v9
	v_pk_fma_f32 v[50:51], v[246:247], v[210:211], v[50:51]
	v_max_f32_e32 v108, 0, v10
	v_max_f32_e32 v109, 0, v11
	v_pk_fma_f32 v[50:51], v[248:249], v[108:109], v[50:51]
	s_waitcnt lgkmcnt(2)
	v_mfma_f32_32x32x16_bf16 v[212:227], v[74:77], v[42:45], v[212:227]
	v_max_f32_e32 v210, 0, v12
	v_max_f32_e32 v211, 0, v13
	v_pk_fma_f32 v[50:51], v[250:251], v[210:211], v[50:51]
	v_max_f32_e32 v108, 0, v14
	v_max_f32_e32 v109, 0, v15
	v_pk_fma_f32 v[50:51], v[252:253], v[108:109], v[50:51]
	v_max_f32_e32 v210, 0, v16
	v_max_f32_e32 v211, 0, v17
	v_pk_fma_f32 v[50:51], v[254:255], v[210:211], v[50:51]
	s_waitcnt lgkmcnt(1)
	v_mfma_f32_32x32x16_bf16 v[212:227], v[78:81], v[46:49], v[212:227]
	v_max_f32_e32 v108, 0, v18
	v_max_f32_e32 v109, 0, v19
	v_pk_fma_f32 v[50:51], v[200:201], v[108:109], v[50:51]
	v_max_f32_e32 v210, 0, v20
	v_max_f32_e32 v211, 0, v21
	v_pk_fma_f32 v[50:51], v[202:203], v[210:211], v[50:51]
	v_add_f32_e32 v50, v50, v51
	v_ashrrev_i32_e32 v51, 31, v50
	s_waitcnt lgkmcnt(0)
	v_mfma_f32_32x32x16_bf16 v[212:227], v[82:85], v[196:199], v[212:227]
	v_or_b32_e32 v51, 0x80000000, v51
	s_cmpk_gt_i32 s11, 424
	s_cselect_b64 vcc, -1, 0
	v_xor_b32_e32 v50, v51, v50
	v_cndmask_b32_e32 v50, v123, v50, vcc
	global_store_dword v243, v50, s[8:9] offset:2048
	s_add_u32 s8, s8, 0x1000
	s_addc_u32 s9, s9, 0
	v_mfma_f32_32x32x16_bf16 v[6:21], v[86:89], v[38:41], 0
	s_add_i32 m0, s10, 32768
	s_nop 0
	global_load_lds_dwordx4 v102, s[6:7]
	s_add_i32 m0, s10, 33792
	s_nop 0
	global_load_lds_dwordx4 v110, s[6:7]
	s_add_i32 m0, s10, 34816
	s_nop 0
	global_load_lds_dwordx4 v112, s[6:7]
	s_add_i32 m0, s10, 35840
	s_nop 0
	global_load_lds_dwordx4 v193, s[6:7]
	s_add_u32 s6, s6, 0x8000
	s_addc_u32 s7, s7, 0
	v_max_f32_e32 v108, 0, v212
	v_max_f32_e32 v109, 0, v213
	v_pk_mul_f32 v[0:1], v[22:23], v[108:109]
	v_max_f32_e32 v210, 0, v214
	v_max_f32_e32 v211, 0, v215
	v_pk_fma_f32 v[0:1], v[24:25], v[210:211], v[0:1]
	v_max_f32_e32 v108, 0, v216
	v_max_f32_e32 v109, 0, v217
	v_pk_fma_f32 v[0:1], v[26:27], v[108:109], v[0:1]
	v_mfma_f32_32x32x16_bf16 v[6:21], v[90:93], v[42:45], v[6:21]
	v_max_f32_e32 v210, 0, v218
	v_max_f32_e32 v211, 0, v219
	v_pk_fma_f32 v[0:1], v[28:29], v[210:211], v[0:1]
	v_max_f32_e32 v108, 0, v220
	v_max_f32_e32 v109, 0, v221
	v_pk_fma_f32 v[0:1], v[30:31], v[108:109], v[0:1]
	v_max_f32_e32 v210, 0, v222
	v_max_f32_e32 v211, 0, v223
	v_pk_fma_f32 v[0:1], v[32:33], v[210:211], v[0:1]
	v_mfma_f32_32x32x16_bf16 v[6:21], v[94:97], v[46:49], v[6:21]
	v_max_f32_e32 v108, 0, v224
	v_max_f32_e32 v109, 0, v225
	v_pk_fma_f32 v[0:1], v[34:35], v[108:109], v[0:1]
	v_max_f32_e32 v210, 0, v226
	v_max_f32_e32 v211, 0, v227
	v_pk_fma_f32 v[0:1], v[36:37], v[210:211], v[0:1]
	v_add_f32_e32 v0, v0, v1
	v_ashrrev_i32_e32 v1, 31, v0
	v_mfma_f32_32x32x16_bf16 v[6:21], v[98:101], v[196:199], v[6:21]
	s_waitcnt vmcnt(10)
	v_add_u32_e32 v228, 0x10000, v5
	ds_read_b128 v[38:41], v228 offset:43264
	v_add_u32_e32 v228, 0x10000, v52
	ds_read_b128 v[42:45], v228 offset:43264
	v_add_u32_e32 v228, 0x10000, v55
	ds_read_b128 v[46:49], v228 offset:43264
	v_add_u32_e32 v228, 0x10000, v56
	ds_read_b128 v[196:199], v228 offset:43264
	v_or_b32_e32 v1, 0x80000000, v1
	s_cmpk_gt_i32 s11, 432
	s_cselect_b64 vcc, -1, 0
	v_xor_b32_e32 v0, v1, v0
	v_cndmask_b32_e32 v189, v123, v0, vcc
	s_nop 3
	s_waitcnt lgkmcnt(3)
	v_mfma_f32_32x32x16_bf16 v[212:227], v[70:73], v[38:41], 0
	v_max_f32_e32 v108, 0, v6
	v_max_f32_e32 v109, 0, v7
	v_pk_mul_f32 v[50:51], v[244:245], v[108:109]
	v_max_f32_e32 v210, 0, v8
	v_max_f32_e32 v211, 0, v9
	v_pk_fma_f32 v[50:51], v[246:247], v[210:211], v[50:51]
	v_max_f32_e32 v108, 0, v10
	v_max_f32_e32 v109, 0, v11
	v_pk_fma_f32 v[50:51], v[248:249], v[108:109], v[50:51]
	s_waitcnt lgkmcnt(2)
	v_mfma_f32_32x32x16_bf16 v[212:227], v[74:77], v[42:45], v[212:227]
	v_max_f32_e32 v210, 0, v12
	v_max_f32_e32 v211, 0, v13
	v_pk_fma_f32 v[50:51], v[250:251], v[210:211], v[50:51]
	v_max_f32_e32 v108, 0, v14
	v_max_f32_e32 v109, 0, v15
	v_pk_fma_f32 v[50:51], v[252:253], v[108:109], v[50:51]
	v_max_f32_e32 v210, 0, v16
	v_max_f32_e32 v211, 0, v17
	v_pk_fma_f32 v[50:51], v[254:255], v[210:211], v[50:51]
	s_waitcnt lgkmcnt(1)
	v_mfma_f32_32x32x16_bf16 v[212:227], v[78:81], v[46:49], v[212:227]
	v_max_f32_e32 v108, 0, v18
	v_max_f32_e32 v109, 0, v19
	v_pk_fma_f32 v[50:51], v[200:201], v[108:109], v[50:51]
	v_max_f32_e32 v210, 0, v20
	v_max_f32_e32 v211, 0, v21
	v_pk_fma_f32 v[50:51], v[202:203], v[210:211], v[50:51]
	v_add_f32_e32 v50, v50, v51
	v_ashrrev_i32_e32 v51, 31, v50
	s_waitcnt lgkmcnt(0)
	v_mfma_f32_32x32x16_bf16 v[212:227], v[82:85], v[196:199], v[212:227]
	v_or_b32_e32 v51, 0x80000000, v51
	s_cmpk_gt_i32 s11, 432
	s_cselect_b64 vcc, -1, 0
	v_xor_b32_e32 v50, v51, v50
	v_cndmask_b32_e32 v50, v123, v50, vcc
	global_store_dword v243, v50, s[8:9]
	v_mfma_f32_32x32x16_bf16 v[6:21], v[86:89], v[38:41], 0
	s_add_i32 m0, s10, 65536
	s_nop 0
	global_load_lds_dwordx4 v102, s[6:7]
	s_add_i32 m0, s10, 66560
	s_nop 0
	global_load_lds_dwordx4 v110, s[6:7]
	s_add_i32 m0, s10, 67584
	s_nop 0
	global_load_lds_dwordx4 v112, s[6:7]
	s_add_i32 m0, s10, 68608
	s_nop 0
	global_load_lds_dwordx4 v193, s[6:7]
	s_add_u32 s6, s6, 0x8000
	s_addc_u32 s7, s7, 0
	v_max_f32_e32 v108, 0, v212
	v_max_f32_e32 v109, 0, v213
	v_pk_mul_f32 v[0:1], v[22:23], v[108:109]
	v_max_f32_e32 v210, 0, v214
	v_max_f32_e32 v211, 0, v215
	v_pk_fma_f32 v[0:1], v[24:25], v[210:211], v[0:1]
	v_max_f32_e32 v108, 0, v216
	v_max_f32_e32 v109, 0, v217
	v_pk_fma_f32 v[0:1], v[26:27], v[108:109], v[0:1]
	v_mfma_f32_32x32x16_bf16 v[6:21], v[90:93], v[42:45], v[6:21]
	v_max_f32_e32 v210, 0, v218
	v_max_f32_e32 v211, 0, v219
	v_pk_fma_f32 v[0:1], v[28:29], v[210:211], v[0:1]
	v_max_f32_e32 v108, 0, v220
	v_max_f32_e32 v109, 0, v221
	v_pk_fma_f32 v[0:1], v[30:31], v[108:109], v[0:1]
	v_max_f32_e32 v210, 0, v222
	v_max_f32_e32 v211, 0, v223
	v_pk_fma_f32 v[0:1], v[32:33], v[210:211], v[0:1]
	v_mfma_f32_32x32x16_bf16 v[6:21], v[94:97], v[46:49], v[6:21]
	v_max_f32_e32 v108, 0, v224
	v_max_f32_e32 v109, 0, v225
	v_pk_fma_f32 v[0:1], v[34:35], v[108:109], v[0:1]
	v_max_f32_e32 v210, 0, v226
	v_max_f32_e32 v211, 0, v227
	v_pk_fma_f32 v[0:1], v[36:37], v[210:211], v[0:1]
	v_add_f32_e32 v0, v0, v1
	v_ashrrev_i32_e32 v1, 31, v0
	v_mfma_f32_32x32x16_bf16 v[6:21], v[98:101], v[196:199], v[6:21]
	s_waitcnt vmcnt(10)
	ds_read_b128 v[38:41], v5 offset:10496
	ds_read_b128 v[42:45], v52 offset:10496
	ds_read_b128 v[46:49], v55 offset:10496
	ds_read_b128 v[196:199], v56 offset:10496
	v_or_b32_e32 v1, 0x80000000, v1
	s_cmpk_gt_i32 s11, 440
	s_cselect_b64 vcc, -1, 0
	v_xor_b32_e32 v0, v1, v0
	v_cndmask_b32_e32 v188, v123, v0, vcc
	s_nop 3
	v_max_f32_e32 v108, 0, v6
	v_max_f32_e32 v109, 0, v7
	v_pk_mul_f32 v[50:51], v[244:245], v[108:109]
	v_max_f32_e32 v210, 0, v8
	v_max_f32_e32 v211, 0, v9
	v_pk_fma_f32 v[50:51], v[246:247], v[210:211], v[50:51]
	v_max_f32_e32 v108, 0, v10
	v_max_f32_e32 v109, 0, v11
	v_pk_fma_f32 v[50:51], v[248:249], v[108:109], v[50:51]
	v_max_f32_e32 v210, 0, v12
	v_max_f32_e32 v211, 0, v13
	v_pk_fma_f32 v[50:51], v[250:251], v[210:211], v[50:51]
	v_max_f32_e32 v108, 0, v14
	v_max_f32_e32 v109, 0, v15
	v_pk_fma_f32 v[50:51], v[252:253], v[108:109], v[50:51]
	v_max_f32_e32 v210, 0, v16
	v_max_f32_e32 v211, 0, v17
	v_pk_fma_f32 v[50:51], v[254:255], v[210:211], v[50:51]
	v_max_f32_e32 v108, 0, v18
	v_max_f32_e32 v109, 0, v19
	v_pk_fma_f32 v[50:51], v[200:201], v[108:109], v[50:51]
	v_max_f32_e32 v210, 0, v20
	v_max_f32_e32 v211, 0, v21
	v_pk_fma_f32 v[50:51], v[202:203], v[210:211], v[50:51]
	v_add_f32_e32 v50, v50, v51
	v_ashrrev_i32_e32 v51, 31, v50
	v_or_b32_e32 v51, 0x80000000, v51
	s_cmpk_gt_i32 s11, 440
	s_cselect_b64 vcc, -1, 0
	v_xor_b32_e32 v50, v51, v50
	v_cndmask_b32_e32 v50, v123, v50, vcc
	global_store_dword v243, v50, s[8:9] offset:2048
	s_add_u32 s8, s8, 0x1000
	s_addc_u32 s9, s9, 0
	s_cmpk_gt_i32 s81, 56
	s_cbranch_scc0 .Lix_fill_7
	s_waitcnt lgkmcnt(3)
	v_mfma_f32_32x32x16_bf16 v[212:227], v[70:73], v[38:41], 0
	s_add_i32 m0, s10, 98304
	s_nop 0
	global_load_lds_dwordx4 v102, s[6:7]
	s_waitcnt lgkmcnt(2)
	v_mfma_f32_32x32x16_bf16 v[212:227], v[74:77], v[42:45], v[212:227]
	s_add_i32 m0, s10, 99328
	s_nop 0
	global_load_lds_dwordx4 v110, s[6:7]
	s_waitcnt lgkmcnt(1)
	v_mfma_f32_32x32x16_bf16 v[212:227], v[78:81], v[46:49], v[212:227]
	s_add_i32 m0, s10, 100352
	s_nop 0
	global_load_lds_dwordx4 v112, s[6:7]
	s_waitcnt lgkmcnt(0)
	v_mfma_f32_32x32x16_bf16 v[212:227], v[82:85], v[196:199], v[212:227]
	s_add_i32 m0, s10, 101376
	s_nop 0
	global_load_lds_dwordx4 v193, s[6:7]
	s_add_u32 s6, s6, 0x8000
	s_addc_u32 s7, s7, 0
	v_mfma_f32_32x32x16_bf16 v[6:21], v[86:89], v[38:41], 0
	s_nop 7
	s_nop 2
	v_max_f32_e32 v108, 0, v212
	v_max_f32_e32 v109, 0, v213
	v_pk_mul_f32 v[0:1], v[22:23], v[108:109]
	v_max_f32_e32 v210, 0, v214
	v_max_f32_e32 v211, 0, v215
	v_pk_fma_f32 v[0:1], v[24:25], v[210:211], v[0:1]
	v_max_f32_e32 v108, 0, v216
	v_max_f32_e32 v109, 0, v217
	v_pk_fma_f32 v[0:1], v[26:27], v[108:109], v[0:1]
	v_mfma_f32_32x32x16_bf16 v[6:21], v[90:93], v[42:45], v[6:21]
	v_max_f32_e32 v210, 0, v218
	v_max_f32_e32 v211, 0, v219
	v_pk_fma_f32 v[0:1], v[28:29], v[210:211], v[0:1]
	v_max_f32_e32 v108, 0, v220
	v_max_f32_e32 v109, 0, v221
	v_pk_fma_f32 v[0:1], v[30:31], v[108:109], v[0:1]
	v_max_f32_e32 v210, 0, v222
	v_max_f32_e32 v211, 0, v223
	v_pk_fma_f32 v[0:1], v[32:33], v[210:211], v[0:1]
	v_mfma_f32_32x32x16_bf16 v[6:21], v[94:97], v[46:49], v[6:21]
	v_max_f32_e32 v108, 0, v224
	v_max_f32_e32 v109, 0, v225
	v_pk_fma_f32 v[0:1], v[34:35], v[108:109], v[0:1]
	v_max_f32_e32 v210, 0, v226
	v_max_f32_e32 v211, 0, v227
	v_pk_fma_f32 v[0:1], v[36:37], v[210:211], v[0:1]
	v_add_f32_e32 v0, v0, v1
	v_ashrrev_i32_e32 v1, 31, v0
	v_mfma_f32_32x32x16_bf16 v[6:21], v[98:101], v[196:199], v[6:21]
	s_waitcnt vmcnt(10)
	ds_read_b128 v[38:41], v5 offset:43264
	ds_read_b128 v[42:45], v52 offset:43264
	ds_read_b128 v[46:49], v55 offset:43264
	ds_read_b128 v[196:199], v56 offset:43264
	v_or_b32_e32 v1, 0x80000000, v1
	s_cmpk_gt_i32 s11, 448
	s_cselect_b64 vcc, -1, 0
	v_xor_b32_e32 v0, v1, v0
	v_cndmask_b32_e32 v190, v123, v0, vcc
	s_nop 3
	s_waitcnt lgkmcnt(3)
	v_mfma_f32_32x32x16_bf16 v[212:227], v[70:73], v[38:41], 0
	v_max_f32_e32 v108, 0, v6
	v_max_f32_e32 v109, 0, v7
	v_pk_mul_f32 v[50:51], v[244:245], v[108:109]
	v_max_f32_e32 v210, 0, v8
	v_max_f32_e32 v211, 0, v9
	v_pk_fma_f32 v[50:51], v[246:247], v[210:211], v[50:51]
	v_max_f32_e32 v108, 0, v10
	v_max_f32_e32 v109, 0, v11
	v_pk_fma_f32 v[50:51], v[248:249], v[108:109], v[50:51]
	s_waitcnt lgkmcnt(2)
	v_mfma_f32_32x32x16_bf16 v[212:227], v[74:77], v[42:45], v[212:227]
	v_max_f32_e32 v210, 0, v12
	v_max_f32_e32 v211, 0, v13
	v_pk_fma_f32 v[50:51], v[250:251], v[210:211], v[50:51]
	v_max_f32_e32 v108, 0, v14
	v_max_f32_e32 v109, 0, v15
	v_pk_fma_f32 v[50:51], v[252:253], v[108:109], v[50:51]
	v_max_f32_e32 v210, 0, v16
	v_max_f32_e32 v211, 0, v17
	v_pk_fma_f32 v[50:51], v[254:255], v[210:211], v[50:51]
	s_waitcnt lgkmcnt(1)
	v_mfma_f32_32x32x16_bf16 v[212:227], v[78:81], v[46:49], v[212:227]
	v_max_f32_e32 v108, 0, v18
	v_max_f32_e32 v109, 0, v19
	v_pk_fma_f32 v[50:51], v[200:201], v[108:109], v[50:51]
	v_max_f32_e32 v210, 0, v20
	v_max_f32_e32 v211, 0, v21
	v_pk_fma_f32 v[50:51], v[202:203], v[210:211], v[50:51]
	v_add_f32_e32 v50, v50, v51
	v_ashrrev_i32_e32 v51, 31, v50
	s_waitcnt lgkmcnt(0)
	v_mfma_f32_32x32x16_bf16 v[212:227], v[82:85], v[196:199], v[212:227]
	v_or_b32_e32 v51, 0x80000000, v51
	s_cmpk_gt_i32 s11, 448
	s_cselect_b64 vcc, -1, 0
	v_xor_b32_e32 v50, v51, v50
	v_cndmask_b32_e32 v50, v123, v50, vcc
	global_store_dword v243, v50, s[8:9]
	v_mfma_f32_32x32x16_bf16 v[6:21], v[86:89], v[38:41], 0
	s_add_i32 m0, s10, 0
	s_nop 0
	global_load_lds_dwordx4 v102, s[6:7]
	s_add_i32 m0, s10, 1024
	s_nop 0
	global_load_lds_dwordx4 v110, s[6:7]
	s_add_i32 m0, s10, 2048
	s_nop 0
	global_load_lds_dwordx4 v112, s[6:7]
	s_add_i32 m0, s10, 3072
	s_nop 0
	global_load_lds_dwordx4 v193, s[6:7]
	s_add_u32 s6, s6, 0x8000
	s_addc_u32 s7, s7, 0
	v_max_f32_e32 v108, 0, v212
	v_max_f32_e32 v109, 0, v213
	v_pk_mul_f32 v[0:1], v[22:23], v[108:109]
	v_max_f32_e32 v210, 0, v214
	v_max_f32_e32 v211, 0, v215
	v_pk_fma_f32 v[0:1], v[24:25], v[210:211], v[0:1]
	v_max_f32_e32 v108, 0, v216
	v_max_f32_e32 v109, 0, v217
	v_pk_fma_f32 v[0:1], v[26:27], v[108:109], v[0:1]
	v_mfma_f32_32x32x16_bf16 v[6:21], v[90:93], v[42:45], v[6:21]
	v_max_f32_e32 v210, 0, v218
	v_max_f32_e32 v211, 0, v219
	v_pk_fma_f32 v[0:1], v[28:29], v[210:211], v[0:1]
	v_max_f32_e32 v108, 0, v220
	v_max_f32_e32 v109, 0, v221
	v_pk_fma_f32 v[0:1], v[30:31], v[108:109], v[0:1]
	v_max_f32_e32 v210, 0, v222
	v_max_f32_e32 v211, 0, v223
	v_pk_fma_f32 v[0:1], v[32:33], v[210:211], v[0:1]
	v_mfma_f32_32x32x16_bf16 v[6:21], v[94:97], v[46:49], v[6:21]
	v_max_f32_e32 v108, 0, v224
	v_max_f32_e32 v109, 0, v225
	v_pk_fma_f32 v[0:1], v[34:35], v[108:109], v[0:1]
	v_max_f32_e32 v210, 0, v226
	v_max_f32_e32 v211, 0, v227
	v_pk_fma_f32 v[0:1], v[36:37], v[210:211], v[0:1]
	v_add_f32_e32 v0, v0, v1
	v_ashrrev_i32_e32 v1, 31, v0
	v_mfma_f32_32x32x16_bf16 v[6:21], v[98:101], v[196:199], v[6:21]
	s_waitcnt vmcnt(10)
	v_add_u32_e32 v228, 0x10000, v5
	ds_read_b128 v[38:41], v228 offset:10496
	v_add_u32_e32 v228, 0x10000, v52
	ds_read_b128 v[42:45], v228 offset:10496
	v_add_u32_e32 v228, 0x10000, v55
	ds_read_b128 v[46:49], v228 offset:10496
	v_add_u32_e32 v228, 0x10000, v56
	ds_read_b128 v[196:199], v228 offset:10496
	v_or_b32_e32 v1, 0x80000000, v1
	s_cmpk_gt_i32 s11, 456
	s_cselect_b64 vcc, -1, 0
	v_xor_b32_e32 v0, v1, v0
	v_cndmask_b32_e32 v53, v123, v0, vcc
	s_nop 3
	s_waitcnt lgkmcnt(3)
	v_mfma_f32_32x32x16_bf16 v[212:227], v[70:73], v[38:41], 0
	v_max_f32_e32 v108, 0, v6
	v_max_f32_e32 v109, 0, v7
	v_pk_mul_f32 v[50:51], v[244:245], v[108:109]
	v_max_f32_e32 v210, 0, v8
	v_max_f32_e32 v211, 0, v9
	v_pk_fma_f32 v[50:51], v[246:247], v[210:211], v[50:51]
	v_max_f32_e32 v108, 0, v10
	v_max_f32_e32 v109, 0, v11
	v_pk_fma_f32 v[50:51], v[248:249], v[108:109], v[50:51]
	s_waitcnt lgkmcnt(2)
	v_mfma_f32_32x32x16_bf16 v[212:227], v[74:77], v[42:45], v[212:227]
	v_max_f32_e32 v210, 0, v12
	v_max_f32_e32 v211, 0, v13
	v_pk_fma_f32 v[50:51], v[250:251], v[210:211], v[50:51]
	v_max_f32_e32 v108, 0, v14
	v_max_f32_e32 v109, 0, v15
	v_pk_fma_f32 v[50:51], v[252:253], v[108:109], v[50:51]
	v_max_f32_e32 v210, 0, v16
	v_max_f32_e32 v211, 0, v17
	v_pk_fma_f32 v[50:51], v[254:255], v[210:211], v[50:51]
	s_waitcnt lgkmcnt(1)
	v_mfma_f32_32x32x16_bf16 v[212:227], v[78:81], v[46:49], v[212:227]
	v_max_f32_e32 v108, 0, v18
	v_max_f32_e32 v109, 0, v19
	v_pk_fma_f32 v[50:51], v[200:201], v[108:109], v[50:51]
	v_max_f32_e32 v210, 0, v20
	v_max_f32_e32 v211, 0, v21
	v_pk_fma_f32 v[50:51], v[202:203], v[210:211], v[50:51]
	v_add_f32_e32 v50, v50, v51
	v_ashrrev_i32_e32 v51, 31, v50
	s_waitcnt lgkmcnt(0)
	v_mfma_f32_32x32x16_bf16 v[212:227], v[82:85], v[196:199], v[212:227]
	v_or_b32_e32 v51, 0x80000000, v51
	s_cmpk_gt_i32 s11, 456
	s_cselect_b64 vcc, -1, 0
	v_xor_b32_e32 v50, v51, v50
	v_cndmask_b32_e32 v50, v123, v50, vcc
	global_store_dword v243, v50, s[8:9] offset:2048
	s_add_u32 s8, s8, 0x1000
	s_addc_u32 s9, s9, 0
	v_mfma_f32_32x32x16_bf16 v[6:21], v[86:89], v[38:41], 0
	s_add_i32 m0, s10, 32768
	s_nop 0
	global_load_lds_dwordx4 v102, s[6:7]
	s_add_i32 m0, s10, 33792
	s_nop 0
	global_load_lds_dwordx4 v110, s[6:7]
	s_add_i32 m0, s10, 34816
	s_nop 0
	global_load_lds_dwordx4 v112, s[6:7]
	s_add_i32 m0, s10, 35840
	s_nop 0
	global_load_lds_dwordx4 v193, s[6:7]
	s_add_u32 s6, s6, 0x8000
	s_addc_u32 s7, s7, 0
	v_max_f32_e32 v108, 0, v212
	v_max_f32_e32 v109, 0, v213
	v_pk_mul_f32 v[0:1], v[22:23], v[108:109]
	v_max_f32_e32 v210, 0, v214
	v_max_f32_e32 v211, 0, v215
	v_pk_fma_f32 v[0:1], v[24:25], v[210:211], v[0:1]
	v_max_f32_e32 v108, 0, v216
	v_max_f32_e32 v109, 0, v217
	v_pk_fma_f32 v[0:1], v[26:27], v[108:109], v[0:1]
	v_mfma_f32_32x32x16_bf16 v[6:21], v[90:93], v[42:45], v[6:21]
	v_max_f32_e32 v210, 0, v218
	v_max_f32_e32 v211, 0, v219
	v_pk_fma_f32 v[0:1], v[28:29], v[210:211], v[0:1]
	v_max_f32_e32 v108, 0, v220
	v_max_f32_e32 v109, 0, v221
	v_pk_fma_f32 v[0:1], v[30:31], v[108:109], v[0:1]
	v_max_f32_e32 v210, 0, v222
	v_max_f32_e32 v211, 0, v223
	v_pk_fma_f32 v[0:1], v[32:33], v[210:211], v[0:1]
	v_mfma_f32_32x32x16_bf16 v[6:21], v[94:97], v[46:49], v[6:21]
	v_max_f32_e32 v108, 0, v224
	v_max_f32_e32 v109, 0, v225
	v_pk_fma_f32 v[0:1], v[34:35], v[108:109], v[0:1]
	v_max_f32_e32 v210, 0, v226
	v_max_f32_e32 v211, 0, v227
	v_pk_fma_f32 v[0:1], v[36:37], v[210:211], v[0:1]
	v_add_f32_e32 v0, v0, v1
	v_ashrrev_i32_e32 v1, 31, v0
	v_mfma_f32_32x32x16_bf16 v[6:21], v[98:101], v[196:199], v[6:21]
	s_waitcnt vmcnt(10)
	v_add_u32_e32 v228, 0x10000, v5
	ds_read_b128 v[38:41], v228 offset:43264
	v_add_u32_e32 v228, 0x10000, v52
	ds_read_b128 v[42:45], v228 offset:43264
	v_add_u32_e32 v228, 0x10000, v55
	ds_read_b128 v[46:49], v228 offset:43264
	v_add_u32_e32 v228, 0x10000, v56
	ds_read_b128 v[196:199], v228 offset:43264
	v_or_b32_e32 v1, 0x80000000, v1
	s_cmpk_gt_i32 s11, 464
	s_cselect_b64 vcc, -1, 0
	v_xor_b32_e32 v0, v1, v0
	v_cndmask_b32_e32 v192, v123, v0, vcc
	s_nop 3
	s_waitcnt lgkmcnt(3)
	v_mfma_f32_32x32x16_bf16 v[212:227], v[70:73], v[38:41], 0
	v_max_f32_e32 v108, 0, v6
	v_max_f32_e32 v109, 0, v7
	v_pk_mul_f32 v[50:51], v[244:245], v[108:109]
	v_max_f32_e32 v210, 0, v8
	v_max_f32_e32 v211, 0, v9
	v_pk_fma_f32 v[50:51], v[246:247], v[210:211], v[50:51]
	v_max_f32_e32 v108, 0, v10
	v_max_f32_e32 v109, 0, v11
	v_pk_fma_f32 v[50:51], v[248:249], v[108:109], v[50:51]
	s_waitcnt lgkmcnt(2)
	v_mfma_f32_32x32x16_bf16 v[212:227], v[74:77], v[42:45], v[212:227]
	v_max_f32_e32 v210, 0, v12
	v_max_f32_e32 v211, 0, v13
	v_pk_fma_f32 v[50:51], v[250:251], v[210:211], v[50:51]
	v_max_f32_e32 v108, 0, v14
	v_max_f32_e32 v109, 0, v15
	v_pk_fma_f32 v[50:51], v[252:253], v[108:109], v[50:51]
	v_max_f32_e32 v210, 0, v16
	v_max_f32_e32 v211, 0, v17
	v_pk_fma_f32 v[50:51], v[254:255], v[210:211], v[50:51]
	s_waitcnt lgkmcnt(1)
	v_mfma_f32_32x32x16_bf16 v[212:227], v[78:81], v[46:49], v[212:227]
	v_max_f32_e32 v108, 0, v18
	v_max_f32_e32 v109, 0, v19
	v_pk_fma_f32 v[50:51], v[200:201], v[108:109], v[50:51]
	v_max_f32_e32 v210, 0, v20
	v_max_f32_e32 v211, 0, v21
	v_pk_fma_f32 v[50:51], v[202:203], v[210:211], v[50:51]
	v_add_f32_e32 v50, v50, v51
	v_ashrrev_i32_e32 v51, 31, v50
	s_waitcnt lgkmcnt(0)
	v_mfma_f32_32x32x16_bf16 v[212:227], v[82:85], v[196:199], v[212:227]
	v_or_b32_e32 v51, 0x80000000, v51
	s_cmpk_gt_i32 s11, 464
	s_cselect_b64 vcc, -1, 0
	v_xor_b32_e32 v50, v51, v50
	v_cndmask_b32_e32 v50, v123, v50, vcc
	global_store_dword v243, v50, s[8:9]
	v_mfma_f32_32x32x16_bf16 v[6:21], v[86:89], v[38:41], 0
	s_add_i32 m0, s10, 65536
	s_nop 0
	global_load_lds_dwordx4 v102, s[6:7]
	s_add_i32 m0, s10, 66560
	s_nop 0
	global_load_lds_dwordx4 v110, s[6:7]
	s_add_i32 m0, s10, 67584
	s_nop 0
	global_load_lds_dwordx4 v112, s[6:7]
	s_add_i32 m0, s10, 68608
	s_nop 0
	global_load_lds_dwordx4 v193, s[6:7]
	s_add_u32 s6, s6, 0x8000
	s_addc_u32 s7, s7, 0
	v_max_f32_e32 v108, 0, v212
	v_max_f32_e32 v109, 0, v213
	v_pk_mul_f32 v[0:1], v[22:23], v[108:109]
	v_max_f32_e32 v210, 0, v214
	v_max_f32_e32 v211, 0, v215
	v_pk_fma_f32 v[0:1], v[24:25], v[210:211], v[0:1]
	v_max_f32_e32 v108, 0, v216
	v_max_f32_e32 v109, 0, v217
	v_pk_fma_f32 v[0:1], v[26:27], v[108:109], v[0:1]
	v_mfma_f32_32x32x16_bf16 v[6:21], v[90:93], v[42:45], v[6:21]
	v_max_f32_e32 v210, 0, v218
	v_max_f32_e32 v211, 0, v219
	v_pk_fma_f32 v[0:1], v[28:29], v[210:211], v[0:1]
	v_max_f32_e32 v108, 0, v220
	v_max_f32_e32 v109, 0, v221
	v_pk_fma_f32 v[0:1], v[30:31], v[108:109], v[0:1]
	v_max_f32_e32 v210, 0, v222
	v_max_f32_e32 v211, 0, v223
	v_pk_fma_f32 v[0:1], v[32:33], v[210:211], v[0:1]
	v_mfma_f32_32x32x16_bf16 v[6:21], v[94:97], v[46:49], v[6:21]
	v_max_f32_e32 v108, 0, v224
	v_max_f32_e32 v109, 0, v225
	v_pk_fma_f32 v[0:1], v[34:35], v[108:109], v[0:1]
	v_max_f32_e32 v210, 0, v226
	v_max_f32_e32 v211, 0, v227
	v_pk_fma_f32 v[0:1], v[36:37], v[210:211], v[0:1]
	v_add_f32_e32 v0, v0, v1
	v_ashrrev_i32_e32 v1, 31, v0
	v_mfma_f32_32x32x16_bf16 v[6:21], v[98:101], v[196:199], v[6:21]
	s_waitcnt vmcnt(10)
	ds_read_b128 v[38:41], v5 offset:10496
	ds_read_b128 v[42:45], v52 offset:10496
	ds_read_b128 v[46:49], v55 offset:10496
	ds_read_b128 v[196:199], v56 offset:10496
	v_or_b32_e32 v1, 0x80000000, v1
	s_cmpk_gt_i32 s11, 472
	s_cselect_b64 vcc, -1, 0
	v_xor_b32_e32 v0, v1, v0
	v_cndmask_b32_e32 v191, v123, v0, vcc
	s_nop 3
	s_waitcnt lgkmcnt(3)
	v_mfma_f32_32x32x16_bf16 v[212:227], v[70:73], v[38:41], 0
	v_max_f32_e32 v108, 0, v6
	v_max_f32_e32 v109, 0, v7
	v_pk_mul_f32 v[50:51], v[244:245], v[108:109]
	v_max_f32_e32 v210, 0, v8
	v_max_f32_e32 v211, 0, v9
	v_pk_fma_f32 v[50:51], v[246:247], v[210:211], v[50:51]
	v_max_f32_e32 v108, 0, v10
	v_max_f32_e32 v109, 0, v11
	v_pk_fma_f32 v[50:51], v[248:249], v[108:109], v[50:51]
	s_waitcnt lgkmcnt(2)
	v_mfma_f32_32x32x16_bf16 v[212:227], v[74:77], v[42:45], v[212:227]
	v_max_f32_e32 v210, 0, v12
	v_max_f32_e32 v211, 0, v13
	v_pk_fma_f32 v[50:51], v[250:251], v[210:211], v[50:51]
	v_max_f32_e32 v108, 0, v14
	v_max_f32_e32 v109, 0, v15
	v_pk_fma_f32 v[50:51], v[252:253], v[108:109], v[50:51]
	v_max_f32_e32 v210, 0, v16
	v_max_f32_e32 v211, 0, v17
	v_pk_fma_f32 v[50:51], v[254:255], v[210:211], v[50:51]
	s_waitcnt lgkmcnt(1)
	v_mfma_f32_32x32x16_bf16 v[212:227], v[78:81], v[46:49], v[212:227]
	v_max_f32_e32 v108, 0, v18
	v_max_f32_e32 v109, 0, v19
	v_pk_fma_f32 v[50:51], v[200:201], v[108:109], v[50:51]
	v_max_f32_e32 v210, 0, v20
	v_max_f32_e32 v211, 0, v21
	v_pk_fma_f32 v[50:51], v[202:203], v[210:211], v[50:51]
	v_add_f32_e32 v50, v50, v51
	v_ashrrev_i32_e32 v51, 31, v50
	s_waitcnt lgkmcnt(0)
	v_mfma_f32_32x32x16_bf16 v[212:227], v[82:85], v[196:199], v[212:227]
	v_or_b32_e32 v51, 0x80000000, v51
	s_cmpk_gt_i32 s11, 472
	s_cselect_b64 vcc, -1, 0
	v_xor_b32_e32 v50, v51, v50
	v_cndmask_b32_e32 v50, v123, v50, vcc
	global_store_dword v243, v50, s[8:9] offset:2048
	s_add_u32 s8, s8, 0x1000
	s_addc_u32 s9, s9, 0
	v_mfma_f32_32x32x16_bf16 v[6:21], v[86:89], v[38:41], 0
	s_add_i32 m0, s10, 98304
	s_nop 0
	global_load_lds_dwordx4 v102, s[6:7]
	s_add_i32 m0, s10, 99328
	s_nop 0
	global_load_lds_dwordx4 v110, s[6:7]
	s_add_i32 m0, s10, 100352
	s_nop 0
	global_load_lds_dwordx4 v112, s[6:7]
	s_add_i32 m0, s10, 101376
	s_nop 0
	global_load_lds_dwordx4 v193, s[6:7]
	s_add_u32 s6, s6, 0x8000
	s_addc_u32 s7, s7, 0
	v_max_f32_e32 v108, 0, v212
	v_max_f32_e32 v109, 0, v213
	v_pk_mul_f32 v[0:1], v[22:23], v[108:109]
	v_max_f32_e32 v210, 0, v214
	v_max_f32_e32 v211, 0, v215
	v_pk_fma_f32 v[0:1], v[24:25], v[210:211], v[0:1]
	v_max_f32_e32 v108, 0, v216
	v_max_f32_e32 v109, 0, v217
	v_pk_fma_f32 v[0:1], v[26:27], v[108:109], v[0:1]
	v_mfma_f32_32x32x16_bf16 v[6:21], v[90:93], v[42:45], v[6:21]
	v_max_f32_e32 v210, 0, v218
	v_max_f32_e32 v211, 0, v219
	v_pk_fma_f32 v[0:1], v[28:29], v[210:211], v[0:1]
	v_max_f32_e32 v108, 0, v220
	v_max_f32_e32 v109, 0, v221
	v_pk_fma_f32 v[0:1], v[30:31], v[108:109], v[0:1]
	v_max_f32_e32 v210, 0, v222
	v_max_f32_e32 v211, 0, v223
	v_pk_fma_f32 v[0:1], v[32:33], v[210:211], v[0:1]
	v_mfma_f32_32x32x16_bf16 v[6:21], v[94:97], v[46:49], v[6:21]
	v_max_f32_e32 v108, 0, v224
	v_max_f32_e32 v109, 0, v225
	v_pk_fma_f32 v[0:1], v[34:35], v[108:109], v[0:1]
	v_max_f32_e32 v210, 0, v226
	v_max_f32_e32 v211, 0, v227
	v_pk_fma_f32 v[0:1], v[36:37], v[210:211], v[0:1]
	v_add_f32_e32 v0, v0, v1
	v_ashrrev_i32_e32 v1, 31, v0
	v_mfma_f32_32x32x16_bf16 v[6:21], v[98:101], v[196:199], v[6:21]
	s_waitcnt vmcnt(10)
	ds_read_b128 v[38:41], v5 offset:43264
	ds_read_b128 v[42:45], v52 offset:43264
	ds_read_b128 v[46:49], v55 offset:43264
	ds_read_b128 v[196:199], v56 offset:43264
	v_or_b32_e32 v1, 0x80000000, v1
	s_cmpk_gt_i32 s11, 480
	s_cselect_b64 vcc, -1, 0
	v_xor_b32_e32 v0, v1, v0
	v_cndmask_b32_e32 v3, v123, v0, vcc
	s_nop 3
	s_waitcnt lgkmcnt(3)
	v_mfma_f32_32x32x16_bf16 v[212:227], v[70:73], v[38:41], 0
	v_max_f32_e32 v108, 0, v6
	v_max_f32_e32 v109, 0, v7
	v_pk_mul_f32 v[50:51], v[244:245], v[108:109]
	v_max_f32_e32 v210, 0, v8
	v_max_f32_e32 v211, 0, v9
	v_pk_fma_f32 v[50:51], v[246:247], v[210:211], v[50:51]
	v_max_f32_e32 v108, 0, v10
	v_max_f32_e32 v109, 0, v11
	v_pk_fma_f32 v[50:51], v[248:249], v[108:109], v[50:51]
	s_waitcnt lgkmcnt(2)
	v_mfma_f32_32x32x16_bf16 v[212:227], v[74:77], v[42:45], v[212:227]
	v_max_f32_e32 v210, 0, v12
	v_max_f32_e32 v211, 0, v13
	v_pk_fma_f32 v[50:51], v[250:251], v[210:211], v[50:51]
	v_max_f32_e32 v108, 0, v14
	v_max_f32_e32 v109, 0, v15
	v_pk_fma_f32 v[50:51], v[252:253], v[108:109], v[50:51]
	v_max_f32_e32 v210, 0, v16
	v_max_f32_e32 v211, 0, v17
	v_pk_fma_f32 v[50:51], v[254:255], v[210:211], v[50:51]
	s_waitcnt lgkmcnt(1)
	v_mfma_f32_32x32x16_bf16 v[212:227], v[78:81], v[46:49], v[212:227]
	v_max_f32_e32 v108, 0, v18
	v_max_f32_e32 v109, 0, v19
	v_pk_fma_f32 v[50:51], v[200:201], v[108:109], v[50:51]
	v_max_f32_e32 v210, 0, v20
	v_max_f32_e32 v211, 0, v21
	v_pk_fma_f32 v[50:51], v[202:203], v[210:211], v[50:51]
	v_add_f32_e32 v50, v50, v51
	v_ashrrev_i32_e32 v51, 31, v50
	s_waitcnt lgkmcnt(0)
	v_mfma_f32_32x32x16_bf16 v[212:227], v[82:85], v[196:199], v[212:227]
	v_or_b32_e32 v51, 0x80000000, v51
	s_cmpk_gt_i32 s11, 480
	s_cselect_b64 vcc, -1, 0
	v_xor_b32_e32 v50, v51, v50
	v_cndmask_b32_e32 v50, v123, v50, vcc
	global_store_dword v243, v50, s[8:9]
	v_mfma_f32_32x32x16_bf16 v[6:21], v[86:89], v[38:41], 0
	s_add_i32 m0, s10, 0
	s_nop 0
	global_load_lds_dwordx4 v102, s[6:7]
	s_add_i32 m0, s10, 1024
	s_nop 0
	global_load_lds_dwordx4 v110, s[6:7]
	s_add_i32 m0, s10, 2048
	s_nop 0
	global_load_lds_dwordx4 v112, s[6:7]
	s_add_i32 m0, s10, 3072
	s_nop 0
	global_load_lds_dwordx4 v193, s[6:7]
	s_add_u32 s6, s6, 0x8000
	s_addc_u32 s7, s7, 0
	v_max_f32_e32 v108, 0, v212
	v_max_f32_e32 v109, 0, v213
	v_pk_mul_f32 v[0:1], v[22:23], v[108:109]
	v_max_f32_e32 v210, 0, v214
	v_max_f32_e32 v211, 0, v215
	v_pk_fma_f32 v[0:1], v[24:25], v[210:211], v[0:1]
	v_max_f32_e32 v108, 0, v216
	v_max_f32_e32 v109, 0, v217
	v_pk_fma_f32 v[0:1], v[26:27], v[108:109], v[0:1]
	v_mfma_f32_32x32x16_bf16 v[6:21], v[90:93], v[42:45], v[6:21]
	v_max_f32_e32 v210, 0, v218
	v_max_f32_e32 v211, 0, v219
	v_pk_fma_f32 v[0:1], v[28:29], v[210:211], v[0:1]
	v_max_f32_e32 v108, 0, v220
	v_max_f32_e32 v109, 0, v221
	v_pk_fma_f32 v[0:1], v[30:31], v[108:109], v[0:1]
	v_max_f32_e32 v210, 0, v222
	v_max_f32_e32 v211, 0, v223
	v_pk_fma_f32 v[0:1], v[32:33], v[210:211], v[0:1]
	v_mfma_f32_32x32x16_bf16 v[6:21], v[94:97], v[46:49], v[6:21]
	v_max_f32_e32 v108, 0, v224
	v_max_f32_e32 v109, 0, v225
	v_pk_fma_f32 v[0:1], v[34:35], v[108:109], v[0:1]
	v_max_f32_e32 v210, 0, v226
	v_max_f32_e32 v211, 0, v227
	v_pk_fma_f32 v[0:1], v[36:37], v[210:211], v[0:1]
	v_add_f32_e32 v0, v0, v1
	v_ashrrev_i32_e32 v1, 31, v0
	v_mfma_f32_32x32x16_bf16 v[6:21], v[98:101], v[196:199], v[6:21]
	s_waitcnt vmcnt(10)
	v_add_u32_e32 v228, 0x10000, v5
	ds_read_b128 v[38:41], v228 offset:10496
	v_add_u32_e32 v228, 0x10000, v52
	ds_read_b128 v[42:45], v228 offset:10496
	v_add_u32_e32 v228, 0x10000, v55
	ds_read_b128 v[46:49], v228 offset:10496
	v_add_u32_e32 v228, 0x10000, v56
	ds_read_b128 v[196:199], v228 offset:10496
	v_or_b32_e32 v1, 0x80000000, v1
	s_cmpk_gt_i32 s11, 488
	s_cselect_b64 vcc, -1, 0
	v_xor_b32_e32 v0, v1, v0
	v_cndmask_b32_e32 v2, v123, v0, vcc
	s_nop 3
	s_waitcnt lgkmcnt(3)
	v_mfma_f32_32x32x16_bf16 v[212:227], v[70:73], v[38:41], 0
	v_max_f32_e32 v108, 0, v6
	v_max_f32_e32 v109, 0, v7
	v_pk_mul_f32 v[50:51], v[244:245], v[108:109]
	v_max_f32_e32 v210, 0, v8
	v_max_f32_e32 v211, 0, v9
	v_pk_fma_f32 v[50:51], v[246:247], v[210:211], v[50:51]
	v_max_f32_e32 v108, 0, v10
	v_max_f32_e32 v109, 0, v11
	v_pk_fma_f32 v[50:51], v[248:249], v[108:109], v[50:51]
	s_waitcnt lgkmcnt(2)
	v_mfma_f32_32x32x16_bf16 v[212:227], v[74:77], v[42:45], v[212:227]
	v_max_f32_e32 v210, 0, v12
	v_max_f32_e32 v211, 0, v13
	v_pk_fma_f32 v[50:51], v[250:251], v[210:211], v[50:51]
	v_max_f32_e32 v108, 0, v14
	v_max_f32_e32 v109, 0, v15
	v_pk_fma_f32 v[50:51], v[252:253], v[108:109], v[50:51]
	v_max_f32_e32 v210, 0, v16
	v_max_f32_e32 v211, 0, v17
	v_pk_fma_f32 v[50:51], v[254:255], v[210:211], v[50:51]
	s_waitcnt lgkmcnt(1)
	v_mfma_f32_32x32x16_bf16 v[212:227], v[78:81], v[46:49], v[212:227]
	v_max_f32_e32 v108, 0, v18
	v_max_f32_e32 v109, 0, v19
	v_pk_fma_f32 v[50:51], v[200:201], v[108:109], v[50:51]
	v_max_f32_e32 v210, 0, v20
	v_max_f32_e32 v211, 0, v21
	v_pk_fma_f32 v[50:51], v[202:203], v[210:211], v[50:51]
	v_add_f32_e32 v50, v50, v51
	v_ashrrev_i32_e32 v51, 31, v50
	s_waitcnt lgkmcnt(0)
	v_mfma_f32_32x32x16_bf16 v[212:227], v[82:85], v[196:199], v[212:227]
	v_or_b32_e32 v51, 0x80000000, v51
	s_cmpk_gt_i32 s11, 488
	s_cselect_b64 vcc, -1, 0
	v_xor_b32_e32 v50, v51, v50
	v_cndmask_b32_e32 v50, v123, v50, vcc
	global_store_dword v243, v50, s[8:9] offset:2048
	s_add_u32 s8, s8, 0x1000
	s_addc_u32 s9, s9, 0
	v_mfma_f32_32x32x16_bf16 v[6:21], v[86:89], v[38:41], 0
	s_add_i32 m0, s10, 32768
	s_nop 0
	global_load_lds_dwordx4 v102, s[6:7]
	s_add_i32 m0, s10, 33792
	s_nop 0
	global_load_lds_dwordx4 v110, s[6:7]
	s_add_i32 m0, s10, 34816
	s_nop 0
	global_load_lds_dwordx4 v112, s[6:7]
	s_add_i32 m0, s10, 35840
	s_nop 0
	global_load_lds_dwordx4 v193, s[6:7]
	s_add_u32 s6, s6, 0x8000
	s_addc_u32 s7, s7, 0
	v_max_f32_e32 v108, 0, v212
	v_max_f32_e32 v109, 0, v213
	v_pk_mul_f32 v[0:1], v[22:23], v[108:109]
	v_max_f32_e32 v210, 0, v214
	v_max_f32_e32 v211, 0, v215
	v_pk_fma_f32 v[0:1], v[24:25], v[210:211], v[0:1]
	v_max_f32_e32 v108, 0, v216
	v_max_f32_e32 v109, 0, v217
	v_pk_fma_f32 v[0:1], v[26:27], v[108:109], v[0:1]
	v_mfma_f32_32x32x16_bf16 v[6:21], v[90:93], v[42:45], v[6:21]
	v_max_f32_e32 v210, 0, v218
	v_max_f32_e32 v211, 0, v219
	v_pk_fma_f32 v[0:1], v[28:29], v[210:211], v[0:1]
	v_max_f32_e32 v108, 0, v220
	v_max_f32_e32 v109, 0, v221
	v_pk_fma_f32 v[0:1], v[30:31], v[108:109], v[0:1]
	v_max_f32_e32 v210, 0, v222
	v_max_f32_e32 v211, 0, v223
	v_pk_fma_f32 v[0:1], v[32:33], v[210:211], v[0:1]
	v_mfma_f32_32x32x16_bf16 v[6:21], v[94:97], v[46:49], v[6:21]
	v_max_f32_e32 v108, 0, v224
	v_max_f32_e32 v109, 0, v225
	v_pk_fma_f32 v[0:1], v[34:35], v[108:109], v[0:1]
	v_max_f32_e32 v210, 0, v226
	v_max_f32_e32 v211, 0, v227
	v_pk_fma_f32 v[0:1], v[36:37], v[210:211], v[0:1]
	v_add_f32_e32 v0, v0, v1
	v_ashrrev_i32_e32 v1, 31, v0
	v_mfma_f32_32x32x16_bf16 v[6:21], v[98:101], v[196:199], v[6:21]
	s_waitcnt vmcnt(10)
	v_add_u32_e32 v228, 0x10000, v5
	ds_read_b128 v[38:41], v228 offset:43264
	v_add_u32_e32 v228, 0x10000, v52
	ds_read_b128 v[42:45], v228 offset:43264
	v_add_u32_e32 v228, 0x10000, v55
	ds_read_b128 v[46:49], v228 offset:43264
	v_add_u32_e32 v228, 0x10000, v56
	ds_read_b128 v[196:199], v228 offset:43264
	v_or_b32_e32 v1, 0x80000000, v1
	s_cmpk_gt_i32 s11, 496
	s_cselect_b64 vcc, -1, 0
	v_xor_b32_e32 v0, v1, v0
	v_cndmask_b32_e32 v4, v123, v0, vcc
	s_nop 3
	s_waitcnt lgkmcnt(3)
	v_mfma_f32_32x32x16_bf16 v[212:227], v[70:73], v[38:41], 0
	v_max_f32_e32 v108, 0, v6
	v_max_f32_e32 v109, 0, v7
	v_pk_mul_f32 v[50:51], v[244:245], v[108:109]
	v_max_f32_e32 v210, 0, v8
	v_max_f32_e32 v211, 0, v9
	v_pk_fma_f32 v[50:51], v[246:247], v[210:211], v[50:51]
	v_max_f32_e32 v108, 0, v10
	v_max_f32_e32 v109, 0, v11
	v_pk_fma_f32 v[50:51], v[248:249], v[108:109], v[50:51]
	s_waitcnt lgkmcnt(2)
	v_mfma_f32_32x32x16_bf16 v[212:227], v[74:77], v[42:45], v[212:227]
	v_max_f32_e32 v210, 0, v12
	v_max_f32_e32 v211, 0, v13
	v_pk_fma_f32 v[50:51], v[250:251], v[210:211], v[50:51]
	v_max_f32_e32 v108, 0, v14
	v_max_f32_e32 v109, 0, v15
	v_pk_fma_f32 v[50:51], v[252:253], v[108:109], v[50:51]
	v_max_f32_e32 v210, 0, v16
	v_max_f32_e32 v211, 0, v17
	v_pk_fma_f32 v[50:51], v[254:255], v[210:211], v[50:51]
	s_waitcnt lgkmcnt(1)
	v_mfma_f32_32x32x16_bf16 v[212:227], v[78:81], v[46:49], v[212:227]
	v_max_f32_e32 v108, 0, v18
	v_max_f32_e32 v109, 0, v19
	v_pk_fma_f32 v[50:51], v[200:201], v[108:109], v[50:51]
	v_max_f32_e32 v210, 0, v20
	v_max_f32_e32 v211, 0, v21
	v_pk_fma_f32 v[50:51], v[202:203], v[210:211], v[50:51]
	v_add_f32_e32 v50, v50, v51
	v_ashrrev_i32_e32 v51, 31, v50
	s_waitcnt lgkmcnt(0)
	v_mfma_f32_32x32x16_bf16 v[212:227], v[82:85], v[196:199], v[212:227]
	v_or_b32_e32 v51, 0x80000000, v51
	s_cmpk_gt_i32 s11, 496
	s_cselect_b64 vcc, -1, 0
	v_xor_b32_e32 v50, v51, v50
	v_cndmask_b32_e32 v50, v123, v50, vcc
	global_store_dword v243, v50, s[8:9]
	v_mfma_f32_32x32x16_bf16 v[6:21], v[86:89], v[38:41], 0
	s_add_i32 m0, s10, 65536
	s_nop 0
	global_load_lds_dwordx4 v102, s[6:7]
	s_add_i32 m0, s10, 66560
	s_nop 0
	global_load_lds_dwordx4 v110, s[6:7]
	s_add_i32 m0, s10, 67584
	s_nop 0
	global_load_lds_dwordx4 v112, s[6:7]
	s_add_i32 m0, s10, 68608
	s_nop 0
	global_load_lds_dwordx4 v193, s[6:7]
	s_add_u32 s6, s6, 0x8000
	s_addc_u32 s7, s7, 0
	v_max_f32_e32 v108, 0, v212
	v_max_f32_e32 v109, 0, v213
	v_pk_mul_f32 v[0:1], v[22:23], v[108:109]
	v_max_f32_e32 v210, 0, v214
	v_max_f32_e32 v211, 0, v215
	v_pk_fma_f32 v[0:1], v[24:25], v[210:211], v[0:1]
	v_max_f32_e32 v108, 0, v216
	v_max_f32_e32 v109, 0, v217
	v_pk_fma_f32 v[0:1], v[26:27], v[108:109], v[0:1]
	v_mfma_f32_32x32x16_bf16 v[6:21], v[90:93], v[42:45], v[6:21]
	v_max_f32_e32 v210, 0, v218
	v_max_f32_e32 v211, 0, v219
	v_pk_fma_f32 v[0:1], v[28:29], v[210:211], v[0:1]
	v_max_f32_e32 v108, 0, v220
	v_max_f32_e32 v109, 0, v221
	v_pk_fma_f32 v[0:1], v[30:31], v[108:109], v[0:1]
	v_max_f32_e32 v210, 0, v222
	v_max_f32_e32 v211, 0, v223
	v_pk_fma_f32 v[0:1], v[32:33], v[210:211], v[0:1]
	v_mfma_f32_32x32x16_bf16 v[6:21], v[94:97], v[46:49], v[6:21]
	v_max_f32_e32 v108, 0, v224
	v_max_f32_e32 v109, 0, v225
	v_pk_fma_f32 v[0:1], v[34:35], v[108:109], v[0:1]
	v_max_f32_e32 v210, 0, v226
	v_max_f32_e32 v211, 0, v227
	v_pk_fma_f32 v[0:1], v[36:37], v[210:211], v[0:1]
	v_add_f32_e32 v0, v0, v1
	v_ashrrev_i32_e32 v1, 31, v0
	v_mfma_f32_32x32x16_bf16 v[6:21], v[98:101], v[196:199], v[6:21]
	s_waitcnt vmcnt(10)
	ds_read_b128 v[38:41], v5 offset:10496
	ds_read_b128 v[42:45], v52 offset:10496
	ds_read_b128 v[46:49], v55 offset:10496
	ds_read_b128 v[196:199], v56 offset:10496
	v_or_b32_e32 v1, 0x80000000, v1
	s_cmpk_gt_i32 s11, 504
	s_cselect_b64 vcc, -1, 0
	v_xor_b32_e32 v0, v1, v0
	v_cndmask_b32_e32 v185, v123, v0, vcc
	s_nop 3
	v_max_f32_e32 v108, 0, v6
	v_max_f32_e32 v109, 0, v7
	v_pk_mul_f32 v[50:51], v[244:245], v[108:109]
	v_max_f32_e32 v210, 0, v8
	v_max_f32_e32 v211, 0, v9
	v_pk_fma_f32 v[50:51], v[246:247], v[210:211], v[50:51]
	v_max_f32_e32 v108, 0, v10
	v_max_f32_e32 v109, 0, v11
	v_pk_fma_f32 v[50:51], v[248:249], v[108:109], v[50:51]
	v_max_f32_e32 v210, 0, v12
	v_max_f32_e32 v211, 0, v13
	v_pk_fma_f32 v[50:51], v[250:251], v[210:211], v[50:51]
	v_max_f32_e32 v108, 0, v14
	v_max_f32_e32 v109, 0, v15
	v_pk_fma_f32 v[50:51], v[252:253], v[108:109], v[50:51]
	v_max_f32_e32 v210, 0, v16
	v_max_f32_e32 v211, 0, v17
	v_pk_fma_f32 v[50:51], v[254:255], v[210:211], v[50:51]
	v_max_f32_e32 v108, 0, v18
	v_max_f32_e32 v109, 0, v19
	v_pk_fma_f32 v[50:51], v[200:201], v[108:109], v[50:51]
	v_max_f32_e32 v210, 0, v20
	v_max_f32_e32 v211, 0, v21
	v_pk_fma_f32 v[50:51], v[202:203], v[210:211], v[50:51]
	v_add_f32_e32 v50, v50, v51
	v_ashrrev_i32_e32 v51, 31, v50
	v_or_b32_e32 v51, 0x80000000, v51
	s_cmpk_gt_i32 s11, 504
	s_cselect_b64 vcc, -1, 0
	v_xor_b32_e32 v50, v51, v50
	v_cndmask_b32_e32 v50, v123, v50, vcc
	global_store_dword v243, v50, s[8:9] offset:2048
	s_add_u32 s8, s8, 0x1000
	s_addc_u32 s9, s9, 0
	s_branch .Lix_done

.Lqk_fast:
	v_and_b32_e32 v244, 63, v194
	v_readfirstlane_b32 s89, v194
	v_lshrrev_b32_e32 v245, 3, v244
	v_lshrrev_b32_e32 v246, 4, v244
	v_and_b32_e32 v247, 7, v244
	v_xor_b32_e32 v246, v247, v246
	v_xor_b32_e32 v247, 4, v246
	s_lshr_b32 s89, s89, 6
	s_lshl_b32 s89, s89, 12
	v_lshl_add_u32 v245, v245, 7, s89
	v_lshl_add_u32 v246, v246, 4, v245
	v_lshl_add_u32 v247, v247, 4, v245
	v_add_u32_e32 v247, 0x400, v247
	v_add_u32_e32 v248, 0x800, v246
	v_add_u32_e32 v249, 0x800, v247
	s_add_i32 s88, s89, 10496
	s_mov_b32 s86, s60
	s_mov_b32 s87, s61
	s_add_i32 m0, s88, 0
	s_nop 0
	global_load_lds_dwordx4 v246, s[86:87]
	s_add_i32 m0, s88, 1024
	s_nop 0
	global_load_lds_dwordx4 v247, s[86:87]
	s_add_i32 m0, s88, 2048
	s_nop 0
	global_load_lds_dwordx4 v248, s[86:87]
	s_add_i32 m0, s88, 3072
	s_nop 0
	global_load_lds_dwordx4 v249, s[86:87]
	s_add_u32 s86, s86, 0x10000
	s_addc_u32 s87, s87, 0
	s_add_i32 m0, s88, 65536
	s_nop 0
	global_load_lds_dwordx4 v246, s[86:87]
	s_add_i32 m0, s88, 66560
	s_nop 0
	global_load_lds_dwordx4 v247, s[86:87]
	s_add_i32 m0, s88, 67584
	s_nop 0
	global_load_lds_dwordx4 v248, s[86:87]
	s_add_i32 m0, s88, 68608
	s_nop 0
	global_load_lds_dwordx4 v249, s[86:87]
	s_mov_b32 s101, 1
	v_lshlrev_b32_e32 v24, 4, v55
	v_lshl_add_u32 v25, v56, 2, s66
	ds_read_b32 v16, v25 offset:6400
	ds_read_b32 v17, v25 offset:6464
	ds_read_b32 v18, v25 offset:6528
	ds_read_b32 v19, v25 offset:6592
	s_waitcnt lgkmcnt(3)
	v_add_u32_e32 v26, s42, v16
	v_lshl_add_u32 v26, v26, 9, v24
	global_load_dwordx4 v[130:133], v26, s[44:45]
	global_load_dwordx4 v[134:137], v26, s[44:45] offset:64
	global_load_dwordx4 v[138:141], v26, s[44:45] offset:128
	global_load_dwordx4 v[142:145], v26, s[44:45] offset:192
	s_waitcnt lgkmcnt(2)
	v_add_u32_e32 v27, s42, v17
	v_lshl_add_u32 v27, v27, 9, v24
	global_load_dwordx4 v[146:149], v27, s[44:45]
	global_load_dwordx4 v[150:153], v27, s[44:45] offset:64
	global_load_dwordx4 v[154:157], v27, s[44:45] offset:128
	global_load_dwordx4 v[158:161], v27, s[44:45] offset:192
	s_waitcnt lgkmcnt(1)
	v_add_u32_e32 v28, s42, v18
	v_lshl_add_u32 v28, v28, 9, v24
	global_load_dwordx4 v[162:165], v28, s[44:45]
	global_load_dwordx4 v[166:169], v28, s[44:45] offset:64
	global_load_dwordx4 v[170:173], v28, s[44:45] offset:128
	global_load_dwordx4 v[174:177], v28, s[44:45] offset:192
	s_waitcnt lgkmcnt(0)
	v_add_u32_e32 v29, s42, v19
	v_lshl_add_u32 v29, v29, 9, v24
	global_load_dwordx4 v[178:181], v29, s[44:45]
	global_load_dwordx4 v[182:185], v29, s[44:45] offset:64
	global_load_dwordx4 v[186:189], v29, s[44:45] offset:128
	global_load_dwordx4 v[190:193], v29, s[44:45] offset:192
	ds_read_b32 v20, v25 offset:6656
	ds_read_b32 v21, v25 offset:6720
	ds_read_b32 v22, v25 offset:6784
	ds_read_b32 v23, v25 offset:6848
	s_waitcnt lgkmcnt(3)
	v_add_u32_e32 v26, s42, v20
	v_lshl_add_u32 v26, v26, 9, v24
	global_load_dwordx4 v[210:213], v26, s[44:45]
	global_load_dwordx4 v[214:217], v26, s[44:45] offset:64
	global_load_dwordx4 v[218:221], v26, s[44:45] offset:128
	global_load_dwordx4 v[222:225], v26, s[44:45] offset:192
	s_waitcnt lgkmcnt(2)
	v_add_u32_e32 v27, s42, v21
	v_lshl_add_u32 v27, v27, 9, v24
	global_load_dwordx4 v[226:229], v27, s[44:45]
	global_load_dwordx4 v[230:233], v27, s[44:45] offset:64
	global_load_dwordx4 v[234:237], v27, s[44:45] offset:128
	global_load_dwordx4 v[238:241], v27, s[44:45] offset:192
	s_waitcnt lgkmcnt(1)
	v_add_u32_e32 v28, s42, v22
	v_lshl_add_u32 v28, v28, 9, v24
	global_load_dwordx4 v[70:73], v28, s[44:45]
	global_load_dwordx4 v[74:77], v28, s[44:45] offset:64
	global_load_dwordx4 v[78:81], v28, s[44:45] offset:128
	global_load_dwordx4 v[82:85], v28, s[44:45] offset:192
	s_waitcnt lgkmcnt(0)
	v_add_u32_e32 v29, s42, v23
	v_lshl_add_u32 v29, v29, 9, v24
	global_load_dwordx4 v[196:199], v29, s[44:45]
	global_load_dwordx4 v[200:203], v29, s[44:45] offset:64
	global_load_dwordx4 v[244:247], v29, s[44:45] offset:128
	global_load_dwordx4 v[248:251], v29, s[44:45] offset:192
	v_subrev_u32_e32 v30, s80, v16
	v_max_i32_e32 v30, 0xffffff80, v30
	v_lshl_add_u32 v30, v30, 2, s72
	ds_read2st64_b32 v[40:41], v30 offset0:2 offset1:5
	ds_read2st64_b32 v[42:43], v30 offset0:8 offset1:11
	s_waitcnt vmcnt(31)
	v_mfma_f32_16x16x32_bf16 v[32:35], v[4:7], v[130:133], 0
	s_waitcnt vmcnt(30)
	v_mfma_f32_16x16x32_bf16 v[32:35], v[0:3], v[134:137], v[32:35]
	s_waitcnt vmcnt(29)
	v_mfma_f32_16x16x32_bf16 v[32:35], v[12:15], v[138:141], v[32:35]
	s_waitcnt vmcnt(28)
	v_mfma_f32_16x16x32_bf16 v[32:35], v[8:11], v[142:145], v[32:35]
	v_add_u32_e32 v30, 0, v87
	s_waitcnt lgkmcnt(0)
	s_nop 7
	v_fmamk_f32 v32, v32, 0x3db504f3, v40
	v_fmac_f32_e32 v41, 0x3db504f3, v33
	v_fmamk_f32 v34, v34, 0x3db504f3, v42
	v_fmac_f32_e32 v43, 0x3db504f3, v35
	v_mov_b32_e32 v33, v41
	v_mov_b32_e32 v35, v43
	s_mov_b64 exec, s[6:7]
	ds_write_b128 v30, v[32:35]
	s_mov_b64 exec, -1
	v_subrev_u32_e32 v30, s80, v17
	v_max_i32_e32 v30, 0xffffff80, v30
	v_lshl_add_u32 v30, v30, 2, s72
	ds_read2st64_b32 v[44:45], v30 offset0:2 offset1:5
	ds_read2st64_b32 v[46:47], v30 offset0:8 offset1:11
	s_waitcnt vmcnt(27)
	v_mfma_f32_16x16x32_bf16 v[36:39], v[4:7], v[146:149], 0
	s_waitcnt vmcnt(26)
	v_mfma_f32_16x16x32_bf16 v[36:39], v[0:3], v[150:153], v[36:39]
	s_waitcnt vmcnt(25)
	v_mfma_f32_16x16x32_bf16 v[36:39], v[12:15], v[154:157], v[36:39]
	s_waitcnt vmcnt(24)
	v_mfma_f32_16x16x32_bf16 v[36:39], v[8:11], v[158:161], v[36:39]
	v_add_u32_e32 v30, 256, v87
	s_waitcnt lgkmcnt(0)
	s_nop 7
	v_fmamk_f32 v36, v36, 0x3db504f3, v44
	v_fmac_f32_e32 v45, 0x3db504f3, v37
	v_fmamk_f32 v38, v38, 0x3db504f3, v46
	v_fmac_f32_e32 v47, 0x3db504f3, v39
	v_mov_b32_e32 v37, v45
	v_mov_b32_e32 v39, v47
	s_mov_b64 exec, s[6:7]
	ds_write_b128 v30, v[36:39]
	s_mov_b64 exec, -1
	v_subrev_u32_e32 v30, s80, v18
	v_max_i32_e32 v30, 0xffffff80, v30
	v_lshl_add_u32 v30, v30, 2, s72
	ds_read2st64_b32 v[40:41], v30 offset0:2 offset1:5
	ds_read2st64_b32 v[42:43], v30 offset0:8 offset1:11
	s_waitcnt vmcnt(23)
	v_mfma_f32_16x16x32_bf16 v[32:35], v[4:7], v[162:165], 0
	s_waitcnt vmcnt(22)
	v_mfma_f32_16x16x32_bf16 v[32:35], v[0:3], v[166:169], v[32:35]
	s_waitcnt vmcnt(21)
	v_mfma_f32_16x16x32_bf16 v[32:35], v[12:15], v[170:173], v[32:35]
	s_waitcnt vmcnt(20)
	v_mfma_f32_16x16x32_bf16 v[32:35], v[8:11], v[174:177], v[32:35]
	v_add_u32_e32 v30, 512, v87
	s_waitcnt lgkmcnt(0)
	s_nop 7
	v_fmamk_f32 v32, v32, 0x3db504f3, v40
	v_fmac_f32_e32 v41, 0x3db504f3, v33
	v_fmamk_f32 v34, v34, 0x3db504f3, v42
	v_fmac_f32_e32 v43, 0x3db504f3, v35
	v_mov_b32_e32 v33, v41
	v_mov_b32_e32 v35, v43
	s_mov_b64 exec, s[6:7]
	ds_write_b128 v30, v[32:35]
	s_mov_b64 exec, -1
	v_subrev_u32_e32 v30, s80, v19
	v_max_i32_e32 v30, 0xffffff80, v30
	v_lshl_add_u32 v30, v30, 2, s72
	ds_read2st64_b32 v[44:45], v30 offset0:2 offset1:5
	ds_read2st64_b32 v[46:47], v30 offset0:8 offset1:11
	s_waitcnt vmcnt(19)
	v_mfma_f32_16x16x32_bf16 v[36:39], v[4:7], v[178:181], 0
	s_waitcnt vmcnt(18)
	v_mfma_f32_16x16x32_bf16 v[36:39], v[0:3], v[182:185], v[36:39]
	s_waitcnt vmcnt(17)
	v_mfma_f32_16x16x32_bf16 v[36:39], v[12:15], v[186:189], v[36:39]
	s_waitcnt vmcnt(16)
	v_mfma_f32_16x16x32_bf16 v[36:39], v[8:11], v[190:193], v[36:39]
	v_add_u32_e32 v30, 768, v87
	s_waitcnt lgkmcnt(0)
	s_nop 7
	v_fmamk_f32 v36, v36, 0x3db504f3, v44
	v_fmac_f32_e32 v45, 0x3db504f3, v37
	v_fmamk_f32 v38, v38, 0x3db504f3, v46
	v_fmac_f32_e32 v47, 0x3db504f3, v39
	v_mov_b32_e32 v37, v45
	v_mov_b32_e32 v39, v47
	s_mov_b64 exec, s[6:7]
	ds_write_b128 v30, v[36:39]
	s_mov_b64 exec, -1
	ds_read_b32 v16, v25 offset:6912
	ds_read_b32 v17, v25 offset:6976
	ds_read_b32 v18, v25 offset:7040
	ds_read_b32 v19, v25 offset:7104
	s_waitcnt lgkmcnt(3)
	v_add_u32_e32 v26, s42, v16
	v_lshl_add_u32 v26, v26, 9, v24
	global_load_dwordx4 v[130:133], v26, s[44:45]
	global_load_dwordx4 v[134:137], v26, s[44:45] offset:64
	global_load_dwordx4 v[138:141], v26, s[44:45] offset:128
	global_load_dwordx4 v[142:145], v26, s[44:45] offset:192
	s_waitcnt lgkmcnt(2)
	v_add_u32_e32 v27, s42, v17
	v_lshl_add_u32 v27, v27, 9, v24
	global_load_dwordx4 v[146:149], v27, s[44:45]
	global_load_dwordx4 v[150:153], v27, s[44:45] offset:64
	global_load_dwordx4 v[154:157], v27, s[44:45] offset:128
	global_load_dwordx4 v[158:161], v27, s[44:45] offset:192
	s_waitcnt lgkmcnt(1)
	v_add_u32_e32 v28, s42, v18
	v_lshl_add_u32 v28, v28, 9, v24
	global_load_dwordx4 v[162:165], v28, s[44:45]
	global_load_dwordx4 v[166:169], v28, s[44:45] offset:64
	global_load_dwordx4 v[170:173], v28, s[44:45] offset:128
	global_load_dwordx4 v[174:177], v28, s[44:45] offset:192
	s_waitcnt lgkmcnt(0)
	v_add_u32_e32 v29, s42, v19
	v_lshl_add_u32 v29, v29, 9, v24
	global_load_dwordx4 v[178:181], v29, s[44:45]
	global_load_dwordx4 v[182:185], v29, s[44:45] offset:64
	global_load_dwordx4 v[186:189], v29, s[44:45] offset:128
	global_load_dwordx4 v[190:193], v29, s[44:45] offset:192
	v_subrev_u32_e32 v30, s80, v20
	v_max_i32_e32 v30, 0xffffff80, v30
	v_lshl_add_u32 v30, v30, 2, s72
	ds_read2st64_b32 v[40:41], v30 offset0:2 offset1:5
	ds_read2st64_b32 v[42:43], v30 offset0:8 offset1:11
	s_waitcnt vmcnt(31)
	v_mfma_f32_16x16x32_bf16 v[32:35], v[4:7], v[210:213], 0
	s_waitcnt vmcnt(30)
	v_mfma_f32_16x16x32_bf16 v[32:35], v[0:3], v[214:217], v[32:35]
	s_waitcnt vmcnt(29)
	v_mfma_f32_16x16x32_bf16 v[32:35], v[12:15], v[218:221], v[32:35]
	s_waitcnt vmcnt(28)
	v_mfma_f32_16x16x32_bf16 v[32:35], v[8:11], v[222:225], v[32:35]
	v_add_u32_e32 v30, 1024, v87
	s_waitcnt lgkmcnt(0)
	s_nop 7
	v_fmamk_f32 v32, v32, 0x3db504f3, v40
	v_fmac_f32_e32 v41, 0x3db504f3, v33
	v_fmamk_f32 v34, v34, 0x3db504f3, v42
	v_fmac_f32_e32 v43, 0x3db504f3, v35
	v_mov_b32_e32 v33, v41
	v_mov_b32_e32 v35, v43
	s_mov_b64 exec, s[6:7]
	ds_write_b128 v30, v[32:35]
	s_mov_b64 exec, -1
	v_subrev_u32_e32 v30, s80, v21
	v_max_i32_e32 v30, 0xffffff80, v30
	v_lshl_add_u32 v30, v30, 2, s72
	ds_read2st64_b32 v[44:45], v30 offset0:2 offset1:5
	ds_read2st64_b32 v[46:47], v30 offset0:8 offset1:11
	s_waitcnt vmcnt(27)
	v_mfma_f32_16x16x32_bf16 v[36:39], v[4:7], v[226:229], 0
	s_waitcnt vmcnt(26)
	v_mfma_f32_16x16x32_bf16 v[36:39], v[0:3], v[230:233], v[36:39]
	s_waitcnt vmcnt(25)
	v_mfma_f32_16x16x32_bf16 v[36:39], v[12:15], v[234:237], v[36:39]
	s_waitcnt vmcnt(24)
	v_mfma_f32_16x16x32_bf16 v[36:39], v[8:11], v[238:241], v[36:39]
	v_add_u32_e32 v30, 1280, v87
	s_waitcnt lgkmcnt(0)
	s_nop 7
	v_fmamk_f32 v36, v36, 0x3db504f3, v44
	v_fmac_f32_e32 v45, 0x3db504f3, v37
	v_fmamk_f32 v38, v38, 0x3db504f3, v46
	v_fmac_f32_e32 v47, 0x3db504f3, v39
	v_mov_b32_e32 v37, v45
	v_mov_b32_e32 v39, v47
	s_mov_b64 exec, s[6:7]
	ds_write_b128 v30, v[36:39]
	s_mov_b64 exec, -1
	v_subrev_u32_e32 v30, s80, v22
	v_max_i32_e32 v30, 0xffffff80, v30
	v_lshl_add_u32 v30, v30, 2, s72
	ds_read2st64_b32 v[40:41], v30 offset0:2 offset1:5
	ds_read2st64_b32 v[42:43], v30 offset0:8 offset1:11
	s_waitcnt vmcnt(23)
	v_mfma_f32_16x16x32_bf16 v[32:35], v[4:7], v[70:73], 0
	s_waitcnt vmcnt(22)
	v_mfma_f32_16x16x32_bf16 v[32:35], v[0:3], v[74:77], v[32:35]
	s_waitcnt vmcnt(21)
	v_mfma_f32_16x16x32_bf16 v[32:35], v[12:15], v[78:81], v[32:35]
	s_waitcnt vmcnt(20)
	v_mfma_f32_16x16x32_bf16 v[32:35], v[8:11], v[82:85], v[32:35]
	v_add_u32_e32 v30, 1536, v87
	s_waitcnt lgkmcnt(0)
	s_nop 7
	v_fmamk_f32 v32, v32, 0x3db504f3, v40
	v_fmac_f32_e32 v41, 0x3db504f3, v33
	v_fmamk_f32 v34, v34, 0x3db504f3, v42
	v_fmac_f32_e32 v43, 0x3db504f3, v35
	v_mov_b32_e32 v33, v41
	v_mov_b32_e32 v35, v43
	s_mov_b64 exec, s[6:7]
	ds_write_b128 v30, v[32:35]
	s_mov_b64 exec, -1
	v_subrev_u32_e32 v30, s80, v23
	v_max_i32_e32 v30, 0xffffff80, v30
	v_lshl_add_u32 v30, v30, 2, s72
	ds_read2st64_b32 v[44:45], v30 offset0:2 offset1:5
	ds_read2st64_b32 v[46:47], v30 offset0:8 offset1:11
	s_waitcnt vmcnt(19)
	v_mfma_f32_16x16x32_bf16 v[36:39], v[4:7], v[196:199], 0
	s_waitcnt vmcnt(18)
	v_mfma_f32_16x16x32_bf16 v[36:39], v[0:3], v[200:203], v[36:39]
	s_waitcnt vmcnt(17)
	v_mfma_f32_16x16x32_bf16 v[36:39], v[12:15], v[244:247], v[36:39]
	s_waitcnt vmcnt(16)
	v_mfma_f32_16x16x32_bf16 v[36:39], v[8:11], v[248:251], v[36:39]
	v_add_u32_e32 v30, 1792, v87
	s_waitcnt lgkmcnt(0)
	s_nop 7
	v_fmamk_f32 v36, v36, 0x3db504f3, v44
	v_fmac_f32_e32 v45, 0x3db504f3, v37
	v_fmamk_f32 v38, v38, 0x3db504f3, v46
	v_fmac_f32_e32 v47, 0x3db504f3, v39
	v_mov_b32_e32 v37, v45
	v_mov_b32_e32 v39, v47
	s_mov_b64 exec, s[6:7]
	ds_write_b128 v30, v[36:39]
	s_mov_b64 exec, -1
	ds_read_b32 v20, v25 offset:7168
	ds_read_b32 v21, v25 offset:7232
	ds_read_b32 v22, v25 offset:7296
	ds_read_b32 v23, v25 offset:7360
	s_waitcnt lgkmcnt(3)
	v_add_u32_e32 v26, s42, v20
	v_lshl_add_u32 v26, v26, 9, v24
	global_load_dwordx4 v[210:213], v26, s[44:45]
	global_load_dwordx4 v[214:217], v26, s[44:45] offset:64
	global_load_dwordx4 v[218:221], v26, s[44:45] offset:128
	global_load_dwordx4 v[222:225], v26, s[44:45] offset:192
	s_waitcnt lgkmcnt(2)
	v_add_u32_e32 v27, s42, v21
	v_lshl_add_u32 v27, v27, 9, v24
	global_load_dwordx4 v[226:229], v27, s[44:45]
	global_load_dwordx4 v[230:233], v27, s[44:45] offset:64
	global_load_dwordx4 v[234:237], v27, s[44:45] offset:128
	global_load_dwordx4 v[238:241], v27, s[44:45] offset:192
	s_waitcnt lgkmcnt(1)
	v_add_u32_e32 v28, s42, v22
	v_lshl_add_u32 v28, v28, 9, v24
	global_load_dwordx4 v[70:73], v28, s[44:45]
	global_load_dwordx4 v[74:77], v28, s[44:45] offset:64
	global_load_dwordx4 v[78:81], v28, s[44:45] offset:128
	global_load_dwordx4 v[82:85], v28, s[44:45] offset:192
	s_waitcnt lgkmcnt(0)
	v_add_u32_e32 v29, s42, v23
	v_lshl_add_u32 v29, v29, 9, v24
	global_load_dwordx4 v[196:199], v29, s[44:45]
	global_load_dwordx4 v[200:203], v29, s[44:45] offset:64
	global_load_dwordx4 v[244:247], v29, s[44:45] offset:128
	global_load_dwordx4 v[248:251], v29, s[44:45] offset:192
	v_subrev_u32_e32 v30, s80, v16
	v_max_i32_e32 v30, 0xffffff80, v30
	v_lshl_add_u32 v30, v30, 2, s72
	ds_read2st64_b32 v[40:41], v30 offset0:2 offset1:5
	ds_read2st64_b32 v[42:43], v30 offset0:8 offset1:11
	s_waitcnt vmcnt(31)
	v_mfma_f32_16x16x32_bf16 v[32:35], v[4:7], v[130:133], 0
	s_waitcnt vmcnt(30)
	v_mfma_f32_16x16x32_bf16 v[32:35], v[0:3], v[134:137], v[32:35]
	s_waitcnt vmcnt(29)
	v_mfma_f32_16x16x32_bf16 v[32:35], v[12:15], v[138:141], v[32:35]
	s_waitcnt vmcnt(28)
	v_mfma_f32_16x16x32_bf16 v[32:35], v[8:11], v[142:145], v[32:35]
	v_add_u32_e32 v30, 2048, v87
	s_waitcnt lgkmcnt(0)
	s_nop 7
	v_fmamk_f32 v32, v32, 0x3db504f3, v40
	v_fmac_f32_e32 v41, 0x3db504f3, v33
	v_fmamk_f32 v34, v34, 0x3db504f3, v42
	v_fmac_f32_e32 v43, 0x3db504f3, v35
	v_mov_b32_e32 v33, v41
	v_mov_b32_e32 v35, v43
	s_mov_b64 exec, s[6:7]
	ds_write_b128 v30, v[32:35]
	s_mov_b64 exec, -1
	v_subrev_u32_e32 v30, s80, v17
	v_max_i32_e32 v30, 0xffffff80, v30
	v_lshl_add_u32 v30, v30, 2, s72
	ds_read2st64_b32 v[44:45], v30 offset0:2 offset1:5
	ds_read2st64_b32 v[46:47], v30 offset0:8 offset1:11
	s_waitcnt vmcnt(27)
	v_mfma_f32_16x16x32_bf16 v[36:39], v[4:7], v[146:149], 0
	s_waitcnt vmcnt(26)
	v_mfma_f32_16x16x32_bf16 v[36:39], v[0:3], v[150:153], v[36:39]
	s_waitcnt vmcnt(25)
	v_mfma_f32_16x16x32_bf16 v[36:39], v[12:15], v[154:157], v[36:39]
	s_waitcnt vmcnt(24)
	v_mfma_f32_16x16x32_bf16 v[36:39], v[8:11], v[158:161], v[36:39]
	v_add_u32_e32 v30, 2304, v87
	s_waitcnt lgkmcnt(0)
	s_nop 7
	v_fmamk_f32 v36, v36, 0x3db504f3, v44
	v_fmac_f32_e32 v45, 0x3db504f3, v37
	v_fmamk_f32 v38, v38, 0x3db504f3, v46
	v_fmac_f32_e32 v47, 0x3db504f3, v39
	v_mov_b32_e32 v37, v45
	v_mov_b32_e32 v39, v47
	s_mov_b64 exec, s[6:7]
	ds_write_b128 v30, v[36:39]
	s_mov_b64 exec, -1
	v_subrev_u32_e32 v30, s80, v18
	v_max_i32_e32 v30, 0xffffff80, v30
	v_lshl_add_u32 v30, v30, 2, s72
	ds_read2st64_b32 v[40:41], v30 offset0:2 offset1:5
	ds_read2st64_b32 v[42:43], v30 offset0:8 offset1:11
	s_waitcnt vmcnt(23)
	v_mfma_f32_16x16x32_bf16 v[32:35], v[4:7], v[162:165], 0
	s_waitcnt vmcnt(22)
	v_mfma_f32_16x16x32_bf16 v[32:35], v[0:3], v[166:169], v[32:35]
	s_waitcnt vmcnt(21)
	v_mfma_f32_16x16x32_bf16 v[32:35], v[12:15], v[170:173], v[32:35]
	s_waitcnt vmcnt(20)
	v_mfma_f32_16x16x32_bf16 v[32:35], v[8:11], v[174:177], v[32:35]
	v_add_u32_e32 v30, 2560, v87
	s_waitcnt lgkmcnt(0)
	s_nop 7
	v_fmamk_f32 v32, v32, 0x3db504f3, v40
	v_fmac_f32_e32 v41, 0x3db504f3, v33
	v_fmamk_f32 v34, v34, 0x3db504f3, v42
	v_fmac_f32_e32 v43, 0x3db504f3, v35
	v_mov_b32_e32 v33, v41
	v_mov_b32_e32 v35, v43
	s_mov_b64 exec, s[6:7]
	ds_write_b128 v30, v[32:35]
	s_mov_b64 exec, -1
	v_subrev_u32_e32 v30, s80, v19
	v_max_i32_e32 v30, 0xffffff80, v30
	v_lshl_add_u32 v30, v30, 2, s72
	ds_read2st64_b32 v[44:45], v30 offset0:2 offset1:5
	ds_read2st64_b32 v[46:47], v30 offset0:8 offset1:11
	s_waitcnt vmcnt(19)
	v_mfma_f32_16x16x32_bf16 v[36:39], v[4:7], v[178:181], 0
	s_waitcnt vmcnt(18)
	v_mfma_f32_16x16x32_bf16 v[36:39], v[0:3], v[182:185], v[36:39]
	s_waitcnt vmcnt(17)
	v_mfma_f32_16x16x32_bf16 v[36:39], v[12:15], v[186:189], v[36:39]
	s_waitcnt vmcnt(16)
	v_mfma_f32_16x16x32_bf16 v[36:39], v[8:11], v[190:193], v[36:39]
	v_add_u32_e32 v30, 2816, v87
	s_waitcnt lgkmcnt(0)
	s_nop 7
	v_fmamk_f32 v36, v36, 0x3db504f3, v44
	v_fmac_f32_e32 v45, 0x3db504f3, v37
	v_fmamk_f32 v38, v38, 0x3db504f3, v46
	v_fmac_f32_e32 v47, 0x3db504f3, v39
	v_mov_b32_e32 v37, v45
	v_mov_b32_e32 v39, v47
	s_mov_b64 exec, s[6:7]
	ds_write_b128 v30, v[36:39]
	s_mov_b64 exec, -1
	v_subrev_u32_e32 v30, s80, v20
	v_max_i32_e32 v30, 0xffffff80, v30
	v_lshl_add_u32 v30, v30, 2, s72
	ds_read2st64_b32 v[40:41], v30 offset0:2 offset1:5
	ds_read2st64_b32 v[42:43], v30 offset0:8 offset1:11
	s_waitcnt vmcnt(15)
	v_mfma_f32_16x16x32_bf16 v[32:35], v[4:7], v[210:213], 0
	s_waitcnt vmcnt(14)
	v_mfma_f32_16x16x32_bf16 v[32:35], v[0:3], v[214:217], v[32:35]
	s_waitcnt vmcnt(13)
	v_mfma_f32_16x16x32_bf16 v[32:35], v[12:15], v[218:221], v[32:35]
	s_waitcnt vmcnt(12)
	v_mfma_f32_16x16x32_bf16 v[32:35], v[8:11], v[222:225], v[32:35]
	v_add_u32_e32 v30, 3072, v87
	s_waitcnt lgkmcnt(0)
	s_nop 7
	v_fmamk_f32 v32, v32, 0x3db504f3, v40
	v_fmac_f32_e32 v41, 0x3db504f3, v33
	v_fmamk_f32 v34, v34, 0x3db504f3, v42
	v_fmac_f32_e32 v43, 0x3db504f3, v35
	v_mov_b32_e32 v33, v41
	v_mov_b32_e32 v35, v43
	s_mov_b64 exec, s[6:7]
	ds_write_b128 v30, v[32:35]
	s_mov_b64 exec, -1
	v_subrev_u32_e32 v30, s80, v21
	v_max_i32_e32 v30, 0xffffff80, v30
	v_lshl_add_u32 v30, v30, 2, s72
	ds_read2st64_b32 v[44:45], v30 offset0:2 offset1:5
	ds_read2st64_b32 v[46:47], v30 offset0:8 offset1:11
	s_waitcnt vmcnt(11)
	v_mfma_f32_16x16x32_bf16 v[36:39], v[4:7], v[226:229], 0
	s_waitcnt vmcnt(10)
	v_mfma_f32_16x16x32_bf16 v[36:39], v[0:3], v[230:233], v[36:39]
	s_waitcnt vmcnt(9)
	v_mfma_f32_16x16x32_bf16 v[36:39], v[12:15], v[234:237], v[36:39]
	s_waitcnt vmcnt(8)
	v_mfma_f32_16x16x32_bf16 v[36:39], v[8:11], v[238:241], v[36:39]
	v_add_u32_e32 v30, 3328, v87
	s_waitcnt lgkmcnt(0)
	s_nop 7
	v_fmamk_f32 v36, v36, 0x3db504f3, v44
	v_fmac_f32_e32 v45, 0x3db504f3, v37
	v_fmamk_f32 v38, v38, 0x3db504f3, v46
	v_fmac_f32_e32 v47, 0x3db504f3, v39
	v_mov_b32_e32 v37, v45
	v_mov_b32_e32 v39, v47
	s_mov_b64 exec, s[6:7]
	ds_write_b128 v30, v[36:39]
	s_mov_b64 exec, -1
	v_subrev_u32_e32 v30, s80, v22
	v_max_i32_e32 v30, 0xffffff80, v30
	v_lshl_add_u32 v30, v30, 2, s72
	ds_read2st64_b32 v[40:41], v30 offset0:2 offset1:5
	ds_read2st64_b32 v[42:43], v30 offset0:8 offset1:11
	s_waitcnt vmcnt(7)
	v_mfma_f32_16x16x32_bf16 v[32:35], v[4:7], v[70:73], 0
	s_waitcnt vmcnt(6)
	v_mfma_f32_16x16x32_bf16 v[32:35], v[0:3], v[74:77], v[32:35]
	s_waitcnt vmcnt(5)
	v_mfma_f32_16x16x32_bf16 v[32:35], v[12:15], v[78:81], v[32:35]
	s_waitcnt vmcnt(4)
	v_mfma_f32_16x16x32_bf16 v[32:35], v[8:11], v[82:85], v[32:35]
	v_add_u32_e32 v30, 3584, v87
	s_waitcnt lgkmcnt(0)
	s_nop 7
	v_fmamk_f32 v32, v32, 0x3db504f3, v40
	v_fmac_f32_e32 v41, 0x3db504f3, v33
	v_fmamk_f32 v34, v34, 0x3db504f3, v42
	v_fmac_f32_e32 v43, 0x3db504f3, v35
	v_mov_b32_e32 v33, v41
	v_mov_b32_e32 v35, v43
	s_mov_b64 exec, s[6:7]
	ds_write_b128 v30, v[32:35]
	s_mov_b64 exec, -1
	v_subrev_u32_e32 v30, s80, v23
	v_max_i32_e32 v30, 0xffffff80, v30
	v_lshl_add_u32 v30, v30, 2, s72
	ds_read2st64_b32 v[44:45], v30 offset0:2 offset1:5
	ds_read2st64_b32 v[46:47], v30 offset0:8 offset1:11
	s_waitcnt vmcnt(3)
	v_mfma_f32_16x16x32_bf16 v[36:39], v[4:7], v[196:199], 0
	s_waitcnt vmcnt(2)
	v_mfma_f32_16x16x32_bf16 v[36:39], v[0:3], v[200:203], v[36:39]
	s_waitcnt vmcnt(1)
	v_mfma_f32_16x16x32_bf16 v[36:39], v[12:15], v[244:247], v[36:39]
	s_waitcnt vmcnt(0)
	v_mfma_f32_16x16x32_bf16 v[36:39], v[8:11], v[248:251], v[36:39]
	v_add_u32_e32 v30, 3840, v87
	s_waitcnt lgkmcnt(0)
	s_nop 7
	v_fmamk_f32 v36, v36, 0x3db504f3, v44
	v_fmac_f32_e32 v45, 0x3db504f3, v37
	v_fmamk_f32 v38, v38, 0x3db504f3, v46
	v_fmac_f32_e32 v47, 0x3db504f3, v39
	v_mov_b32_e32 v37, v45
	v_mov_b32_e32 v39, v47
	s_mov_b64 exec, s[6:7]
	ds_write_b128 v30, v[36:39]
	s_mov_b64 exec, -1
	s_branch .LBB0_1532
